# strategy 9 (guide 7.11): GEMM K-loop counter/exit-test scalars rotated in front of the loop-back barrier
# baseline (speedup 1.0000x reference)
; #define STAGE(P, g) do { const char* g_ = (const char*)(g); \
;         __builtin_amdgcn_global_load_lds((const unsigned*)(g_ + so0), (lds_u32*)((lds_u8*)(P) + sb0), 16, 0, 0); \
;         __builtin_amdgcn_global_load_lds((const unsigned*)(g_ + so1), (lds_u32*)((lds_u8*)(P) + sb0 + 8192), 16, 0, 0); } while (0)
; #define LDA(dst, b, h) for (int m = 0; m < 4; ++m) for (int k = 0; k < 2; ++k) \
;         dst[m][k] = *reinterpret_cast<const bf16x8*>((char*)SA(b, h) + lds_byte(wr * 64 + m * 16 + fr, k * 32 + fq * 8))
; #define LDB(dst, b, h) for (int n = 0; n < 2; ++n) for (int k = 0; k < 2; ++k) \
;         dst[n][k] = *reinterpret_cast<const bf16x8*>((char*)SB(b, h) + lds_byte(wc * 32 + n * 16 + fr, k * 32 + fq * 8))
; #define MMA(ai, bj, At_, Bt_) do { __builtin_amdgcn_s_setprio(1); \
;         for (int m = 0; m < 4; ++m) for (int n = 0; n < 2; ++n) for (int k = 0; k < 2; ++k) \
;             acc[ai][bj][m][n] = __builtin_amdgcn_mfma_f32_16x16x32_bf16(At_[m][k], Bt_[n][k], acc[ai][bj][m][n], 0, 0, 0); \
;         __builtin_amdgcn_s_setprio(0); } while (0)
; #define WAIT_V(n) asm volatile("s_waitcnt vmcnt(" #n ")" ::: "memory")
; #define WAIT_L(n) asm volatile("s_waitcnt lgkmcnt(" #n ")" ::: "memory")
; #define BAR __builtin_amdgcn_s_barrier()
; #define SCHED __builtin_amdgcn_sched_barrier(0)
; template <int EPI, int K, int LNI = -1>
; DI void ph_gemm(const Params& p, const bf16_t* __restrict__ A, const bf16_t* __restrict__ Bt, int N, float* s_aux) {
;     ...
;         for (int t = 0; t < nt; t += 2) {
;             const bool last = (t == nt - 2);
;             const bf16_t* a1 = cA + (size_t)(t + 1) * kstep;
;             const bf16_t* a2 = last ? nA : cA + (size_t)(t + 2) * kstep; const bf16_t* b2 = last ? nB : cB + (size_t)(t + 2) * kstep;
;             const bf16_t* a3 = a2 + kstep; const bf16_t* b3 = b2 + kstep;
;             LDB(B0, 0, 0); LDB(B1, 0, 1); SCHED; LDA(At, 0, 0); STAGE(SA(1, 1), a1 + hstep);
;             WAIT_V(8); WAIT_L(0); BAR; MMA(0, 0, At, B0); MMA(0, 1, At, B1); BAR; SCHED;
;             LDA(At, 0, 1); STAGE(SB(0, 0), b2); STAGE(SB(0, 1), b2 + hstep); STAGE(SA(0, 0), a2);
;             WAIT_V(8); WAIT_L(0); BAR; MMA(1, 0, At, B0); MMA(1, 1, At, B1); BAR; SCHED;
.LBB0_136:
	s_ashr_i32 s53, s52, 31
	s_lshl_b64 s[66:67], s[52:53], 19
	s_add_u32 s7, s40, s66
	s_addc_u32 s13, s41, s67
	s_ashr_i32 s61, s60, 31
	s_lshl_b64 s[70:71], s[60:61], 19
	s_add_u32 s16, s56, s70
	s_addc_u32 s17, s57, s71
	s_add_u32 s18, s56, s8
	s_addc_u32 s19, s57, s9
	s_add_u32 s20, s35, s10
	v_lshl_add_u64 v[138:139], v[134:135], 0, s[8:9]
	v_lshl_add_u64 v[140:141], v[136:137], 0, s[8:9]
	s_addc_u32 s21, s79, s11
	s_mov_b32 s22, -2
	s_mov_b64 s[8:9], 0
	ds_read_b128 v[142:145], v164
	ds_read_b128 v[178:181], v164 offset:1024
	ds_read_b128 v[182:185], v164 offset:2048
	ds_read_b128 v[186:189], v164 offset:3072
	ds_read_b128 v[190:193], v165
	ds_read_b128 v[194:197], v165 offset:1024
	ds_read_b128 v[198:201], v165 offset:2048
	ds_read_b128 v[202:205], v165 offset:3072
	s_add_u32 s10, s18, s8
	s_addc_u32 s11, s19, s9
	s_add_u32 s10, s10, 0xb840100
	s_addc_u32 s11, s11, 0
	s_add_u32 s23, s20, s8
	s_addc_u32 s24, s21, s9
	s_cmpk_eq_i32 s8, 0x700
	s_cselect_b32 s15, s13, s11
	s_cselect_b32 s14, s7, s10
	s_cselect_b32 s11, s17, s24
	s_cselect_b32 s10, s16, s23
	v_readfirstlane_b32 s23, v170
	v_lshl_add_u64 v[146:147], v[138:139], 0, s[8:9]
	s_mov_b32 m0, s23
	v_readfirstlane_b32 s23, v171
	ds_read_b128 v[206:209], v166
	ds_read_b128 v[212:215], v166 offset:1024
	ds_read_b128 v[216:219], v167
	ds_read_b128 v[220:223], v167 offset:1024
	ds_read_b128 v[224:227], v168
	ds_read_b128 v[228:231], v168 offset:1024
	ds_read_b128 v[232:235], v169
	ds_read_b128 v[236:239], v169 offset:1024
	global_load_lds_dwordx4 v[146:147], off
	v_lshl_add_u64 v[146:147], v[140:141], 0, s[8:9]
	s_mov_b32 m0, s23
	s_nop 0
	global_load_lds_dwordx4 v[146:147], off
	s_waitcnt vmcnt(8)
	s_waitcnt lgkmcnt(0)
	s_barrier
	s_setprio 1
	s_waitcnt lgkmcnt(0)
	v_mfma_f32_16x16x32_bf16 v[124:127], v[206:209], v[142:145], 0
	v_mfma_f32_16x16x32_bf16 v[120:123], v[206:209], v[182:185], 0
	v_mfma_f32_16x16x32_bf16 v[108:111], v[216:219], v[142:145], 0
	v_mfma_f32_16x16x32_bf16 v[104:107], v[216:219], v[182:185], 0
	v_mfma_f32_16x16x32_bf16 v[92:95], v[224:227], v[142:145], 0
	v_mfma_f32_16x16x32_bf16 v[88:91], v[224:227], v[182:185], 0
	v_mfma_f32_16x16x32_bf16 v[76:79], v[232:235], v[142:145], 0
	v_mfma_f32_16x16x32_bf16 v[72:75], v[232:235], v[182:185], 0
	v_mfma_f32_16x16x32_bf16 v[124:127], v[212:215], v[178:181], v[124:127]
	v_mfma_f32_16x16x32_bf16 v[120:123], v[212:215], v[186:189], v[120:123]
	v_mfma_f32_16x16x32_bf16 v[108:111], v[220:223], v[178:181], v[108:111]
	v_mfma_f32_16x16x32_bf16 v[104:107], v[220:223], v[186:189], v[104:107]
	v_mfma_f32_16x16x32_bf16 v[92:95], v[228:231], v[178:181], v[92:95]
	v_mfma_f32_16x16x32_bf16 v[88:91], v[228:231], v[186:189], v[88:91]
	v_mfma_f32_16x16x32_bf16 v[76:79], v[236:239], v[178:181], v[76:79]
	v_mfma_f32_16x16x32_bf16 v[72:75], v[236:239], v[186:189], v[72:75]
	s_setprio 0
	s_setprio 1
	v_mfma_f32_16x16x32_bf16 v[116:119], v[206:209], v[190:193], 0
	v_mfma_f32_16x16x32_bf16 v[112:115], v[206:209], v[198:201], 0
	v_mfma_f32_16x16x32_bf16 v[100:103], v[216:219], v[190:193], 0
	v_mfma_f32_16x16x32_bf16 v[96:99], v[216:219], v[198:201], 0
	v_mfma_f32_16x16x32_bf16 v[84:87], v[224:227], v[190:193], 0
	v_mfma_f32_16x16x32_bf16 v[80:83], v[224:227], v[198:201], 0
	v_mfma_f32_16x16x32_bf16 v[68:71], v[232:235], v[190:193], 0
	v_mfma_f32_16x16x32_bf16 v[64:67], v[232:235], v[198:201], 0
	v_mfma_f32_16x16x32_bf16 v[116:119], v[212:215], v[194:197], v[116:119]
	v_mfma_f32_16x16x32_bf16 v[112:115], v[212:215], v[202:205], v[112:115]
	v_mfma_f32_16x16x32_bf16 v[100:103], v[220:223], v[194:197], v[100:103]
	v_mfma_f32_16x16x32_bf16 v[96:99], v[220:223], v[202:205], v[96:99]
	v_mfma_f32_16x16x32_bf16 v[84:87], v[228:231], v[194:197], v[84:87]
	v_mfma_f32_16x16x32_bf16 v[80:83], v[228:231], v[202:205], v[80:83]
	v_mfma_f32_16x16x32_bf16 v[68:71], v[236:239], v[194:197], v[68:71]
	v_mfma_f32_16x16x32_bf16 v[64:67], v[236:239], v[202:205], v[64:67]
	s_setprio 0
	s_barrier
	v_readfirstlane_b32 s23, v148
	v_lshl_add_u64 v[146:147], s[10:11], 0, v[128:129]
	s_mov_b32 m0, s23
	v_readfirstlane_b32 s23, v149
	s_add_u32 s24, s10, 0x40000
	ds_read_b128 v[206:209], v166 offset:16384
	ds_read_b128 v[212:215], v166 offset:17408
	ds_read_b128 v[216:219], v167 offset:16384
	ds_read_b128 v[220:223], v167 offset:17408
	ds_read_b128 v[224:227], v168 offset:16384
	ds_read_b128 v[228:231], v168 offset:17408
	ds_read_b128 v[232:235], v169 offset:16384
	ds_read_b128 v[236:239], v169 offset:17408
	global_load_lds_dwordx4 v[146:147], off
	v_lshl_add_u64 v[240:241], s[10:11], 0, v[130:131]
	s_mov_b32 m0, s23
	s_addc_u32 s25, s11, 0
	v_readfirstlane_b32 s23, v150
	global_load_lds_dwordx4 v[240:241], off
	v_lshl_add_u64 v[242:243], s[24:25], 0, v[128:129]
	s_mov_b32 m0, s23
	v_readfirstlane_b32 s23, v151
	global_load_lds_dwordx4 v[242:243], off
	v_lshl_add_u64 v[242:243], s[24:25], 0, v[130:131]
	s_mov_b32 m0, s23
	v_readfirstlane_b32 s23, v152
	global_load_lds_dwordx4 v[242:243], off
	v_lshl_add_u64 v[242:243], s[14:15], 0, v[128:129]
	s_mov_b32 m0, s23
	v_readfirstlane_b32 s23, v153
	global_load_lds_dwordx4 v[242:243], off
	v_lshl_add_u64 v[244:245], s[14:15], 0, v[130:131]
	s_mov_b32 m0, s23
	s_nop 0
	global_load_lds_dwordx4 v[244:245], off
	s_waitcnt vmcnt(8)
	s_waitcnt lgkmcnt(0)
	s_barrier
; #define STAGE(P, g) do { const char* g_ = (const char*)(g); \
;         __builtin_amdgcn_global_load_lds((const unsigned*)(g_ + so0), (lds_u32*)((lds_u8*)(P) + sb0), 16, 0, 0); \
;         __builtin_amdgcn_global_load_lds((const unsigned*)(g_ + so1), (lds_u32*)((lds_u8*)(P) + sb0 + 8192), 16, 0, 0); } while (0)
; #define LDA(dst, b, h) for (int m = 0; m < 4; ++m) for (int k = 0; k < 2; ++k) \
;         dst[m][k] = *reinterpret_cast<const bf16x8*>((char*)SA(b, h) + lds_byte(wr * 64 + m * 16 + fr, k * 32 + fq * 8))
; #define LDB(dst, b, h) for (int n = 0; n < 2; ++n) for (int k = 0; k < 2; ++k) \
;         dst[n][k] = *reinterpret_cast<const bf16x8*>((char*)SB(b, h) + lds_byte(wc * 32 + n * 16 + fr, k * 32 + fq * 8))
; #define MMA(ai, bj, At_, Bt_) do { __builtin_amdgcn_s_setprio(1); \
;         for (int m = 0; m < 4; ++m) for (int n = 0; n < 2; ++n) for (int k = 0; k < 2; ++k) \
;             acc[ai][bj][m][n] = __builtin_amdgcn_mfma_f32_16x16x32_bf16(At_[m][k], Bt_[n][k], acc[ai][bj][m][n], 0, 0, 0); \
;         __builtin_amdgcn_s_setprio(0); } while (0)
; #define WAIT_V(n) asm volatile("s_waitcnt vmcnt(" #n ")" ::: "memory")
; #define WAIT_L(n) asm volatile("s_waitcnt lgkmcnt(" #n ")" ::: "memory")
; #define BAR __builtin_amdgcn_s_barrier()
; #define SCHED __builtin_amdgcn_sched_barrier(0)
; template <int EPI, int K, int LNI = -1>
; DI void ph_gemm(const Params& p, const bf16_t* __restrict__ A, const bf16_t* __restrict__ Bt, int N, float* s_aux) {
;     ...
;             WAIT_V(8); WAIT_L(0); BAR; MMA(0, 0, At, B0); MMA(0, 1, At, B1); BAR; SCHED;
;             LDA(At, 0, 1); STAGE(SB(0, 0), b2); STAGE(SB(0, 1), b2 + hstep); STAGE(SA(0, 0), a2);
;             WAIT_V(8); WAIT_L(0); BAR; MMA(1, 0, At, B0); MMA(1, 1, At, B1); BAR; SCHED;
;             LDB(B0, 1, 0); LDB(B1, 1, 1); SCHED; LDA(At, 1, 0); STAGE(SA(0, 1), a2 + hstep);
;             WAIT_V(8); WAIT_L(0); BAR; MMA(0, 0, At, B0); MMA(0, 1, At, B1); BAR; SCHED;
	s_setprio 1
	s_waitcnt lgkmcnt(0)
	v_mfma_f32_16x16x32_bf16 v[60:63], v[206:209], v[142:145], 0
	v_mfma_f32_16x16x32_bf16 v[56:59], v[206:209], v[182:185], 0
	v_mfma_f32_16x16x32_bf16 v[44:47], v[216:219], v[142:145], 0
	v_mfma_f32_16x16x32_bf16 v[40:43], v[216:219], v[182:185], 0
	v_mfma_f32_16x16x32_bf16 v[28:31], v[224:227], v[142:145], 0
	v_mfma_f32_16x16x32_bf16 v[24:27], v[224:227], v[182:185], 0
	v_mfma_f32_16x16x32_bf16 v[12:15], v[232:235], v[142:145], 0
	v_mfma_f32_16x16x32_bf16 v[8:11], v[232:235], v[182:185], 0
	v_mfma_f32_16x16x32_bf16 v[60:63], v[212:215], v[178:181], v[60:63]
	v_mfma_f32_16x16x32_bf16 v[56:59], v[212:215], v[186:189], v[56:59]
	v_mfma_f32_16x16x32_bf16 v[44:47], v[220:223], v[178:181], v[44:47]
	v_mfma_f32_16x16x32_bf16 v[40:43], v[220:223], v[186:189], v[40:43]
	v_mfma_f32_16x16x32_bf16 v[28:31], v[228:231], v[178:181], v[28:31]
	v_mfma_f32_16x16x32_bf16 v[24:27], v[228:231], v[186:189], v[24:27]
	v_mfma_f32_16x16x32_bf16 v[12:15], v[236:239], v[178:181], v[12:15]
	v_mfma_f32_16x16x32_bf16 v[8:11], v[236:239], v[186:189], v[8:11]
	s_setprio 0
	s_setprio 1
	v_mfma_f32_16x16x32_bf16 v[52:55], v[206:209], v[190:193], 0
	v_mfma_f32_16x16x32_bf16 v[48:51], v[206:209], v[198:201], 0
	v_mfma_f32_16x16x32_bf16 v[36:39], v[216:219], v[190:193], 0
	v_mfma_f32_16x16x32_bf16 v[32:35], v[216:219], v[198:201], 0
	v_mfma_f32_16x16x32_bf16 v[20:23], v[224:227], v[190:193], 0
	v_mfma_f32_16x16x32_bf16 v[16:19], v[224:227], v[198:201], 0
	v_mfma_f32_16x16x32_bf16 v[4:7], v[232:235], v[190:193], 0
	v_mfma_f32_16x16x32_bf16 v[0:3], v[232:235], v[198:201], 0
	v_mfma_f32_16x16x32_bf16 v[52:55], v[212:215], v[194:197], v[52:55]
	v_mfma_f32_16x16x32_bf16 v[48:51], v[212:215], v[202:205], v[48:51]
	v_mfma_f32_16x16x32_bf16 v[36:39], v[220:223], v[194:197], v[36:39]
	v_mfma_f32_16x16x32_bf16 v[32:35], v[220:223], v[202:205], v[32:35]
	v_mfma_f32_16x16x32_bf16 v[20:23], v[228:231], v[194:197], v[20:23]
	v_mfma_f32_16x16x32_bf16 v[16:19], v[228:231], v[202:205], v[16:19]
	v_mfma_f32_16x16x32_bf16 v[4:7], v[236:239], v[194:197], v[4:7]
	v_mfma_f32_16x16x32_bf16 v[0:3], v[236:239], v[202:205], v[0:3]
	s_setprio 0
	s_barrier
	ds_read_b128 v[142:145], v172
	ds_read_b128 v[178:181], v172 offset:1024
	ds_read_b128 v[182:185], v172 offset:2048
	ds_read_b128 v[186:189], v172 offset:3072
	ds_read_b128 v[190:193], v173
	ds_read_b128 v[194:197], v173 offset:1024
	ds_read_b128 v[198:201], v173 offset:2048
	ds_read_b128 v[202:205], v173 offset:3072
	s_add_u32 s14, s14, 0x40000
	s_addc_u32 s15, s15, 0
	v_readfirstlane_b32 s23, v154
	v_lshl_add_u64 v[246:247], s[14:15], 0, v[128:129]
	s_mov_b32 m0, s23
	ds_read_b128 v[206:209], v166 offset:32768
	ds_read_b128 v[212:215], v166 offset:33792
	ds_read_b128 v[216:219], v167 offset:32768
	ds_read_b128 v[220:223], v167 offset:33792
	ds_read_b128 v[224:227], v168 offset:32768
	ds_read_b128 v[228:231], v168 offset:33792
	ds_read_b128 v[232:235], v169 offset:32768
	ds_read_b128 v[236:239], v169 offset:33792
	global_load_lds_dwordx4 v[246:247], off
	v_lshl_add_u64 v[246:247], s[14:15], 0, v[130:131]
	v_readfirstlane_b32 s14, v155
	s_mov_b32 m0, s14
	s_nop 0
	global_load_lds_dwordx4 v[246:247], off
	s_waitcnt vmcnt(8)
	s_waitcnt lgkmcnt(0)
	s_barrier
	s_setprio 1
	s_waitcnt lgkmcnt(0)
	v_mfma_f32_16x16x32_bf16 v[124:127], v[206:209], v[142:145], v[124:127]
	v_mfma_f32_16x16x32_bf16 v[120:123], v[206:209], v[182:185], v[120:123]
	v_mfma_f32_16x16x32_bf16 v[108:111], v[216:219], v[142:145], v[108:111]
	v_mfma_f32_16x16x32_bf16 v[104:107], v[216:219], v[182:185], v[104:107]
	v_mfma_f32_16x16x32_bf16 v[92:95], v[224:227], v[142:145], v[92:95]
	v_mfma_f32_16x16x32_bf16 v[88:91], v[224:227], v[182:185], v[88:91]
	v_mfma_f32_16x16x32_bf16 v[76:79], v[232:235], v[142:145], v[76:79]
	v_mfma_f32_16x16x32_bf16 v[72:75], v[232:235], v[182:185], v[72:75]
	v_mfma_f32_16x16x32_bf16 v[124:127], v[212:215], v[178:181], v[124:127]
	v_mfma_f32_16x16x32_bf16 v[120:123], v[212:215], v[186:189], v[120:123]
	v_mfma_f32_16x16x32_bf16 v[108:111], v[220:223], v[178:181], v[108:111]
	v_mfma_f32_16x16x32_bf16 v[104:107], v[220:223], v[186:189], v[104:107]
	v_mfma_f32_16x16x32_bf16 v[92:95], v[228:231], v[178:181], v[92:95]
	v_mfma_f32_16x16x32_bf16 v[88:91], v[228:231], v[186:189], v[88:91]
	v_mfma_f32_16x16x32_bf16 v[76:79], v[236:239], v[178:181], v[76:79]
	v_mfma_f32_16x16x32_bf16 v[72:75], v[236:239], v[186:189], v[72:75]
	s_setprio 0
	s_setprio 1
	v_mfma_f32_16x16x32_bf16 v[116:119], v[206:209], v[190:193], v[116:119]
	v_mfma_f32_16x16x32_bf16 v[112:115], v[206:209], v[198:201], v[112:115]
	v_mfma_f32_16x16x32_bf16 v[100:103], v[216:219], v[190:193], v[100:103]
	v_mfma_f32_16x16x32_bf16 v[96:99], v[216:219], v[198:201], v[96:99]
	v_mfma_f32_16x16x32_bf16 v[84:87], v[224:227], v[190:193], v[84:87]
	v_mfma_f32_16x16x32_bf16 v[80:83], v[224:227], v[198:201], v[80:83]
	v_mfma_f32_16x16x32_bf16 v[68:71], v[232:235], v[190:193], v[68:71]
	v_mfma_f32_16x16x32_bf16 v[64:67], v[232:235], v[198:201], v[64:67]
	v_mfma_f32_16x16x32_bf16 v[116:119], v[212:215], v[194:197], v[116:119]
	v_mfma_f32_16x16x32_bf16 v[112:115], v[212:215], v[202:205], v[112:115]
	v_mfma_f32_16x16x32_bf16 v[100:103], v[220:223], v[194:197], v[100:103]
	v_mfma_f32_16x16x32_bf16 v[96:99], v[220:223], v[202:205], v[96:99]
	v_mfma_f32_16x16x32_bf16 v[84:87], v[228:231], v[194:197], v[84:87]
	v_mfma_f32_16x16x32_bf16 v[80:83], v[228:231], v[202:205], v[80:83]
	v_mfma_f32_16x16x32_bf16 v[68:71], v[236:239], v[194:197], v[68:71]
	v_mfma_f32_16x16x32_bf16 v[64:67], v[236:239], v[202:205], v[64:67]
	s_setprio 0
	s_barrier
; #define STAGE(P, g) do { const char* g_ = (const char*)(g); \
;         __builtin_amdgcn_global_load_lds((const unsigned*)(g_ + so0), (lds_u32*)((lds_u8*)(P) + sb0), 16, 0, 0); \
;         __builtin_amdgcn_global_load_lds((const unsigned*)(g_ + so1), (lds_u32*)((lds_u8*)(P) + sb0 + 8192), 16, 0, 0); } while (0)
; #define LDA(dst, b, h) for (int m = 0; m < 4; ++m) for (int k = 0; k < 2; ++k) \
;         dst[m][k] = *reinterpret_cast<const bf16x8*>((char*)SA(b, h) + lds_byte(wr * 64 + m * 16 + fr, k * 32 + fq * 8))
; #define LDB(dst, b, h) for (int n = 0; n < 2; ++n) for (int k = 0; k < 2; ++k) \
;         dst[n][k] = *reinterpret_cast<const bf16x8*>((char*)SB(b, h) + lds_byte(wc * 32 + n * 16 + fr, k * 32 + fq * 8))
; #define MMA(ai, bj, At_, Bt_) do { __builtin_amdgcn_s_setprio(1); \
;         for (int m = 0; m < 4; ++m) for (int n = 0; n < 2; ++n) for (int k = 0; k < 2; ++k) \
;             acc[ai][bj][m][n] = __builtin_amdgcn_mfma_f32_16x16x32_bf16(At_[m][k], Bt_[n][k], acc[ai][bj][m][n], 0, 0, 0); \
;         __builtin_amdgcn_s_setprio(0); } while (0)
; #define WAIT_V(n) asm volatile("s_waitcnt vmcnt(" #n ")" ::: "memory")
; #define WAIT_L(n) asm volatile("s_waitcnt lgkmcnt(" #n ")" ::: "memory")
; #define BAR __builtin_amdgcn_s_barrier()
; #define SCHED __builtin_amdgcn_sched_barrier(0)
; template <int EPI, int K, int LNI = -1>
; DI void ph_gemm(const Params& p, const bf16_t* __restrict__ A, const bf16_t* __restrict__ Bt, int N, float* s_aux) {
;     ...
;             LDA(At, 0, 1); STAGE(SB(0, 0), b2); STAGE(SB(0, 1), b2 + hstep); STAGE(SA(0, 0), a2);
;             WAIT_V(8); WAIT_L(0); BAR; MMA(1, 0, At, B0); MMA(1, 1, At, B1); BAR; SCHED;
;             LDB(B0, 1, 0); LDB(B1, 1, 1); SCHED; LDA(At, 1, 0); STAGE(SA(0, 1), a2 + hstep);
;             WAIT_V(8); WAIT_L(0); BAR; MMA(0, 0, At, B0); MMA(0, 1, At, B1); BAR; SCHED;
;             LDA(At, 1, 1); STAGE(SB(1, 0), b3); STAGE(SB(1, 1), b3 + hstep); STAGE(SA(1, 0), a3);
;             WAIT_V(8); WAIT_L(0); BAR; MMA(1, 0, At, B0); MMA(1, 1, At, B1); BAR; SCHED;
	v_readfirstlane_b32 s14, v156
	v_lshl_add_u64 v[146:147], v[146:147], 0, s[42:43]
	s_mov_b32 m0, s14
	v_readfirstlane_b32 s14, v157
	s_add_u32 s10, s10, 0x40080
	ds_read_b128 v[206:209], v166 offset:49152
	ds_read_b128 v[212:215], v166 offset:50176
	ds_read_b128 v[216:219], v167 offset:49152
	ds_read_b128 v[220:223], v167 offset:50176
	ds_read_b128 v[224:227], v168 offset:49152
	ds_read_b128 v[228:231], v168 offset:50176
	ds_read_b128 v[232:235], v169 offset:49152
	ds_read_b128 v[236:239], v169 offset:50176
	global_load_lds_dwordx4 v[146:147], off
	v_lshl_add_u64 v[146:147], v[240:241], 0, s[42:43]
	s_mov_b32 m0, s14
	s_addc_u32 s11, s11, 0
	v_readfirstlane_b32 s14, v160
	global_load_lds_dwordx4 v[146:147], off
	v_lshl_add_u64 v[146:147], s[10:11], 0, v[128:129]
	s_mov_b32 m0, s14
	s_nop 0
	global_load_lds_dwordx4 v[146:147], off
	v_lshl_add_u64 v[146:147], s[10:11], 0, v[130:131]
	v_readfirstlane_b32 s10, v161
	s_mov_b32 m0, s10
	v_readfirstlane_b32 s10, v158
	global_load_lds_dwordx4 v[146:147], off
	v_lshl_add_u64 v[146:147], v[242:243], 0, s[42:43]
	s_mov_b32 m0, s10
	v_readfirstlane_b32 s10, v159
	global_load_lds_dwordx4 v[146:147], off
	v_lshl_add_u64 v[146:147], v[244:245], 0, s[42:43]
	s_mov_b32 m0, s10
	s_nop 0
	global_load_lds_dwordx4 v[146:147], off
	s_waitcnt vmcnt(8)
	s_waitcnt lgkmcnt(0)
	s_barrier
	s_setprio 1
	s_waitcnt lgkmcnt(0)
	v_mfma_f32_16x16x32_bf16 v[60:63], v[206:209], v[142:145], v[60:63]
	v_mfma_f32_16x16x32_bf16 v[56:59], v[206:209], v[182:185], v[56:59]
	v_mfma_f32_16x16x32_bf16 v[44:47], v[216:219], v[142:145], v[44:47]
	v_mfma_f32_16x16x32_bf16 v[40:43], v[216:219], v[182:185], v[40:43]
	v_mfma_f32_16x16x32_bf16 v[28:31], v[224:227], v[142:145], v[28:31]
	v_mfma_f32_16x16x32_bf16 v[24:27], v[224:227], v[182:185], v[24:27]
	v_mfma_f32_16x16x32_bf16 v[12:15], v[232:235], v[142:145], v[12:15]
	v_mfma_f32_16x16x32_bf16 v[8:11], v[232:235], v[182:185], v[8:11]
	v_mfma_f32_16x16x32_bf16 v[60:63], v[212:215], v[178:181], v[60:63]
	v_mfma_f32_16x16x32_bf16 v[56:59], v[212:215], v[186:189], v[56:59]
	v_mfma_f32_16x16x32_bf16 v[44:47], v[220:223], v[178:181], v[44:47]
	v_mfma_f32_16x16x32_bf16 v[40:43], v[220:223], v[186:189], v[40:43]
	v_mfma_f32_16x16x32_bf16 v[28:31], v[228:231], v[178:181], v[28:31]
	v_mfma_f32_16x16x32_bf16 v[24:27], v[228:231], v[186:189], v[24:27]
	v_mfma_f32_16x16x32_bf16 v[12:15], v[236:239], v[178:181], v[12:15]
	v_mfma_f32_16x16x32_bf16 v[8:11], v[236:239], v[186:189], v[8:11]
	s_setprio 0
	s_setprio 1
	v_mfma_f32_16x16x32_bf16 v[52:55], v[206:209], v[190:193], v[52:55]
	v_mfma_f32_16x16x32_bf16 v[48:51], v[206:209], v[198:201], v[48:51]
	v_mfma_f32_16x16x32_bf16 v[36:39], v[216:219], v[190:193], v[36:39]
	v_mfma_f32_16x16x32_bf16 v[32:35], v[216:219], v[198:201], v[32:35]
	v_mfma_f32_16x16x32_bf16 v[20:23], v[224:227], v[190:193], v[20:23]
	v_mfma_f32_16x16x32_bf16 v[16:19], v[224:227], v[198:201], v[16:19]
	v_mfma_f32_16x16x32_bf16 v[4:7], v[232:235], v[190:193], v[4:7]
	v_mfma_f32_16x16x32_bf16 v[0:3], v[232:235], v[198:201], v[0:3]
	v_mfma_f32_16x16x32_bf16 v[52:55], v[212:215], v[194:197], v[52:55]
	v_mfma_f32_16x16x32_bf16 v[48:51], v[212:215], v[202:205], v[48:51]
	v_mfma_f32_16x16x32_bf16 v[36:39], v[220:223], v[194:197], v[36:39]
	v_mfma_f32_16x16x32_bf16 v[32:35], v[220:223], v[202:205], v[32:35]
	v_mfma_f32_16x16x32_bf16 v[20:23], v[228:231], v[194:197], v[20:23]
	v_mfma_f32_16x16x32_bf16 v[16:19], v[228:231], v[202:205], v[16:19]
	v_mfma_f32_16x16x32_bf16 v[4:7], v[236:239], v[194:197], v[4:7]
	v_mfma_f32_16x16x32_bf16 v[0:3], v[236:239], v[202:205], v[0:3]
	s_setprio 0
	s_add_i32 s22, s22, 2
	s_add_u32 s8, s8, 0x100
	s_addc_u32 s9, s9, 0
	s_cmp_gt_u32 s22, 13
	s_barrier
.LBB0_137:
	ds_read_b128 v[142:145], v164
	ds_read_b128 v[178:181], v164 offset:1024
	ds_read_b128 v[182:185], v164 offset:2048
	ds_read_b128 v[186:189], v164 offset:3072
	ds_read_b128 v[190:193], v165
	ds_read_b128 v[194:197], v165 offset:1024
	ds_read_b128 v[198:201], v165 offset:2048
	ds_read_b128 v[202:205], v165 offset:3072
	s_add_u32 s10, s18, s8
	s_addc_u32 s11, s19, s9
	s_add_u32 s10, s10, 0xb840100
	s_addc_u32 s11, s11, 0
	s_add_u32 s23, s20, s8
	s_addc_u32 s24, s21, s9
	s_cmpk_eq_i32 s8, 0x700
	s_cselect_b32 s15, s13, s11
	s_cselect_b32 s14, s7, s10
	s_cselect_b32 s11, s17, s24
	s_cselect_b32 s10, s16, s23
	v_readfirstlane_b32 s23, v170
	v_lshl_add_u64 v[146:147], v[138:139], 0, s[8:9]
	s_mov_b32 m0, s23
	v_readfirstlane_b32 s23, v171
	ds_read_b128 v[206:209], v166
	ds_read_b128 v[212:215], v166 offset:1024
	ds_read_b128 v[216:219], v167
	ds_read_b128 v[220:223], v167 offset:1024
	ds_read_b128 v[224:227], v168
	ds_read_b128 v[228:231], v168 offset:1024
	ds_read_b128 v[232:235], v169
	ds_read_b128 v[236:239], v169 offset:1024
	global_load_lds_dwordx4 v[146:147], off
	v_lshl_add_u64 v[146:147], v[140:141], 0, s[8:9]
	s_mov_b32 m0, s23
	s_nop 0
	global_load_lds_dwordx4 v[146:147], off
	s_waitcnt vmcnt(8)
	s_waitcnt lgkmcnt(0)
	s_barrier
; #define STAGE(P, g) do { const char* g_ = (const char*)(g); \
;         __builtin_amdgcn_global_load_lds((const unsigned*)(g_ + so0), (lds_u32*)((lds_u8*)(P) + sb0), 16, 0, 0); \
;         __builtin_amdgcn_global_load_lds((const unsigned*)(g_ + so1), (lds_u32*)((lds_u8*)(P) + sb0 + 8192), 16, 0, 0); } while (0)
; #define LDA(dst, b, h) for (int m = 0; m < 4; ++m) for (int k = 0; k < 2; ++k) \
;         dst[m][k] = *reinterpret_cast<const bf16x8*>((char*)SA(b, h) + lds_byte(wr * 64 + m * 16 + fr, k * 32 + fq * 8))
; #define MMA(ai, bj, At_, Bt_) do { __builtin_amdgcn_s_setprio(1); \
;         for (int m = 0; m < 4; ++m) for (int n = 0; n < 2; ++n) for (int k = 0; k < 2; ++k) \
;             acc[ai][bj][m][n] = __builtin_amdgcn_mfma_f32_16x16x32_bf16(At_[m][k], Bt_[n][k], acc[ai][bj][m][n], 0, 0, 0); \
;         __builtin_amdgcn_s_setprio(0); } while (0)
; #define WAIT_V(n) asm volatile("s_waitcnt vmcnt(" #n ")" ::: "memory")
; #define WAIT_L(n) asm volatile("s_waitcnt lgkmcnt(" #n ")" ::: "memory")
; #define BAR __builtin_amdgcn_s_barrier()
; #define SCHED __builtin_amdgcn_sched_barrier(0)
; template <int EPI, int K, int LNI = -1>
; DI void ph_gemm(const Params& p, const bf16_t* __restrict__ A, const bf16_t* __restrict__ Bt, int N, float* s_aux) {
;     ...
;             WAIT_V(8); WAIT_L(0); BAR; MMA(0, 0, At, B0); MMA(0, 1, At, B1); BAR; SCHED;
;             LDA(At, 0, 1); STAGE(SB(0, 0), b2); STAGE(SB(0, 1), b2 + hstep); STAGE(SA(0, 0), a2);
;             WAIT_V(8); WAIT_L(0); BAR; MMA(1, 0, At, B0); MMA(1, 1, At, B1); BAR; SCHED;
	s_setprio 1
	s_waitcnt lgkmcnt(0)
	v_mfma_f32_16x16x32_bf16 v[124:127], v[206:209], v[142:145], v[124:127]
	v_mfma_f32_16x16x32_bf16 v[120:123], v[206:209], v[182:185], v[120:123]
	v_mfma_f32_16x16x32_bf16 v[108:111], v[216:219], v[142:145], v[108:111]
	v_mfma_f32_16x16x32_bf16 v[104:107], v[216:219], v[182:185], v[104:107]
	v_mfma_f32_16x16x32_bf16 v[92:95], v[224:227], v[142:145], v[92:95]
	v_mfma_f32_16x16x32_bf16 v[88:91], v[224:227], v[182:185], v[88:91]
	v_mfma_f32_16x16x32_bf16 v[76:79], v[232:235], v[142:145], v[76:79]
	v_mfma_f32_16x16x32_bf16 v[72:75], v[232:235], v[182:185], v[72:75]
	v_mfma_f32_16x16x32_bf16 v[124:127], v[212:215], v[178:181], v[124:127]
	v_mfma_f32_16x16x32_bf16 v[120:123], v[212:215], v[186:189], v[120:123]
	v_mfma_f32_16x16x32_bf16 v[108:111], v[220:223], v[178:181], v[108:111]
	v_mfma_f32_16x16x32_bf16 v[104:107], v[220:223], v[186:189], v[104:107]
	v_mfma_f32_16x16x32_bf16 v[92:95], v[228:231], v[178:181], v[92:95]
	v_mfma_f32_16x16x32_bf16 v[88:91], v[228:231], v[186:189], v[88:91]
	v_mfma_f32_16x16x32_bf16 v[76:79], v[236:239], v[178:181], v[76:79]
	v_mfma_f32_16x16x32_bf16 v[72:75], v[236:239], v[186:189], v[72:75]
	s_setprio 0
	s_setprio 1
	v_mfma_f32_16x16x32_bf16 v[116:119], v[206:209], v[190:193], v[116:119]
	v_mfma_f32_16x16x32_bf16 v[112:115], v[206:209], v[198:201], v[112:115]
	v_mfma_f32_16x16x32_bf16 v[100:103], v[216:219], v[190:193], v[100:103]
	v_mfma_f32_16x16x32_bf16 v[96:99], v[216:219], v[198:201], v[96:99]
	v_mfma_f32_16x16x32_bf16 v[84:87], v[224:227], v[190:193], v[84:87]
	v_mfma_f32_16x16x32_bf16 v[80:83], v[224:227], v[198:201], v[80:83]
	v_mfma_f32_16x16x32_bf16 v[68:71], v[232:235], v[190:193], v[68:71]
	v_mfma_f32_16x16x32_bf16 v[64:67], v[232:235], v[198:201], v[64:67]
	v_mfma_f32_16x16x32_bf16 v[116:119], v[212:215], v[194:197], v[116:119]
	v_mfma_f32_16x16x32_bf16 v[112:115], v[212:215], v[202:205], v[112:115]
	v_mfma_f32_16x16x32_bf16 v[100:103], v[220:223], v[194:197], v[100:103]
	v_mfma_f32_16x16x32_bf16 v[96:99], v[220:223], v[202:205], v[96:99]
	v_mfma_f32_16x16x32_bf16 v[84:87], v[228:231], v[194:197], v[84:87]
	v_mfma_f32_16x16x32_bf16 v[80:83], v[228:231], v[202:205], v[80:83]
	v_mfma_f32_16x16x32_bf16 v[68:71], v[236:239], v[194:197], v[68:71]
	v_mfma_f32_16x16x32_bf16 v[64:67], v[236:239], v[202:205], v[64:67]
	s_setprio 0
	s_barrier
	v_readfirstlane_b32 s23, v148
	v_lshl_add_u64 v[146:147], s[10:11], 0, v[128:129]
	s_mov_b32 m0, s23
	v_readfirstlane_b32 s23, v149
	s_add_u32 s24, s10, 0x40000
	ds_read_b128 v[206:209], v166 offset:16384
	ds_read_b128 v[212:215], v166 offset:17408
	ds_read_b128 v[216:219], v167 offset:16384
	ds_read_b128 v[220:223], v167 offset:17408
	ds_read_b128 v[224:227], v168 offset:16384
	ds_read_b128 v[228:231], v168 offset:17408
	ds_read_b128 v[232:235], v169 offset:16384
	ds_read_b128 v[236:239], v169 offset:17408
	global_load_lds_dwordx4 v[146:147], off
	v_lshl_add_u64 v[240:241], s[10:11], 0, v[130:131]
	s_mov_b32 m0, s23
	s_addc_u32 s25, s11, 0
	v_readfirstlane_b32 s23, v150
	global_load_lds_dwordx4 v[240:241], off
	v_lshl_add_u64 v[242:243], s[24:25], 0, v[128:129]
	s_mov_b32 m0, s23
	v_readfirstlane_b32 s23, v151
	global_load_lds_dwordx4 v[242:243], off
	v_lshl_add_u64 v[242:243], s[24:25], 0, v[130:131]
	s_mov_b32 m0, s23
	v_readfirstlane_b32 s23, v152
	global_load_lds_dwordx4 v[242:243], off
	v_lshl_add_u64 v[242:243], s[14:15], 0, v[128:129]
	s_mov_b32 m0, s23
	v_readfirstlane_b32 s23, v153
	global_load_lds_dwordx4 v[242:243], off
	v_lshl_add_u64 v[244:245], s[14:15], 0, v[130:131]
	s_mov_b32 m0, s23
	s_nop 0
	global_load_lds_dwordx4 v[244:245], off
	s_waitcnt vmcnt(8)
	s_waitcnt lgkmcnt(0)
	s_barrier
	s_setprio 1
	s_waitcnt lgkmcnt(0)
	v_mfma_f32_16x16x32_bf16 v[60:63], v[206:209], v[142:145], v[60:63]
	v_mfma_f32_16x16x32_bf16 v[56:59], v[206:209], v[182:185], v[56:59]
	v_mfma_f32_16x16x32_bf16 v[44:47], v[216:219], v[142:145], v[44:47]
	v_mfma_f32_16x16x32_bf16 v[40:43], v[216:219], v[182:185], v[40:43]
	v_mfma_f32_16x16x32_bf16 v[28:31], v[224:227], v[142:145], v[28:31]
	v_mfma_f32_16x16x32_bf16 v[24:27], v[224:227], v[182:185], v[24:27]
	v_mfma_f32_16x16x32_bf16 v[12:15], v[232:235], v[142:145], v[12:15]
	v_mfma_f32_16x16x32_bf16 v[8:11], v[232:235], v[182:185], v[8:11]
	v_mfma_f32_16x16x32_bf16 v[60:63], v[212:215], v[178:181], v[60:63]
	v_mfma_f32_16x16x32_bf16 v[56:59], v[212:215], v[186:189], v[56:59]
	v_mfma_f32_16x16x32_bf16 v[44:47], v[220:223], v[178:181], v[44:47]
	v_mfma_f32_16x16x32_bf16 v[40:43], v[220:223], v[186:189], v[40:43]
	v_mfma_f32_16x16x32_bf16 v[28:31], v[228:231], v[178:181], v[28:31]
	v_mfma_f32_16x16x32_bf16 v[24:27], v[228:231], v[186:189], v[24:27]
	v_mfma_f32_16x16x32_bf16 v[12:15], v[236:239], v[178:181], v[12:15]
	v_mfma_f32_16x16x32_bf16 v[8:11], v[236:239], v[186:189], v[8:11]
	s_setprio 0
	s_setprio 1
	v_mfma_f32_16x16x32_bf16 v[52:55], v[206:209], v[190:193], v[52:55]
	v_mfma_f32_16x16x32_bf16 v[48:51], v[206:209], v[198:201], v[48:51]
	v_mfma_f32_16x16x32_bf16 v[36:39], v[216:219], v[190:193], v[36:39]
	v_mfma_f32_16x16x32_bf16 v[32:35], v[216:219], v[198:201], v[32:35]
	v_mfma_f32_16x16x32_bf16 v[20:23], v[224:227], v[190:193], v[20:23]
	v_mfma_f32_16x16x32_bf16 v[16:19], v[224:227], v[198:201], v[16:19]
	v_mfma_f32_16x16x32_bf16 v[4:7], v[232:235], v[190:193], v[4:7]
	v_mfma_f32_16x16x32_bf16 v[0:3], v[232:235], v[198:201], v[0:3]
	v_mfma_f32_16x16x32_bf16 v[52:55], v[212:215], v[194:197], v[52:55]
	v_mfma_f32_16x16x32_bf16 v[48:51], v[212:215], v[202:205], v[48:51]
	v_mfma_f32_16x16x32_bf16 v[36:39], v[220:223], v[194:197], v[36:39]
	v_mfma_f32_16x16x32_bf16 v[32:35], v[220:223], v[202:205], v[32:35]
	v_mfma_f32_16x16x32_bf16 v[20:23], v[228:231], v[194:197], v[20:23]
	v_mfma_f32_16x16x32_bf16 v[16:19], v[228:231], v[202:205], v[16:19]
	v_mfma_f32_16x16x32_bf16 v[4:7], v[236:239], v[194:197], v[4:7]
	v_mfma_f32_16x16x32_bf16 v[0:3], v[236:239], v[202:205], v[0:3]
	s_setprio 0
	s_barrier
; #define STAGE(P, g) do { const char* g_ = (const char*)(g); \
;         __builtin_amdgcn_global_load_lds((const unsigned*)(g_ + so0), (lds_u32*)((lds_u8*)(P) + sb0), 16, 0, 0); \
;         __builtin_amdgcn_global_load_lds((const unsigned*)(g_ + so1), (lds_u32*)((lds_u8*)(P) + sb0 + 8192), 16, 0, 0); } while (0)
; #define LDA(dst, b, h) for (int m = 0; m < 4; ++m) for (int k = 0; k < 2; ++k) \
;         dst[m][k] = *reinterpret_cast<const bf16x8*>((char*)SA(b, h) + lds_byte(wr * 64 + m * 16 + fr, k * 32 + fq * 8))
; #define LDB(dst, b, h) for (int n = 0; n < 2; ++n) for (int k = 0; k < 2; ++k) \
;         dst[n][k] = *reinterpret_cast<const bf16x8*>((char*)SB(b, h) + lds_byte(wc * 32 + n * 16 + fr, k * 32 + fq * 8))
; #define MMA(ai, bj, At_, Bt_) do { __builtin_amdgcn_s_setprio(1); \
;         for (int m = 0; m < 4; ++m) for (int n = 0; n < 2; ++n) for (int k = 0; k < 2; ++k) \
;             acc[ai][bj][m][n] = __builtin_amdgcn_mfma_f32_16x16x32_bf16(At_[m][k], Bt_[n][k], acc[ai][bj][m][n], 0, 0, 0); \
;         __builtin_amdgcn_s_setprio(0); } while (0)
; #define WAIT_V(n) asm volatile("s_waitcnt vmcnt(" #n ")" ::: "memory")
; #define WAIT_L(n) asm volatile("s_waitcnt lgkmcnt(" #n ")" ::: "memory")
; #define BAR __builtin_amdgcn_s_barrier()
; #define SCHED __builtin_amdgcn_sched_barrier(0)
; template <int EPI, int K, int LNI = -1>
; DI void ph_gemm(const Params& p, const bf16_t* __restrict__ A, const bf16_t* __restrict__ Bt, int N, float* s_aux) {
;     ...
;             LDB(B0, 1, 0); LDB(B1, 1, 1); SCHED; LDA(At, 1, 0); STAGE(SA(0, 1), a2 + hstep);
;             WAIT_V(8); WAIT_L(0); BAR; MMA(0, 0, At, B0); MMA(0, 1, At, B1); BAR; SCHED;
	ds_read_b128 v[142:145], v172
	ds_read_b128 v[178:181], v172 offset:1024
	ds_read_b128 v[182:185], v172 offset:2048
	ds_read_b128 v[186:189], v172 offset:3072
	ds_read_b128 v[190:193], v173
	ds_read_b128 v[194:197], v173 offset:1024
	ds_read_b128 v[198:201], v173 offset:2048
	ds_read_b128 v[202:205], v173 offset:3072
	s_add_u32 s14, s14, 0x40000
	s_addc_u32 s15, s15, 0
	v_readfirstlane_b32 s23, v154
	v_lshl_add_u64 v[246:247], s[14:15], 0, v[128:129]
	s_mov_b32 m0, s23
	ds_read_b128 v[206:209], v166 offset:32768
	ds_read_b128 v[212:215], v166 offset:33792
	ds_read_b128 v[216:219], v167 offset:32768
	ds_read_b128 v[220:223], v167 offset:33792
	ds_read_b128 v[224:227], v168 offset:32768
	ds_read_b128 v[228:231], v168 offset:33792
	ds_read_b128 v[232:235], v169 offset:32768
	ds_read_b128 v[236:239], v169 offset:33792
	global_load_lds_dwordx4 v[246:247], off
	v_lshl_add_u64 v[246:247], s[14:15], 0, v[130:131]
	v_readfirstlane_b32 s14, v155
	s_mov_b32 m0, s14
	s_nop 0
	global_load_lds_dwordx4 v[246:247], off
	s_waitcnt vmcnt(8)
	s_waitcnt lgkmcnt(0)
	s_barrier
	s_setprio 1
	s_waitcnt lgkmcnt(0)
	v_mfma_f32_16x16x32_bf16 v[124:127], v[206:209], v[142:145], v[124:127]
	v_mfma_f32_16x16x32_bf16 v[120:123], v[206:209], v[182:185], v[120:123]
	v_mfma_f32_16x16x32_bf16 v[108:111], v[216:219], v[142:145], v[108:111]
	v_mfma_f32_16x16x32_bf16 v[104:107], v[216:219], v[182:185], v[104:107]
	v_mfma_f32_16x16x32_bf16 v[92:95], v[224:227], v[142:145], v[92:95]
	v_mfma_f32_16x16x32_bf16 v[88:91], v[224:227], v[182:185], v[88:91]
	v_mfma_f32_16x16x32_bf16 v[76:79], v[232:235], v[142:145], v[76:79]
	v_mfma_f32_16x16x32_bf16 v[72:75], v[232:235], v[182:185], v[72:75]
	v_mfma_f32_16x16x32_bf16 v[124:127], v[212:215], v[178:181], v[124:127]
	v_mfma_f32_16x16x32_bf16 v[120:123], v[212:215], v[186:189], v[120:123]
	v_mfma_f32_16x16x32_bf16 v[108:111], v[220:223], v[178:181], v[108:111]
	v_mfma_f32_16x16x32_bf16 v[104:107], v[220:223], v[186:189], v[104:107]
	v_mfma_f32_16x16x32_bf16 v[92:95], v[228:231], v[178:181], v[92:95]
	v_mfma_f32_16x16x32_bf16 v[88:91], v[228:231], v[186:189], v[88:91]
	v_mfma_f32_16x16x32_bf16 v[76:79], v[236:239], v[178:181], v[76:79]
	v_mfma_f32_16x16x32_bf16 v[72:75], v[236:239], v[186:189], v[72:75]
	s_setprio 0
	s_setprio 1
	v_mfma_f32_16x16x32_bf16 v[116:119], v[206:209], v[190:193], v[116:119]
	v_mfma_f32_16x16x32_bf16 v[112:115], v[206:209], v[198:201], v[112:115]
	v_mfma_f32_16x16x32_bf16 v[100:103], v[216:219], v[190:193], v[100:103]
	v_mfma_f32_16x16x32_bf16 v[96:99], v[216:219], v[198:201], v[96:99]
	v_mfma_f32_16x16x32_bf16 v[84:87], v[224:227], v[190:193], v[84:87]
	v_mfma_f32_16x16x32_bf16 v[80:83], v[224:227], v[198:201], v[80:83]
	v_mfma_f32_16x16x32_bf16 v[68:71], v[232:235], v[190:193], v[68:71]
	v_mfma_f32_16x16x32_bf16 v[64:67], v[232:235], v[198:201], v[64:67]
	v_mfma_f32_16x16x32_bf16 v[116:119], v[212:215], v[194:197], v[116:119]
	v_mfma_f32_16x16x32_bf16 v[112:115], v[212:215], v[202:205], v[112:115]
	v_mfma_f32_16x16x32_bf16 v[100:103], v[220:223], v[194:197], v[100:103]
	v_mfma_f32_16x16x32_bf16 v[96:99], v[220:223], v[202:205], v[96:99]
	v_mfma_f32_16x16x32_bf16 v[84:87], v[228:231], v[194:197], v[84:87]
	v_mfma_f32_16x16x32_bf16 v[80:83], v[228:231], v[202:205], v[80:83]
	v_mfma_f32_16x16x32_bf16 v[68:71], v[236:239], v[194:197], v[68:71]
	v_mfma_f32_16x16x32_bf16 v[64:67], v[236:239], v[202:205], v[64:67]
	s_setprio 0
	s_barrier
; #define STAGE(P, g) do { const char* g_ = (const char*)(g); \
;         __builtin_amdgcn_global_load_lds((const unsigned*)(g_ + so0), (lds_u32*)((lds_u8*)(P) + sb0), 16, 0, 0); \
;         __builtin_amdgcn_global_load_lds((const unsigned*)(g_ + so1), (lds_u32*)((lds_u8*)(P) + sb0 + 8192), 16, 0, 0); } while (0)
; #define LDA(dst, b, h) for (int m = 0; m < 4; ++m) for (int k = 0; k < 2; ++k) \
;         dst[m][k] = *reinterpret_cast<const bf16x8*>((char*)SA(b, h) + lds_byte(wr * 64 + m * 16 + fr, k * 32 + fq * 8))
; #define MMA(ai, bj, At_, Bt_) do { __builtin_amdgcn_s_setprio(1); \
;         for (int m = 0; m < 4; ++m) for (int n = 0; n < 2; ++n) for (int k = 0; k < 2; ++k) \
;             acc[ai][bj][m][n] = __builtin_amdgcn_mfma_f32_16x16x32_bf16(At_[m][k], Bt_[n][k], acc[ai][bj][m][n], 0, 0, 0); \
;         __builtin_amdgcn_s_setprio(0); } while (0)
; #define WAIT_V(n) asm volatile("s_waitcnt vmcnt(" #n ")" ::: "memory")
; #define WAIT_L(n) asm volatile("s_waitcnt lgkmcnt(" #n ")" ::: "memory")
; #define BAR __builtin_amdgcn_s_barrier()
; #define SCHED __builtin_amdgcn_sched_barrier(0)
; template <int EPI, int K, int LNI = -1>
; DI void ph_gemm(const Params& p, const bf16_t* __restrict__ A, const bf16_t* __restrict__ Bt, int N, float* s_aux) {
;     ...
;             LDA(At, 1, 1); STAGE(SB(1, 0), b3); STAGE(SB(1, 1), b3 + hstep); STAGE(SA(1, 0), a3);
;             WAIT_V(8); WAIT_L(0); BAR; MMA(1, 0, At, B0); MMA(1, 1, At, B1); BAR; SCHED;
;         }
;         if (wr == 0) BAR;
	v_readfirstlane_b32 s14, v156
	v_lshl_add_u64 v[146:147], v[146:147], 0, s[42:43]
	s_mov_b32 m0, s14
	v_readfirstlane_b32 s14, v157
	s_add_u32 s10, s10, 0x40080
	ds_read_b128 v[206:209], v166 offset:49152
	ds_read_b128 v[212:215], v166 offset:50176
	ds_read_b128 v[216:219], v167 offset:49152
	ds_read_b128 v[220:223], v167 offset:50176
	ds_read_b128 v[224:227], v168 offset:49152
	ds_read_b128 v[228:231], v168 offset:50176
	ds_read_b128 v[232:235], v169 offset:49152
	ds_read_b128 v[236:239], v169 offset:50176
	global_load_lds_dwordx4 v[146:147], off
	v_lshl_add_u64 v[146:147], v[240:241], 0, s[42:43]
	s_mov_b32 m0, s14
	s_addc_u32 s11, s11, 0
	v_readfirstlane_b32 s14, v160
	global_load_lds_dwordx4 v[146:147], off
	v_lshl_add_u64 v[146:147], s[10:11], 0, v[128:129]
	s_mov_b32 m0, s14
	s_nop 0
	global_load_lds_dwordx4 v[146:147], off
	v_lshl_add_u64 v[146:147], s[10:11], 0, v[130:131]
	v_readfirstlane_b32 s10, v161
	s_mov_b32 m0, s10
	v_readfirstlane_b32 s10, v158
	global_load_lds_dwordx4 v[146:147], off
	v_lshl_add_u64 v[146:147], v[242:243], 0, s[42:43]
	s_mov_b32 m0, s10
	v_readfirstlane_b32 s10, v159
	global_load_lds_dwordx4 v[146:147], off
	v_lshl_add_u64 v[146:147], v[244:245], 0, s[42:43]
	s_mov_b32 m0, s10
	s_nop 0
	global_load_lds_dwordx4 v[146:147], off
	s_waitcnt vmcnt(8)
	s_waitcnt lgkmcnt(0)
	s_barrier
	s_setprio 1
	s_waitcnt lgkmcnt(0)
	v_mfma_f32_16x16x32_bf16 v[60:63], v[206:209], v[142:145], v[60:63]
	v_mfma_f32_16x16x32_bf16 v[56:59], v[206:209], v[182:185], v[56:59]
	v_mfma_f32_16x16x32_bf16 v[44:47], v[216:219], v[142:145], v[44:47]
	v_mfma_f32_16x16x32_bf16 v[40:43], v[216:219], v[182:185], v[40:43]
	v_mfma_f32_16x16x32_bf16 v[28:31], v[224:227], v[142:145], v[28:31]
	v_mfma_f32_16x16x32_bf16 v[24:27], v[224:227], v[182:185], v[24:27]
	v_mfma_f32_16x16x32_bf16 v[12:15], v[232:235], v[142:145], v[12:15]
	v_mfma_f32_16x16x32_bf16 v[8:11], v[232:235], v[182:185], v[8:11]
	v_mfma_f32_16x16x32_bf16 v[60:63], v[212:215], v[178:181], v[60:63]
	v_mfma_f32_16x16x32_bf16 v[56:59], v[212:215], v[186:189], v[56:59]
	v_mfma_f32_16x16x32_bf16 v[44:47], v[220:223], v[178:181], v[44:47]
	v_mfma_f32_16x16x32_bf16 v[40:43], v[220:223], v[186:189], v[40:43]
	v_mfma_f32_16x16x32_bf16 v[28:31], v[228:231], v[178:181], v[28:31]
	v_mfma_f32_16x16x32_bf16 v[24:27], v[228:231], v[186:189], v[24:27]
	v_mfma_f32_16x16x32_bf16 v[12:15], v[236:239], v[178:181], v[12:15]
	v_mfma_f32_16x16x32_bf16 v[8:11], v[236:239], v[186:189], v[8:11]
	s_setprio 0
	s_setprio 1
	v_mfma_f32_16x16x32_bf16 v[52:55], v[206:209], v[190:193], v[52:55]
	v_mfma_f32_16x16x32_bf16 v[48:51], v[206:209], v[198:201], v[48:51]
	v_mfma_f32_16x16x32_bf16 v[36:39], v[216:219], v[190:193], v[36:39]
	v_mfma_f32_16x16x32_bf16 v[32:35], v[216:219], v[198:201], v[32:35]
	v_mfma_f32_16x16x32_bf16 v[20:23], v[224:227], v[190:193], v[20:23]
	v_mfma_f32_16x16x32_bf16 v[16:19], v[224:227], v[198:201], v[16:19]
	v_mfma_f32_16x16x32_bf16 v[4:7], v[232:235], v[190:193], v[4:7]
	v_mfma_f32_16x16x32_bf16 v[0:3], v[232:235], v[198:201], v[0:3]
	v_mfma_f32_16x16x32_bf16 v[52:55], v[212:215], v[194:197], v[52:55]
	v_mfma_f32_16x16x32_bf16 v[48:51], v[212:215], v[202:205], v[48:51]
	v_mfma_f32_16x16x32_bf16 v[36:39], v[220:223], v[194:197], v[36:39]
	v_mfma_f32_16x16x32_bf16 v[32:35], v[220:223], v[202:205], v[32:35]
	v_mfma_f32_16x16x32_bf16 v[20:23], v[228:231], v[194:197], v[20:23]
	v_mfma_f32_16x16x32_bf16 v[16:19], v[228:231], v[202:205], v[16:19]
	v_mfma_f32_16x16x32_bf16 v[4:7], v[236:239], v[194:197], v[4:7]
	v_mfma_f32_16x16x32_bf16 v[0:3], v[236:239], v[202:205], v[0:3]
	s_setprio 0
	s_add_i32 s22, s22, 2
	s_add_u32 s8, s8, 0x100
	s_addc_u32 s9, s9, 0
	s_cmp_gt_u32 s22, 13
	s_barrier
	s_cbranch_scc0 .LBB0_137
	s_and_saveexec_b64 s[8:9], s[4:5]
	s_cbranch_execz .LBB0_140
	s_barrier

; #define STAGE(P, g) do { const char* g_ = (const char*)(g); \
;         __builtin_amdgcn_global_load_lds((const unsigned*)(g_ + so0), (lds_u32*)((lds_u8*)(P) + sb0), 16, 0, 0); \
;         __builtin_amdgcn_global_load_lds((const unsigned*)(g_ + so1), (lds_u32*)((lds_u8*)(P) + sb0 + 8192), 16, 0, 0); } while (0)
; #define LDA(dst, b, h) for (int m = 0; m < 4; ++m) for (int k = 0; k < 2; ++k) \
;         dst[m][k] = *reinterpret_cast<const bf16x8*>((char*)SA(b, h) + lds_byte(wr * 64 + m * 16 + fr, k * 32 + fq * 8))
; #define LDB(dst, b, h) for (int n = 0; n < 2; ++n) for (int k = 0; k < 2; ++k) \
;         dst[n][k] = *reinterpret_cast<const bf16x8*>((char*)SB(b, h) + lds_byte(wc * 32 + n * 16 + fr, k * 32 + fq * 8))
; #define MMA(ai, bj, At_, Bt_) do { __builtin_amdgcn_s_setprio(1); \
;         for (int m = 0; m < 4; ++m) for (int n = 0; n < 2; ++n) for (int k = 0; k < 2; ++k) \
;             acc[ai][bj][m][n] = __builtin_amdgcn_mfma_f32_16x16x32_bf16(At_[m][k], Bt_[n][k], acc[ai][bj][m][n], 0, 0, 0); \
;         __builtin_amdgcn_s_setprio(0); } while (0)
; #define WAIT_V(n) asm volatile("s_waitcnt vmcnt(" #n ")" ::: "memory")
; #define WAIT_L(n) asm volatile("s_waitcnt lgkmcnt(" #n ")" ::: "memory")
; #define BAR __builtin_amdgcn_s_barrier()
; #define SCHED __builtin_amdgcn_sched_barrier(0)
; template <int EPI, int K, int LNI = -1>
; DI void ph_gemm(const Params& p, const bf16_t* __restrict__ A, const bf16_t* __restrict__ Bt, int N, float* s_aux) {
;     ...
;         for (int t = 0; t < nt; t += 2) {
;             const bool last = (t == nt - 2);
;             const bf16_t* a1 = cA + (size_t)(t + 1) * kstep;
;             const bf16_t* a2 = last ? nA : cA + (size_t)(t + 2) * kstep; const bf16_t* b2 = last ? nB : cB + (size_t)(t + 2) * kstep;
;             const bf16_t* a3 = a2 + kstep; const bf16_t* b3 = b2 + kstep;
;             LDB(B0, 0, 0); LDB(B1, 0, 1); SCHED; LDA(At, 0, 0); STAGE(SA(1, 1), a1 + hstep);
;             WAIT_V(8); WAIT_L(0); BAR; MMA(0, 0, At, B0); MMA(0, 1, At, B1); BAR; SCHED;
;             LDA(At, 0, 1); STAGE(SB(0, 0), b2); STAGE(SB(0, 1), b2 + hstep); STAGE(SA(0, 0), a2);
;             WAIT_V(8); WAIT_L(0); BAR; MMA(1, 0, At, B0); MMA(1, 1, At, B1); BAR; SCHED;
.LBB0_793:
	s_ashr_i32 s13, s12, 31
	s_lshl_b64 s[18:19], s[12:13], 19
	s_add_u32 s13, s40, s18
	s_addc_u32 s42, s41, s19
	s_ashr_i32 s15, s14, 31
	s_lshl_b64 s[20:21], s[14:15], 19
	s_add_u32 s15, s8, s20
	s_addc_u32 s43, s9, s21
	s_add_u32 s48, s56, s26
	s_addc_u32 s49, s57, s27
	s_add_u32 s50, s25, s28
	v_lshl_add_u64 v[136:137], v[132:133], 0, s[26:27]
	v_lshl_add_u64 v[138:139], v[134:135], 0, s[26:27]
	s_addc_u32 s51, s35, s29
	s_mov_b32 s52, -2
	s_mov_b64 s[26:27], 0
	ds_read_b128 v[168:171], v158
	ds_read_b128 v[172:175], v158 offset:1024
	ds_read_b128 v[176:179], v158 offset:2048
	ds_read_b128 v[180:183], v158 offset:3072
	ds_read_b128 v[184:187], v159
	ds_read_b128 v[188:191], v159 offset:1024
	ds_read_b128 v[192:195], v159 offset:2048
	ds_read_b128 v[196:199], v159 offset:3072
	s_add_u32 s28, s48, s26
	s_addc_u32 s29, s49, s27
	s_add_u32 s28, s28, 0xb840100
	s_addc_u32 s29, s29, 0
	s_add_u32 s53, s50, s26
	s_addc_u32 s60, s51, s27
	s_cmpk_eq_i32 s26, 0x700
	s_cselect_b32 s45, s42, s29
	s_cselect_b32 s44, s13, s28
	s_cselect_b32 s29, s43, s60
	s_cselect_b32 s28, s15, s53
	v_readfirstlane_b32 s53, v164
	v_lshl_add_u64 v[140:141], v[136:137], 0, s[26:27]
	s_mov_b32 m0, s53
	v_readfirstlane_b32 s53, v165
	ds_read_b128 v[200:203], v160
	ds_read_b128 v[204:207], v160 offset:1024
	ds_read_b128 v[212:215], v161
	ds_read_b128 v[216:219], v161 offset:1024
	ds_read_b128 v[220:223], v162
	ds_read_b128 v[224:227], v162 offset:1024
	ds_read_b128 v[228:231], v163
	ds_read_b128 v[232:235], v163 offset:1024
	global_load_lds_dwordx4 v[140:141], off
	v_lshl_add_u64 v[140:141], v[138:139], 0, s[26:27]
	s_mov_b32 m0, s53
	s_nop 0
	global_load_lds_dwordx4 v[140:141], off
	s_waitcnt vmcnt(8)
	s_waitcnt lgkmcnt(0)
	s_barrier
	s_setprio 1
	s_waitcnt lgkmcnt(0)
	v_mfma_f32_16x16x32_bf16 v[124:127], v[200:203], v[168:171], 0
	v_mfma_f32_16x16x32_bf16 v[120:123], v[200:203], v[176:179], 0
	v_mfma_f32_16x16x32_bf16 v[116:119], v[212:215], v[168:171], 0
	v_mfma_f32_16x16x32_bf16 v[108:111], v[212:215], v[176:179], 0
	v_mfma_f32_16x16x32_bf16 v[100:103], v[220:223], v[168:171], 0
	v_mfma_f32_16x16x32_bf16 v[88:91], v[220:223], v[176:179], 0
	v_mfma_f32_16x16x32_bf16 v[84:87], v[228:231], v[168:171], 0
	v_mfma_f32_16x16x32_bf16 v[76:79], v[228:231], v[176:179], 0
	v_mfma_f32_16x16x32_bf16 v[124:127], v[204:207], v[172:175], v[124:127]
	v_mfma_f32_16x16x32_bf16 v[120:123], v[204:207], v[180:183], v[120:123]
	v_mfma_f32_16x16x32_bf16 v[116:119], v[216:219], v[172:175], v[116:119]
	v_mfma_f32_16x16x32_bf16 v[108:111], v[216:219], v[180:183], v[108:111]
	v_mfma_f32_16x16x32_bf16 v[100:103], v[224:227], v[172:175], v[100:103]
	v_mfma_f32_16x16x32_bf16 v[88:91], v[224:227], v[180:183], v[88:91]
	v_mfma_f32_16x16x32_bf16 v[84:87], v[232:235], v[172:175], v[84:87]
	v_mfma_f32_16x16x32_bf16 v[76:79], v[232:235], v[180:183], v[76:79]
	s_setprio 0
	s_setprio 1
	v_mfma_f32_16x16x32_bf16 v[112:115], v[200:203], v[184:187], 0
	v_mfma_f32_16x16x32_bf16 v[104:107], v[200:203], v[192:195], 0
	v_mfma_f32_16x16x32_bf16 v[96:99], v[212:215], v[184:187], 0
	v_mfma_f32_16x16x32_bf16 v[92:95], v[212:215], v[192:195], 0
	v_mfma_f32_16x16x32_bf16 v[80:83], v[220:223], v[184:187], 0
	v_mfma_f32_16x16x32_bf16 v[72:75], v[220:223], v[192:195], 0
	v_mfma_f32_16x16x32_bf16 v[68:71], v[228:231], v[184:187], 0
	v_mfma_f32_16x16x32_bf16 v[64:67], v[228:231], v[192:195], 0
	v_mfma_f32_16x16x32_bf16 v[112:115], v[204:207], v[188:191], v[112:115]
	v_mfma_f32_16x16x32_bf16 v[104:107], v[204:207], v[196:199], v[104:107]
	v_mfma_f32_16x16x32_bf16 v[96:99], v[216:219], v[188:191], v[96:99]
	v_mfma_f32_16x16x32_bf16 v[92:95], v[216:219], v[196:199], v[92:95]
	v_mfma_f32_16x16x32_bf16 v[80:83], v[224:227], v[188:191], v[80:83]
	v_mfma_f32_16x16x32_bf16 v[72:75], v[224:227], v[196:199], v[72:75]
	v_mfma_f32_16x16x32_bf16 v[68:71], v[232:235], v[188:191], v[68:71]
	v_mfma_f32_16x16x32_bf16 v[64:67], v[232:235], v[196:199], v[64:67]
	s_setprio 0
	s_barrier
	v_readfirstlane_b32 s53, v142
	v_lshl_add_u64 v[140:141], s[28:29], 0, v[128:129]
	s_mov_b32 m0, s53
	v_readfirstlane_b32 s53, v143
	s_add_u32 s60, s28, 0x40000
	ds_read_b128 v[200:203], v160 offset:16384
	ds_read_b128 v[204:207], v160 offset:17408
	ds_read_b128 v[212:215], v161 offset:16384
	ds_read_b128 v[216:219], v161 offset:17408
	ds_read_b128 v[220:223], v162 offset:16384
	ds_read_b128 v[224:227], v162 offset:17408
	ds_read_b128 v[228:231], v163 offset:16384
	ds_read_b128 v[232:235], v163 offset:17408
	global_load_lds_dwordx4 v[140:141], off
	v_lshl_add_u64 v[208:209], s[28:29], 0, v[130:131]
	s_mov_b32 m0, s53
	s_addc_u32 s61, s29, 0
	v_readfirstlane_b32 s53, v144
	global_load_lds_dwordx4 v[208:209], off
	v_lshl_add_u64 v[236:237], s[60:61], 0, v[128:129]
	s_mov_b32 m0, s53
	v_readfirstlane_b32 s53, v145
	global_load_lds_dwordx4 v[236:237], off
	v_lshl_add_u64 v[236:237], s[60:61], 0, v[130:131]
	s_mov_b32 m0, s53
	v_readfirstlane_b32 s53, v146
	global_load_lds_dwordx4 v[236:237], off
	v_lshl_add_u64 v[236:237], s[44:45], 0, v[128:129]
	s_mov_b32 m0, s53
	v_readfirstlane_b32 s53, v147
	global_load_lds_dwordx4 v[236:237], off
	v_lshl_add_u64 v[238:239], s[44:45], 0, v[130:131]
	s_mov_b32 m0, s53
	s_nop 0
	global_load_lds_dwordx4 v[238:239], off
	s_waitcnt vmcnt(8)
	s_waitcnt lgkmcnt(0)
	s_barrier
; #define STAGE(P, g) do { const char* g_ = (const char*)(g); \
;         __builtin_amdgcn_global_load_lds((const unsigned*)(g_ + so0), (lds_u32*)((lds_u8*)(P) + sb0), 16, 0, 0); \
;         __builtin_amdgcn_global_load_lds((const unsigned*)(g_ + so1), (lds_u32*)((lds_u8*)(P) + sb0 + 8192), 16, 0, 0); } while (0)
; #define LDA(dst, b, h) for (int m = 0; m < 4; ++m) for (int k = 0; k < 2; ++k) \
;         dst[m][k] = *reinterpret_cast<const bf16x8*>((char*)SA(b, h) + lds_byte(wr * 64 + m * 16 + fr, k * 32 + fq * 8))
; #define LDB(dst, b, h) for (int n = 0; n < 2; ++n) for (int k = 0; k < 2; ++k) \
;         dst[n][k] = *reinterpret_cast<const bf16x8*>((char*)SB(b, h) + lds_byte(wc * 32 + n * 16 + fr, k * 32 + fq * 8))
; #define MMA(ai, bj, At_, Bt_) do { __builtin_amdgcn_s_setprio(1); \
;         for (int m = 0; m < 4; ++m) for (int n = 0; n < 2; ++n) for (int k = 0; k < 2; ++k) \
;             acc[ai][bj][m][n] = __builtin_amdgcn_mfma_f32_16x16x32_bf16(At_[m][k], Bt_[n][k], acc[ai][bj][m][n], 0, 0, 0); \
;         __builtin_amdgcn_s_setprio(0); } while (0)
; #define WAIT_V(n) asm volatile("s_waitcnt vmcnt(" #n ")" ::: "memory")
; #define WAIT_L(n) asm volatile("s_waitcnt lgkmcnt(" #n ")" ::: "memory")
; #define BAR __builtin_amdgcn_s_barrier()
; #define SCHED __builtin_amdgcn_sched_barrier(0)
; template <int EPI, int K, int LNI = -1>
; DI void ph_gemm(const Params& p, const bf16_t* __restrict__ A, const bf16_t* __restrict__ Bt, int N, float* s_aux) {
;     ...
;             WAIT_V(8); WAIT_L(0); BAR; MMA(0, 0, At, B0); MMA(0, 1, At, B1); BAR; SCHED;
;             LDA(At, 0, 1); STAGE(SB(0, 0), b2); STAGE(SB(0, 1), b2 + hstep); STAGE(SA(0, 0), a2);
;             WAIT_V(8); WAIT_L(0); BAR; MMA(1, 0, At, B0); MMA(1, 1, At, B1); BAR; SCHED;
;             LDB(B0, 1, 0); LDB(B1, 1, 1); SCHED; LDA(At, 1, 0); STAGE(SA(0, 1), a2 + hstep);
;             WAIT_V(8); WAIT_L(0); BAR; MMA(0, 0, At, B0); MMA(0, 1, At, B1); BAR; SCHED;
	s_setprio 1
	s_waitcnt lgkmcnt(0)
	v_mfma_f32_16x16x32_bf16 v[60:63], v[200:203], v[168:171], 0
	v_mfma_f32_16x16x32_bf16 v[56:59], v[200:203], v[176:179], 0
	v_mfma_f32_16x16x32_bf16 v[44:47], v[212:215], v[168:171], 0
	v_mfma_f32_16x16x32_bf16 v[40:43], v[212:215], v[176:179], 0
	v_mfma_f32_16x16x32_bf16 v[36:39], v[220:223], v[168:171], 0
	v_mfma_f32_16x16x32_bf16 v[28:31], v[220:223], v[176:179], 0
	v_mfma_f32_16x16x32_bf16 v[20:23], v[228:231], v[168:171], 0
	v_mfma_f32_16x16x32_bf16 v[12:15], v[228:231], v[176:179], 0
	v_mfma_f32_16x16x32_bf16 v[60:63], v[204:207], v[172:175], v[60:63]
	v_mfma_f32_16x16x32_bf16 v[56:59], v[204:207], v[180:183], v[56:59]
	v_mfma_f32_16x16x32_bf16 v[44:47], v[216:219], v[172:175], v[44:47]
	v_mfma_f32_16x16x32_bf16 v[40:43], v[216:219], v[180:183], v[40:43]
	v_mfma_f32_16x16x32_bf16 v[36:39], v[224:227], v[172:175], v[36:39]
	v_mfma_f32_16x16x32_bf16 v[28:31], v[224:227], v[180:183], v[28:31]
	v_mfma_f32_16x16x32_bf16 v[20:23], v[232:235], v[172:175], v[20:23]
	v_mfma_f32_16x16x32_bf16 v[12:15], v[232:235], v[180:183], v[12:15]
	s_setprio 0
	s_setprio 1
	v_mfma_f32_16x16x32_bf16 v[52:55], v[200:203], v[184:187], 0
	v_mfma_f32_16x16x32_bf16 v[48:51], v[200:203], v[192:195], 0
	v_mfma_f32_16x16x32_bf16 v[32:35], v[212:215], v[184:187], 0
	v_mfma_f32_16x16x32_bf16 v[24:27], v[212:215], v[192:195], 0
	v_mfma_f32_16x16x32_bf16 v[16:19], v[220:223], v[184:187], 0
	v_mfma_f32_16x16x32_bf16 v[8:11], v[220:223], v[192:195], 0
	v_mfma_f32_16x16x32_bf16 v[4:7], v[228:231], v[184:187], 0
	v_mfma_f32_16x16x32_bf16 v[0:3], v[228:231], v[192:195], 0
	v_mfma_f32_16x16x32_bf16 v[52:55], v[204:207], v[188:191], v[52:55]
	v_mfma_f32_16x16x32_bf16 v[48:51], v[204:207], v[196:199], v[48:51]
	v_mfma_f32_16x16x32_bf16 v[32:35], v[216:219], v[188:191], v[32:35]
	v_mfma_f32_16x16x32_bf16 v[24:27], v[216:219], v[196:199], v[24:27]
	v_mfma_f32_16x16x32_bf16 v[16:19], v[224:227], v[188:191], v[16:19]
	v_mfma_f32_16x16x32_bf16 v[8:11], v[224:227], v[196:199], v[8:11]
	v_mfma_f32_16x16x32_bf16 v[4:7], v[232:235], v[188:191], v[4:7]
	v_mfma_f32_16x16x32_bf16 v[0:3], v[232:235], v[196:199], v[0:3]
	s_setprio 0
	s_barrier
	ds_read_b128 v[168:171], v166
	ds_read_b128 v[172:175], v166 offset:1024
	ds_read_b128 v[176:179], v166 offset:2048
	ds_read_b128 v[180:183], v166 offset:3072
	ds_read_b128 v[184:187], v167
	ds_read_b128 v[188:191], v167 offset:1024
	ds_read_b128 v[192:195], v167 offset:2048
	ds_read_b128 v[196:199], v167 offset:3072
	s_add_u32 s44, s44, 0x40000
	s_addc_u32 s45, s45, 0
	v_readfirstlane_b32 s53, v148
	v_lshl_add_u64 v[240:241], s[44:45], 0, v[128:129]
	s_mov_b32 m0, s53
	ds_read_b128 v[200:203], v160 offset:32768
	ds_read_b128 v[204:207], v160 offset:33792
	ds_read_b128 v[212:215], v161 offset:32768
	ds_read_b128 v[216:219], v161 offset:33792
	ds_read_b128 v[220:223], v162 offset:32768
	ds_read_b128 v[224:227], v162 offset:33792
	ds_read_b128 v[228:231], v163 offset:32768
	ds_read_b128 v[232:235], v163 offset:33792
	global_load_lds_dwordx4 v[240:241], off
	v_lshl_add_u64 v[240:241], s[44:45], 0, v[130:131]
	v_readfirstlane_b32 s44, v149
	s_mov_b32 m0, s44
	s_nop 0
	global_load_lds_dwordx4 v[240:241], off
	s_waitcnt vmcnt(8)
	s_waitcnt lgkmcnt(0)
	s_barrier
	s_setprio 1
	s_waitcnt lgkmcnt(0)
	v_mfma_f32_16x16x32_bf16 v[124:127], v[200:203], v[168:171], v[124:127]
	v_mfma_f32_16x16x32_bf16 v[120:123], v[200:203], v[176:179], v[120:123]
	v_mfma_f32_16x16x32_bf16 v[116:119], v[212:215], v[168:171], v[116:119]
	v_mfma_f32_16x16x32_bf16 v[108:111], v[212:215], v[176:179], v[108:111]
	v_mfma_f32_16x16x32_bf16 v[100:103], v[220:223], v[168:171], v[100:103]
	v_mfma_f32_16x16x32_bf16 v[88:91], v[220:223], v[176:179], v[88:91]
	v_mfma_f32_16x16x32_bf16 v[84:87], v[228:231], v[168:171], v[84:87]
	v_mfma_f32_16x16x32_bf16 v[76:79], v[228:231], v[176:179], v[76:79]
	v_mfma_f32_16x16x32_bf16 v[124:127], v[204:207], v[172:175], v[124:127]
	v_mfma_f32_16x16x32_bf16 v[120:123], v[204:207], v[180:183], v[120:123]
	v_mfma_f32_16x16x32_bf16 v[116:119], v[216:219], v[172:175], v[116:119]
	v_mfma_f32_16x16x32_bf16 v[108:111], v[216:219], v[180:183], v[108:111]
	v_mfma_f32_16x16x32_bf16 v[100:103], v[224:227], v[172:175], v[100:103]
	v_mfma_f32_16x16x32_bf16 v[88:91], v[224:227], v[180:183], v[88:91]
	v_mfma_f32_16x16x32_bf16 v[84:87], v[232:235], v[172:175], v[84:87]
	v_mfma_f32_16x16x32_bf16 v[76:79], v[232:235], v[180:183], v[76:79]
	s_setprio 0
	s_setprio 1
	v_mfma_f32_16x16x32_bf16 v[112:115], v[200:203], v[184:187], v[112:115]
	v_mfma_f32_16x16x32_bf16 v[104:107], v[200:203], v[192:195], v[104:107]
	v_mfma_f32_16x16x32_bf16 v[96:99], v[212:215], v[184:187], v[96:99]
	v_mfma_f32_16x16x32_bf16 v[92:95], v[212:215], v[192:195], v[92:95]
	v_mfma_f32_16x16x32_bf16 v[80:83], v[220:223], v[184:187], v[80:83]
	v_mfma_f32_16x16x32_bf16 v[72:75], v[220:223], v[192:195], v[72:75]
	v_mfma_f32_16x16x32_bf16 v[68:71], v[228:231], v[184:187], v[68:71]
	v_mfma_f32_16x16x32_bf16 v[64:67], v[228:231], v[192:195], v[64:67]
	v_mfma_f32_16x16x32_bf16 v[112:115], v[204:207], v[188:191], v[112:115]
	v_mfma_f32_16x16x32_bf16 v[104:107], v[204:207], v[196:199], v[104:107]
	v_mfma_f32_16x16x32_bf16 v[96:99], v[216:219], v[188:191], v[96:99]
	v_mfma_f32_16x16x32_bf16 v[92:95], v[216:219], v[196:199], v[92:95]
	v_mfma_f32_16x16x32_bf16 v[80:83], v[224:227], v[188:191], v[80:83]
	v_mfma_f32_16x16x32_bf16 v[72:75], v[224:227], v[196:199], v[72:75]
	v_mfma_f32_16x16x32_bf16 v[68:71], v[232:235], v[188:191], v[68:71]
	v_mfma_f32_16x16x32_bf16 v[64:67], v[232:235], v[196:199], v[64:67]
	s_setprio 0
	s_barrier
; #define STAGE(P, g) do { const char* g_ = (const char*)(g); \
;         __builtin_amdgcn_global_load_lds((const unsigned*)(g_ + so0), (lds_u32*)((lds_u8*)(P) + sb0), 16, 0, 0); \
;         __builtin_amdgcn_global_load_lds((const unsigned*)(g_ + so1), (lds_u32*)((lds_u8*)(P) + sb0 + 8192), 16, 0, 0); } while (0)
; #define LDA(dst, b, h) for (int m = 0; m < 4; ++m) for (int k = 0; k < 2; ++k) \
;         dst[m][k] = *reinterpret_cast<const bf16x8*>((char*)SA(b, h) + lds_byte(wr * 64 + m * 16 + fr, k * 32 + fq * 8))
; #define LDB(dst, b, h) for (int n = 0; n < 2; ++n) for (int k = 0; k < 2; ++k) \
;         dst[n][k] = *reinterpret_cast<const bf16x8*>((char*)SB(b, h) + lds_byte(wc * 32 + n * 16 + fr, k * 32 + fq * 8))
; #define MMA(ai, bj, At_, Bt_) do { __builtin_amdgcn_s_setprio(1); \
;         for (int m = 0; m < 4; ++m) for (int n = 0; n < 2; ++n) for (int k = 0; k < 2; ++k) \
;             acc[ai][bj][m][n] = __builtin_amdgcn_mfma_f32_16x16x32_bf16(At_[m][k], Bt_[n][k], acc[ai][bj][m][n], 0, 0, 0); \
;         __builtin_amdgcn_s_setprio(0); } while (0)
; #define WAIT_V(n) asm volatile("s_waitcnt vmcnt(" #n ")" ::: "memory")
; #define WAIT_L(n) asm volatile("s_waitcnt lgkmcnt(" #n ")" ::: "memory")
; #define BAR __builtin_amdgcn_s_barrier()
; #define SCHED __builtin_amdgcn_sched_barrier(0)
; template <int EPI, int K, int LNI = -1>
; DI void ph_gemm(const Params& p, const bf16_t* __restrict__ A, const bf16_t* __restrict__ Bt, int N, float* s_aux) {
;     ...
;             LDA(At, 0, 1); STAGE(SB(0, 0), b2); STAGE(SB(0, 1), b2 + hstep); STAGE(SA(0, 0), a2);
;             WAIT_V(8); WAIT_L(0); BAR; MMA(1, 0, At, B0); MMA(1, 1, At, B1); BAR; SCHED;
;             LDB(B0, 1, 0); LDB(B1, 1, 1); SCHED; LDA(At, 1, 0); STAGE(SA(0, 1), a2 + hstep);
;             WAIT_V(8); WAIT_L(0); BAR; MMA(0, 0, At, B0); MMA(0, 1, At, B1); BAR; SCHED;
;             LDA(At, 1, 1); STAGE(SB(1, 0), b3); STAGE(SB(1, 1), b3 + hstep); STAGE(SA(1, 0), a3);
;             WAIT_V(8); WAIT_L(0); BAR; MMA(1, 0, At, B0); MMA(1, 1, At, B1); BAR; SCHED;
	v_readfirstlane_b32 s44, v150
	v_lshl_add_u64 v[140:141], v[140:141], 0, s[6:7]
	s_mov_b32 m0, s44
	v_readfirstlane_b32 s44, v151
	s_add_u32 s28, s28, 0x40080
	ds_read_b128 v[200:203], v160 offset:49152
	ds_read_b128 v[204:207], v160 offset:50176
	ds_read_b128 v[212:215], v161 offset:49152
	ds_read_b128 v[216:219], v161 offset:50176
	ds_read_b128 v[220:223], v162 offset:49152
	ds_read_b128 v[224:227], v162 offset:50176
	ds_read_b128 v[228:231], v163 offset:49152
	ds_read_b128 v[232:235], v163 offset:50176
	global_load_lds_dwordx4 v[140:141], off
	v_lshl_add_u64 v[140:141], v[208:209], 0, s[6:7]
	s_mov_b32 m0, s44
	s_addc_u32 s29, s29, 0
	v_readfirstlane_b32 s44, v154
	global_load_lds_dwordx4 v[140:141], off
	v_lshl_add_u64 v[140:141], s[28:29], 0, v[128:129]
	s_mov_b32 m0, s44
	s_nop 0
	global_load_lds_dwordx4 v[140:141], off
	v_lshl_add_u64 v[140:141], s[28:29], 0, v[130:131]
	v_readfirstlane_b32 s28, v155
	s_mov_b32 m0, s28
	v_readfirstlane_b32 s28, v152
	global_load_lds_dwordx4 v[140:141], off
	v_lshl_add_u64 v[140:141], v[236:237], 0, s[6:7]
	s_mov_b32 m0, s28
	v_readfirstlane_b32 s28, v153
	global_load_lds_dwordx4 v[140:141], off
	v_lshl_add_u64 v[140:141], v[238:239], 0, s[6:7]
	s_mov_b32 m0, s28
	s_nop 0
	global_load_lds_dwordx4 v[140:141], off
	s_waitcnt vmcnt(8)
	s_waitcnt lgkmcnt(0)
	s_barrier
	s_setprio 1
	s_waitcnt lgkmcnt(0)
	v_mfma_f32_16x16x32_bf16 v[60:63], v[200:203], v[168:171], v[60:63]
	v_mfma_f32_16x16x32_bf16 v[56:59], v[200:203], v[176:179], v[56:59]
	v_mfma_f32_16x16x32_bf16 v[44:47], v[212:215], v[168:171], v[44:47]
	v_mfma_f32_16x16x32_bf16 v[40:43], v[212:215], v[176:179], v[40:43]
	v_mfma_f32_16x16x32_bf16 v[36:39], v[220:223], v[168:171], v[36:39]
	v_mfma_f32_16x16x32_bf16 v[28:31], v[220:223], v[176:179], v[28:31]
	v_mfma_f32_16x16x32_bf16 v[20:23], v[228:231], v[168:171], v[20:23]
	v_mfma_f32_16x16x32_bf16 v[12:15], v[228:231], v[176:179], v[12:15]
	v_mfma_f32_16x16x32_bf16 v[60:63], v[204:207], v[172:175], v[60:63]
	v_mfma_f32_16x16x32_bf16 v[56:59], v[204:207], v[180:183], v[56:59]
	v_mfma_f32_16x16x32_bf16 v[44:47], v[216:219], v[172:175], v[44:47]
	v_mfma_f32_16x16x32_bf16 v[40:43], v[216:219], v[180:183], v[40:43]
	v_mfma_f32_16x16x32_bf16 v[36:39], v[224:227], v[172:175], v[36:39]
	v_mfma_f32_16x16x32_bf16 v[28:31], v[224:227], v[180:183], v[28:31]
	v_mfma_f32_16x16x32_bf16 v[20:23], v[232:235], v[172:175], v[20:23]
	v_mfma_f32_16x16x32_bf16 v[12:15], v[232:235], v[180:183], v[12:15]
	s_setprio 0
	s_setprio 1
	v_mfma_f32_16x16x32_bf16 v[52:55], v[200:203], v[184:187], v[52:55]
	v_mfma_f32_16x16x32_bf16 v[48:51], v[200:203], v[192:195], v[48:51]
	v_mfma_f32_16x16x32_bf16 v[32:35], v[212:215], v[184:187], v[32:35]
	v_mfma_f32_16x16x32_bf16 v[24:27], v[212:215], v[192:195], v[24:27]
	v_mfma_f32_16x16x32_bf16 v[16:19], v[220:223], v[184:187], v[16:19]
	v_mfma_f32_16x16x32_bf16 v[8:11], v[220:223], v[192:195], v[8:11]
	v_mfma_f32_16x16x32_bf16 v[4:7], v[228:231], v[184:187], v[4:7]
	v_mfma_f32_16x16x32_bf16 v[0:3], v[228:231], v[192:195], v[0:3]
	v_mfma_f32_16x16x32_bf16 v[52:55], v[204:207], v[188:191], v[52:55]
	v_mfma_f32_16x16x32_bf16 v[48:51], v[204:207], v[196:199], v[48:51]
	v_mfma_f32_16x16x32_bf16 v[32:35], v[216:219], v[188:191], v[32:35]
	v_mfma_f32_16x16x32_bf16 v[24:27], v[216:219], v[196:199], v[24:27]
	v_mfma_f32_16x16x32_bf16 v[16:19], v[224:227], v[188:191], v[16:19]
	v_mfma_f32_16x16x32_bf16 v[8:11], v[224:227], v[196:199], v[8:11]
	v_mfma_f32_16x16x32_bf16 v[4:7], v[232:235], v[188:191], v[4:7]
	v_mfma_f32_16x16x32_bf16 v[0:3], v[232:235], v[196:199], v[0:3]
	s_setprio 0
	s_add_i32 s52, s52, 2
	s_add_u32 s26, s26, 0x100
	s_addc_u32 s27, s27, 0
	s_cmp_gt_u32 s52, 13
	s_barrier
.LBB0_794:
	ds_read_b128 v[168:171], v158
	ds_read_b128 v[172:175], v158 offset:1024
	ds_read_b128 v[176:179], v158 offset:2048
	ds_read_b128 v[180:183], v158 offset:3072
	ds_read_b128 v[184:187], v159
	ds_read_b128 v[188:191], v159 offset:1024
	ds_read_b128 v[192:195], v159 offset:2048
	ds_read_b128 v[196:199], v159 offset:3072
	s_add_u32 s28, s48, s26
	s_addc_u32 s29, s49, s27
	s_add_u32 s28, s28, 0xb840100
	s_addc_u32 s29, s29, 0
	s_add_u32 s53, s50, s26
	s_addc_u32 s60, s51, s27
	s_cmpk_eq_i32 s26, 0x700
	s_cselect_b32 s45, s42, s29
	s_cselect_b32 s44, s13, s28
	s_cselect_b32 s29, s43, s60
	s_cselect_b32 s28, s15, s53
	v_readfirstlane_b32 s53, v164
	v_lshl_add_u64 v[140:141], v[136:137], 0, s[26:27]
	s_mov_b32 m0, s53
	v_readfirstlane_b32 s53, v165
	ds_read_b128 v[200:203], v160
	ds_read_b128 v[204:207], v160 offset:1024
	ds_read_b128 v[212:215], v161
	ds_read_b128 v[216:219], v161 offset:1024
	ds_read_b128 v[220:223], v162
	ds_read_b128 v[224:227], v162 offset:1024
	ds_read_b128 v[228:231], v163
	ds_read_b128 v[232:235], v163 offset:1024
	global_load_lds_dwordx4 v[140:141], off
	v_lshl_add_u64 v[140:141], v[138:139], 0, s[26:27]
	s_mov_b32 m0, s53
	s_nop 0
	global_load_lds_dwordx4 v[140:141], off
	s_waitcnt vmcnt(8)
	s_waitcnt lgkmcnt(0)
	s_barrier
; #define STAGE(P, g) do { const char* g_ = (const char*)(g); \
;         __builtin_amdgcn_global_load_lds((const unsigned*)(g_ + so0), (lds_u32*)((lds_u8*)(P) + sb0), 16, 0, 0); \
;         __builtin_amdgcn_global_load_lds((const unsigned*)(g_ + so1), (lds_u32*)((lds_u8*)(P) + sb0 + 8192), 16, 0, 0); } while (0)
; #define LDA(dst, b, h) for (int m = 0; m < 4; ++m) for (int k = 0; k < 2; ++k) \
;         dst[m][k] = *reinterpret_cast<const bf16x8*>((char*)SA(b, h) + lds_byte(wr * 64 + m * 16 + fr, k * 32 + fq * 8))
; #define MMA(ai, bj, At_, Bt_) do { __builtin_amdgcn_s_setprio(1); \
;         for (int m = 0; m < 4; ++m) for (int n = 0; n < 2; ++n) for (int k = 0; k < 2; ++k) \
;             acc[ai][bj][m][n] = __builtin_amdgcn_mfma_f32_16x16x32_bf16(At_[m][k], Bt_[n][k], acc[ai][bj][m][n], 0, 0, 0); \
;         __builtin_amdgcn_s_setprio(0); } while (0)
; #define WAIT_V(n) asm volatile("s_waitcnt vmcnt(" #n ")" ::: "memory")
; #define WAIT_L(n) asm volatile("s_waitcnt lgkmcnt(" #n ")" ::: "memory")
; #define BAR __builtin_amdgcn_s_barrier()
; #define SCHED __builtin_amdgcn_sched_barrier(0)
; template <int EPI, int K, int LNI = -1>
; DI void ph_gemm(const Params& p, const bf16_t* __restrict__ A, const bf16_t* __restrict__ Bt, int N, float* s_aux) {
;     ...
;             WAIT_V(8); WAIT_L(0); BAR; MMA(0, 0, At, B0); MMA(0, 1, At, B1); BAR; SCHED;
;             LDA(At, 0, 1); STAGE(SB(0, 0), b2); STAGE(SB(0, 1), b2 + hstep); STAGE(SA(0, 0), a2);
;             WAIT_V(8); WAIT_L(0); BAR; MMA(1, 0, At, B0); MMA(1, 1, At, B1); BAR; SCHED;
	s_setprio 1
	s_waitcnt lgkmcnt(0)
	v_mfma_f32_16x16x32_bf16 v[124:127], v[200:203], v[168:171], v[124:127]
	v_mfma_f32_16x16x32_bf16 v[120:123], v[200:203], v[176:179], v[120:123]
	v_mfma_f32_16x16x32_bf16 v[116:119], v[212:215], v[168:171], v[116:119]
	v_mfma_f32_16x16x32_bf16 v[108:111], v[212:215], v[176:179], v[108:111]
	v_mfma_f32_16x16x32_bf16 v[100:103], v[220:223], v[168:171], v[100:103]
	v_mfma_f32_16x16x32_bf16 v[88:91], v[220:223], v[176:179], v[88:91]
	v_mfma_f32_16x16x32_bf16 v[84:87], v[228:231], v[168:171], v[84:87]
	v_mfma_f32_16x16x32_bf16 v[76:79], v[228:231], v[176:179], v[76:79]
	v_mfma_f32_16x16x32_bf16 v[124:127], v[204:207], v[172:175], v[124:127]
	v_mfma_f32_16x16x32_bf16 v[120:123], v[204:207], v[180:183], v[120:123]
	v_mfma_f32_16x16x32_bf16 v[116:119], v[216:219], v[172:175], v[116:119]
	v_mfma_f32_16x16x32_bf16 v[108:111], v[216:219], v[180:183], v[108:111]
	v_mfma_f32_16x16x32_bf16 v[100:103], v[224:227], v[172:175], v[100:103]
	v_mfma_f32_16x16x32_bf16 v[88:91], v[224:227], v[180:183], v[88:91]
	v_mfma_f32_16x16x32_bf16 v[84:87], v[232:235], v[172:175], v[84:87]
	v_mfma_f32_16x16x32_bf16 v[76:79], v[232:235], v[180:183], v[76:79]
	s_setprio 0
	s_setprio 1
	v_mfma_f32_16x16x32_bf16 v[112:115], v[200:203], v[184:187], v[112:115]
	v_mfma_f32_16x16x32_bf16 v[104:107], v[200:203], v[192:195], v[104:107]
	v_mfma_f32_16x16x32_bf16 v[96:99], v[212:215], v[184:187], v[96:99]
	v_mfma_f32_16x16x32_bf16 v[92:95], v[212:215], v[192:195], v[92:95]
	v_mfma_f32_16x16x32_bf16 v[80:83], v[220:223], v[184:187], v[80:83]
	v_mfma_f32_16x16x32_bf16 v[72:75], v[220:223], v[192:195], v[72:75]
	v_mfma_f32_16x16x32_bf16 v[68:71], v[228:231], v[184:187], v[68:71]
	v_mfma_f32_16x16x32_bf16 v[64:67], v[228:231], v[192:195], v[64:67]
	v_mfma_f32_16x16x32_bf16 v[112:115], v[204:207], v[188:191], v[112:115]
	v_mfma_f32_16x16x32_bf16 v[104:107], v[204:207], v[196:199], v[104:107]
	v_mfma_f32_16x16x32_bf16 v[96:99], v[216:219], v[188:191], v[96:99]
	v_mfma_f32_16x16x32_bf16 v[92:95], v[216:219], v[196:199], v[92:95]
	v_mfma_f32_16x16x32_bf16 v[80:83], v[224:227], v[188:191], v[80:83]
	v_mfma_f32_16x16x32_bf16 v[72:75], v[224:227], v[196:199], v[72:75]
	v_mfma_f32_16x16x32_bf16 v[68:71], v[232:235], v[188:191], v[68:71]
	v_mfma_f32_16x16x32_bf16 v[64:67], v[232:235], v[196:199], v[64:67]
	s_setprio 0
	s_barrier
	v_readfirstlane_b32 s53, v142
	v_lshl_add_u64 v[140:141], s[28:29], 0, v[128:129]
	s_mov_b32 m0, s53
	v_readfirstlane_b32 s53, v143
	s_add_u32 s60, s28, 0x40000
	ds_read_b128 v[200:203], v160 offset:16384
	ds_read_b128 v[204:207], v160 offset:17408
	ds_read_b128 v[212:215], v161 offset:16384
	ds_read_b128 v[216:219], v161 offset:17408
	ds_read_b128 v[220:223], v162 offset:16384
	ds_read_b128 v[224:227], v162 offset:17408
	ds_read_b128 v[228:231], v163 offset:16384
	ds_read_b128 v[232:235], v163 offset:17408
	global_load_lds_dwordx4 v[140:141], off
	v_lshl_add_u64 v[208:209], s[28:29], 0, v[130:131]
	s_mov_b32 m0, s53
	s_addc_u32 s61, s29, 0
	v_readfirstlane_b32 s53, v144
	global_load_lds_dwordx4 v[208:209], off
	v_lshl_add_u64 v[236:237], s[60:61], 0, v[128:129]
	s_mov_b32 m0, s53
	v_readfirstlane_b32 s53, v145
	global_load_lds_dwordx4 v[236:237], off
	v_lshl_add_u64 v[236:237], s[60:61], 0, v[130:131]
	s_mov_b32 m0, s53
	v_readfirstlane_b32 s53, v146
	global_load_lds_dwordx4 v[236:237], off
	v_lshl_add_u64 v[236:237], s[44:45], 0, v[128:129]
	s_mov_b32 m0, s53
	v_readfirstlane_b32 s53, v147
	global_load_lds_dwordx4 v[236:237], off
	v_lshl_add_u64 v[238:239], s[44:45], 0, v[130:131]
	s_mov_b32 m0, s53
	s_nop 0
	global_load_lds_dwordx4 v[238:239], off
	s_waitcnt vmcnt(8)
	s_waitcnt lgkmcnt(0)
	s_barrier
	s_setprio 1
	s_waitcnt lgkmcnt(0)
	v_mfma_f32_16x16x32_bf16 v[60:63], v[200:203], v[168:171], v[60:63]
	v_mfma_f32_16x16x32_bf16 v[56:59], v[200:203], v[176:179], v[56:59]
	v_mfma_f32_16x16x32_bf16 v[44:47], v[212:215], v[168:171], v[44:47]
	v_mfma_f32_16x16x32_bf16 v[40:43], v[212:215], v[176:179], v[40:43]
	v_mfma_f32_16x16x32_bf16 v[36:39], v[220:223], v[168:171], v[36:39]
	v_mfma_f32_16x16x32_bf16 v[28:31], v[220:223], v[176:179], v[28:31]
	v_mfma_f32_16x16x32_bf16 v[20:23], v[228:231], v[168:171], v[20:23]
	v_mfma_f32_16x16x32_bf16 v[12:15], v[228:231], v[176:179], v[12:15]
	v_mfma_f32_16x16x32_bf16 v[60:63], v[204:207], v[172:175], v[60:63]
	v_mfma_f32_16x16x32_bf16 v[56:59], v[204:207], v[180:183], v[56:59]
	v_mfma_f32_16x16x32_bf16 v[44:47], v[216:219], v[172:175], v[44:47]
	v_mfma_f32_16x16x32_bf16 v[40:43], v[216:219], v[180:183], v[40:43]
	v_mfma_f32_16x16x32_bf16 v[36:39], v[224:227], v[172:175], v[36:39]
	v_mfma_f32_16x16x32_bf16 v[28:31], v[224:227], v[180:183], v[28:31]
	v_mfma_f32_16x16x32_bf16 v[20:23], v[232:235], v[172:175], v[20:23]
	v_mfma_f32_16x16x32_bf16 v[12:15], v[232:235], v[180:183], v[12:15]
	s_setprio 0
	s_setprio 1
	v_mfma_f32_16x16x32_bf16 v[52:55], v[200:203], v[184:187], v[52:55]
	v_mfma_f32_16x16x32_bf16 v[48:51], v[200:203], v[192:195], v[48:51]
	v_mfma_f32_16x16x32_bf16 v[32:35], v[212:215], v[184:187], v[32:35]
	v_mfma_f32_16x16x32_bf16 v[24:27], v[212:215], v[192:195], v[24:27]
	v_mfma_f32_16x16x32_bf16 v[16:19], v[220:223], v[184:187], v[16:19]
	v_mfma_f32_16x16x32_bf16 v[8:11], v[220:223], v[192:195], v[8:11]
	v_mfma_f32_16x16x32_bf16 v[4:7], v[228:231], v[184:187], v[4:7]
	v_mfma_f32_16x16x32_bf16 v[0:3], v[228:231], v[192:195], v[0:3]
	v_mfma_f32_16x16x32_bf16 v[52:55], v[204:207], v[188:191], v[52:55]
	v_mfma_f32_16x16x32_bf16 v[48:51], v[204:207], v[196:199], v[48:51]
	v_mfma_f32_16x16x32_bf16 v[32:35], v[216:219], v[188:191], v[32:35]
	v_mfma_f32_16x16x32_bf16 v[24:27], v[216:219], v[196:199], v[24:27]
	v_mfma_f32_16x16x32_bf16 v[16:19], v[224:227], v[188:191], v[16:19]
	v_mfma_f32_16x16x32_bf16 v[8:11], v[224:227], v[196:199], v[8:11]
	v_mfma_f32_16x16x32_bf16 v[4:7], v[232:235], v[188:191], v[4:7]
	v_mfma_f32_16x16x32_bf16 v[0:3], v[232:235], v[196:199], v[0:3]
	s_setprio 0
	s_barrier
; #define STAGE(P, g) do { const char* g_ = (const char*)(g); \
;         __builtin_amdgcn_global_load_lds((const unsigned*)(g_ + so0), (lds_u32*)((lds_u8*)(P) + sb0), 16, 0, 0); \
;         __builtin_amdgcn_global_load_lds((const unsigned*)(g_ + so1), (lds_u32*)((lds_u8*)(P) + sb0 + 8192), 16, 0, 0); } while (0)
; #define LDA(dst, b, h) for (int m = 0; m < 4; ++m) for (int k = 0; k < 2; ++k) \
;         dst[m][k] = *reinterpret_cast<const bf16x8*>((char*)SA(b, h) + lds_byte(wr * 64 + m * 16 + fr, k * 32 + fq * 8))
; #define LDB(dst, b, h) for (int n = 0; n < 2; ++n) for (int k = 0; k < 2; ++k) \
;         dst[n][k] = *reinterpret_cast<const bf16x8*>((char*)SB(b, h) + lds_byte(wc * 32 + n * 16 + fr, k * 32 + fq * 8))
; #define MMA(ai, bj, At_, Bt_) do { __builtin_amdgcn_s_setprio(1); \
;         for (int m = 0; m < 4; ++m) for (int n = 0; n < 2; ++n) for (int k = 0; k < 2; ++k) \
;             acc[ai][bj][m][n] = __builtin_amdgcn_mfma_f32_16x16x32_bf16(At_[m][k], Bt_[n][k], acc[ai][bj][m][n], 0, 0, 0); \
;         __builtin_amdgcn_s_setprio(0); } while (0)
; #define WAIT_V(n) asm volatile("s_waitcnt vmcnt(" #n ")" ::: "memory")
; #define WAIT_L(n) asm volatile("s_waitcnt lgkmcnt(" #n ")" ::: "memory")
; #define BAR __builtin_amdgcn_s_barrier()
; #define SCHED __builtin_amdgcn_sched_barrier(0)
; template <int EPI, int K, int LNI = -1>
; DI void ph_gemm(const Params& p, const bf16_t* __restrict__ A, const bf16_t* __restrict__ Bt, int N, float* s_aux) {
;     ...
;             LDB(B0, 1, 0); LDB(B1, 1, 1); SCHED; LDA(At, 1, 0); STAGE(SA(0, 1), a2 + hstep);
;             WAIT_V(8); WAIT_L(0); BAR; MMA(0, 0, At, B0); MMA(0, 1, At, B1); BAR; SCHED;
	ds_read_b128 v[168:171], v166
	ds_read_b128 v[172:175], v166 offset:1024
	ds_read_b128 v[176:179], v166 offset:2048
	ds_read_b128 v[180:183], v166 offset:3072
	ds_read_b128 v[184:187], v167
	ds_read_b128 v[188:191], v167 offset:1024
	ds_read_b128 v[192:195], v167 offset:2048
	ds_read_b128 v[196:199], v167 offset:3072
	s_add_u32 s44, s44, 0x40000
	s_addc_u32 s45, s45, 0
	v_readfirstlane_b32 s53, v148
	v_lshl_add_u64 v[240:241], s[44:45], 0, v[128:129]
	s_mov_b32 m0, s53
	ds_read_b128 v[200:203], v160 offset:32768
	ds_read_b128 v[204:207], v160 offset:33792
	ds_read_b128 v[212:215], v161 offset:32768
	ds_read_b128 v[216:219], v161 offset:33792
	ds_read_b128 v[220:223], v162 offset:32768
	ds_read_b128 v[224:227], v162 offset:33792
	ds_read_b128 v[228:231], v163 offset:32768
	ds_read_b128 v[232:235], v163 offset:33792
	global_load_lds_dwordx4 v[240:241], off
	v_lshl_add_u64 v[240:241], s[44:45], 0, v[130:131]
	v_readfirstlane_b32 s44, v149
	s_mov_b32 m0, s44
	s_nop 0
	global_load_lds_dwordx4 v[240:241], off
	s_waitcnt vmcnt(8)
	s_waitcnt lgkmcnt(0)
	s_barrier
	s_setprio 1
	s_waitcnt lgkmcnt(0)
	v_mfma_f32_16x16x32_bf16 v[124:127], v[200:203], v[168:171], v[124:127]
	v_mfma_f32_16x16x32_bf16 v[120:123], v[200:203], v[176:179], v[120:123]
	v_mfma_f32_16x16x32_bf16 v[116:119], v[212:215], v[168:171], v[116:119]
	v_mfma_f32_16x16x32_bf16 v[108:111], v[212:215], v[176:179], v[108:111]
	v_mfma_f32_16x16x32_bf16 v[100:103], v[220:223], v[168:171], v[100:103]
	v_mfma_f32_16x16x32_bf16 v[88:91], v[220:223], v[176:179], v[88:91]
	v_mfma_f32_16x16x32_bf16 v[84:87], v[228:231], v[168:171], v[84:87]
	v_mfma_f32_16x16x32_bf16 v[76:79], v[228:231], v[176:179], v[76:79]
	v_mfma_f32_16x16x32_bf16 v[124:127], v[204:207], v[172:175], v[124:127]
	v_mfma_f32_16x16x32_bf16 v[120:123], v[204:207], v[180:183], v[120:123]
	v_mfma_f32_16x16x32_bf16 v[116:119], v[216:219], v[172:175], v[116:119]
	v_mfma_f32_16x16x32_bf16 v[108:111], v[216:219], v[180:183], v[108:111]
	v_mfma_f32_16x16x32_bf16 v[100:103], v[224:227], v[172:175], v[100:103]
	v_mfma_f32_16x16x32_bf16 v[88:91], v[224:227], v[180:183], v[88:91]
	v_mfma_f32_16x16x32_bf16 v[84:87], v[232:235], v[172:175], v[84:87]
	v_mfma_f32_16x16x32_bf16 v[76:79], v[232:235], v[180:183], v[76:79]
	s_setprio 0
	s_setprio 1
	v_mfma_f32_16x16x32_bf16 v[112:115], v[200:203], v[184:187], v[112:115]
	v_mfma_f32_16x16x32_bf16 v[104:107], v[200:203], v[192:195], v[104:107]
	v_mfma_f32_16x16x32_bf16 v[96:99], v[212:215], v[184:187], v[96:99]
	v_mfma_f32_16x16x32_bf16 v[92:95], v[212:215], v[192:195], v[92:95]
	v_mfma_f32_16x16x32_bf16 v[80:83], v[220:223], v[184:187], v[80:83]
	v_mfma_f32_16x16x32_bf16 v[72:75], v[220:223], v[192:195], v[72:75]
	v_mfma_f32_16x16x32_bf16 v[68:71], v[228:231], v[184:187], v[68:71]
	v_mfma_f32_16x16x32_bf16 v[64:67], v[228:231], v[192:195], v[64:67]
	v_mfma_f32_16x16x32_bf16 v[112:115], v[204:207], v[188:191], v[112:115]
	v_mfma_f32_16x16x32_bf16 v[104:107], v[204:207], v[196:199], v[104:107]
	v_mfma_f32_16x16x32_bf16 v[96:99], v[216:219], v[188:191], v[96:99]
	v_mfma_f32_16x16x32_bf16 v[92:95], v[216:219], v[196:199], v[92:95]
	v_mfma_f32_16x16x32_bf16 v[80:83], v[224:227], v[188:191], v[80:83]
	v_mfma_f32_16x16x32_bf16 v[72:75], v[224:227], v[196:199], v[72:75]
	v_mfma_f32_16x16x32_bf16 v[68:71], v[232:235], v[188:191], v[68:71]
	v_mfma_f32_16x16x32_bf16 v[64:67], v[232:235], v[196:199], v[64:67]
	s_setprio 0
	s_barrier
; #define STAGE(P, g) do { const char* g_ = (const char*)(g); \
;         __builtin_amdgcn_global_load_lds((const unsigned*)(g_ + so0), (lds_u32*)((lds_u8*)(P) + sb0), 16, 0, 0); \
;         __builtin_amdgcn_global_load_lds((const unsigned*)(g_ + so1), (lds_u32*)((lds_u8*)(P) + sb0 + 8192), 16, 0, 0); } while (0)
; #define LDA(dst, b, h) for (int m = 0; m < 4; ++m) for (int k = 0; k < 2; ++k) \
;         dst[m][k] = *reinterpret_cast<const bf16x8*>((char*)SA(b, h) + lds_byte(wr * 64 + m * 16 + fr, k * 32 + fq * 8))
; #define MMA(ai, bj, At_, Bt_) do { __builtin_amdgcn_s_setprio(1); \
;         for (int m = 0; m < 4; ++m) for (int n = 0; n < 2; ++n) for (int k = 0; k < 2; ++k) \
;             acc[ai][bj][m][n] = __builtin_amdgcn_mfma_f32_16x16x32_bf16(At_[m][k], Bt_[n][k], acc[ai][bj][m][n], 0, 0, 0); \
;         __builtin_amdgcn_s_setprio(0); } while (0)
; #define WAIT_V(n) asm volatile("s_waitcnt vmcnt(" #n ")" ::: "memory")
; #define WAIT_L(n) asm volatile("s_waitcnt lgkmcnt(" #n ")" ::: "memory")
; #define BAR __builtin_amdgcn_s_barrier()
; #define SCHED __builtin_amdgcn_sched_barrier(0)
; template <int EPI, int K, int LNI = -1>
; DI void ph_gemm(const Params& p, const bf16_t* __restrict__ A, const bf16_t* __restrict__ Bt, int N, float* s_aux) {
;     ...
;             LDA(At, 1, 1); STAGE(SB(1, 0), b3); STAGE(SB(1, 1), b3 + hstep); STAGE(SA(1, 0), a3);
;             WAIT_V(8); WAIT_L(0); BAR; MMA(1, 0, At, B0); MMA(1, 1, At, B1); BAR; SCHED;
;         }
;         if (wr == 0) BAR;
	v_readfirstlane_b32 s44, v150
	v_lshl_add_u64 v[140:141], v[140:141], 0, s[6:7]
	s_mov_b32 m0, s44
	v_readfirstlane_b32 s44, v151
	s_add_u32 s28, s28, 0x40080
	ds_read_b128 v[200:203], v160 offset:49152
	ds_read_b128 v[204:207], v160 offset:50176
	ds_read_b128 v[212:215], v161 offset:49152
	ds_read_b128 v[216:219], v161 offset:50176
	ds_read_b128 v[220:223], v162 offset:49152
	ds_read_b128 v[224:227], v162 offset:50176
	ds_read_b128 v[228:231], v163 offset:49152
	ds_read_b128 v[232:235], v163 offset:50176
	global_load_lds_dwordx4 v[140:141], off
	v_lshl_add_u64 v[140:141], v[208:209], 0, s[6:7]
	s_mov_b32 m0, s44
	s_addc_u32 s29, s29, 0
	v_readfirstlane_b32 s44, v154
	global_load_lds_dwordx4 v[140:141], off
	v_lshl_add_u64 v[140:141], s[28:29], 0, v[128:129]
	s_mov_b32 m0, s44
	s_nop 0
	global_load_lds_dwordx4 v[140:141], off
	v_lshl_add_u64 v[140:141], s[28:29], 0, v[130:131]
	v_readfirstlane_b32 s28, v155
	s_mov_b32 m0, s28
	v_readfirstlane_b32 s28, v152
	global_load_lds_dwordx4 v[140:141], off
	v_lshl_add_u64 v[140:141], v[236:237], 0, s[6:7]
	s_mov_b32 m0, s28
	v_readfirstlane_b32 s28, v153
	global_load_lds_dwordx4 v[140:141], off
	v_lshl_add_u64 v[140:141], v[238:239], 0, s[6:7]
	s_mov_b32 m0, s28
	s_nop 0
	global_load_lds_dwordx4 v[140:141], off
	s_waitcnt vmcnt(8)
	s_waitcnt lgkmcnt(0)
	s_barrier
	s_setprio 1
	s_waitcnt lgkmcnt(0)
	v_mfma_f32_16x16x32_bf16 v[60:63], v[200:203], v[168:171], v[60:63]
	v_mfma_f32_16x16x32_bf16 v[56:59], v[200:203], v[176:179], v[56:59]
	v_mfma_f32_16x16x32_bf16 v[44:47], v[212:215], v[168:171], v[44:47]
	v_mfma_f32_16x16x32_bf16 v[40:43], v[212:215], v[176:179], v[40:43]
	v_mfma_f32_16x16x32_bf16 v[36:39], v[220:223], v[168:171], v[36:39]
	v_mfma_f32_16x16x32_bf16 v[28:31], v[220:223], v[176:179], v[28:31]
	v_mfma_f32_16x16x32_bf16 v[20:23], v[228:231], v[168:171], v[20:23]
	v_mfma_f32_16x16x32_bf16 v[12:15], v[228:231], v[176:179], v[12:15]
	v_mfma_f32_16x16x32_bf16 v[60:63], v[204:207], v[172:175], v[60:63]
	v_mfma_f32_16x16x32_bf16 v[56:59], v[204:207], v[180:183], v[56:59]
	v_mfma_f32_16x16x32_bf16 v[44:47], v[216:219], v[172:175], v[44:47]
	v_mfma_f32_16x16x32_bf16 v[40:43], v[216:219], v[180:183], v[40:43]
	v_mfma_f32_16x16x32_bf16 v[36:39], v[224:227], v[172:175], v[36:39]
	v_mfma_f32_16x16x32_bf16 v[28:31], v[224:227], v[180:183], v[28:31]
	v_mfma_f32_16x16x32_bf16 v[20:23], v[232:235], v[172:175], v[20:23]
	v_mfma_f32_16x16x32_bf16 v[12:15], v[232:235], v[180:183], v[12:15]
	s_setprio 0
	s_setprio 1
	v_mfma_f32_16x16x32_bf16 v[52:55], v[200:203], v[184:187], v[52:55]
	v_mfma_f32_16x16x32_bf16 v[48:51], v[200:203], v[192:195], v[48:51]
	v_mfma_f32_16x16x32_bf16 v[32:35], v[212:215], v[184:187], v[32:35]
	v_mfma_f32_16x16x32_bf16 v[24:27], v[212:215], v[192:195], v[24:27]
	v_mfma_f32_16x16x32_bf16 v[16:19], v[220:223], v[184:187], v[16:19]
	v_mfma_f32_16x16x32_bf16 v[8:11], v[220:223], v[192:195], v[8:11]
	v_mfma_f32_16x16x32_bf16 v[4:7], v[228:231], v[184:187], v[4:7]
	v_mfma_f32_16x16x32_bf16 v[0:3], v[228:231], v[192:195], v[0:3]
	v_mfma_f32_16x16x32_bf16 v[52:55], v[204:207], v[188:191], v[52:55]
	v_mfma_f32_16x16x32_bf16 v[48:51], v[204:207], v[196:199], v[48:51]
	v_mfma_f32_16x16x32_bf16 v[32:35], v[216:219], v[188:191], v[32:35]
	v_mfma_f32_16x16x32_bf16 v[24:27], v[216:219], v[196:199], v[24:27]
	v_mfma_f32_16x16x32_bf16 v[16:19], v[224:227], v[188:191], v[16:19]
	v_mfma_f32_16x16x32_bf16 v[8:11], v[224:227], v[196:199], v[8:11]
	v_mfma_f32_16x16x32_bf16 v[4:7], v[232:235], v[188:191], v[4:7]
	v_mfma_f32_16x16x32_bf16 v[0:3], v[232:235], v[196:199], v[0:3]
	s_setprio 0
	s_add_i32 s52, s52, 2
	s_add_u32 s26, s26, 0x100
	s_addc_u32 s27, s27, 0
	s_cmp_gt_u32 s52, 13
	s_barrier
	s_cbranch_scc0 .LBB0_794
	s_and_saveexec_b64 s[26:27], s[4:5]
	s_cbranch_execz .LBB0_797
	s_barrier

; #define STAGE(P, g) do { const char* g_ = (const char*)(g); \
;         __builtin_amdgcn_global_load_lds((const unsigned*)(g_ + so0), (lds_u32*)((lds_u8*)(P) + sb0), 16, 0, 0); \
;         __builtin_amdgcn_global_load_lds((const unsigned*)(g_ + so1), (lds_u32*)((lds_u8*)(P) + sb0 + 8192), 16, 0, 0); } while (0)
; #define LDA(dst, b, h) for (int m = 0; m < 4; ++m) for (int k = 0; k < 2; ++k) \
;         dst[m][k] = *reinterpret_cast<const bf16x8*>((char*)SA(b, h) + lds_byte(wr * 64 + m * 16 + fr, k * 32 + fq * 8))
; #define LDB(dst, b, h) for (int n = 0; n < 2; ++n) for (int k = 0; k < 2; ++k) \
;         dst[n][k] = *reinterpret_cast<const bf16x8*>((char*)SB(b, h) + lds_byte(wc * 32 + n * 16 + fr, k * 32 + fq * 8))
; #define MMA(ai, bj, At_, Bt_) do { __builtin_amdgcn_s_setprio(1); \
;         for (int m = 0; m < 4; ++m) for (int n = 0; n < 2; ++n) for (int k = 0; k < 2; ++k) \
;             acc[ai][bj][m][n] = __builtin_amdgcn_mfma_f32_16x16x32_bf16(At_[m][k], Bt_[n][k], acc[ai][bj][m][n], 0, 0, 0); \
;         __builtin_amdgcn_s_setprio(0); } while (0)
; #define WAIT_V(n) asm volatile("s_waitcnt vmcnt(" #n ")" ::: "memory")
; #define WAIT_L(n) asm volatile("s_waitcnt lgkmcnt(" #n ")" ::: "memory")
; #define BAR __builtin_amdgcn_s_barrier()
; #define SCHED __builtin_amdgcn_sched_barrier(0)
; template <int EPI, int K, int LNI = -1>
; DI void ph_gemm(const Params& p, const bf16_t* __restrict__ A, const bf16_t* __restrict__ Bt, int N, float* s_aux) {
;     ...
;         for (int t = 0; t < nt; t += 2) {
;             const bool last = (t == nt - 2);
;             const bf16_t* a1 = cA + (size_t)(t + 1) * kstep;
;             const bf16_t* a2 = last ? nA : cA + (size_t)(t + 2) * kstep; const bf16_t* b2 = last ? nB : cB + (size_t)(t + 2) * kstep;
;             const bf16_t* a3 = a2 + kstep; const bf16_t* b3 = b2 + kstep;
;             LDB(B0, 0, 0); LDB(B1, 0, 1); SCHED; LDA(At, 0, 0); STAGE(SA(1, 1), a1 + hstep);
;             WAIT_V(8); WAIT_L(0); BAR; MMA(0, 0, At, B0); MMA(0, 1, At, B1); BAR; SCHED;
;             LDA(At, 0, 1); STAGE(SB(0, 0), b2); STAGE(SB(0, 1), b2 + hstep); STAGE(SA(0, 0), a2);
;             WAIT_V(8); WAIT_L(0); BAR; MMA(1, 0, At, B0); MMA(1, 1, At, B1); BAR; SCHED;
.LBB0_927:
	s_ashr_i32 s15, s14, 31
	s_lshl_b64 s[20:21], s[14:15], 19
	s_add_u32 s15, s40, s20
	s_addc_u32 s42, s41, s21
	s_ashr_i32 s19, s18, 31
	s_lshl_b64 s[22:23], s[18:19], 19
	s_add_u32 s19, s8, s22
	s_addc_u32 s43, s9, s23
	s_add_u32 s50, s56, s28
	s_addc_u32 s51, s57, s29
	s_add_u32 s52, s35, s44
	v_lshl_add_u64 v[136:137], v[132:133], 0, s[28:29]
	v_lshl_add_u64 v[138:139], v[134:135], 0, s[28:29]
	s_addc_u32 s53, s48, s45
	s_mov_b32 s60, -2
	s_mov_b64 s[28:29], 0
	ds_read_b128 v[166:169], v156
	ds_read_b128 v[170:173], v156 offset:1024
	ds_read_b128 v[174:177], v156 offset:2048
	ds_read_b128 v[178:181], v156 offset:3072
	ds_read_b128 v[182:185], v157
	ds_read_b128 v[186:189], v157 offset:1024
	ds_read_b128 v[190:193], v157 offset:2048
	ds_read_b128 v[194:197], v157 offset:3072
	s_add_u32 s44, s50, s28
	s_addc_u32 s45, s51, s29
	s_add_u32 s44, s44, 0xb840100
	s_addc_u32 s45, s45, 0
	s_add_u32 s61, s52, s28
	s_addc_u32 s66, s53, s29
	s_cmpk_eq_i32 s28, 0x700
	s_cselect_b32 s47, s42, s45
	s_cselect_b32 s46, s15, s44
	s_cselect_b32 s45, s43, s66
	s_cselect_b32 s44, s19, s61
	v_readfirstlane_b32 s61, v162
	v_lshl_add_u64 v[232:233], v[136:137], 0, s[28:29]
	s_mov_b32 m0, s61
	v_readfirstlane_b32 s61, v163
	ds_read_b128 v[198:201], v158
	ds_read_b128 v[202:205], v158 offset:1024
	ds_read_b128 v[206:209], v159
	ds_read_b128 v[212:215], v159 offset:1024
	ds_read_b128 v[216:219], v160
	ds_read_b128 v[220:223], v160 offset:1024
	ds_read_b128 v[224:227], v161
	ds_read_b128 v[228:231], v161 offset:1024
	global_load_lds_dwordx4 v[232:233], off
	v_lshl_add_u64 v[232:233], v[138:139], 0, s[28:29]
	s_mov_b32 m0, s61
	s_nop 0
	global_load_lds_dwordx4 v[232:233], off
	s_waitcnt vmcnt(8)
	s_waitcnt lgkmcnt(0)
	s_barrier
	s_setprio 1
	s_waitcnt lgkmcnt(0)
	v_mfma_f32_16x16x32_bf16 v[124:127], v[198:201], v[166:169], 0
	v_mfma_f32_16x16x32_bf16 v[120:123], v[198:201], v[174:177], 0
	v_mfma_f32_16x16x32_bf16 v[108:111], v[206:209], v[166:169], 0
	v_mfma_f32_16x16x32_bf16 v[104:107], v[206:209], v[174:177], 0
	v_mfma_f32_16x16x32_bf16 v[92:95], v[216:219], v[166:169], 0
	v_mfma_f32_16x16x32_bf16 v[88:91], v[216:219], v[174:177], 0
	v_mfma_f32_16x16x32_bf16 v[76:79], v[224:227], v[166:169], 0
	v_mfma_f32_16x16x32_bf16 v[72:75], v[224:227], v[174:177], 0
	v_mfma_f32_16x16x32_bf16 v[124:127], v[202:205], v[170:173], v[124:127]
	v_mfma_f32_16x16x32_bf16 v[120:123], v[202:205], v[178:181], v[120:123]
	v_mfma_f32_16x16x32_bf16 v[108:111], v[212:215], v[170:173], v[108:111]
	v_mfma_f32_16x16x32_bf16 v[104:107], v[212:215], v[178:181], v[104:107]
	v_mfma_f32_16x16x32_bf16 v[92:95], v[220:223], v[170:173], v[92:95]
	v_mfma_f32_16x16x32_bf16 v[88:91], v[220:223], v[178:181], v[88:91]
	v_mfma_f32_16x16x32_bf16 v[76:79], v[228:231], v[170:173], v[76:79]
	v_mfma_f32_16x16x32_bf16 v[72:75], v[228:231], v[178:181], v[72:75]
	s_setprio 0
	s_setprio 1
	v_mfma_f32_16x16x32_bf16 v[116:119], v[198:201], v[182:185], 0
	v_mfma_f32_16x16x32_bf16 v[112:115], v[198:201], v[190:193], 0
	v_mfma_f32_16x16x32_bf16 v[100:103], v[206:209], v[182:185], 0
	v_mfma_f32_16x16x32_bf16 v[96:99], v[206:209], v[190:193], 0
	v_mfma_f32_16x16x32_bf16 v[84:87], v[216:219], v[182:185], 0
	v_mfma_f32_16x16x32_bf16 v[80:83], v[216:219], v[190:193], 0
	v_mfma_f32_16x16x32_bf16 v[68:71], v[224:227], v[182:185], 0
	v_mfma_f32_16x16x32_bf16 v[64:67], v[224:227], v[190:193], 0
	v_mfma_f32_16x16x32_bf16 v[116:119], v[202:205], v[186:189], v[116:119]
	v_mfma_f32_16x16x32_bf16 v[112:115], v[202:205], v[194:197], v[112:115]
	v_mfma_f32_16x16x32_bf16 v[100:103], v[212:215], v[186:189], v[100:103]
	v_mfma_f32_16x16x32_bf16 v[96:99], v[212:215], v[194:197], v[96:99]
	v_mfma_f32_16x16x32_bf16 v[84:87], v[220:223], v[186:189], v[84:87]
	v_mfma_f32_16x16x32_bf16 v[80:83], v[220:223], v[194:197], v[80:83]
	v_mfma_f32_16x16x32_bf16 v[68:71], v[228:231], v[186:189], v[68:71]
	v_mfma_f32_16x16x32_bf16 v[64:67], v[228:231], v[194:197], v[64:67]
	s_setprio 0
	s_barrier
	v_readfirstlane_b32 s61, v140
	v_lshl_add_u64 v[232:233], s[44:45], 0, v[128:129]
	s_mov_b32 m0, s61
	v_readfirstlane_b32 s61, v141
	s_add_u32 s66, s44, 0x40000
	ds_read_b128 v[198:201], v158 offset:16384
	ds_read_b128 v[202:205], v158 offset:17408
	ds_read_b128 v[206:209], v159 offset:16384
	ds_read_b128 v[212:215], v159 offset:17408
	ds_read_b128 v[216:219], v160 offset:16384
	ds_read_b128 v[220:223], v160 offset:17408
	ds_read_b128 v[224:227], v161 offset:16384
	ds_read_b128 v[228:231], v161 offset:17408
	global_load_lds_dwordx4 v[232:233], off
	v_lshl_add_u64 v[234:235], s[44:45], 0, v[130:131]
	s_mov_b32 m0, s61
	s_addc_u32 s67, s45, 0
	v_readfirstlane_b32 s61, v142
	global_load_lds_dwordx4 v[234:235], off
	v_lshl_add_u64 v[236:237], s[66:67], 0, v[128:129]
	s_mov_b32 m0, s61
	v_readfirstlane_b32 s61, v143
	global_load_lds_dwordx4 v[236:237], off
	v_lshl_add_u64 v[236:237], s[66:67], 0, v[130:131]
	s_mov_b32 m0, s61
	v_readfirstlane_b32 s61, v144
	global_load_lds_dwordx4 v[236:237], off
	v_lshl_add_u64 v[236:237], s[46:47], 0, v[128:129]
	s_mov_b32 m0, s61
	v_readfirstlane_b32 s61, v145
	global_load_lds_dwordx4 v[236:237], off
	v_lshl_add_u64 v[238:239], s[46:47], 0, v[130:131]
	s_mov_b32 m0, s61
	s_nop 0
	global_load_lds_dwordx4 v[238:239], off
	s_waitcnt vmcnt(8)
	s_waitcnt lgkmcnt(0)
	s_barrier
; #define STAGE(P, g) do { const char* g_ = (const char*)(g); \
;         __builtin_amdgcn_global_load_lds((const unsigned*)(g_ + so0), (lds_u32*)((lds_u8*)(P) + sb0), 16, 0, 0); \
;         __builtin_amdgcn_global_load_lds((const unsigned*)(g_ + so1), (lds_u32*)((lds_u8*)(P) + sb0 + 8192), 16, 0, 0); } while (0)
; #define LDA(dst, b, h) for (int m = 0; m < 4; ++m) for (int k = 0; k < 2; ++k) \
;         dst[m][k] = *reinterpret_cast<const bf16x8*>((char*)SA(b, h) + lds_byte(wr * 64 + m * 16 + fr, k * 32 + fq * 8))
; #define LDB(dst, b, h) for (int n = 0; n < 2; ++n) for (int k = 0; k < 2; ++k) \
;         dst[n][k] = *reinterpret_cast<const bf16x8*>((char*)SB(b, h) + lds_byte(wc * 32 + n * 16 + fr, k * 32 + fq * 8))
; #define MMA(ai, bj, At_, Bt_) do { __builtin_amdgcn_s_setprio(1); \
;         for (int m = 0; m < 4; ++m) for (int n = 0; n < 2; ++n) for (int k = 0; k < 2; ++k) \
;             acc[ai][bj][m][n] = __builtin_amdgcn_mfma_f32_16x16x32_bf16(At_[m][k], Bt_[n][k], acc[ai][bj][m][n], 0, 0, 0); \
;         __builtin_amdgcn_s_setprio(0); } while (0)
; #define WAIT_V(n) asm volatile("s_waitcnt vmcnt(" #n ")" ::: "memory")
; #define WAIT_L(n) asm volatile("s_waitcnt lgkmcnt(" #n ")" ::: "memory")
; #define BAR __builtin_amdgcn_s_barrier()
; #define SCHED __builtin_amdgcn_sched_barrier(0)
; template <int EPI, int K, int LNI = -1>
; DI void ph_gemm(const Params& p, const bf16_t* __restrict__ A, const bf16_t* __restrict__ Bt, int N, float* s_aux) {
;     ...
;             WAIT_V(8); WAIT_L(0); BAR; MMA(0, 0, At, B0); MMA(0, 1, At, B1); BAR; SCHED;
;             LDA(At, 0, 1); STAGE(SB(0, 0), b2); STAGE(SB(0, 1), b2 + hstep); STAGE(SA(0, 0), a2);
;             WAIT_V(8); WAIT_L(0); BAR; MMA(1, 0, At, B0); MMA(1, 1, At, B1); BAR; SCHED;
;             LDB(B0, 1, 0); LDB(B1, 1, 1); SCHED; LDA(At, 1, 0); STAGE(SA(0, 1), a2 + hstep);
;             WAIT_V(8); WAIT_L(0); BAR; MMA(0, 0, At, B0); MMA(0, 1, At, B1); BAR; SCHED;
	s_setprio 1
	s_waitcnt lgkmcnt(0)
	v_mfma_f32_16x16x32_bf16 v[60:63], v[198:201], v[166:169], 0
	v_mfma_f32_16x16x32_bf16 v[56:59], v[198:201], v[174:177], 0
	v_mfma_f32_16x16x32_bf16 v[44:47], v[206:209], v[166:169], 0
	v_mfma_f32_16x16x32_bf16 v[40:43], v[206:209], v[174:177], 0
	v_mfma_f32_16x16x32_bf16 v[28:31], v[216:219], v[166:169], 0
	v_mfma_f32_16x16x32_bf16 v[24:27], v[216:219], v[174:177], 0
	v_mfma_f32_16x16x32_bf16 v[12:15], v[224:227], v[166:169], 0
	v_mfma_f32_16x16x32_bf16 v[8:11], v[224:227], v[174:177], 0
	v_mfma_f32_16x16x32_bf16 v[60:63], v[202:205], v[170:173], v[60:63]
	v_mfma_f32_16x16x32_bf16 v[56:59], v[202:205], v[178:181], v[56:59]
	v_mfma_f32_16x16x32_bf16 v[44:47], v[212:215], v[170:173], v[44:47]
	v_mfma_f32_16x16x32_bf16 v[40:43], v[212:215], v[178:181], v[40:43]
	v_mfma_f32_16x16x32_bf16 v[28:31], v[220:223], v[170:173], v[28:31]
	v_mfma_f32_16x16x32_bf16 v[24:27], v[220:223], v[178:181], v[24:27]
	v_mfma_f32_16x16x32_bf16 v[12:15], v[228:231], v[170:173], v[12:15]
	v_mfma_f32_16x16x32_bf16 v[8:11], v[228:231], v[178:181], v[8:11]
	s_setprio 0
	s_setprio 1
	v_mfma_f32_16x16x32_bf16 v[52:55], v[198:201], v[182:185], 0
	v_mfma_f32_16x16x32_bf16 v[48:51], v[198:201], v[190:193], 0
	v_mfma_f32_16x16x32_bf16 v[36:39], v[206:209], v[182:185], 0
	v_mfma_f32_16x16x32_bf16 v[32:35], v[206:209], v[190:193], 0
	v_mfma_f32_16x16x32_bf16 v[20:23], v[216:219], v[182:185], 0
	v_mfma_f32_16x16x32_bf16 v[16:19], v[216:219], v[190:193], 0
	v_mfma_f32_16x16x32_bf16 v[4:7], v[224:227], v[182:185], 0
	v_mfma_f32_16x16x32_bf16 v[0:3], v[224:227], v[190:193], 0
	v_mfma_f32_16x16x32_bf16 v[52:55], v[202:205], v[186:189], v[52:55]
	v_mfma_f32_16x16x32_bf16 v[48:51], v[202:205], v[194:197], v[48:51]
	v_mfma_f32_16x16x32_bf16 v[36:39], v[212:215], v[186:189], v[36:39]
	v_mfma_f32_16x16x32_bf16 v[32:35], v[212:215], v[194:197], v[32:35]
	v_mfma_f32_16x16x32_bf16 v[20:23], v[220:223], v[186:189], v[20:23]
	v_mfma_f32_16x16x32_bf16 v[16:19], v[220:223], v[194:197], v[16:19]
	v_mfma_f32_16x16x32_bf16 v[4:7], v[228:231], v[186:189], v[4:7]
	v_mfma_f32_16x16x32_bf16 v[0:3], v[228:231], v[194:197], v[0:3]
	s_setprio 0
	s_barrier
	ds_read_b128 v[166:169], v164
	ds_read_b128 v[170:173], v164 offset:1024
	ds_read_b128 v[174:177], v164 offset:2048
	ds_read_b128 v[178:181], v164 offset:3072
	ds_read_b128 v[182:185], v165
	ds_read_b128 v[186:189], v165 offset:1024
	ds_read_b128 v[190:193], v165 offset:2048
	ds_read_b128 v[194:197], v165 offset:3072
	s_add_u32 s46, s46, 0x40000
	s_addc_u32 s47, s47, 0
	v_readfirstlane_b32 s61, v146
	v_lshl_add_u64 v[240:241], s[46:47], 0, v[128:129]
	s_mov_b32 m0, s61
	ds_read_b128 v[198:201], v158 offset:32768
	ds_read_b128 v[202:205], v158 offset:33792
	ds_read_b128 v[206:209], v159 offset:32768
	ds_read_b128 v[212:215], v159 offset:33792
	ds_read_b128 v[216:219], v160 offset:32768
	ds_read_b128 v[220:223], v160 offset:33792
	ds_read_b128 v[224:227], v161 offset:32768
	ds_read_b128 v[228:231], v161 offset:33792
	global_load_lds_dwordx4 v[240:241], off
	v_lshl_add_u64 v[240:241], s[46:47], 0, v[130:131]
	v_readfirstlane_b32 s46, v147
	s_mov_b32 m0, s46
	s_nop 0
	global_load_lds_dwordx4 v[240:241], off
	s_waitcnt vmcnt(8)
	s_waitcnt lgkmcnt(0)
	s_barrier
	s_setprio 1
	s_waitcnt lgkmcnt(0)
	v_mfma_f32_16x16x32_bf16 v[124:127], v[198:201], v[166:169], v[124:127]
	v_mfma_f32_16x16x32_bf16 v[120:123], v[198:201], v[174:177], v[120:123]
	v_mfma_f32_16x16x32_bf16 v[108:111], v[206:209], v[166:169], v[108:111]
	v_mfma_f32_16x16x32_bf16 v[104:107], v[206:209], v[174:177], v[104:107]
	v_mfma_f32_16x16x32_bf16 v[92:95], v[216:219], v[166:169], v[92:95]
	v_mfma_f32_16x16x32_bf16 v[88:91], v[216:219], v[174:177], v[88:91]
	v_mfma_f32_16x16x32_bf16 v[76:79], v[224:227], v[166:169], v[76:79]
	v_mfma_f32_16x16x32_bf16 v[72:75], v[224:227], v[174:177], v[72:75]
	v_mfma_f32_16x16x32_bf16 v[124:127], v[202:205], v[170:173], v[124:127]
	v_mfma_f32_16x16x32_bf16 v[120:123], v[202:205], v[178:181], v[120:123]
	v_mfma_f32_16x16x32_bf16 v[108:111], v[212:215], v[170:173], v[108:111]
	v_mfma_f32_16x16x32_bf16 v[104:107], v[212:215], v[178:181], v[104:107]
	v_mfma_f32_16x16x32_bf16 v[92:95], v[220:223], v[170:173], v[92:95]
	v_mfma_f32_16x16x32_bf16 v[88:91], v[220:223], v[178:181], v[88:91]
	v_mfma_f32_16x16x32_bf16 v[76:79], v[228:231], v[170:173], v[76:79]
	v_mfma_f32_16x16x32_bf16 v[72:75], v[228:231], v[178:181], v[72:75]
	s_setprio 0
	s_setprio 1
	v_mfma_f32_16x16x32_bf16 v[116:119], v[198:201], v[182:185], v[116:119]
	v_mfma_f32_16x16x32_bf16 v[112:115], v[198:201], v[190:193], v[112:115]
	v_mfma_f32_16x16x32_bf16 v[100:103], v[206:209], v[182:185], v[100:103]
	v_mfma_f32_16x16x32_bf16 v[96:99], v[206:209], v[190:193], v[96:99]
	v_mfma_f32_16x16x32_bf16 v[84:87], v[216:219], v[182:185], v[84:87]
	v_mfma_f32_16x16x32_bf16 v[80:83], v[216:219], v[190:193], v[80:83]
	v_mfma_f32_16x16x32_bf16 v[68:71], v[224:227], v[182:185], v[68:71]
	v_mfma_f32_16x16x32_bf16 v[64:67], v[224:227], v[190:193], v[64:67]
	v_mfma_f32_16x16x32_bf16 v[116:119], v[202:205], v[186:189], v[116:119]
	v_mfma_f32_16x16x32_bf16 v[112:115], v[202:205], v[194:197], v[112:115]
	v_mfma_f32_16x16x32_bf16 v[100:103], v[212:215], v[186:189], v[100:103]
	v_mfma_f32_16x16x32_bf16 v[96:99], v[212:215], v[194:197], v[96:99]
	v_mfma_f32_16x16x32_bf16 v[84:87], v[220:223], v[186:189], v[84:87]
	v_mfma_f32_16x16x32_bf16 v[80:83], v[220:223], v[194:197], v[80:83]
	v_mfma_f32_16x16x32_bf16 v[68:71], v[228:231], v[186:189], v[68:71]
	v_mfma_f32_16x16x32_bf16 v[64:67], v[228:231], v[194:197], v[64:67]
	s_setprio 0
	s_barrier
; #define STAGE(P, g) do { const char* g_ = (const char*)(g); \
;         __builtin_amdgcn_global_load_lds((const unsigned*)(g_ + so0), (lds_u32*)((lds_u8*)(P) + sb0), 16, 0, 0); \
;         __builtin_amdgcn_global_load_lds((const unsigned*)(g_ + so1), (lds_u32*)((lds_u8*)(P) + sb0 + 8192), 16, 0, 0); } while (0)
; #define LDA(dst, b, h) for (int m = 0; m < 4; ++m) for (int k = 0; k < 2; ++k) \
;         dst[m][k] = *reinterpret_cast<const bf16x8*>((char*)SA(b, h) + lds_byte(wr * 64 + m * 16 + fr, k * 32 + fq * 8))
; #define LDB(dst, b, h) for (int n = 0; n < 2; ++n) for (int k = 0; k < 2; ++k) \
;         dst[n][k] = *reinterpret_cast<const bf16x8*>((char*)SB(b, h) + lds_byte(wc * 32 + n * 16 + fr, k * 32 + fq * 8))
; #define MMA(ai, bj, At_, Bt_) do { __builtin_amdgcn_s_setprio(1); \
;         for (int m = 0; m < 4; ++m) for (int n = 0; n < 2; ++n) for (int k = 0; k < 2; ++k) \
;             acc[ai][bj][m][n] = __builtin_amdgcn_mfma_f32_16x16x32_bf16(At_[m][k], Bt_[n][k], acc[ai][bj][m][n], 0, 0, 0); \
;         __builtin_amdgcn_s_setprio(0); } while (0)
; #define WAIT_V(n) asm volatile("s_waitcnt vmcnt(" #n ")" ::: "memory")
; #define WAIT_L(n) asm volatile("s_waitcnt lgkmcnt(" #n ")" ::: "memory")
; #define BAR __builtin_amdgcn_s_barrier()
; #define SCHED __builtin_amdgcn_sched_barrier(0)
; template <int EPI, int K, int LNI = -1>
; DI void ph_gemm(const Params& p, const bf16_t* __restrict__ A, const bf16_t* __restrict__ Bt, int N, float* s_aux) {
;     ...
;         for (int t = 0; t < nt; t += 2) {
;             const bool last = (t == nt - 2);
;             const bf16_t* a1 = cA + (size_t)(t + 1) * kstep;
;             const bf16_t* a2 = last ? nA : cA + (size_t)(t + 2) * kstep; const bf16_t* b2 = last ? nB : cB + (size_t)(t + 2) * kstep;
;             const bf16_t* a3 = a2 + kstep; const bf16_t* b3 = b2 + kstep;
;             LDB(B0, 0, 0); LDB(B1, 0, 1); SCHED; LDA(At, 0, 0); STAGE(SA(1, 1), a1 + hstep);
;             WAIT_V(8); WAIT_L(0); BAR; MMA(0, 0, At, B0); MMA(0, 1, At, B1); BAR; SCHED;
;     ...
;             LDA(At, 1, 1); STAGE(SB(1, 0), b3); STAGE(SB(1, 1), b3 + hstep); STAGE(SA(1, 0), a3);
;             WAIT_V(8); WAIT_L(0); BAR; MMA(1, 0, At, B0); MMA(1, 1, At, B1); BAR; SCHED;
	v_readfirstlane_b32 s46, v148
	v_lshl_add_u64 v[232:233], v[232:233], 0, s[10:11]
	s_mov_b32 m0, s46
	v_readfirstlane_b32 s46, v149
	s_add_u32 s44, s44, 0x40080
	ds_read_b128 v[198:201], v158 offset:49152
	ds_read_b128 v[202:205], v158 offset:50176
	ds_read_b128 v[206:209], v159 offset:49152
	ds_read_b128 v[212:215], v159 offset:50176
	ds_read_b128 v[216:219], v160 offset:49152
	ds_read_b128 v[220:223], v160 offset:50176
	ds_read_b128 v[224:227], v161 offset:49152
	ds_read_b128 v[228:231], v161 offset:50176
	global_load_lds_dwordx4 v[232:233], off
	v_lshl_add_u64 v[232:233], v[234:235], 0, s[10:11]
	s_mov_b32 m0, s46
	s_addc_u32 s45, s45, 0
	v_readfirstlane_b32 s46, v152
	global_load_lds_dwordx4 v[232:233], off
	v_lshl_add_u64 v[232:233], s[44:45], 0, v[128:129]
	s_mov_b32 m0, s46
	s_nop 0
	global_load_lds_dwordx4 v[232:233], off
	v_lshl_add_u64 v[232:233], s[44:45], 0, v[130:131]
	v_readfirstlane_b32 s44, v153
	s_mov_b32 m0, s44
	v_readfirstlane_b32 s44, v150
	global_load_lds_dwordx4 v[232:233], off
	v_lshl_add_u64 v[232:233], v[236:237], 0, s[10:11]
	s_mov_b32 m0, s44
	v_readfirstlane_b32 s44, v151
	global_load_lds_dwordx4 v[232:233], off
	v_lshl_add_u64 v[232:233], v[238:239], 0, s[10:11]
	s_mov_b32 m0, s44
	s_nop 0
	global_load_lds_dwordx4 v[232:233], off
	s_waitcnt vmcnt(8)
	s_waitcnt lgkmcnt(0)
	s_barrier
	s_setprio 1
	s_waitcnt lgkmcnt(0)
	v_mfma_f32_16x16x32_bf16 v[60:63], v[198:201], v[166:169], v[60:63]
	v_mfma_f32_16x16x32_bf16 v[56:59], v[198:201], v[174:177], v[56:59]
	v_mfma_f32_16x16x32_bf16 v[44:47], v[206:209], v[166:169], v[44:47]
	v_mfma_f32_16x16x32_bf16 v[40:43], v[206:209], v[174:177], v[40:43]
	v_mfma_f32_16x16x32_bf16 v[28:31], v[216:219], v[166:169], v[28:31]
	v_mfma_f32_16x16x32_bf16 v[24:27], v[216:219], v[174:177], v[24:27]
	v_mfma_f32_16x16x32_bf16 v[12:15], v[224:227], v[166:169], v[12:15]
	v_mfma_f32_16x16x32_bf16 v[8:11], v[224:227], v[174:177], v[8:11]
	v_mfma_f32_16x16x32_bf16 v[60:63], v[202:205], v[170:173], v[60:63]
	v_mfma_f32_16x16x32_bf16 v[56:59], v[202:205], v[178:181], v[56:59]
	v_mfma_f32_16x16x32_bf16 v[44:47], v[212:215], v[170:173], v[44:47]
	v_mfma_f32_16x16x32_bf16 v[40:43], v[212:215], v[178:181], v[40:43]
	v_mfma_f32_16x16x32_bf16 v[28:31], v[220:223], v[170:173], v[28:31]
	v_mfma_f32_16x16x32_bf16 v[24:27], v[220:223], v[178:181], v[24:27]
	v_mfma_f32_16x16x32_bf16 v[12:15], v[228:231], v[170:173], v[12:15]
	v_mfma_f32_16x16x32_bf16 v[8:11], v[228:231], v[178:181], v[8:11]
	s_setprio 0
	s_setprio 1
	v_mfma_f32_16x16x32_bf16 v[52:55], v[198:201], v[182:185], v[52:55]
	v_mfma_f32_16x16x32_bf16 v[48:51], v[198:201], v[190:193], v[48:51]
	v_mfma_f32_16x16x32_bf16 v[36:39], v[206:209], v[182:185], v[36:39]
	v_mfma_f32_16x16x32_bf16 v[32:35], v[206:209], v[190:193], v[32:35]
	v_mfma_f32_16x16x32_bf16 v[20:23], v[216:219], v[182:185], v[20:23]
	v_mfma_f32_16x16x32_bf16 v[16:19], v[216:219], v[190:193], v[16:19]
	v_mfma_f32_16x16x32_bf16 v[4:7], v[224:227], v[182:185], v[4:7]
	v_mfma_f32_16x16x32_bf16 v[0:3], v[224:227], v[190:193], v[0:3]
	v_mfma_f32_16x16x32_bf16 v[52:55], v[202:205], v[186:189], v[52:55]
	v_mfma_f32_16x16x32_bf16 v[48:51], v[202:205], v[194:197], v[48:51]
	v_mfma_f32_16x16x32_bf16 v[36:39], v[212:215], v[186:189], v[36:39]
	v_mfma_f32_16x16x32_bf16 v[32:35], v[212:215], v[194:197], v[32:35]
	v_mfma_f32_16x16x32_bf16 v[20:23], v[220:223], v[186:189], v[20:23]
	v_mfma_f32_16x16x32_bf16 v[16:19], v[220:223], v[194:197], v[16:19]
	v_mfma_f32_16x16x32_bf16 v[4:7], v[228:231], v[186:189], v[4:7]
	v_mfma_f32_16x16x32_bf16 v[0:3], v[228:231], v[194:197], v[0:3]
	s_setprio 0
	s_add_i32 s60, s60, 2
	s_add_u32 s28, s28, 0x100
	s_addc_u32 s29, s29, 0
	s_cmp_gt_u32 s60, 13
	s_barrier
.LBB0_928:
	ds_read_b128 v[166:169], v156
	ds_read_b128 v[170:173], v156 offset:1024
	ds_read_b128 v[174:177], v156 offset:2048
	ds_read_b128 v[178:181], v156 offset:3072
	ds_read_b128 v[182:185], v157
	ds_read_b128 v[186:189], v157 offset:1024
	ds_read_b128 v[190:193], v157 offset:2048
	ds_read_b128 v[194:197], v157 offset:3072
	s_add_u32 s44, s50, s28
	s_addc_u32 s45, s51, s29
	s_add_u32 s44, s44, 0xb840100
	s_addc_u32 s45, s45, 0
	s_add_u32 s61, s52, s28
	s_addc_u32 s66, s53, s29
	s_cmpk_eq_i32 s28, 0x700
	s_cselect_b32 s47, s42, s45
	s_cselect_b32 s46, s15, s44
	s_cselect_b32 s45, s43, s66
	s_cselect_b32 s44, s19, s61
	v_readfirstlane_b32 s61, v162
	v_lshl_add_u64 v[232:233], v[136:137], 0, s[28:29]
	s_mov_b32 m0, s61
	v_readfirstlane_b32 s61, v163
	ds_read_b128 v[198:201], v158
	ds_read_b128 v[202:205], v158 offset:1024
	ds_read_b128 v[206:209], v159
	ds_read_b128 v[212:215], v159 offset:1024
	ds_read_b128 v[216:219], v160
	ds_read_b128 v[220:223], v160 offset:1024
	ds_read_b128 v[224:227], v161
	ds_read_b128 v[228:231], v161 offset:1024
	global_load_lds_dwordx4 v[232:233], off
	v_lshl_add_u64 v[232:233], v[138:139], 0, s[28:29]
	s_mov_b32 m0, s61
	s_nop 0
	global_load_lds_dwordx4 v[232:233], off
	s_waitcnt vmcnt(8)
	s_waitcnt lgkmcnt(0)
	s_barrier
; #define STAGE(P, g) do { const char* g_ = (const char*)(g); \
;         __builtin_amdgcn_global_load_lds((const unsigned*)(g_ + so0), (lds_u32*)((lds_u8*)(P) + sb0), 16, 0, 0); \
;         __builtin_amdgcn_global_load_lds((const unsigned*)(g_ + so1), (lds_u32*)((lds_u8*)(P) + sb0 + 8192), 16, 0, 0); } while (0)
; #define LDA(dst, b, h) for (int m = 0; m < 4; ++m) for (int k = 0; k < 2; ++k) \
;         dst[m][k] = *reinterpret_cast<const bf16x8*>((char*)SA(b, h) + lds_byte(wr * 64 + m * 16 + fr, k * 32 + fq * 8))
; #define LDB(dst, b, h) for (int n = 0; n < 2; ++n) for (int k = 0; k < 2; ++k) \
;         dst[n][k] = *reinterpret_cast<const bf16x8*>((char*)SB(b, h) + lds_byte(wc * 32 + n * 16 + fr, k * 32 + fq * 8))
; #define MMA(ai, bj, At_, Bt_) do { __builtin_amdgcn_s_setprio(1); \
;         for (int m = 0; m < 4; ++m) for (int n = 0; n < 2; ++n) for (int k = 0; k < 2; ++k) \
;             acc[ai][bj][m][n] = __builtin_amdgcn_mfma_f32_16x16x32_bf16(At_[m][k], Bt_[n][k], acc[ai][bj][m][n], 0, 0, 0); \
;         __builtin_amdgcn_s_setprio(0); } while (0)
; #define WAIT_V(n) asm volatile("s_waitcnt vmcnt(" #n ")" ::: "memory")
; #define WAIT_L(n) asm volatile("s_waitcnt lgkmcnt(" #n ")" ::: "memory")
; #define BAR __builtin_amdgcn_s_barrier()
; #define SCHED __builtin_amdgcn_sched_barrier(0)
; template <int EPI, int K, int LNI = -1>
; DI void ph_gemm(const Params& p, const bf16_t* __restrict__ A, const bf16_t* __restrict__ Bt, int N, float* s_aux) {
;     ...
;             WAIT_V(8); WAIT_L(0); BAR; MMA(0, 0, At, B0); MMA(0, 1, At, B1); BAR; SCHED;
;             LDA(At, 0, 1); STAGE(SB(0, 0), b2); STAGE(SB(0, 1), b2 + hstep); STAGE(SA(0, 0), a2);
;             WAIT_V(8); WAIT_L(0); BAR; MMA(1, 0, At, B0); MMA(1, 1, At, B1); BAR; SCHED;
;             LDB(B0, 1, 0); LDB(B1, 1, 1); SCHED; LDA(At, 1, 0); STAGE(SA(0, 1), a2 + hstep);
;             WAIT_V(8); WAIT_L(0); BAR; MMA(0, 0, At, B0); MMA(0, 1, At, B1); BAR; SCHED;
	s_setprio 1
	s_waitcnt lgkmcnt(0)
	v_mfma_f32_16x16x32_bf16 v[124:127], v[198:201], v[166:169], v[124:127]
	v_mfma_f32_16x16x32_bf16 v[120:123], v[198:201], v[174:177], v[120:123]
	v_mfma_f32_16x16x32_bf16 v[108:111], v[206:209], v[166:169], v[108:111]
	v_mfma_f32_16x16x32_bf16 v[104:107], v[206:209], v[174:177], v[104:107]
	v_mfma_f32_16x16x32_bf16 v[92:95], v[216:219], v[166:169], v[92:95]
	v_mfma_f32_16x16x32_bf16 v[88:91], v[216:219], v[174:177], v[88:91]
	v_mfma_f32_16x16x32_bf16 v[76:79], v[224:227], v[166:169], v[76:79]
	v_mfma_f32_16x16x32_bf16 v[72:75], v[224:227], v[174:177], v[72:75]
	v_mfma_f32_16x16x32_bf16 v[124:127], v[202:205], v[170:173], v[124:127]
	v_mfma_f32_16x16x32_bf16 v[120:123], v[202:205], v[178:181], v[120:123]
	v_mfma_f32_16x16x32_bf16 v[108:111], v[212:215], v[170:173], v[108:111]
	v_mfma_f32_16x16x32_bf16 v[104:107], v[212:215], v[178:181], v[104:107]
	v_mfma_f32_16x16x32_bf16 v[92:95], v[220:223], v[170:173], v[92:95]
	v_mfma_f32_16x16x32_bf16 v[88:91], v[220:223], v[178:181], v[88:91]
	v_mfma_f32_16x16x32_bf16 v[76:79], v[228:231], v[170:173], v[76:79]
	v_mfma_f32_16x16x32_bf16 v[72:75], v[228:231], v[178:181], v[72:75]
	s_setprio 0
	s_setprio 1
	v_mfma_f32_16x16x32_bf16 v[116:119], v[198:201], v[182:185], v[116:119]
	v_mfma_f32_16x16x32_bf16 v[112:115], v[198:201], v[190:193], v[112:115]
	v_mfma_f32_16x16x32_bf16 v[100:103], v[206:209], v[182:185], v[100:103]
	v_mfma_f32_16x16x32_bf16 v[96:99], v[206:209], v[190:193], v[96:99]
	v_mfma_f32_16x16x32_bf16 v[84:87], v[216:219], v[182:185], v[84:87]
	v_mfma_f32_16x16x32_bf16 v[80:83], v[216:219], v[190:193], v[80:83]
	v_mfma_f32_16x16x32_bf16 v[68:71], v[224:227], v[182:185], v[68:71]
	v_mfma_f32_16x16x32_bf16 v[64:67], v[224:227], v[190:193], v[64:67]
	v_mfma_f32_16x16x32_bf16 v[116:119], v[202:205], v[186:189], v[116:119]
	v_mfma_f32_16x16x32_bf16 v[112:115], v[202:205], v[194:197], v[112:115]
	v_mfma_f32_16x16x32_bf16 v[100:103], v[212:215], v[186:189], v[100:103]
	v_mfma_f32_16x16x32_bf16 v[96:99], v[212:215], v[194:197], v[96:99]
	v_mfma_f32_16x16x32_bf16 v[84:87], v[220:223], v[186:189], v[84:87]
	v_mfma_f32_16x16x32_bf16 v[80:83], v[220:223], v[194:197], v[80:83]
	v_mfma_f32_16x16x32_bf16 v[68:71], v[228:231], v[186:189], v[68:71]
	v_mfma_f32_16x16x32_bf16 v[64:67], v[228:231], v[194:197], v[64:67]
	s_setprio 0
	s_barrier
	v_readfirstlane_b32 s61, v140
	v_lshl_add_u64 v[232:233], s[44:45], 0, v[128:129]
	s_mov_b32 m0, s61
	v_readfirstlane_b32 s61, v141
	s_add_u32 s66, s44, 0x40000
	ds_read_b128 v[198:201], v158 offset:16384
	ds_read_b128 v[202:205], v158 offset:17408
	ds_read_b128 v[206:209], v159 offset:16384
	ds_read_b128 v[212:215], v159 offset:17408
	ds_read_b128 v[216:219], v160 offset:16384
	ds_read_b128 v[220:223], v160 offset:17408
	ds_read_b128 v[224:227], v161 offset:16384
	ds_read_b128 v[228:231], v161 offset:17408
	global_load_lds_dwordx4 v[232:233], off
	v_lshl_add_u64 v[234:235], s[44:45], 0, v[130:131]
	s_mov_b32 m0, s61
	s_addc_u32 s67, s45, 0
	v_readfirstlane_b32 s61, v142
	global_load_lds_dwordx4 v[234:235], off
	v_lshl_add_u64 v[236:237], s[66:67], 0, v[128:129]
	s_mov_b32 m0, s61
	v_readfirstlane_b32 s61, v143
	global_load_lds_dwordx4 v[236:237], off
	v_lshl_add_u64 v[236:237], s[66:67], 0, v[130:131]
	s_mov_b32 m0, s61
	v_readfirstlane_b32 s61, v144
	global_load_lds_dwordx4 v[236:237], off
	v_lshl_add_u64 v[236:237], s[46:47], 0, v[128:129]
	s_mov_b32 m0, s61
	v_readfirstlane_b32 s61, v145
	global_load_lds_dwordx4 v[236:237], off
	v_lshl_add_u64 v[238:239], s[46:47], 0, v[130:131]
	s_mov_b32 m0, s61
	s_nop 0
	global_load_lds_dwordx4 v[238:239], off
	s_waitcnt vmcnt(8)
	s_waitcnt lgkmcnt(0)
	s_barrier
	s_setprio 1
	s_waitcnt lgkmcnt(0)
	v_mfma_f32_16x16x32_bf16 v[60:63], v[198:201], v[166:169], v[60:63]
	v_mfma_f32_16x16x32_bf16 v[56:59], v[198:201], v[174:177], v[56:59]
	v_mfma_f32_16x16x32_bf16 v[44:47], v[206:209], v[166:169], v[44:47]
	v_mfma_f32_16x16x32_bf16 v[40:43], v[206:209], v[174:177], v[40:43]
	v_mfma_f32_16x16x32_bf16 v[28:31], v[216:219], v[166:169], v[28:31]
	v_mfma_f32_16x16x32_bf16 v[24:27], v[216:219], v[174:177], v[24:27]
	v_mfma_f32_16x16x32_bf16 v[12:15], v[224:227], v[166:169], v[12:15]
	v_mfma_f32_16x16x32_bf16 v[8:11], v[224:227], v[174:177], v[8:11]
	v_mfma_f32_16x16x32_bf16 v[60:63], v[202:205], v[170:173], v[60:63]
	v_mfma_f32_16x16x32_bf16 v[56:59], v[202:205], v[178:181], v[56:59]
	v_mfma_f32_16x16x32_bf16 v[44:47], v[212:215], v[170:173], v[44:47]
	v_mfma_f32_16x16x32_bf16 v[40:43], v[212:215], v[178:181], v[40:43]
	v_mfma_f32_16x16x32_bf16 v[28:31], v[220:223], v[170:173], v[28:31]
	v_mfma_f32_16x16x32_bf16 v[24:27], v[220:223], v[178:181], v[24:27]
	v_mfma_f32_16x16x32_bf16 v[12:15], v[228:231], v[170:173], v[12:15]
	v_mfma_f32_16x16x32_bf16 v[8:11], v[228:231], v[178:181], v[8:11]
	s_setprio 0
	s_setprio 1
	v_mfma_f32_16x16x32_bf16 v[52:55], v[198:201], v[182:185], v[52:55]
	v_mfma_f32_16x16x32_bf16 v[48:51], v[198:201], v[190:193], v[48:51]
	v_mfma_f32_16x16x32_bf16 v[36:39], v[206:209], v[182:185], v[36:39]
	v_mfma_f32_16x16x32_bf16 v[32:35], v[206:209], v[190:193], v[32:35]
	v_mfma_f32_16x16x32_bf16 v[20:23], v[216:219], v[182:185], v[20:23]
	v_mfma_f32_16x16x32_bf16 v[16:19], v[216:219], v[190:193], v[16:19]
	v_mfma_f32_16x16x32_bf16 v[4:7], v[224:227], v[182:185], v[4:7]
	v_mfma_f32_16x16x32_bf16 v[0:3], v[224:227], v[190:193], v[0:3]
	v_mfma_f32_16x16x32_bf16 v[52:55], v[202:205], v[186:189], v[52:55]
	v_mfma_f32_16x16x32_bf16 v[48:51], v[202:205], v[194:197], v[48:51]
	v_mfma_f32_16x16x32_bf16 v[36:39], v[212:215], v[186:189], v[36:39]
	v_mfma_f32_16x16x32_bf16 v[32:35], v[212:215], v[194:197], v[32:35]
	v_mfma_f32_16x16x32_bf16 v[20:23], v[220:223], v[186:189], v[20:23]
	v_mfma_f32_16x16x32_bf16 v[16:19], v[220:223], v[194:197], v[16:19]
	v_mfma_f32_16x16x32_bf16 v[4:7], v[228:231], v[186:189], v[4:7]
	v_mfma_f32_16x16x32_bf16 v[0:3], v[228:231], v[194:197], v[0:3]
	s_setprio 0
	s_barrier
; #define STAGE(P, g) do { const char* g_ = (const char*)(g); \
;         __builtin_amdgcn_global_load_lds((const unsigned*)(g_ + so0), (lds_u32*)((lds_u8*)(P) + sb0), 16, 0, 0); \
;         __builtin_amdgcn_global_load_lds((const unsigned*)(g_ + so1), (lds_u32*)((lds_u8*)(P) + sb0 + 8192), 16, 0, 0); } while (0)
; #define LDA(dst, b, h) for (int m = 0; m < 4; ++m) for (int k = 0; k < 2; ++k) \
;         dst[m][k] = *reinterpret_cast<const bf16x8*>((char*)SA(b, h) + lds_byte(wr * 64 + m * 16 + fr, k * 32 + fq * 8))
; #define LDB(dst, b, h) for (int n = 0; n < 2; ++n) for (int k = 0; k < 2; ++k) \
;         dst[n][k] = *reinterpret_cast<const bf16x8*>((char*)SB(b, h) + lds_byte(wc * 32 + n * 16 + fr, k * 32 + fq * 8))
; #define MMA(ai, bj, At_, Bt_) do { __builtin_amdgcn_s_setprio(1); \
;         for (int m = 0; m < 4; ++m) for (int n = 0; n < 2; ++n) for (int k = 0; k < 2; ++k) \
;             acc[ai][bj][m][n] = __builtin_amdgcn_mfma_f32_16x16x32_bf16(At_[m][k], Bt_[n][k], acc[ai][bj][m][n], 0, 0, 0); \
;         __builtin_amdgcn_s_setprio(0); } while (0)
; #define WAIT_V(n) asm volatile("s_waitcnt vmcnt(" #n ")" ::: "memory")
; #define WAIT_L(n) asm volatile("s_waitcnt lgkmcnt(" #n ")" ::: "memory")
; #define BAR __builtin_amdgcn_s_barrier()
; #define SCHED __builtin_amdgcn_sched_barrier(0)
; template <int EPI, int K, int LNI = -1>
; DI void ph_gemm(const Params& p, const bf16_t* __restrict__ A, const bf16_t* __restrict__ Bt, int N, float* s_aux) {
;     ...
;             LDB(B0, 1, 0); LDB(B1, 1, 1); SCHED; LDA(At, 1, 0); STAGE(SA(0, 1), a2 + hstep);
;             WAIT_V(8); WAIT_L(0); BAR; MMA(0, 0, At, B0); MMA(0, 1, At, B1); BAR; SCHED;
	ds_read_b128 v[166:169], v164
	ds_read_b128 v[170:173], v164 offset:1024
	ds_read_b128 v[174:177], v164 offset:2048
	ds_read_b128 v[178:181], v164 offset:3072
	ds_read_b128 v[182:185], v165
	ds_read_b128 v[186:189], v165 offset:1024
	ds_read_b128 v[190:193], v165 offset:2048
	ds_read_b128 v[194:197], v165 offset:3072
	s_add_u32 s46, s46, 0x40000
	s_addc_u32 s47, s47, 0
	v_readfirstlane_b32 s61, v146
	v_lshl_add_u64 v[240:241], s[46:47], 0, v[128:129]
	s_mov_b32 m0, s61
	ds_read_b128 v[198:201], v158 offset:32768
	ds_read_b128 v[202:205], v158 offset:33792
	ds_read_b128 v[206:209], v159 offset:32768
	ds_read_b128 v[212:215], v159 offset:33792
	ds_read_b128 v[216:219], v160 offset:32768
	ds_read_b128 v[220:223], v160 offset:33792
	ds_read_b128 v[224:227], v161 offset:32768
	ds_read_b128 v[228:231], v161 offset:33792
	global_load_lds_dwordx4 v[240:241], off
	v_lshl_add_u64 v[240:241], s[46:47], 0, v[130:131]
	v_readfirstlane_b32 s46, v147
	s_mov_b32 m0, s46
	s_nop 0
	global_load_lds_dwordx4 v[240:241], off
	s_waitcnt vmcnt(8)
	s_waitcnt lgkmcnt(0)
	s_barrier
	s_setprio 1
	s_waitcnt lgkmcnt(0)
	v_mfma_f32_16x16x32_bf16 v[124:127], v[198:201], v[166:169], v[124:127]
	v_mfma_f32_16x16x32_bf16 v[120:123], v[198:201], v[174:177], v[120:123]
	v_mfma_f32_16x16x32_bf16 v[108:111], v[206:209], v[166:169], v[108:111]
	v_mfma_f32_16x16x32_bf16 v[104:107], v[206:209], v[174:177], v[104:107]
	v_mfma_f32_16x16x32_bf16 v[92:95], v[216:219], v[166:169], v[92:95]
	v_mfma_f32_16x16x32_bf16 v[88:91], v[216:219], v[174:177], v[88:91]
	v_mfma_f32_16x16x32_bf16 v[76:79], v[224:227], v[166:169], v[76:79]
	v_mfma_f32_16x16x32_bf16 v[72:75], v[224:227], v[174:177], v[72:75]
	v_mfma_f32_16x16x32_bf16 v[124:127], v[202:205], v[170:173], v[124:127]
	v_mfma_f32_16x16x32_bf16 v[120:123], v[202:205], v[178:181], v[120:123]
	v_mfma_f32_16x16x32_bf16 v[108:111], v[212:215], v[170:173], v[108:111]
	v_mfma_f32_16x16x32_bf16 v[104:107], v[212:215], v[178:181], v[104:107]
	v_mfma_f32_16x16x32_bf16 v[92:95], v[220:223], v[170:173], v[92:95]
	v_mfma_f32_16x16x32_bf16 v[88:91], v[220:223], v[178:181], v[88:91]
	v_mfma_f32_16x16x32_bf16 v[76:79], v[228:231], v[170:173], v[76:79]
	v_mfma_f32_16x16x32_bf16 v[72:75], v[228:231], v[178:181], v[72:75]
	s_setprio 0
	s_setprio 1
	v_mfma_f32_16x16x32_bf16 v[116:119], v[198:201], v[182:185], v[116:119]
	v_mfma_f32_16x16x32_bf16 v[112:115], v[198:201], v[190:193], v[112:115]
	v_mfma_f32_16x16x32_bf16 v[100:103], v[206:209], v[182:185], v[100:103]
	v_mfma_f32_16x16x32_bf16 v[96:99], v[206:209], v[190:193], v[96:99]
	v_mfma_f32_16x16x32_bf16 v[84:87], v[216:219], v[182:185], v[84:87]
	v_mfma_f32_16x16x32_bf16 v[80:83], v[216:219], v[190:193], v[80:83]
	v_mfma_f32_16x16x32_bf16 v[68:71], v[224:227], v[182:185], v[68:71]
	v_mfma_f32_16x16x32_bf16 v[64:67], v[224:227], v[190:193], v[64:67]
	v_mfma_f32_16x16x32_bf16 v[116:119], v[202:205], v[186:189], v[116:119]
	v_mfma_f32_16x16x32_bf16 v[112:115], v[202:205], v[194:197], v[112:115]
	v_mfma_f32_16x16x32_bf16 v[100:103], v[212:215], v[186:189], v[100:103]
	v_mfma_f32_16x16x32_bf16 v[96:99], v[212:215], v[194:197], v[96:99]
	v_mfma_f32_16x16x32_bf16 v[84:87], v[220:223], v[186:189], v[84:87]
	v_mfma_f32_16x16x32_bf16 v[80:83], v[220:223], v[194:197], v[80:83]
	v_mfma_f32_16x16x32_bf16 v[68:71], v[228:231], v[186:189], v[68:71]
	v_mfma_f32_16x16x32_bf16 v[64:67], v[228:231], v[194:197], v[64:67]
	s_setprio 0
	s_barrier
; #define STAGE(P, g) do { const char* g_ = (const char*)(g); \
;         __builtin_amdgcn_global_load_lds((const unsigned*)(g_ + so0), (lds_u32*)((lds_u8*)(P) + sb0), 16, 0, 0); \
;         __builtin_amdgcn_global_load_lds((const unsigned*)(g_ + so1), (lds_u32*)((lds_u8*)(P) + sb0 + 8192), 16, 0, 0); } while (0)
; #define LDA(dst, b, h) for (int m = 0; m < 4; ++m) for (int k = 0; k < 2; ++k) \
;         dst[m][k] = *reinterpret_cast<const bf16x8*>((char*)SA(b, h) + lds_byte(wr * 64 + m * 16 + fr, k * 32 + fq * 8))
; #define MMA(ai, bj, At_, Bt_) do { __builtin_amdgcn_s_setprio(1); \
;         for (int m = 0; m < 4; ++m) for (int n = 0; n < 2; ++n) for (int k = 0; k < 2; ++k) \
;             acc[ai][bj][m][n] = __builtin_amdgcn_mfma_f32_16x16x32_bf16(At_[m][k], Bt_[n][k], acc[ai][bj][m][n], 0, 0, 0); \
;         __builtin_amdgcn_s_setprio(0); } while (0)
; #define WAIT_V(n) asm volatile("s_waitcnt vmcnt(" #n ")" ::: "memory")
; #define WAIT_L(n) asm volatile("s_waitcnt lgkmcnt(" #n ")" ::: "memory")
; #define BAR __builtin_amdgcn_s_barrier()
; #define SCHED __builtin_amdgcn_sched_barrier(0)
; template <int EPI, int K, int LNI = -1>
; DI void ph_gemm(const Params& p, const bf16_t* __restrict__ A, const bf16_t* __restrict__ Bt, int N, float* s_aux) {
;     ...
;             LDA(At, 1, 1); STAGE(SB(1, 0), b3); STAGE(SB(1, 1), b3 + hstep); STAGE(SA(1, 0), a3);
;             WAIT_V(8); WAIT_L(0); BAR; MMA(1, 0, At, B0); MMA(1, 1, At, B1); BAR; SCHED;
;         }
;         if (wr == 0) BAR;
	v_readfirstlane_b32 s46, v148
	v_lshl_add_u64 v[232:233], v[232:233], 0, s[10:11]
	s_mov_b32 m0, s46
	v_readfirstlane_b32 s46, v149
	s_add_u32 s44, s44, 0x40080
	ds_read_b128 v[198:201], v158 offset:49152
	ds_read_b128 v[202:205], v158 offset:50176
	ds_read_b128 v[206:209], v159 offset:49152
	ds_read_b128 v[212:215], v159 offset:50176
	ds_read_b128 v[216:219], v160 offset:49152
	ds_read_b128 v[220:223], v160 offset:50176
	ds_read_b128 v[224:227], v161 offset:49152
	ds_read_b128 v[228:231], v161 offset:50176
	global_load_lds_dwordx4 v[232:233], off
	v_lshl_add_u64 v[232:233], v[234:235], 0, s[10:11]
	s_mov_b32 m0, s46
	s_addc_u32 s45, s45, 0
	v_readfirstlane_b32 s46, v152
	global_load_lds_dwordx4 v[232:233], off
	v_lshl_add_u64 v[232:233], s[44:45], 0, v[128:129]
	s_mov_b32 m0, s46
	s_nop 0
	global_load_lds_dwordx4 v[232:233], off
	v_lshl_add_u64 v[232:233], s[44:45], 0, v[130:131]
	v_readfirstlane_b32 s44, v153
	s_mov_b32 m0, s44
	v_readfirstlane_b32 s44, v150
	global_load_lds_dwordx4 v[232:233], off
	v_lshl_add_u64 v[232:233], v[236:237], 0, s[10:11]
	s_mov_b32 m0, s44
	v_readfirstlane_b32 s44, v151
	global_load_lds_dwordx4 v[232:233], off
	v_lshl_add_u64 v[232:233], v[238:239], 0, s[10:11]
	s_mov_b32 m0, s44
	s_nop 0
	global_load_lds_dwordx4 v[232:233], off
	s_waitcnt vmcnt(8)
	s_waitcnt lgkmcnt(0)
	s_barrier
	s_setprio 1
	s_waitcnt lgkmcnt(0)
	v_mfma_f32_16x16x32_bf16 v[60:63], v[198:201], v[166:169], v[60:63]
	v_mfma_f32_16x16x32_bf16 v[56:59], v[198:201], v[174:177], v[56:59]
	v_mfma_f32_16x16x32_bf16 v[44:47], v[206:209], v[166:169], v[44:47]
	v_mfma_f32_16x16x32_bf16 v[40:43], v[206:209], v[174:177], v[40:43]
	v_mfma_f32_16x16x32_bf16 v[28:31], v[216:219], v[166:169], v[28:31]
	v_mfma_f32_16x16x32_bf16 v[24:27], v[216:219], v[174:177], v[24:27]
	v_mfma_f32_16x16x32_bf16 v[12:15], v[224:227], v[166:169], v[12:15]
	v_mfma_f32_16x16x32_bf16 v[8:11], v[224:227], v[174:177], v[8:11]
	v_mfma_f32_16x16x32_bf16 v[60:63], v[202:205], v[170:173], v[60:63]
	v_mfma_f32_16x16x32_bf16 v[56:59], v[202:205], v[178:181], v[56:59]
	v_mfma_f32_16x16x32_bf16 v[44:47], v[212:215], v[170:173], v[44:47]
	v_mfma_f32_16x16x32_bf16 v[40:43], v[212:215], v[178:181], v[40:43]
	v_mfma_f32_16x16x32_bf16 v[28:31], v[220:223], v[170:173], v[28:31]
	v_mfma_f32_16x16x32_bf16 v[24:27], v[220:223], v[178:181], v[24:27]
	v_mfma_f32_16x16x32_bf16 v[12:15], v[228:231], v[170:173], v[12:15]
	v_mfma_f32_16x16x32_bf16 v[8:11], v[228:231], v[178:181], v[8:11]
	s_setprio 0
	s_setprio 1
	v_mfma_f32_16x16x32_bf16 v[52:55], v[198:201], v[182:185], v[52:55]
	v_mfma_f32_16x16x32_bf16 v[48:51], v[198:201], v[190:193], v[48:51]
	v_mfma_f32_16x16x32_bf16 v[36:39], v[206:209], v[182:185], v[36:39]
	v_mfma_f32_16x16x32_bf16 v[32:35], v[206:209], v[190:193], v[32:35]
	v_mfma_f32_16x16x32_bf16 v[20:23], v[216:219], v[182:185], v[20:23]
	v_mfma_f32_16x16x32_bf16 v[16:19], v[216:219], v[190:193], v[16:19]
	v_mfma_f32_16x16x32_bf16 v[4:7], v[224:227], v[182:185], v[4:7]
	v_mfma_f32_16x16x32_bf16 v[0:3], v[224:227], v[190:193], v[0:3]
	v_mfma_f32_16x16x32_bf16 v[52:55], v[202:205], v[186:189], v[52:55]
	v_mfma_f32_16x16x32_bf16 v[48:51], v[202:205], v[194:197], v[48:51]
	v_mfma_f32_16x16x32_bf16 v[36:39], v[212:215], v[186:189], v[36:39]
	v_mfma_f32_16x16x32_bf16 v[32:35], v[212:215], v[194:197], v[32:35]
	v_mfma_f32_16x16x32_bf16 v[20:23], v[220:223], v[186:189], v[20:23]
	v_mfma_f32_16x16x32_bf16 v[16:19], v[220:223], v[194:197], v[16:19]
	v_mfma_f32_16x16x32_bf16 v[4:7], v[228:231], v[186:189], v[4:7]
	v_mfma_f32_16x16x32_bf16 v[0:3], v[228:231], v[194:197], v[0:3]
	s_setprio 0
	s_add_i32 s60, s60, 2
	s_add_u32 s28, s28, 0x100
	s_addc_u32 s29, s29, 0
	s_cmp_gt_u32 s60, 13
	s_barrier
	s_cbranch_scc0 .LBB0_928
	s_and_saveexec_b64 s[28:29], s[4:5]
	s_cbranch_execz .LBB0_931
	s_barrier

; #define STAGE(P, g) do { const char* g_ = (const char*)(g); \
;         __builtin_amdgcn_global_load_lds((const unsigned*)(g_ + so0), (lds_u32*)((lds_u8*)(P) + sb0), 16, 0, 0); \
;         __builtin_amdgcn_global_load_lds((const unsigned*)(g_ + so1), (lds_u32*)((lds_u8*)(P) + sb0 + 8192), 16, 0, 0); } while (0)
; #define LDA(dst, b, h) for (int m = 0; m < 4; ++m) for (int k = 0; k < 2; ++k) \
;         dst[m][k] = *reinterpret_cast<const bf16x8*>((char*)SA(b, h) + lds_byte(wr * 64 + m * 16 + fr, k * 32 + fq * 8))
; #define LDB(dst, b, h) for (int n = 0; n < 2; ++n) for (int k = 0; k < 2; ++k) \
;         dst[n][k] = *reinterpret_cast<const bf16x8*>((char*)SB(b, h) + lds_byte(wc * 32 + n * 16 + fr, k * 32 + fq * 8))
; #define MMA(ai, bj, At_, Bt_) do { __builtin_amdgcn_s_setprio(1); \
;         for (int m = 0; m < 4; ++m) for (int n = 0; n < 2; ++n) for (int k = 0; k < 2; ++k) \
;             acc[ai][bj][m][n] = __builtin_amdgcn_mfma_f32_16x16x32_bf16(At_[m][k], Bt_[n][k], acc[ai][bj][m][n], 0, 0, 0); \
;         __builtin_amdgcn_s_setprio(0); } while (0)
; #define WAIT_V(n) asm volatile("s_waitcnt vmcnt(" #n ")" ::: "memory")
; #define WAIT_L(n) asm volatile("s_waitcnt lgkmcnt(" #n ")" ::: "memory")
; #define BAR __builtin_amdgcn_s_barrier()
; #define SCHED __builtin_amdgcn_sched_barrier(0)
; template <int EPI, int K, int LNI = -1>
; DI void ph_gemm(const Params& p, const bf16_t* __restrict__ A, const bf16_t* __restrict__ Bt, int N, float* s_aux) {
;     ...
;         for (int t = 0; t < nt; t += 2) {
;             const bool last = (t == nt - 2);
;             const bf16_t* a1 = cA + (size_t)(t + 1) * kstep;
;             const bf16_t* a2 = last ? nA : cA + (size_t)(t + 2) * kstep; const bf16_t* b2 = last ? nB : cB + (size_t)(t + 2) * kstep;
;             const bf16_t* a3 = a2 + kstep; const bf16_t* b3 = b2 + kstep;
;             LDB(B0, 0, 0); LDB(B1, 0, 1); SCHED; LDA(At, 0, 0); STAGE(SA(1, 1), a1 + hstep);
;             WAIT_V(8); WAIT_L(0); BAR; MMA(0, 0, At, B0); MMA(0, 1, At, B1); BAR; SCHED;
;             LDA(At, 0, 1); STAGE(SB(0, 0), b2); STAGE(SB(0, 1), b2 + hstep); STAGE(SA(0, 0), a2);
;             WAIT_V(8); WAIT_L(0); BAR; MMA(1, 0, At, B0); MMA(1, 1, At, B1); BAR; SCHED;
.LBB0_1004:
	s_ashr_i32 s15, s14, 31
	s_lshl_b64 s[20:21], s[14:15], 21
	s_add_u32 s15, s36, s20
	s_addc_u32 s42, s37, s21
	s_ashr_i32 s13, s12, 31
	s_lshl_b64 s[24:25], s[12:13], 21
	s_add_u32 s13, s3, s24
	s_addc_u32 s43, s35, s25
	s_add_u32 s60, s56, s44
	s_addc_u32 s61, s57, s45
	s_add_u32 s66, s50, s46
	v_lshl_add_u64 v[128:129], v[140:141], 0, s[44:45]
	v_lshl_add_u64 v[130:131], v[142:143], 0, s[44:45]
	s_addc_u32 s67, s51, s47
	s_mov_b32 s68, -2
	s_mov_b64 s[44:45], 0
	ds_read_b128 v[132:135], v176
	ds_read_b128 v[144:147], v176 offset:1024
	ds_read_b128 v[148:151], v176 offset:2048
	ds_read_b128 v[152:155], v176 offset:3072
	ds_read_b128 v[156:159], v177
	ds_read_b128 v[186:189], v177 offset:1024
	ds_read_b128 v[190:193], v177 offset:2048
	ds_read_b128 v[194:197], v177 offset:3072
	s_add_u32 s46, s60, s44
	s_addc_u32 s47, s61, s45
	s_add_u32 s46, s46, 0xfa70100
	s_addc_u32 s47, s47, 0
	s_add_u32 s69, s66, s44
	s_addc_u32 s70, s67, s45
	s_cmpk_eq_i32 s44, 0x1f00
	s_cselect_b32 s49, s42, s47
	s_cselect_b32 s48, s15, s46
	s_cselect_b32 s47, s43, s70
	s_cselect_b32 s46, s13, s69
	v_readfirstlane_b32 s69, v182
	v_lshl_add_u64 v[232:233], v[128:129], 0, s[44:45]
	s_mov_b32 m0, s69
	v_readfirstlane_b32 s69, v183
	ds_read_b128 v[198:201], v178
	ds_read_b128 v[202:205], v178 offset:1024
	ds_read_b128 v[206:209], v179
	ds_read_b128 v[212:215], v179 offset:1024
	ds_read_b128 v[216:219], v180
	ds_read_b128 v[220:223], v180 offset:1024
	ds_read_b128 v[224:227], v181
	ds_read_b128 v[228:231], v181 offset:1024
	global_load_lds_dwordx4 v[232:233], off
	v_lshl_add_u64 v[232:233], v[130:131], 0, s[44:45]
	s_mov_b32 m0, s69
	s_nop 0
	global_load_lds_dwordx4 v[232:233], off
	s_waitcnt vmcnt(8)
	s_waitcnt lgkmcnt(0)
	s_barrier
	s_setprio 1
	s_waitcnt lgkmcnt(0)
	v_mfma_f32_16x16x32_bf16 v[124:127], v[198:201], v[132:135], 0
	v_mfma_f32_16x16x32_bf16 v[120:123], v[198:201], v[148:151], 0
	v_mfma_f32_16x16x32_bf16 v[108:111], v[206:209], v[132:135], 0
	v_mfma_f32_16x16x32_bf16 v[104:107], v[206:209], v[148:151], 0
	v_mfma_f32_16x16x32_bf16 v[92:95], v[216:219], v[132:135], 0
	v_mfma_f32_16x16x32_bf16 v[88:91], v[216:219], v[148:151], 0
	v_mfma_f32_16x16x32_bf16 v[76:79], v[224:227], v[132:135], 0
	v_mfma_f32_16x16x32_bf16 v[72:75], v[224:227], v[148:151], 0
	v_mfma_f32_16x16x32_bf16 v[124:127], v[202:205], v[144:147], v[124:127]
	v_mfma_f32_16x16x32_bf16 v[120:123], v[202:205], v[152:155], v[120:123]
	v_mfma_f32_16x16x32_bf16 v[108:111], v[212:215], v[144:147], v[108:111]
	v_mfma_f32_16x16x32_bf16 v[104:107], v[212:215], v[152:155], v[104:107]
	v_mfma_f32_16x16x32_bf16 v[92:95], v[220:223], v[144:147], v[92:95]
	v_mfma_f32_16x16x32_bf16 v[88:91], v[220:223], v[152:155], v[88:91]
	v_mfma_f32_16x16x32_bf16 v[76:79], v[228:231], v[144:147], v[76:79]
	v_mfma_f32_16x16x32_bf16 v[72:75], v[228:231], v[152:155], v[72:75]
	s_setprio 0
	s_setprio 1
	v_mfma_f32_16x16x32_bf16 v[116:119], v[198:201], v[156:159], 0
	v_mfma_f32_16x16x32_bf16 v[112:115], v[198:201], v[190:193], 0
	v_mfma_f32_16x16x32_bf16 v[100:103], v[206:209], v[156:159], 0
	v_mfma_f32_16x16x32_bf16 v[96:99], v[206:209], v[190:193], 0
	v_mfma_f32_16x16x32_bf16 v[84:87], v[216:219], v[156:159], 0
	v_mfma_f32_16x16x32_bf16 v[80:83], v[216:219], v[190:193], 0
	v_mfma_f32_16x16x32_bf16 v[68:71], v[224:227], v[156:159], 0
	v_mfma_f32_16x16x32_bf16 v[64:67], v[224:227], v[190:193], 0
	v_mfma_f32_16x16x32_bf16 v[116:119], v[202:205], v[186:189], v[116:119]
	v_mfma_f32_16x16x32_bf16 v[112:115], v[202:205], v[194:197], v[112:115]
	v_mfma_f32_16x16x32_bf16 v[100:103], v[212:215], v[186:189], v[100:103]
	v_mfma_f32_16x16x32_bf16 v[96:99], v[212:215], v[194:197], v[96:99]
	v_mfma_f32_16x16x32_bf16 v[84:87], v[220:223], v[186:189], v[84:87]
	v_mfma_f32_16x16x32_bf16 v[80:83], v[220:223], v[194:197], v[80:83]
	v_mfma_f32_16x16x32_bf16 v[68:71], v[228:231], v[186:189], v[68:71]
	v_mfma_f32_16x16x32_bf16 v[64:67], v[228:231], v[194:197], v[64:67]
	s_setprio 0
	s_barrier
	v_readfirstlane_b32 s69, v160
	v_lshl_add_u64 v[232:233], s[46:47], 0, v[136:137]
	s_mov_b32 m0, s69
	v_readfirstlane_b32 s69, v161
	s_add_u32 s70, s46, 0x100000
	ds_read_b128 v[198:201], v178 offset:16384
	ds_read_b128 v[202:205], v178 offset:17408
	ds_read_b128 v[206:209], v179 offset:16384
	ds_read_b128 v[212:215], v179 offset:17408
	ds_read_b128 v[216:219], v180 offset:16384
	ds_read_b128 v[220:223], v180 offset:17408
	ds_read_b128 v[224:227], v181 offset:16384
	ds_read_b128 v[228:231], v181 offset:17408
	global_load_lds_dwordx4 v[232:233], off
	v_lshl_add_u64 v[234:235], s[46:47], 0, v[138:139]
	s_mov_b32 m0, s69
	s_addc_u32 s71, s47, 0
	v_readfirstlane_b32 s69, v162
	global_load_lds_dwordx4 v[234:235], off
	v_lshl_add_u64 v[236:237], s[70:71], 0, v[136:137]
	s_mov_b32 m0, s69
	v_readfirstlane_b32 s69, v163
	global_load_lds_dwordx4 v[236:237], off
	v_lshl_add_u64 v[236:237], s[70:71], 0, v[138:139]
	s_mov_b32 m0, s69
	v_readfirstlane_b32 s69, v164
	global_load_lds_dwordx4 v[236:237], off
	v_lshl_add_u64 v[236:237], s[48:49], 0, v[136:137]
	s_mov_b32 m0, s69
	v_readfirstlane_b32 s69, v165
	global_load_lds_dwordx4 v[236:237], off
	v_lshl_add_u64 v[238:239], s[48:49], 0, v[138:139]
	s_mov_b32 m0, s69
	s_nop 0
	global_load_lds_dwordx4 v[238:239], off
	s_waitcnt vmcnt(8)
	s_waitcnt lgkmcnt(0)
	s_barrier
; #define STAGE(P, g) do { const char* g_ = (const char*)(g); \
;         __builtin_amdgcn_global_load_lds((const unsigned*)(g_ + so0), (lds_u32*)((lds_u8*)(P) + sb0), 16, 0, 0); \
;         __builtin_amdgcn_global_load_lds((const unsigned*)(g_ + so1), (lds_u32*)((lds_u8*)(P) + sb0 + 8192), 16, 0, 0); } while (0)
; #define LDA(dst, b, h) for (int m = 0; m < 4; ++m) for (int k = 0; k < 2; ++k) \
;         dst[m][k] = *reinterpret_cast<const bf16x8*>((char*)SA(b, h) + lds_byte(wr * 64 + m * 16 + fr, k * 32 + fq * 8))
; #define LDB(dst, b, h) for (int n = 0; n < 2; ++n) for (int k = 0; k < 2; ++k) \
;         dst[n][k] = *reinterpret_cast<const bf16x8*>((char*)SB(b, h) + lds_byte(wc * 32 + n * 16 + fr, k * 32 + fq * 8))
; #define MMA(ai, bj, At_, Bt_) do { __builtin_amdgcn_s_setprio(1); \
;         for (int m = 0; m < 4; ++m) for (int n = 0; n < 2; ++n) for (int k = 0; k < 2; ++k) \
;             acc[ai][bj][m][n] = __builtin_amdgcn_mfma_f32_16x16x32_bf16(At_[m][k], Bt_[n][k], acc[ai][bj][m][n], 0, 0, 0); \
;         __builtin_amdgcn_s_setprio(0); } while (0)
; #define WAIT_V(n) asm volatile("s_waitcnt vmcnt(" #n ")" ::: "memory")
; #define WAIT_L(n) asm volatile("s_waitcnt lgkmcnt(" #n ")" ::: "memory")
; #define BAR __builtin_amdgcn_s_barrier()
; #define SCHED __builtin_amdgcn_sched_barrier(0)
; template <int EPI, int K, int LNI = -1>
; DI void ph_gemm(const Params& p, const bf16_t* __restrict__ A, const bf16_t* __restrict__ Bt, int N, float* s_aux) {
;     ...
;             WAIT_V(8); WAIT_L(0); BAR; MMA(0, 0, At, B0); MMA(0, 1, At, B1); BAR; SCHED;
;             LDA(At, 0, 1); STAGE(SB(0, 0), b2); STAGE(SB(0, 1), b2 + hstep); STAGE(SA(0, 0), a2);
;             WAIT_V(8); WAIT_L(0); BAR; MMA(1, 0, At, B0); MMA(1, 1, At, B1); BAR; SCHED;
;             LDB(B0, 1, 0); LDB(B1, 1, 1); SCHED; LDA(At, 1, 0); STAGE(SA(0, 1), a2 + hstep);
;             WAIT_V(8); WAIT_L(0); BAR; MMA(0, 0, At, B0); MMA(0, 1, At, B1); BAR; SCHED;
	s_setprio 1
	s_waitcnt lgkmcnt(0)
	v_mfma_f32_16x16x32_bf16 v[60:63], v[198:201], v[132:135], 0
	v_mfma_f32_16x16x32_bf16 v[56:59], v[198:201], v[148:151], 0
	v_mfma_f32_16x16x32_bf16 v[44:47], v[206:209], v[132:135], 0
	v_mfma_f32_16x16x32_bf16 v[40:43], v[206:209], v[148:151], 0
	v_mfma_f32_16x16x32_bf16 v[28:31], v[216:219], v[132:135], 0
	v_mfma_f32_16x16x32_bf16 v[24:27], v[216:219], v[148:151], 0
	v_mfma_f32_16x16x32_bf16 v[12:15], v[224:227], v[132:135], 0
	v_mfma_f32_16x16x32_bf16 v[8:11], v[224:227], v[148:151], 0
	v_mfma_f32_16x16x32_bf16 v[60:63], v[202:205], v[144:147], v[60:63]
	v_mfma_f32_16x16x32_bf16 v[56:59], v[202:205], v[152:155], v[56:59]
	v_mfma_f32_16x16x32_bf16 v[44:47], v[212:215], v[144:147], v[44:47]
	v_mfma_f32_16x16x32_bf16 v[40:43], v[212:215], v[152:155], v[40:43]
	v_mfma_f32_16x16x32_bf16 v[28:31], v[220:223], v[144:147], v[28:31]
	v_mfma_f32_16x16x32_bf16 v[24:27], v[220:223], v[152:155], v[24:27]
	v_mfma_f32_16x16x32_bf16 v[12:15], v[228:231], v[144:147], v[12:15]
	v_mfma_f32_16x16x32_bf16 v[8:11], v[228:231], v[152:155], v[8:11]
	s_setprio 0
	s_setprio 1
	v_mfma_f32_16x16x32_bf16 v[52:55], v[198:201], v[156:159], 0
	v_mfma_f32_16x16x32_bf16 v[48:51], v[198:201], v[190:193], 0
	v_mfma_f32_16x16x32_bf16 v[36:39], v[206:209], v[156:159], 0
	v_mfma_f32_16x16x32_bf16 v[32:35], v[206:209], v[190:193], 0
	v_mfma_f32_16x16x32_bf16 v[20:23], v[216:219], v[156:159], 0
	v_mfma_f32_16x16x32_bf16 v[16:19], v[216:219], v[190:193], 0
	v_mfma_f32_16x16x32_bf16 v[4:7], v[224:227], v[156:159], 0
	v_mfma_f32_16x16x32_bf16 v[0:3], v[224:227], v[190:193], 0
	v_mfma_f32_16x16x32_bf16 v[52:55], v[202:205], v[186:189], v[52:55]
	v_mfma_f32_16x16x32_bf16 v[48:51], v[202:205], v[194:197], v[48:51]
	v_mfma_f32_16x16x32_bf16 v[36:39], v[212:215], v[186:189], v[36:39]
	v_mfma_f32_16x16x32_bf16 v[32:35], v[212:215], v[194:197], v[32:35]
	v_mfma_f32_16x16x32_bf16 v[20:23], v[220:223], v[186:189], v[20:23]
	v_mfma_f32_16x16x32_bf16 v[16:19], v[220:223], v[194:197], v[16:19]
	v_mfma_f32_16x16x32_bf16 v[4:7], v[228:231], v[186:189], v[4:7]
	v_mfma_f32_16x16x32_bf16 v[0:3], v[228:231], v[194:197], v[0:3]
	s_setprio 0
	s_barrier
	ds_read_b128 v[132:135], v184
	ds_read_b128 v[144:147], v184 offset:1024
	ds_read_b128 v[148:151], v184 offset:2048
	ds_read_b128 v[152:155], v184 offset:3072
	ds_read_b128 v[156:159], v185
	ds_read_b128 v[186:189], v185 offset:1024
	ds_read_b128 v[190:193], v185 offset:2048
	ds_read_b128 v[194:197], v185 offset:3072
	s_add_u32 s48, s48, 0x100000
	s_addc_u32 s49, s49, 0
	v_readfirstlane_b32 s69, v166
	v_lshl_add_u64 v[240:241], s[48:49], 0, v[136:137]
	s_mov_b32 m0, s69
	ds_read_b128 v[198:201], v178 offset:32768
	ds_read_b128 v[202:205], v178 offset:33792
	ds_read_b128 v[206:209], v179 offset:32768
	ds_read_b128 v[212:215], v179 offset:33792
	ds_read_b128 v[216:219], v180 offset:32768
	ds_read_b128 v[220:223], v180 offset:33792
	ds_read_b128 v[224:227], v181 offset:32768
	ds_read_b128 v[228:231], v181 offset:33792
	global_load_lds_dwordx4 v[240:241], off
	v_lshl_add_u64 v[240:241], s[48:49], 0, v[138:139]
	v_readfirstlane_b32 s48, v167
	s_mov_b32 m0, s48
	s_nop 0
	global_load_lds_dwordx4 v[240:241], off
	s_waitcnt vmcnt(8)
	s_waitcnt lgkmcnt(0)
	s_barrier
	s_setprio 1
	s_waitcnt lgkmcnt(0)
	v_mfma_f32_16x16x32_bf16 v[124:127], v[198:201], v[132:135], v[124:127]
	v_mfma_f32_16x16x32_bf16 v[120:123], v[198:201], v[148:151], v[120:123]
	v_mfma_f32_16x16x32_bf16 v[108:111], v[206:209], v[132:135], v[108:111]
	v_mfma_f32_16x16x32_bf16 v[104:107], v[206:209], v[148:151], v[104:107]
	v_mfma_f32_16x16x32_bf16 v[92:95], v[216:219], v[132:135], v[92:95]
	v_mfma_f32_16x16x32_bf16 v[88:91], v[216:219], v[148:151], v[88:91]
	v_mfma_f32_16x16x32_bf16 v[76:79], v[224:227], v[132:135], v[76:79]
	v_mfma_f32_16x16x32_bf16 v[72:75], v[224:227], v[148:151], v[72:75]
	v_mfma_f32_16x16x32_bf16 v[124:127], v[202:205], v[144:147], v[124:127]
	v_mfma_f32_16x16x32_bf16 v[120:123], v[202:205], v[152:155], v[120:123]
	v_mfma_f32_16x16x32_bf16 v[108:111], v[212:215], v[144:147], v[108:111]
	v_mfma_f32_16x16x32_bf16 v[104:107], v[212:215], v[152:155], v[104:107]
	v_mfma_f32_16x16x32_bf16 v[92:95], v[220:223], v[144:147], v[92:95]
	v_mfma_f32_16x16x32_bf16 v[88:91], v[220:223], v[152:155], v[88:91]
	v_mfma_f32_16x16x32_bf16 v[76:79], v[228:231], v[144:147], v[76:79]
	v_mfma_f32_16x16x32_bf16 v[72:75], v[228:231], v[152:155], v[72:75]
	s_setprio 0
	s_setprio 1
	v_mfma_f32_16x16x32_bf16 v[116:119], v[198:201], v[156:159], v[116:119]
	v_mfma_f32_16x16x32_bf16 v[112:115], v[198:201], v[190:193], v[112:115]
	v_mfma_f32_16x16x32_bf16 v[100:103], v[206:209], v[156:159], v[100:103]
	v_mfma_f32_16x16x32_bf16 v[96:99], v[206:209], v[190:193], v[96:99]
	v_mfma_f32_16x16x32_bf16 v[84:87], v[216:219], v[156:159], v[84:87]
	v_mfma_f32_16x16x32_bf16 v[80:83], v[216:219], v[190:193], v[80:83]
	v_mfma_f32_16x16x32_bf16 v[68:71], v[224:227], v[156:159], v[68:71]
	v_mfma_f32_16x16x32_bf16 v[64:67], v[224:227], v[190:193], v[64:67]
	v_mfma_f32_16x16x32_bf16 v[116:119], v[202:205], v[186:189], v[116:119]
	v_mfma_f32_16x16x32_bf16 v[112:115], v[202:205], v[194:197], v[112:115]
	v_mfma_f32_16x16x32_bf16 v[100:103], v[212:215], v[186:189], v[100:103]
	v_mfma_f32_16x16x32_bf16 v[96:99], v[212:215], v[194:197], v[96:99]
	v_mfma_f32_16x16x32_bf16 v[84:87], v[220:223], v[186:189], v[84:87]
	v_mfma_f32_16x16x32_bf16 v[80:83], v[220:223], v[194:197], v[80:83]
	v_mfma_f32_16x16x32_bf16 v[68:71], v[228:231], v[186:189], v[68:71]
	v_mfma_f32_16x16x32_bf16 v[64:67], v[228:231], v[194:197], v[64:67]
	s_setprio 0
	s_barrier
; #define STAGE(P, g) do { const char* g_ = (const char*)(g); \
;         __builtin_amdgcn_global_load_lds((const unsigned*)(g_ + so0), (lds_u32*)((lds_u8*)(P) + sb0), 16, 0, 0); \
;         __builtin_amdgcn_global_load_lds((const unsigned*)(g_ + so1), (lds_u32*)((lds_u8*)(P) + sb0 + 8192), 16, 0, 0); } while (0)
; #define LDA(dst, b, h) for (int m = 0; m < 4; ++m) for (int k = 0; k < 2; ++k) \
;         dst[m][k] = *reinterpret_cast<const bf16x8*>((char*)SA(b, h) + lds_byte(wr * 64 + m * 16 + fr, k * 32 + fq * 8))
; #define LDB(dst, b, h) for (int n = 0; n < 2; ++n) for (int k = 0; k < 2; ++k) \
;         dst[n][k] = *reinterpret_cast<const bf16x8*>((char*)SB(b, h) + lds_byte(wc * 32 + n * 16 + fr, k * 32 + fq * 8))
; #define MMA(ai, bj, At_, Bt_) do { __builtin_amdgcn_s_setprio(1); \
;         for (int m = 0; m < 4; ++m) for (int n = 0; n < 2; ++n) for (int k = 0; k < 2; ++k) \
;             acc[ai][bj][m][n] = __builtin_amdgcn_mfma_f32_16x16x32_bf16(At_[m][k], Bt_[n][k], acc[ai][bj][m][n], 0, 0, 0); \
;         __builtin_amdgcn_s_setprio(0); } while (0)
; #define WAIT_V(n) asm volatile("s_waitcnt vmcnt(" #n ")" ::: "memory")
; #define WAIT_L(n) asm volatile("s_waitcnt lgkmcnt(" #n ")" ::: "memory")
; #define BAR __builtin_amdgcn_s_barrier()
; #define SCHED __builtin_amdgcn_sched_barrier(0)
; template <int EPI, int K, int LNI = -1>
; DI void ph_gemm(const Params& p, const bf16_t* __restrict__ A, const bf16_t* __restrict__ Bt, int N, float* s_aux) {
;     ...
;         for (int t = 0; t < nt; t += 2) {
;             const bool last = (t == nt - 2);
;             const bf16_t* a1 = cA + (size_t)(t + 1) * kstep;
;             const bf16_t* a2 = last ? nA : cA + (size_t)(t + 2) * kstep; const bf16_t* b2 = last ? nB : cB + (size_t)(t + 2) * kstep;
;             const bf16_t* a3 = a2 + kstep; const bf16_t* b3 = b2 + kstep;
;             LDB(B0, 0, 0); LDB(B1, 0, 1); SCHED; LDA(At, 0, 0); STAGE(SA(1, 1), a1 + hstep);
;             WAIT_V(8); WAIT_L(0); BAR; MMA(0, 0, At, B0); MMA(0, 1, At, B1); BAR; SCHED;
;     ...
;             LDA(At, 1, 1); STAGE(SB(1, 0), b3); STAGE(SB(1, 1), b3 + hstep); STAGE(SA(1, 0), a3);
;             WAIT_V(8); WAIT_L(0); BAR; MMA(1, 0, At, B0); MMA(1, 1, At, B1); BAR; SCHED;
	v_readfirstlane_b32 s48, v168
	v_lshl_add_u64 v[232:233], v[232:233], 0, s[8:9]
	s_mov_b32 m0, s48
	v_readfirstlane_b32 s48, v169
	s_add_u32 s46, s46, 0x100080
	ds_read_b128 v[198:201], v178 offset:49152
	ds_read_b128 v[202:205], v178 offset:50176
	ds_read_b128 v[206:209], v179 offset:49152
	ds_read_b128 v[212:215], v179 offset:50176
	ds_read_b128 v[216:219], v180 offset:49152
	ds_read_b128 v[220:223], v180 offset:50176
	ds_read_b128 v[224:227], v181 offset:49152
	ds_read_b128 v[228:231], v181 offset:50176
	global_load_lds_dwordx4 v[232:233], off
	v_lshl_add_u64 v[232:233], v[234:235], 0, s[8:9]
	s_mov_b32 m0, s48
	s_addc_u32 s47, s47, 0
	v_readfirstlane_b32 s48, v172
	global_load_lds_dwordx4 v[232:233], off
	v_lshl_add_u64 v[232:233], s[46:47], 0, v[136:137]
	s_mov_b32 m0, s48
	s_nop 0
	global_load_lds_dwordx4 v[232:233], off
	v_lshl_add_u64 v[232:233], s[46:47], 0, v[138:139]
	v_readfirstlane_b32 s46, v173
	s_mov_b32 m0, s46
	v_readfirstlane_b32 s46, v170
	global_load_lds_dwordx4 v[232:233], off
	v_lshl_add_u64 v[232:233], v[236:237], 0, s[8:9]
	s_mov_b32 m0, s46
	v_readfirstlane_b32 s46, v171
	global_load_lds_dwordx4 v[232:233], off
	v_lshl_add_u64 v[232:233], v[238:239], 0, s[8:9]
	s_mov_b32 m0, s46
	s_nop 0
	global_load_lds_dwordx4 v[232:233], off
	s_waitcnt vmcnt(8)
	s_waitcnt lgkmcnt(0)
	s_barrier
	s_setprio 1
	s_waitcnt lgkmcnt(0)
	v_mfma_f32_16x16x32_bf16 v[60:63], v[198:201], v[132:135], v[60:63]
	v_mfma_f32_16x16x32_bf16 v[56:59], v[198:201], v[148:151], v[56:59]
	v_mfma_f32_16x16x32_bf16 v[44:47], v[206:209], v[132:135], v[44:47]
	v_mfma_f32_16x16x32_bf16 v[40:43], v[206:209], v[148:151], v[40:43]
	v_mfma_f32_16x16x32_bf16 v[28:31], v[216:219], v[132:135], v[28:31]
	v_mfma_f32_16x16x32_bf16 v[24:27], v[216:219], v[148:151], v[24:27]
	v_mfma_f32_16x16x32_bf16 v[12:15], v[224:227], v[132:135], v[12:15]
	v_mfma_f32_16x16x32_bf16 v[8:11], v[224:227], v[148:151], v[8:11]
	v_mfma_f32_16x16x32_bf16 v[60:63], v[202:205], v[144:147], v[60:63]
	v_mfma_f32_16x16x32_bf16 v[56:59], v[202:205], v[152:155], v[56:59]
	v_mfma_f32_16x16x32_bf16 v[44:47], v[212:215], v[144:147], v[44:47]
	v_mfma_f32_16x16x32_bf16 v[40:43], v[212:215], v[152:155], v[40:43]
	v_mfma_f32_16x16x32_bf16 v[28:31], v[220:223], v[144:147], v[28:31]
	v_mfma_f32_16x16x32_bf16 v[24:27], v[220:223], v[152:155], v[24:27]
	v_mfma_f32_16x16x32_bf16 v[12:15], v[228:231], v[144:147], v[12:15]
	v_mfma_f32_16x16x32_bf16 v[8:11], v[228:231], v[152:155], v[8:11]
	s_setprio 0
	s_setprio 1
	v_mfma_f32_16x16x32_bf16 v[52:55], v[198:201], v[156:159], v[52:55]
	v_mfma_f32_16x16x32_bf16 v[48:51], v[198:201], v[190:193], v[48:51]
	v_mfma_f32_16x16x32_bf16 v[36:39], v[206:209], v[156:159], v[36:39]
	v_mfma_f32_16x16x32_bf16 v[32:35], v[206:209], v[190:193], v[32:35]
	v_mfma_f32_16x16x32_bf16 v[20:23], v[216:219], v[156:159], v[20:23]
	v_mfma_f32_16x16x32_bf16 v[16:19], v[216:219], v[190:193], v[16:19]
	v_mfma_f32_16x16x32_bf16 v[4:7], v[224:227], v[156:159], v[4:7]
	v_mfma_f32_16x16x32_bf16 v[0:3], v[224:227], v[190:193], v[0:3]
	v_mfma_f32_16x16x32_bf16 v[52:55], v[202:205], v[186:189], v[52:55]
	v_mfma_f32_16x16x32_bf16 v[48:51], v[202:205], v[194:197], v[48:51]
	v_mfma_f32_16x16x32_bf16 v[36:39], v[212:215], v[186:189], v[36:39]
	v_mfma_f32_16x16x32_bf16 v[32:35], v[212:215], v[194:197], v[32:35]
	v_mfma_f32_16x16x32_bf16 v[20:23], v[220:223], v[186:189], v[20:23]
	v_mfma_f32_16x16x32_bf16 v[16:19], v[220:223], v[194:197], v[16:19]
	v_mfma_f32_16x16x32_bf16 v[4:7], v[228:231], v[186:189], v[4:7]
	v_mfma_f32_16x16x32_bf16 v[0:3], v[228:231], v[194:197], v[0:3]
	s_setprio 0
	s_add_i32 s68, s68, 2
	s_add_u32 s44, s44, 0x100
	s_addc_u32 s45, s45, 0
	s_cmp_gt_u32 s68, 61
	s_barrier
.LBB0_1005:
	ds_read_b128 v[132:135], v176
	ds_read_b128 v[144:147], v176 offset:1024
	ds_read_b128 v[148:151], v176 offset:2048
	ds_read_b128 v[152:155], v176 offset:3072
	ds_read_b128 v[156:159], v177
	ds_read_b128 v[186:189], v177 offset:1024
	ds_read_b128 v[190:193], v177 offset:2048
	ds_read_b128 v[194:197], v177 offset:3072
	s_add_u32 s46, s60, s44
	s_addc_u32 s47, s61, s45
	s_add_u32 s46, s46, 0xfa70100
	s_addc_u32 s47, s47, 0
	s_add_u32 s69, s66, s44
	s_addc_u32 s70, s67, s45
	s_cmpk_eq_i32 s44, 0x1f00
	s_cselect_b32 s49, s42, s47
	s_cselect_b32 s48, s15, s46
	s_cselect_b32 s47, s43, s70
	s_cselect_b32 s46, s13, s69
	v_readfirstlane_b32 s69, v182
	v_lshl_add_u64 v[232:233], v[128:129], 0, s[44:45]
	s_mov_b32 m0, s69
	v_readfirstlane_b32 s69, v183
	ds_read_b128 v[198:201], v178
	ds_read_b128 v[202:205], v178 offset:1024
	ds_read_b128 v[206:209], v179
	ds_read_b128 v[212:215], v179 offset:1024
	ds_read_b128 v[216:219], v180
	ds_read_b128 v[220:223], v180 offset:1024
	ds_read_b128 v[224:227], v181
	ds_read_b128 v[228:231], v181 offset:1024
	global_load_lds_dwordx4 v[232:233], off
	v_lshl_add_u64 v[232:233], v[130:131], 0, s[44:45]
	s_mov_b32 m0, s69
	s_nop 0
	global_load_lds_dwordx4 v[232:233], off
	s_waitcnt vmcnt(8)
	s_waitcnt lgkmcnt(0)
	s_barrier
; #define STAGE(P, g) do { const char* g_ = (const char*)(g); \
;         __builtin_amdgcn_global_load_lds((const unsigned*)(g_ + so0), (lds_u32*)((lds_u8*)(P) + sb0), 16, 0, 0); \
;         __builtin_amdgcn_global_load_lds((const unsigned*)(g_ + so1), (lds_u32*)((lds_u8*)(P) + sb0 + 8192), 16, 0, 0); } while (0)
; #define LDA(dst, b, h) for (int m = 0; m < 4; ++m) for (int k = 0; k < 2; ++k) \
;         dst[m][k] = *reinterpret_cast<const bf16x8*>((char*)SA(b, h) + lds_byte(wr * 64 + m * 16 + fr, k * 32 + fq * 8))
; #define LDB(dst, b, h) for (int n = 0; n < 2; ++n) for (int k = 0; k < 2; ++k) \
;         dst[n][k] = *reinterpret_cast<const bf16x8*>((char*)SB(b, h) + lds_byte(wc * 32 + n * 16 + fr, k * 32 + fq * 8))
; #define MMA(ai, bj, At_, Bt_) do { __builtin_amdgcn_s_setprio(1); \
;         for (int m = 0; m < 4; ++m) for (int n = 0; n < 2; ++n) for (int k = 0; k < 2; ++k) \
;             acc[ai][bj][m][n] = __builtin_amdgcn_mfma_f32_16x16x32_bf16(At_[m][k], Bt_[n][k], acc[ai][bj][m][n], 0, 0, 0); \
;         __builtin_amdgcn_s_setprio(0); } while (0)
; #define WAIT_V(n) asm volatile("s_waitcnt vmcnt(" #n ")" ::: "memory")
; #define WAIT_L(n) asm volatile("s_waitcnt lgkmcnt(" #n ")" ::: "memory")
; #define BAR __builtin_amdgcn_s_barrier()
; #define SCHED __builtin_amdgcn_sched_barrier(0)
; template <int EPI, int K, int LNI = -1>
; DI void ph_gemm(const Params& p, const bf16_t* __restrict__ A, const bf16_t* __restrict__ Bt, int N, float* s_aux) {
;     ...
;             WAIT_V(8); WAIT_L(0); BAR; MMA(0, 0, At, B0); MMA(0, 1, At, B1); BAR; SCHED;
;             LDA(At, 0, 1); STAGE(SB(0, 0), b2); STAGE(SB(0, 1), b2 + hstep); STAGE(SA(0, 0), a2);
;             WAIT_V(8); WAIT_L(0); BAR; MMA(1, 0, At, B0); MMA(1, 1, At, B1); BAR; SCHED;
;             LDB(B0, 1, 0); LDB(B1, 1, 1); SCHED; LDA(At, 1, 0); STAGE(SA(0, 1), a2 + hstep);
;             WAIT_V(8); WAIT_L(0); BAR; MMA(0, 0, At, B0); MMA(0, 1, At, B1); BAR; SCHED;
	s_setprio 1
	s_waitcnt lgkmcnt(0)
	v_mfma_f32_16x16x32_bf16 v[124:127], v[198:201], v[132:135], v[124:127]
	v_mfma_f32_16x16x32_bf16 v[120:123], v[198:201], v[148:151], v[120:123]
	v_mfma_f32_16x16x32_bf16 v[108:111], v[206:209], v[132:135], v[108:111]
	v_mfma_f32_16x16x32_bf16 v[104:107], v[206:209], v[148:151], v[104:107]
	v_mfma_f32_16x16x32_bf16 v[92:95], v[216:219], v[132:135], v[92:95]
	v_mfma_f32_16x16x32_bf16 v[88:91], v[216:219], v[148:151], v[88:91]
	v_mfma_f32_16x16x32_bf16 v[76:79], v[224:227], v[132:135], v[76:79]
	v_mfma_f32_16x16x32_bf16 v[72:75], v[224:227], v[148:151], v[72:75]
	v_mfma_f32_16x16x32_bf16 v[124:127], v[202:205], v[144:147], v[124:127]
	v_mfma_f32_16x16x32_bf16 v[120:123], v[202:205], v[152:155], v[120:123]
	v_mfma_f32_16x16x32_bf16 v[108:111], v[212:215], v[144:147], v[108:111]
	v_mfma_f32_16x16x32_bf16 v[104:107], v[212:215], v[152:155], v[104:107]
	v_mfma_f32_16x16x32_bf16 v[92:95], v[220:223], v[144:147], v[92:95]
	v_mfma_f32_16x16x32_bf16 v[88:91], v[220:223], v[152:155], v[88:91]
	v_mfma_f32_16x16x32_bf16 v[76:79], v[228:231], v[144:147], v[76:79]
	v_mfma_f32_16x16x32_bf16 v[72:75], v[228:231], v[152:155], v[72:75]
	s_setprio 0
	s_setprio 1
	v_mfma_f32_16x16x32_bf16 v[116:119], v[198:201], v[156:159], v[116:119]
	v_mfma_f32_16x16x32_bf16 v[112:115], v[198:201], v[190:193], v[112:115]
	v_mfma_f32_16x16x32_bf16 v[100:103], v[206:209], v[156:159], v[100:103]
	v_mfma_f32_16x16x32_bf16 v[96:99], v[206:209], v[190:193], v[96:99]
	v_mfma_f32_16x16x32_bf16 v[84:87], v[216:219], v[156:159], v[84:87]
	v_mfma_f32_16x16x32_bf16 v[80:83], v[216:219], v[190:193], v[80:83]
	v_mfma_f32_16x16x32_bf16 v[68:71], v[224:227], v[156:159], v[68:71]
	v_mfma_f32_16x16x32_bf16 v[64:67], v[224:227], v[190:193], v[64:67]
	v_mfma_f32_16x16x32_bf16 v[116:119], v[202:205], v[186:189], v[116:119]
	v_mfma_f32_16x16x32_bf16 v[112:115], v[202:205], v[194:197], v[112:115]
	v_mfma_f32_16x16x32_bf16 v[100:103], v[212:215], v[186:189], v[100:103]
	v_mfma_f32_16x16x32_bf16 v[96:99], v[212:215], v[194:197], v[96:99]
	v_mfma_f32_16x16x32_bf16 v[84:87], v[220:223], v[186:189], v[84:87]
	v_mfma_f32_16x16x32_bf16 v[80:83], v[220:223], v[194:197], v[80:83]
	v_mfma_f32_16x16x32_bf16 v[68:71], v[228:231], v[186:189], v[68:71]
	v_mfma_f32_16x16x32_bf16 v[64:67], v[228:231], v[194:197], v[64:67]
	s_setprio 0
	s_barrier
	v_readfirstlane_b32 s69, v160
	v_lshl_add_u64 v[232:233], s[46:47], 0, v[136:137]
	s_mov_b32 m0, s69
	v_readfirstlane_b32 s69, v161
	s_add_u32 s70, s46, 0x100000
	ds_read_b128 v[198:201], v178 offset:16384
	ds_read_b128 v[202:205], v178 offset:17408
	ds_read_b128 v[206:209], v179 offset:16384
	ds_read_b128 v[212:215], v179 offset:17408
	ds_read_b128 v[216:219], v180 offset:16384
	ds_read_b128 v[220:223], v180 offset:17408
	ds_read_b128 v[224:227], v181 offset:16384
	ds_read_b128 v[228:231], v181 offset:17408
	global_load_lds_dwordx4 v[232:233], off
	v_lshl_add_u64 v[234:235], s[46:47], 0, v[138:139]
	s_mov_b32 m0, s69
	s_addc_u32 s71, s47, 0
	v_readfirstlane_b32 s69, v162
	global_load_lds_dwordx4 v[234:235], off
	v_lshl_add_u64 v[236:237], s[70:71], 0, v[136:137]
	s_mov_b32 m0, s69
	v_readfirstlane_b32 s69, v163
	global_load_lds_dwordx4 v[236:237], off
	v_lshl_add_u64 v[236:237], s[70:71], 0, v[138:139]
	s_mov_b32 m0, s69
	v_readfirstlane_b32 s69, v164
	global_load_lds_dwordx4 v[236:237], off
	v_lshl_add_u64 v[236:237], s[48:49], 0, v[136:137]
	s_mov_b32 m0, s69
	v_readfirstlane_b32 s69, v165
	global_load_lds_dwordx4 v[236:237], off
	v_lshl_add_u64 v[238:239], s[48:49], 0, v[138:139]
	s_mov_b32 m0, s69
	s_nop 0
	global_load_lds_dwordx4 v[238:239], off
	s_waitcnt vmcnt(8)
	s_waitcnt lgkmcnt(0)
	s_barrier
	s_setprio 1
	s_waitcnt lgkmcnt(0)
	v_mfma_f32_16x16x32_bf16 v[60:63], v[198:201], v[132:135], v[60:63]
	v_mfma_f32_16x16x32_bf16 v[56:59], v[198:201], v[148:151], v[56:59]
	v_mfma_f32_16x16x32_bf16 v[44:47], v[206:209], v[132:135], v[44:47]
	v_mfma_f32_16x16x32_bf16 v[40:43], v[206:209], v[148:151], v[40:43]
	v_mfma_f32_16x16x32_bf16 v[28:31], v[216:219], v[132:135], v[28:31]
	v_mfma_f32_16x16x32_bf16 v[24:27], v[216:219], v[148:151], v[24:27]
	v_mfma_f32_16x16x32_bf16 v[12:15], v[224:227], v[132:135], v[12:15]
	v_mfma_f32_16x16x32_bf16 v[8:11], v[224:227], v[148:151], v[8:11]
	v_mfma_f32_16x16x32_bf16 v[60:63], v[202:205], v[144:147], v[60:63]
	v_mfma_f32_16x16x32_bf16 v[56:59], v[202:205], v[152:155], v[56:59]
	v_mfma_f32_16x16x32_bf16 v[44:47], v[212:215], v[144:147], v[44:47]
	v_mfma_f32_16x16x32_bf16 v[40:43], v[212:215], v[152:155], v[40:43]
	v_mfma_f32_16x16x32_bf16 v[28:31], v[220:223], v[144:147], v[28:31]
	v_mfma_f32_16x16x32_bf16 v[24:27], v[220:223], v[152:155], v[24:27]
	v_mfma_f32_16x16x32_bf16 v[12:15], v[228:231], v[144:147], v[12:15]
	v_mfma_f32_16x16x32_bf16 v[8:11], v[228:231], v[152:155], v[8:11]
	s_setprio 0
	s_setprio 1
	v_mfma_f32_16x16x32_bf16 v[52:55], v[198:201], v[156:159], v[52:55]
	v_mfma_f32_16x16x32_bf16 v[48:51], v[198:201], v[190:193], v[48:51]
	v_mfma_f32_16x16x32_bf16 v[36:39], v[206:209], v[156:159], v[36:39]
	v_mfma_f32_16x16x32_bf16 v[32:35], v[206:209], v[190:193], v[32:35]
	v_mfma_f32_16x16x32_bf16 v[20:23], v[216:219], v[156:159], v[20:23]
	v_mfma_f32_16x16x32_bf16 v[16:19], v[216:219], v[190:193], v[16:19]
	v_mfma_f32_16x16x32_bf16 v[4:7], v[224:227], v[156:159], v[4:7]
	v_mfma_f32_16x16x32_bf16 v[0:3], v[224:227], v[190:193], v[0:3]
	v_mfma_f32_16x16x32_bf16 v[52:55], v[202:205], v[186:189], v[52:55]
	v_mfma_f32_16x16x32_bf16 v[48:51], v[202:205], v[194:197], v[48:51]
	v_mfma_f32_16x16x32_bf16 v[36:39], v[212:215], v[186:189], v[36:39]
	v_mfma_f32_16x16x32_bf16 v[32:35], v[212:215], v[194:197], v[32:35]
	v_mfma_f32_16x16x32_bf16 v[20:23], v[220:223], v[186:189], v[20:23]
	v_mfma_f32_16x16x32_bf16 v[16:19], v[220:223], v[194:197], v[16:19]
	v_mfma_f32_16x16x32_bf16 v[4:7], v[228:231], v[186:189], v[4:7]
	v_mfma_f32_16x16x32_bf16 v[0:3], v[228:231], v[194:197], v[0:3]
	s_setprio 0
	s_barrier
; #define STAGE(P, g) do { const char* g_ = (const char*)(g); \
;         __builtin_amdgcn_global_load_lds((const unsigned*)(g_ + so0), (lds_u32*)((lds_u8*)(P) + sb0), 16, 0, 0); \
;         __builtin_amdgcn_global_load_lds((const unsigned*)(g_ + so1), (lds_u32*)((lds_u8*)(P) + sb0 + 8192), 16, 0, 0); } while (0)
; #define LDA(dst, b, h) for (int m = 0; m < 4; ++m) for (int k = 0; k < 2; ++k) \
;         dst[m][k] = *reinterpret_cast<const bf16x8*>((char*)SA(b, h) + lds_byte(wr * 64 + m * 16 + fr, k * 32 + fq * 8))
; #define LDB(dst, b, h) for (int n = 0; n < 2; ++n) for (int k = 0; k < 2; ++k) \
;         dst[n][k] = *reinterpret_cast<const bf16x8*>((char*)SB(b, h) + lds_byte(wc * 32 + n * 16 + fr, k * 32 + fq * 8))
; #define MMA(ai, bj, At_, Bt_) do { __builtin_amdgcn_s_setprio(1); \
;         for (int m = 0; m < 4; ++m) for (int n = 0; n < 2; ++n) for (int k = 0; k < 2; ++k) \
;             acc[ai][bj][m][n] = __builtin_amdgcn_mfma_f32_16x16x32_bf16(At_[m][k], Bt_[n][k], acc[ai][bj][m][n], 0, 0, 0); \
;         __builtin_amdgcn_s_setprio(0); } while (0)
; #define WAIT_V(n) asm volatile("s_waitcnt vmcnt(" #n ")" ::: "memory")
; #define WAIT_L(n) asm volatile("s_waitcnt lgkmcnt(" #n ")" ::: "memory")
; #define BAR __builtin_amdgcn_s_barrier()
; #define SCHED __builtin_amdgcn_sched_barrier(0)
; template <int EPI, int K, int LNI = -1>
; DI void ph_gemm(const Params& p, const bf16_t* __restrict__ A, const bf16_t* __restrict__ Bt, int N, float* s_aux) {
;     ...
;             LDB(B0, 1, 0); LDB(B1, 1, 1); SCHED; LDA(At, 1, 0); STAGE(SA(0, 1), a2 + hstep);
;             WAIT_V(8); WAIT_L(0); BAR; MMA(0, 0, At, B0); MMA(0, 1, At, B1); BAR; SCHED;
	ds_read_b128 v[132:135], v184
	ds_read_b128 v[144:147], v184 offset:1024
	ds_read_b128 v[148:151], v184 offset:2048
	ds_read_b128 v[152:155], v184 offset:3072
	ds_read_b128 v[156:159], v185
	ds_read_b128 v[186:189], v185 offset:1024
	ds_read_b128 v[190:193], v185 offset:2048
	ds_read_b128 v[194:197], v185 offset:3072
	s_add_u32 s48, s48, 0x100000
	s_addc_u32 s49, s49, 0
	v_readfirstlane_b32 s69, v166
	v_lshl_add_u64 v[240:241], s[48:49], 0, v[136:137]
	s_mov_b32 m0, s69
	ds_read_b128 v[198:201], v178 offset:32768
	ds_read_b128 v[202:205], v178 offset:33792
	ds_read_b128 v[206:209], v179 offset:32768
	ds_read_b128 v[212:215], v179 offset:33792
	ds_read_b128 v[216:219], v180 offset:32768
	ds_read_b128 v[220:223], v180 offset:33792
	ds_read_b128 v[224:227], v181 offset:32768
	ds_read_b128 v[228:231], v181 offset:33792
	global_load_lds_dwordx4 v[240:241], off
	v_lshl_add_u64 v[240:241], s[48:49], 0, v[138:139]
	v_readfirstlane_b32 s48, v167
	s_mov_b32 m0, s48
	s_nop 0
	global_load_lds_dwordx4 v[240:241], off
	s_waitcnt vmcnt(8)
	s_waitcnt lgkmcnt(0)
	s_barrier
	s_setprio 1
	s_waitcnt lgkmcnt(0)
	v_mfma_f32_16x16x32_bf16 v[124:127], v[198:201], v[132:135], v[124:127]
	v_mfma_f32_16x16x32_bf16 v[120:123], v[198:201], v[148:151], v[120:123]
	v_mfma_f32_16x16x32_bf16 v[108:111], v[206:209], v[132:135], v[108:111]
	v_mfma_f32_16x16x32_bf16 v[104:107], v[206:209], v[148:151], v[104:107]
	v_mfma_f32_16x16x32_bf16 v[92:95], v[216:219], v[132:135], v[92:95]
	v_mfma_f32_16x16x32_bf16 v[88:91], v[216:219], v[148:151], v[88:91]
	v_mfma_f32_16x16x32_bf16 v[76:79], v[224:227], v[132:135], v[76:79]
	v_mfma_f32_16x16x32_bf16 v[72:75], v[224:227], v[148:151], v[72:75]
	v_mfma_f32_16x16x32_bf16 v[124:127], v[202:205], v[144:147], v[124:127]
	v_mfma_f32_16x16x32_bf16 v[120:123], v[202:205], v[152:155], v[120:123]
	v_mfma_f32_16x16x32_bf16 v[108:111], v[212:215], v[144:147], v[108:111]
	v_mfma_f32_16x16x32_bf16 v[104:107], v[212:215], v[152:155], v[104:107]
	v_mfma_f32_16x16x32_bf16 v[92:95], v[220:223], v[144:147], v[92:95]
	v_mfma_f32_16x16x32_bf16 v[88:91], v[220:223], v[152:155], v[88:91]
	v_mfma_f32_16x16x32_bf16 v[76:79], v[228:231], v[144:147], v[76:79]
	v_mfma_f32_16x16x32_bf16 v[72:75], v[228:231], v[152:155], v[72:75]
	s_setprio 0
	s_setprio 1
	v_mfma_f32_16x16x32_bf16 v[116:119], v[198:201], v[156:159], v[116:119]
	v_mfma_f32_16x16x32_bf16 v[112:115], v[198:201], v[190:193], v[112:115]
	v_mfma_f32_16x16x32_bf16 v[100:103], v[206:209], v[156:159], v[100:103]
	v_mfma_f32_16x16x32_bf16 v[96:99], v[206:209], v[190:193], v[96:99]
	v_mfma_f32_16x16x32_bf16 v[84:87], v[216:219], v[156:159], v[84:87]
	v_mfma_f32_16x16x32_bf16 v[80:83], v[216:219], v[190:193], v[80:83]
	v_mfma_f32_16x16x32_bf16 v[68:71], v[224:227], v[156:159], v[68:71]
	v_mfma_f32_16x16x32_bf16 v[64:67], v[224:227], v[190:193], v[64:67]
	v_mfma_f32_16x16x32_bf16 v[116:119], v[202:205], v[186:189], v[116:119]
	v_mfma_f32_16x16x32_bf16 v[112:115], v[202:205], v[194:197], v[112:115]
	v_mfma_f32_16x16x32_bf16 v[100:103], v[212:215], v[186:189], v[100:103]
	v_mfma_f32_16x16x32_bf16 v[96:99], v[212:215], v[194:197], v[96:99]
	v_mfma_f32_16x16x32_bf16 v[84:87], v[220:223], v[186:189], v[84:87]
	v_mfma_f32_16x16x32_bf16 v[80:83], v[220:223], v[194:197], v[80:83]
	v_mfma_f32_16x16x32_bf16 v[68:71], v[228:231], v[186:189], v[68:71]
	v_mfma_f32_16x16x32_bf16 v[64:67], v[228:231], v[194:197], v[64:67]
	s_setprio 0
	s_barrier
; #define STAGE(P, g) do { const char* g_ = (const char*)(g); \
;         __builtin_amdgcn_global_load_lds((const unsigned*)(g_ + so0), (lds_u32*)((lds_u8*)(P) + sb0), 16, 0, 0); \
;         __builtin_amdgcn_global_load_lds((const unsigned*)(g_ + so1), (lds_u32*)((lds_u8*)(P) + sb0 + 8192), 16, 0, 0); } while (0)
; #define LDA(dst, b, h) for (int m = 0; m < 4; ++m) for (int k = 0; k < 2; ++k) \
;         dst[m][k] = *reinterpret_cast<const bf16x8*>((char*)SA(b, h) + lds_byte(wr * 64 + m * 16 + fr, k * 32 + fq * 8))
; #define MMA(ai, bj, At_, Bt_) do { __builtin_amdgcn_s_setprio(1); \
;         for (int m = 0; m < 4; ++m) for (int n = 0; n < 2; ++n) for (int k = 0; k < 2; ++k) \
;             acc[ai][bj][m][n] = __builtin_amdgcn_mfma_f32_16x16x32_bf16(At_[m][k], Bt_[n][k], acc[ai][bj][m][n], 0, 0, 0); \
;         __builtin_amdgcn_s_setprio(0); } while (0)
; #define WAIT_V(n) asm volatile("s_waitcnt vmcnt(" #n ")" ::: "memory")
; #define WAIT_L(n) asm volatile("s_waitcnt lgkmcnt(" #n ")" ::: "memory")
; #define BAR __builtin_amdgcn_s_barrier()
; #define SCHED __builtin_amdgcn_sched_barrier(0)
; template <int EPI, int K, int LNI = -1>
; DI void ph_gemm(const Params& p, const bf16_t* __restrict__ A, const bf16_t* __restrict__ Bt, int N, float* s_aux) {
;     ...
;             LDA(At, 1, 1); STAGE(SB(1, 0), b3); STAGE(SB(1, 1), b3 + hstep); STAGE(SA(1, 0), a3);
;             WAIT_V(8); WAIT_L(0); BAR; MMA(1, 0, At, B0); MMA(1, 1, At, B1); BAR; SCHED;
;         }
;         if (wr == 0) BAR;
	v_readfirstlane_b32 s48, v168
	v_lshl_add_u64 v[232:233], v[232:233], 0, s[8:9]
	s_mov_b32 m0, s48
	v_readfirstlane_b32 s48, v169
	s_add_u32 s46, s46, 0x100080
	ds_read_b128 v[198:201], v178 offset:49152
	ds_read_b128 v[202:205], v178 offset:50176
	ds_read_b128 v[206:209], v179 offset:49152
	ds_read_b128 v[212:215], v179 offset:50176
	ds_read_b128 v[216:219], v180 offset:49152
	ds_read_b128 v[220:223], v180 offset:50176
	ds_read_b128 v[224:227], v181 offset:49152
	ds_read_b128 v[228:231], v181 offset:50176
	global_load_lds_dwordx4 v[232:233], off
	v_lshl_add_u64 v[232:233], v[234:235], 0, s[8:9]
	s_mov_b32 m0, s48
	s_addc_u32 s47, s47, 0
	v_readfirstlane_b32 s48, v172
	global_load_lds_dwordx4 v[232:233], off
	v_lshl_add_u64 v[232:233], s[46:47], 0, v[136:137]
	s_mov_b32 m0, s48
	s_nop 0
	global_load_lds_dwordx4 v[232:233], off
	v_lshl_add_u64 v[232:233], s[46:47], 0, v[138:139]
	v_readfirstlane_b32 s46, v173
	s_mov_b32 m0, s46
	v_readfirstlane_b32 s46, v170
	global_load_lds_dwordx4 v[232:233], off
	v_lshl_add_u64 v[232:233], v[236:237], 0, s[8:9]
	s_mov_b32 m0, s46
	v_readfirstlane_b32 s46, v171
	global_load_lds_dwordx4 v[232:233], off
	v_lshl_add_u64 v[232:233], v[238:239], 0, s[8:9]
	s_mov_b32 m0, s46
	s_nop 0
	global_load_lds_dwordx4 v[232:233], off
	s_waitcnt vmcnt(8)
	s_waitcnt lgkmcnt(0)
	s_barrier
	s_setprio 1
	s_waitcnt lgkmcnt(0)
	v_mfma_f32_16x16x32_bf16 v[60:63], v[198:201], v[132:135], v[60:63]
	v_mfma_f32_16x16x32_bf16 v[56:59], v[198:201], v[148:151], v[56:59]
	v_mfma_f32_16x16x32_bf16 v[44:47], v[206:209], v[132:135], v[44:47]
	v_mfma_f32_16x16x32_bf16 v[40:43], v[206:209], v[148:151], v[40:43]
	v_mfma_f32_16x16x32_bf16 v[28:31], v[216:219], v[132:135], v[28:31]
	v_mfma_f32_16x16x32_bf16 v[24:27], v[216:219], v[148:151], v[24:27]
	v_mfma_f32_16x16x32_bf16 v[12:15], v[224:227], v[132:135], v[12:15]
	v_mfma_f32_16x16x32_bf16 v[8:11], v[224:227], v[148:151], v[8:11]
	v_mfma_f32_16x16x32_bf16 v[60:63], v[202:205], v[144:147], v[60:63]
	v_mfma_f32_16x16x32_bf16 v[56:59], v[202:205], v[152:155], v[56:59]
	v_mfma_f32_16x16x32_bf16 v[44:47], v[212:215], v[144:147], v[44:47]
	v_mfma_f32_16x16x32_bf16 v[40:43], v[212:215], v[152:155], v[40:43]
	v_mfma_f32_16x16x32_bf16 v[28:31], v[220:223], v[144:147], v[28:31]
	v_mfma_f32_16x16x32_bf16 v[24:27], v[220:223], v[152:155], v[24:27]
	v_mfma_f32_16x16x32_bf16 v[12:15], v[228:231], v[144:147], v[12:15]
	v_mfma_f32_16x16x32_bf16 v[8:11], v[228:231], v[152:155], v[8:11]
	s_setprio 0
	s_setprio 1
	v_mfma_f32_16x16x32_bf16 v[52:55], v[198:201], v[156:159], v[52:55]
	v_mfma_f32_16x16x32_bf16 v[48:51], v[198:201], v[190:193], v[48:51]
	v_mfma_f32_16x16x32_bf16 v[36:39], v[206:209], v[156:159], v[36:39]
	v_mfma_f32_16x16x32_bf16 v[32:35], v[206:209], v[190:193], v[32:35]
	v_mfma_f32_16x16x32_bf16 v[20:23], v[216:219], v[156:159], v[20:23]
	v_mfma_f32_16x16x32_bf16 v[16:19], v[216:219], v[190:193], v[16:19]
	v_mfma_f32_16x16x32_bf16 v[4:7], v[224:227], v[156:159], v[4:7]
	v_mfma_f32_16x16x32_bf16 v[0:3], v[224:227], v[190:193], v[0:3]
	v_mfma_f32_16x16x32_bf16 v[52:55], v[202:205], v[186:189], v[52:55]
	v_mfma_f32_16x16x32_bf16 v[48:51], v[202:205], v[194:197], v[48:51]
	v_mfma_f32_16x16x32_bf16 v[36:39], v[212:215], v[186:189], v[36:39]
	v_mfma_f32_16x16x32_bf16 v[32:35], v[212:215], v[194:197], v[32:35]
	v_mfma_f32_16x16x32_bf16 v[20:23], v[220:223], v[186:189], v[20:23]
	v_mfma_f32_16x16x32_bf16 v[16:19], v[220:223], v[194:197], v[16:19]
	v_mfma_f32_16x16x32_bf16 v[4:7], v[228:231], v[186:189], v[4:7]
	v_mfma_f32_16x16x32_bf16 v[0:3], v[228:231], v[194:197], v[0:3]
	s_setprio 0
	s_add_i32 s68, s68, 2
	s_add_u32 s44, s44, 0x100
	s_addc_u32 s45, s45, 0
	s_cmp_gt_u32 s68, 61
	s_barrier
	s_cbranch_scc0 .LBB0_1005
	s_and_saveexec_b64 s[44:45], s[4:5]
	s_cbranch_execz .LBB0_1008
	s_barrier

; #define STAGE(P, g) do { const char* g_ = (const char*)(g); \
;         __builtin_amdgcn_global_load_lds((const unsigned*)(g_ + so0), (lds_u32*)((lds_u8*)(P) + sb0), 16, 0, 0); \
;         __builtin_amdgcn_global_load_lds((const unsigned*)(g_ + so1), (lds_u32*)((lds_u8*)(P) + sb0 + 8192), 16, 0, 0); } while (0)
; #define LDA(dst, b, h) for (int m = 0; m < 4; ++m) for (int k = 0; k < 2; ++k) \
;         dst[m][k] = *reinterpret_cast<const bf16x8*>((char*)SA(b, h) + lds_byte(wr * 64 + m * 16 + fr, k * 32 + fq * 8))
; #define LDB(dst, b, h) for (int n = 0; n < 2; ++n) for (int k = 0; k < 2; ++k) \
;         dst[n][k] = *reinterpret_cast<const bf16x8*>((char*)SB(b, h) + lds_byte(wc * 32 + n * 16 + fr, k * 32 + fq * 8))
; #define MMA(ai, bj, At_, Bt_) do { __builtin_amdgcn_s_setprio(1); \
;         for (int m = 0; m < 4; ++m) for (int n = 0; n < 2; ++n) for (int k = 0; k < 2; ++k) \
;             acc[ai][bj][m][n] = __builtin_amdgcn_mfma_f32_16x16x32_bf16(At_[m][k], Bt_[n][k], acc[ai][bj][m][n], 0, 0, 0); \
;         __builtin_amdgcn_s_setprio(0); } while (0)
; #define WAIT_V(n) asm volatile("s_waitcnt vmcnt(" #n ")" ::: "memory")
; #define WAIT_L(n) asm volatile("s_waitcnt lgkmcnt(" #n ")" ::: "memory")
; #define BAR __builtin_amdgcn_s_barrier()
; #define SCHED __builtin_amdgcn_sched_barrier(0)
; template <int EPI, int K, int LNI = -1>
; DI void ph_gemm(const Params& p, const bf16_t* __restrict__ A, const bf16_t* __restrict__ Bt, int N, float* s_aux) {
;     ...
;         for (int t = 0; t < nt; t += 2) {
;             const bool last = (t == nt - 2);
;             const bf16_t* a1 = cA + (size_t)(t + 1) * kstep;
;             const bf16_t* a2 = last ? nA : cA + (size_t)(t + 2) * kstep; const bf16_t* b2 = last ? nB : cB + (size_t)(t + 2) * kstep;
;             const bf16_t* a3 = a2 + kstep; const bf16_t* b3 = b2 + kstep;
;             LDB(B0, 0, 0); LDB(B1, 0, 1); SCHED; LDA(At, 0, 0); STAGE(SA(1, 1), a1 + hstep);
;             WAIT_V(8); WAIT_L(0); BAR; MMA(0, 0, At, B0); MMA(0, 1, At, B1); BAR; SCHED;
;             LDA(At, 0, 1); STAGE(SB(0, 0), b2); STAGE(SB(0, 1), b2 + hstep); STAGE(SA(0, 0), a2);
;             WAIT_V(8); WAIT_L(0); BAR; MMA(1, 0, At, B0); MMA(1, 1, At, B1); BAR; SCHED;
.LBB0_1143:
	s_ashr_i32 s51, s50, 31
	s_lshl_b64 s[52:53], s[50:51], 19
	s_add_u32 s9, s40, s52
	s_addc_u32 s11, s41, s53
	s_ashr_i32 s49, s48, 31
	s_lshl_b64 s[60:61], s[48:49], 19
	s_add_u32 s42, s26, s60
	s_addc_u32 s43, s27, s61
	s_add_u32 s49, s56, s12
	s_addc_u32 s51, s57, s13
	s_add_u32 s68, s45, s14
	v_lshl_add_u64 v[138:139], v[134:135], 0, s[12:13]
	v_lshl_add_u64 v[140:141], v[136:137], 0, s[12:13]
	s_addc_u32 s69, s70, s15
	s_mov_b32 s80, -2
	s_mov_b64 s[12:13], 0
	ds_read_b128 v[142:145], v165
	ds_read_b128 v[176:179], v165 offset:1024
	ds_read_b128 v[180:183], v165 offset:2048
	ds_read_b128 v[184:187], v165 offset:3072
	ds_read_b128 v[188:191], v166
	ds_read_b128 v[192:195], v166 offset:1024
	ds_read_b128 v[196:199], v166 offset:2048
	ds_read_b128 v[200:203], v166 offset:3072
	s_add_u32 s14, s49, s12
	s_addc_u32 s15, s51, s13
	s_add_u32 s14, s14, 0xb840100
	s_addc_u32 s15, s15, 0
	s_add_u32 s91, s68, s12
	s_addc_u32 s92, s69, s13
	s_cmpk_eq_i32 s12, 0x700
	s_cselect_b32 s67, s11, s15
	s_cselect_b32 s66, s9, s14
	s_cselect_b32 s15, s43, s92
	s_cselect_b32 s14, s42, s91
	v_readfirstlane_b32 s91, v171
	v_lshl_add_u64 v[146:147], v[138:139], 0, s[12:13]
	s_mov_b32 m0, s91
	v_readfirstlane_b32 s91, v172
	ds_read_b128 v[204:207], v167
	ds_read_b128 v[212:215], v167 offset:1024
	ds_read_b128 v[216:219], v168
	ds_read_b128 v[220:223], v168 offset:1024
	ds_read_b128 v[224:227], v169
	ds_read_b128 v[228:231], v169 offset:1024
	ds_read_b128 v[232:235], v170
	ds_read_b128 v[236:239], v170 offset:1024
	global_load_lds_dwordx4 v[146:147], off
	v_lshl_add_u64 v[146:147], v[140:141], 0, s[12:13]
	s_mov_b32 m0, s91
	s_nop 0
	global_load_lds_dwordx4 v[146:147], off
	s_waitcnt vmcnt(8)
	s_waitcnt lgkmcnt(0)
	s_barrier
	s_setprio 1
	s_waitcnt lgkmcnt(0)
	v_mfma_f32_16x16x32_bf16 v[124:127], v[204:207], v[142:145], 0
	v_mfma_f32_16x16x32_bf16 v[120:123], v[204:207], v[180:183], 0
	v_mfma_f32_16x16x32_bf16 v[108:111], v[216:219], v[142:145], 0
	v_mfma_f32_16x16x32_bf16 v[104:107], v[216:219], v[180:183], 0
	v_mfma_f32_16x16x32_bf16 v[92:95], v[224:227], v[142:145], 0
	v_mfma_f32_16x16x32_bf16 v[88:91], v[224:227], v[180:183], 0
	v_mfma_f32_16x16x32_bf16 v[76:79], v[232:235], v[142:145], 0
	v_mfma_f32_16x16x32_bf16 v[72:75], v[232:235], v[180:183], 0
	v_mfma_f32_16x16x32_bf16 v[124:127], v[212:215], v[176:179], v[124:127]
	v_mfma_f32_16x16x32_bf16 v[120:123], v[212:215], v[184:187], v[120:123]
	v_mfma_f32_16x16x32_bf16 v[108:111], v[220:223], v[176:179], v[108:111]
	v_mfma_f32_16x16x32_bf16 v[104:107], v[220:223], v[184:187], v[104:107]
	v_mfma_f32_16x16x32_bf16 v[92:95], v[228:231], v[176:179], v[92:95]
	v_mfma_f32_16x16x32_bf16 v[88:91], v[228:231], v[184:187], v[88:91]
	v_mfma_f32_16x16x32_bf16 v[76:79], v[236:239], v[176:179], v[76:79]
	v_mfma_f32_16x16x32_bf16 v[72:75], v[236:239], v[184:187], v[72:75]
	s_setprio 0
	s_setprio 1
	v_mfma_f32_16x16x32_bf16 v[116:119], v[204:207], v[188:191], 0
	v_mfma_f32_16x16x32_bf16 v[112:115], v[204:207], v[196:199], 0
	v_mfma_f32_16x16x32_bf16 v[100:103], v[216:219], v[188:191], 0
	v_mfma_f32_16x16x32_bf16 v[96:99], v[216:219], v[196:199], 0
	v_mfma_f32_16x16x32_bf16 v[84:87], v[224:227], v[188:191], 0
	v_mfma_f32_16x16x32_bf16 v[80:83], v[224:227], v[196:199], 0
	v_mfma_f32_16x16x32_bf16 v[68:71], v[232:235], v[188:191], 0
	v_mfma_f32_16x16x32_bf16 v[64:67], v[232:235], v[196:199], 0
	v_mfma_f32_16x16x32_bf16 v[116:119], v[212:215], v[192:195], v[116:119]
	v_mfma_f32_16x16x32_bf16 v[112:115], v[212:215], v[200:203], v[112:115]
	v_mfma_f32_16x16x32_bf16 v[100:103], v[220:223], v[192:195], v[100:103]
	v_mfma_f32_16x16x32_bf16 v[96:99], v[220:223], v[200:203], v[96:99]
	v_mfma_f32_16x16x32_bf16 v[84:87], v[228:231], v[192:195], v[84:87]
	v_mfma_f32_16x16x32_bf16 v[80:83], v[228:231], v[200:203], v[80:83]
	v_mfma_f32_16x16x32_bf16 v[68:71], v[236:239], v[192:195], v[68:71]
	v_mfma_f32_16x16x32_bf16 v[64:67], v[236:239], v[200:203], v[64:67]
	s_setprio 0
	s_barrier
	v_readfirstlane_b32 s91, v148
	v_lshl_add_u64 v[146:147], s[14:15], 0, v[128:129]
	s_mov_b32 m0, s91
	v_readfirstlane_b32 s91, v149
	s_add_u32 s92, s14, 0x40000
	ds_read_b128 v[204:207], v167 offset:16384
	ds_read_b128 v[212:215], v167 offset:17408
	ds_read_b128 v[216:219], v168 offset:16384
	ds_read_b128 v[220:223], v168 offset:17408
	ds_read_b128 v[224:227], v169 offset:16384
	ds_read_b128 v[228:231], v169 offset:17408
	ds_read_b128 v[232:235], v170 offset:16384
	ds_read_b128 v[236:239], v170 offset:17408
	global_load_lds_dwordx4 v[146:147], off
	v_lshl_add_u64 v[208:209], s[14:15], 0, v[130:131]
	s_mov_b32 m0, s91
	s_addc_u32 s93, s15, 0
	v_readfirstlane_b32 s91, v150
	global_load_lds_dwordx4 v[208:209], off
	v_lshl_add_u64 v[240:241], s[92:93], 0, v[128:129]
	s_mov_b32 m0, s91
	v_readfirstlane_b32 s91, v151
	global_load_lds_dwordx4 v[240:241], off
	v_lshl_add_u64 v[240:241], s[92:93], 0, v[130:131]
	s_mov_b32 m0, s91
	v_readfirstlane_b32 s91, v152
	global_load_lds_dwordx4 v[240:241], off
	v_lshl_add_u64 v[240:241], s[66:67], 0, v[128:129]
	s_mov_b32 m0, s91
	v_readfirstlane_b32 s91, v153
	global_load_lds_dwordx4 v[240:241], off
	v_lshl_add_u64 v[242:243], s[66:67], 0, v[130:131]
	s_mov_b32 m0, s91
	s_nop 0
	global_load_lds_dwordx4 v[242:243], off
	s_waitcnt vmcnt(8)
	s_waitcnt lgkmcnt(0)
	s_barrier
; #define STAGE(P, g) do { const char* g_ = (const char*)(g); \
;         __builtin_amdgcn_global_load_lds((const unsigned*)(g_ + so0), (lds_u32*)((lds_u8*)(P) + sb0), 16, 0, 0); \
;         __builtin_amdgcn_global_load_lds((const unsigned*)(g_ + so1), (lds_u32*)((lds_u8*)(P) + sb0 + 8192), 16, 0, 0); } while (0)
; #define LDA(dst, b, h) for (int m = 0; m < 4; ++m) for (int k = 0; k < 2; ++k) \
;         dst[m][k] = *reinterpret_cast<const bf16x8*>((char*)SA(b, h) + lds_byte(wr * 64 + m * 16 + fr, k * 32 + fq * 8))
; #define LDB(dst, b, h) for (int n = 0; n < 2; ++n) for (int k = 0; k < 2; ++k) \
;         dst[n][k] = *reinterpret_cast<const bf16x8*>((char*)SB(b, h) + lds_byte(wc * 32 + n * 16 + fr, k * 32 + fq * 8))
; #define MMA(ai, bj, At_, Bt_) do { __builtin_amdgcn_s_setprio(1); \
;         for (int m = 0; m < 4; ++m) for (int n = 0; n < 2; ++n) for (int k = 0; k < 2; ++k) \
;             acc[ai][bj][m][n] = __builtin_amdgcn_mfma_f32_16x16x32_bf16(At_[m][k], Bt_[n][k], acc[ai][bj][m][n], 0, 0, 0); \
;         __builtin_amdgcn_s_setprio(0); } while (0)
; #define WAIT_V(n) asm volatile("s_waitcnt vmcnt(" #n ")" ::: "memory")
; #define WAIT_L(n) asm volatile("s_waitcnt lgkmcnt(" #n ")" ::: "memory")
; #define BAR __builtin_amdgcn_s_barrier()
; #define SCHED __builtin_amdgcn_sched_barrier(0)
; template <int EPI, int K, int LNI = -1>
; DI void ph_gemm(const Params& p, const bf16_t* __restrict__ A, const bf16_t* __restrict__ Bt, int N, float* s_aux) {
;     ...
;             WAIT_V(8); WAIT_L(0); BAR; MMA(0, 0, At, B0); MMA(0, 1, At, B1); BAR; SCHED;
;             LDA(At, 0, 1); STAGE(SB(0, 0), b2); STAGE(SB(0, 1), b2 + hstep); STAGE(SA(0, 0), a2);
;             WAIT_V(8); WAIT_L(0); BAR; MMA(1, 0, At, B0); MMA(1, 1, At, B1); BAR; SCHED;
;             LDB(B0, 1, 0); LDB(B1, 1, 1); SCHED; LDA(At, 1, 0); STAGE(SA(0, 1), a2 + hstep);
;             WAIT_V(8); WAIT_L(0); BAR; MMA(0, 0, At, B0); MMA(0, 1, At, B1); BAR; SCHED;
	s_setprio 1
	s_waitcnt lgkmcnt(0)
	v_mfma_f32_16x16x32_bf16 v[60:63], v[204:207], v[142:145], 0
	v_mfma_f32_16x16x32_bf16 v[56:59], v[204:207], v[180:183], 0
	v_mfma_f32_16x16x32_bf16 v[44:47], v[216:219], v[142:145], 0
	v_mfma_f32_16x16x32_bf16 v[40:43], v[216:219], v[180:183], 0
	v_mfma_f32_16x16x32_bf16 v[28:31], v[224:227], v[142:145], 0
	v_mfma_f32_16x16x32_bf16 v[24:27], v[224:227], v[180:183], 0
	v_mfma_f32_16x16x32_bf16 v[12:15], v[232:235], v[142:145], 0
	v_mfma_f32_16x16x32_bf16 v[8:11], v[232:235], v[180:183], 0
	v_mfma_f32_16x16x32_bf16 v[60:63], v[212:215], v[176:179], v[60:63]
	v_mfma_f32_16x16x32_bf16 v[56:59], v[212:215], v[184:187], v[56:59]
	v_mfma_f32_16x16x32_bf16 v[44:47], v[220:223], v[176:179], v[44:47]
	v_mfma_f32_16x16x32_bf16 v[40:43], v[220:223], v[184:187], v[40:43]
	v_mfma_f32_16x16x32_bf16 v[28:31], v[228:231], v[176:179], v[28:31]
	v_mfma_f32_16x16x32_bf16 v[24:27], v[228:231], v[184:187], v[24:27]
	v_mfma_f32_16x16x32_bf16 v[12:15], v[236:239], v[176:179], v[12:15]
	v_mfma_f32_16x16x32_bf16 v[8:11], v[236:239], v[184:187], v[8:11]
	s_setprio 0
	s_setprio 1
	v_mfma_f32_16x16x32_bf16 v[52:55], v[204:207], v[188:191], 0
	v_mfma_f32_16x16x32_bf16 v[48:51], v[204:207], v[196:199], 0
	v_mfma_f32_16x16x32_bf16 v[36:39], v[216:219], v[188:191], 0
	v_mfma_f32_16x16x32_bf16 v[32:35], v[216:219], v[196:199], 0
	v_mfma_f32_16x16x32_bf16 v[20:23], v[224:227], v[188:191], 0
	v_mfma_f32_16x16x32_bf16 v[16:19], v[224:227], v[196:199], 0
	v_mfma_f32_16x16x32_bf16 v[4:7], v[232:235], v[188:191], 0
	v_mfma_f32_16x16x32_bf16 v[0:3], v[232:235], v[196:199], 0
	v_mfma_f32_16x16x32_bf16 v[52:55], v[212:215], v[192:195], v[52:55]
	v_mfma_f32_16x16x32_bf16 v[48:51], v[212:215], v[200:203], v[48:51]
	v_mfma_f32_16x16x32_bf16 v[36:39], v[220:223], v[192:195], v[36:39]
	v_mfma_f32_16x16x32_bf16 v[32:35], v[220:223], v[200:203], v[32:35]
	v_mfma_f32_16x16x32_bf16 v[20:23], v[228:231], v[192:195], v[20:23]
	v_mfma_f32_16x16x32_bf16 v[16:19], v[228:231], v[200:203], v[16:19]
	v_mfma_f32_16x16x32_bf16 v[4:7], v[236:239], v[192:195], v[4:7]
	v_mfma_f32_16x16x32_bf16 v[0:3], v[236:239], v[200:203], v[0:3]
	s_setprio 0
	s_barrier
	ds_read_b128 v[142:145], v173
	ds_read_b128 v[176:179], v173 offset:1024
	ds_read_b128 v[180:183], v173 offset:2048
	ds_read_b128 v[184:187], v173 offset:3072
	ds_read_b128 v[188:191], v174
	ds_read_b128 v[192:195], v174 offset:1024
	ds_read_b128 v[196:199], v174 offset:2048
	ds_read_b128 v[200:203], v174 offset:3072
	s_add_u32 s66, s66, 0x40000
	s_addc_u32 s67, s67, 0
	v_readfirstlane_b32 s91, v154
	v_lshl_add_u64 v[244:245], s[66:67], 0, v[128:129]
	s_mov_b32 m0, s91
	ds_read_b128 v[204:207], v167 offset:32768
	ds_read_b128 v[212:215], v167 offset:33792
	ds_read_b128 v[216:219], v168 offset:32768
	ds_read_b128 v[220:223], v168 offset:33792
	ds_read_b128 v[224:227], v169 offset:32768
	ds_read_b128 v[228:231], v169 offset:33792
	ds_read_b128 v[232:235], v170 offset:32768
	ds_read_b128 v[236:239], v170 offset:33792
	global_load_lds_dwordx4 v[244:245], off
	v_lshl_add_u64 v[244:245], s[66:67], 0, v[130:131]
	v_readfirstlane_b32 s66, v155
	s_mov_b32 m0, s66
	s_nop 0
	global_load_lds_dwordx4 v[244:245], off
	s_waitcnt vmcnt(8)
	s_waitcnt lgkmcnt(0)
	s_barrier
	s_setprio 1
	s_waitcnt lgkmcnt(0)
	v_mfma_f32_16x16x32_bf16 v[124:127], v[204:207], v[142:145], v[124:127]
	v_mfma_f32_16x16x32_bf16 v[120:123], v[204:207], v[180:183], v[120:123]
	v_mfma_f32_16x16x32_bf16 v[108:111], v[216:219], v[142:145], v[108:111]
	v_mfma_f32_16x16x32_bf16 v[104:107], v[216:219], v[180:183], v[104:107]
	v_mfma_f32_16x16x32_bf16 v[92:95], v[224:227], v[142:145], v[92:95]
	v_mfma_f32_16x16x32_bf16 v[88:91], v[224:227], v[180:183], v[88:91]
	v_mfma_f32_16x16x32_bf16 v[76:79], v[232:235], v[142:145], v[76:79]
	v_mfma_f32_16x16x32_bf16 v[72:75], v[232:235], v[180:183], v[72:75]
	v_mfma_f32_16x16x32_bf16 v[124:127], v[212:215], v[176:179], v[124:127]
	v_mfma_f32_16x16x32_bf16 v[120:123], v[212:215], v[184:187], v[120:123]
	v_mfma_f32_16x16x32_bf16 v[108:111], v[220:223], v[176:179], v[108:111]
	v_mfma_f32_16x16x32_bf16 v[104:107], v[220:223], v[184:187], v[104:107]
	v_mfma_f32_16x16x32_bf16 v[92:95], v[228:231], v[176:179], v[92:95]
	v_mfma_f32_16x16x32_bf16 v[88:91], v[228:231], v[184:187], v[88:91]
	v_mfma_f32_16x16x32_bf16 v[76:79], v[236:239], v[176:179], v[76:79]
	v_mfma_f32_16x16x32_bf16 v[72:75], v[236:239], v[184:187], v[72:75]
	s_setprio 0
	s_setprio 1
	v_mfma_f32_16x16x32_bf16 v[116:119], v[204:207], v[188:191], v[116:119]
	v_mfma_f32_16x16x32_bf16 v[112:115], v[204:207], v[196:199], v[112:115]
	v_mfma_f32_16x16x32_bf16 v[100:103], v[216:219], v[188:191], v[100:103]
	v_mfma_f32_16x16x32_bf16 v[96:99], v[216:219], v[196:199], v[96:99]
	v_mfma_f32_16x16x32_bf16 v[84:87], v[224:227], v[188:191], v[84:87]
	v_mfma_f32_16x16x32_bf16 v[80:83], v[224:227], v[196:199], v[80:83]
	v_mfma_f32_16x16x32_bf16 v[68:71], v[232:235], v[188:191], v[68:71]
	v_mfma_f32_16x16x32_bf16 v[64:67], v[232:235], v[196:199], v[64:67]
	v_mfma_f32_16x16x32_bf16 v[116:119], v[212:215], v[192:195], v[116:119]
	v_mfma_f32_16x16x32_bf16 v[112:115], v[212:215], v[200:203], v[112:115]
	v_mfma_f32_16x16x32_bf16 v[100:103], v[220:223], v[192:195], v[100:103]
	v_mfma_f32_16x16x32_bf16 v[96:99], v[220:223], v[200:203], v[96:99]
	v_mfma_f32_16x16x32_bf16 v[84:87], v[228:231], v[192:195], v[84:87]
	v_mfma_f32_16x16x32_bf16 v[80:83], v[228:231], v[200:203], v[80:83]
	v_mfma_f32_16x16x32_bf16 v[68:71], v[236:239], v[192:195], v[68:71]
	v_mfma_f32_16x16x32_bf16 v[64:67], v[236:239], v[200:203], v[64:67]
	s_setprio 0
	s_barrier
; #define STAGE(P, g) do { const char* g_ = (const char*)(g); \
;         __builtin_amdgcn_global_load_lds((const unsigned*)(g_ + so0), (lds_u32*)((lds_u8*)(P) + sb0), 16, 0, 0); \
;         __builtin_amdgcn_global_load_lds((const unsigned*)(g_ + so1), (lds_u32*)((lds_u8*)(P) + sb0 + 8192), 16, 0, 0); } while (0)
; #define LDA(dst, b, h) for (int m = 0; m < 4; ++m) for (int k = 0; k < 2; ++k) \
;         dst[m][k] = *reinterpret_cast<const bf16x8*>((char*)SA(b, h) + lds_byte(wr * 64 + m * 16 + fr, k * 32 + fq * 8))
; #define LDB(dst, b, h) for (int n = 0; n < 2; ++n) for (int k = 0; k < 2; ++k) \
;         dst[n][k] = *reinterpret_cast<const bf16x8*>((char*)SB(b, h) + lds_byte(wc * 32 + n * 16 + fr, k * 32 + fq * 8))
; #define MMA(ai, bj, At_, Bt_) do { __builtin_amdgcn_s_setprio(1); \
;         for (int m = 0; m < 4; ++m) for (int n = 0; n < 2; ++n) for (int k = 0; k < 2; ++k) \
;             acc[ai][bj][m][n] = __builtin_amdgcn_mfma_f32_16x16x32_bf16(At_[m][k], Bt_[n][k], acc[ai][bj][m][n], 0, 0, 0); \
;         __builtin_amdgcn_s_setprio(0); } while (0)
; #define WAIT_V(n) asm volatile("s_waitcnt vmcnt(" #n ")" ::: "memory")
; #define WAIT_L(n) asm volatile("s_waitcnt lgkmcnt(" #n ")" ::: "memory")
; #define BAR __builtin_amdgcn_s_barrier()
; #define SCHED __builtin_amdgcn_sched_barrier(0)
; template <int EPI, int K, int LNI = -1>
; DI void ph_gemm(const Params& p, const bf16_t* __restrict__ A, const bf16_t* __restrict__ Bt, int N, float* s_aux) {
;     ...
;         for (int t = 0; t < nt; t += 2) {
;             const bool last = (t == nt - 2);
;             const bf16_t* a1 = cA + (size_t)(t + 1) * kstep;
;             const bf16_t* a2 = last ? nA : cA + (size_t)(t + 2) * kstep; const bf16_t* b2 = last ? nB : cB + (size_t)(t + 2) * kstep;
;             const bf16_t* a3 = a2 + kstep; const bf16_t* b3 = b2 + kstep;
;             LDB(B0, 0, 0); LDB(B1, 0, 1); SCHED; LDA(At, 0, 0); STAGE(SA(1, 1), a1 + hstep);
;             WAIT_V(8); WAIT_L(0); BAR; MMA(0, 0, At, B0); MMA(0, 1, At, B1); BAR; SCHED;
;     ...
;             LDA(At, 1, 1); STAGE(SB(1, 0), b3); STAGE(SB(1, 1), b3 + hstep); STAGE(SA(1, 0), a3);
;             WAIT_V(8); WAIT_L(0); BAR; MMA(1, 0, At, B0); MMA(1, 1, At, B1); BAR; SCHED;
	v_readfirstlane_b32 s66, v156
	v_lshl_add_u64 v[146:147], v[146:147], 0, s[28:29]
	s_mov_b32 m0, s66
	v_readfirstlane_b32 s66, v157
	s_add_u32 s14, s14, 0x40080
	ds_read_b128 v[204:207], v167 offset:49152
	ds_read_b128 v[212:215], v167 offset:50176
	ds_read_b128 v[216:219], v168 offset:49152
	ds_read_b128 v[220:223], v168 offset:50176
	ds_read_b128 v[224:227], v169 offset:49152
	ds_read_b128 v[228:231], v169 offset:50176
	ds_read_b128 v[232:235], v170 offset:49152
	ds_read_b128 v[236:239], v170 offset:50176
	global_load_lds_dwordx4 v[146:147], off
	v_lshl_add_u64 v[146:147], v[208:209], 0, s[28:29]
	s_mov_b32 m0, s66
	s_addc_u32 s15, s15, 0
	v_readfirstlane_b32 s66, v160
	global_load_lds_dwordx4 v[146:147], off
	v_lshl_add_u64 v[146:147], s[14:15], 0, v[128:129]
	s_mov_b32 m0, s66
	s_nop 0
	global_load_lds_dwordx4 v[146:147], off
	v_lshl_add_u64 v[146:147], s[14:15], 0, v[130:131]
	v_readfirstlane_b32 s14, v161
	s_mov_b32 m0, s14
	v_readfirstlane_b32 s14, v158
	global_load_lds_dwordx4 v[146:147], off
	v_lshl_add_u64 v[146:147], v[240:241], 0, s[28:29]
	s_mov_b32 m0, s14
	v_readfirstlane_b32 s14, v159
	global_load_lds_dwordx4 v[146:147], off
	v_lshl_add_u64 v[146:147], v[242:243], 0, s[28:29]
	s_mov_b32 m0, s14
	s_nop 0
	global_load_lds_dwordx4 v[146:147], off
	s_waitcnt vmcnt(8)
	s_waitcnt lgkmcnt(0)
	s_barrier
	s_setprio 1
	s_waitcnt lgkmcnt(0)
	v_mfma_f32_16x16x32_bf16 v[60:63], v[204:207], v[142:145], v[60:63]
	v_mfma_f32_16x16x32_bf16 v[56:59], v[204:207], v[180:183], v[56:59]
	v_mfma_f32_16x16x32_bf16 v[44:47], v[216:219], v[142:145], v[44:47]
	v_mfma_f32_16x16x32_bf16 v[40:43], v[216:219], v[180:183], v[40:43]
	v_mfma_f32_16x16x32_bf16 v[28:31], v[224:227], v[142:145], v[28:31]
	v_mfma_f32_16x16x32_bf16 v[24:27], v[224:227], v[180:183], v[24:27]
	v_mfma_f32_16x16x32_bf16 v[12:15], v[232:235], v[142:145], v[12:15]
	v_mfma_f32_16x16x32_bf16 v[8:11], v[232:235], v[180:183], v[8:11]
	v_mfma_f32_16x16x32_bf16 v[60:63], v[212:215], v[176:179], v[60:63]
	v_mfma_f32_16x16x32_bf16 v[56:59], v[212:215], v[184:187], v[56:59]
	v_mfma_f32_16x16x32_bf16 v[44:47], v[220:223], v[176:179], v[44:47]
	v_mfma_f32_16x16x32_bf16 v[40:43], v[220:223], v[184:187], v[40:43]
	v_mfma_f32_16x16x32_bf16 v[28:31], v[228:231], v[176:179], v[28:31]
	v_mfma_f32_16x16x32_bf16 v[24:27], v[228:231], v[184:187], v[24:27]
	v_mfma_f32_16x16x32_bf16 v[12:15], v[236:239], v[176:179], v[12:15]
	v_mfma_f32_16x16x32_bf16 v[8:11], v[236:239], v[184:187], v[8:11]
	s_setprio 0
	s_setprio 1
	v_mfma_f32_16x16x32_bf16 v[52:55], v[204:207], v[188:191], v[52:55]
	v_mfma_f32_16x16x32_bf16 v[48:51], v[204:207], v[196:199], v[48:51]
	v_mfma_f32_16x16x32_bf16 v[36:39], v[216:219], v[188:191], v[36:39]
	v_mfma_f32_16x16x32_bf16 v[32:35], v[216:219], v[196:199], v[32:35]
	v_mfma_f32_16x16x32_bf16 v[20:23], v[224:227], v[188:191], v[20:23]
	v_mfma_f32_16x16x32_bf16 v[16:19], v[224:227], v[196:199], v[16:19]
	v_mfma_f32_16x16x32_bf16 v[4:7], v[232:235], v[188:191], v[4:7]
	v_mfma_f32_16x16x32_bf16 v[0:3], v[232:235], v[196:199], v[0:3]
	v_mfma_f32_16x16x32_bf16 v[52:55], v[212:215], v[192:195], v[52:55]
	v_mfma_f32_16x16x32_bf16 v[48:51], v[212:215], v[200:203], v[48:51]
	v_mfma_f32_16x16x32_bf16 v[36:39], v[220:223], v[192:195], v[36:39]
	v_mfma_f32_16x16x32_bf16 v[32:35], v[220:223], v[200:203], v[32:35]
	v_mfma_f32_16x16x32_bf16 v[20:23], v[228:231], v[192:195], v[20:23]
	v_mfma_f32_16x16x32_bf16 v[16:19], v[228:231], v[200:203], v[16:19]
	v_mfma_f32_16x16x32_bf16 v[4:7], v[236:239], v[192:195], v[4:7]
	v_mfma_f32_16x16x32_bf16 v[0:3], v[236:239], v[200:203], v[0:3]
	s_setprio 0
	s_add_i32 s80, s80, 2
	s_add_u32 s12, s12, 0x100
	s_addc_u32 s13, s13, 0
	s_cmp_gt_u32 s80, 13
	s_barrier
.LBB0_1144:
	ds_read_b128 v[142:145], v165
	ds_read_b128 v[176:179], v165 offset:1024
	ds_read_b128 v[180:183], v165 offset:2048
	ds_read_b128 v[184:187], v165 offset:3072
	ds_read_b128 v[188:191], v166
	ds_read_b128 v[192:195], v166 offset:1024
	ds_read_b128 v[196:199], v166 offset:2048
	ds_read_b128 v[200:203], v166 offset:3072
	s_add_u32 s14, s49, s12
	s_addc_u32 s15, s51, s13
	s_add_u32 s14, s14, 0xb840100
	s_addc_u32 s15, s15, 0
	s_add_u32 s91, s68, s12
	s_addc_u32 s92, s69, s13
	s_cmpk_eq_i32 s12, 0x700
	s_cselect_b32 s67, s11, s15
	s_cselect_b32 s66, s9, s14
	s_cselect_b32 s15, s43, s92
	s_cselect_b32 s14, s42, s91
	v_readfirstlane_b32 s91, v171
	v_lshl_add_u64 v[146:147], v[138:139], 0, s[12:13]
	s_mov_b32 m0, s91
	v_readfirstlane_b32 s91, v172
	ds_read_b128 v[204:207], v167
	ds_read_b128 v[212:215], v167 offset:1024
	ds_read_b128 v[216:219], v168
	ds_read_b128 v[220:223], v168 offset:1024
	ds_read_b128 v[224:227], v169
	ds_read_b128 v[228:231], v169 offset:1024
	ds_read_b128 v[232:235], v170
	ds_read_b128 v[236:239], v170 offset:1024
	global_load_lds_dwordx4 v[146:147], off
	v_lshl_add_u64 v[146:147], v[140:141], 0, s[12:13]
	s_mov_b32 m0, s91
	s_nop 0
	global_load_lds_dwordx4 v[146:147], off
	s_waitcnt vmcnt(8)
	s_waitcnt lgkmcnt(0)
	s_barrier
; #define STAGE(P, g) do { const char* g_ = (const char*)(g); \
;         __builtin_amdgcn_global_load_lds((const unsigned*)(g_ + so0), (lds_u32*)((lds_u8*)(P) + sb0), 16, 0, 0); \
;         __builtin_amdgcn_global_load_lds((const unsigned*)(g_ + so1), (lds_u32*)((lds_u8*)(P) + sb0 + 8192), 16, 0, 0); } while (0)
; #define LDA(dst, b, h) for (int m = 0; m < 4; ++m) for (int k = 0; k < 2; ++k) \
;         dst[m][k] = *reinterpret_cast<const bf16x8*>((char*)SA(b, h) + lds_byte(wr * 64 + m * 16 + fr, k * 32 + fq * 8))
; #define LDB(dst, b, h) for (int n = 0; n < 2; ++n) for (int k = 0; k < 2; ++k) \
;         dst[n][k] = *reinterpret_cast<const bf16x8*>((char*)SB(b, h) + lds_byte(wc * 32 + n * 16 + fr, k * 32 + fq * 8))
; #define MMA(ai, bj, At_, Bt_) do { __builtin_amdgcn_s_setprio(1); \
;         for (int m = 0; m < 4; ++m) for (int n = 0; n < 2; ++n) for (int k = 0; k < 2; ++k) \
;             acc[ai][bj][m][n] = __builtin_amdgcn_mfma_f32_16x16x32_bf16(At_[m][k], Bt_[n][k], acc[ai][bj][m][n], 0, 0, 0); \
;         __builtin_amdgcn_s_setprio(0); } while (0)
; #define WAIT_V(n) asm volatile("s_waitcnt vmcnt(" #n ")" ::: "memory")
; #define WAIT_L(n) asm volatile("s_waitcnt lgkmcnt(" #n ")" ::: "memory")
; #define BAR __builtin_amdgcn_s_barrier()
; #define SCHED __builtin_amdgcn_sched_barrier(0)
; template <int EPI, int K, int LNI = -1>
; DI void ph_gemm(const Params& p, const bf16_t* __restrict__ A, const bf16_t* __restrict__ Bt, int N, float* s_aux) {
;     ...
;             WAIT_V(8); WAIT_L(0); BAR; MMA(0, 0, At, B0); MMA(0, 1, At, B1); BAR; SCHED;
;             LDA(At, 0, 1); STAGE(SB(0, 0), b2); STAGE(SB(0, 1), b2 + hstep); STAGE(SA(0, 0), a2);
;             WAIT_V(8); WAIT_L(0); BAR; MMA(1, 0, At, B0); MMA(1, 1, At, B1); BAR; SCHED;
;             LDB(B0, 1, 0); LDB(B1, 1, 1); SCHED; LDA(At, 1, 0); STAGE(SA(0, 1), a2 + hstep);
;             WAIT_V(8); WAIT_L(0); BAR; MMA(0, 0, At, B0); MMA(0, 1, At, B1); BAR; SCHED;
	s_setprio 1
	s_waitcnt lgkmcnt(0)
	v_mfma_f32_16x16x32_bf16 v[124:127], v[204:207], v[142:145], v[124:127]
	v_mfma_f32_16x16x32_bf16 v[120:123], v[204:207], v[180:183], v[120:123]
	v_mfma_f32_16x16x32_bf16 v[108:111], v[216:219], v[142:145], v[108:111]
	v_mfma_f32_16x16x32_bf16 v[104:107], v[216:219], v[180:183], v[104:107]
	v_mfma_f32_16x16x32_bf16 v[92:95], v[224:227], v[142:145], v[92:95]
	v_mfma_f32_16x16x32_bf16 v[88:91], v[224:227], v[180:183], v[88:91]
	v_mfma_f32_16x16x32_bf16 v[76:79], v[232:235], v[142:145], v[76:79]
	v_mfma_f32_16x16x32_bf16 v[72:75], v[232:235], v[180:183], v[72:75]
	v_mfma_f32_16x16x32_bf16 v[124:127], v[212:215], v[176:179], v[124:127]
	v_mfma_f32_16x16x32_bf16 v[120:123], v[212:215], v[184:187], v[120:123]
	v_mfma_f32_16x16x32_bf16 v[108:111], v[220:223], v[176:179], v[108:111]
	v_mfma_f32_16x16x32_bf16 v[104:107], v[220:223], v[184:187], v[104:107]
	v_mfma_f32_16x16x32_bf16 v[92:95], v[228:231], v[176:179], v[92:95]
	v_mfma_f32_16x16x32_bf16 v[88:91], v[228:231], v[184:187], v[88:91]
	v_mfma_f32_16x16x32_bf16 v[76:79], v[236:239], v[176:179], v[76:79]
	v_mfma_f32_16x16x32_bf16 v[72:75], v[236:239], v[184:187], v[72:75]
	s_setprio 0
	s_setprio 1
	v_mfma_f32_16x16x32_bf16 v[116:119], v[204:207], v[188:191], v[116:119]
	v_mfma_f32_16x16x32_bf16 v[112:115], v[204:207], v[196:199], v[112:115]
	v_mfma_f32_16x16x32_bf16 v[100:103], v[216:219], v[188:191], v[100:103]
	v_mfma_f32_16x16x32_bf16 v[96:99], v[216:219], v[196:199], v[96:99]
	v_mfma_f32_16x16x32_bf16 v[84:87], v[224:227], v[188:191], v[84:87]
	v_mfma_f32_16x16x32_bf16 v[80:83], v[224:227], v[196:199], v[80:83]
	v_mfma_f32_16x16x32_bf16 v[68:71], v[232:235], v[188:191], v[68:71]
	v_mfma_f32_16x16x32_bf16 v[64:67], v[232:235], v[196:199], v[64:67]
	v_mfma_f32_16x16x32_bf16 v[116:119], v[212:215], v[192:195], v[116:119]
	v_mfma_f32_16x16x32_bf16 v[112:115], v[212:215], v[200:203], v[112:115]
	v_mfma_f32_16x16x32_bf16 v[100:103], v[220:223], v[192:195], v[100:103]
	v_mfma_f32_16x16x32_bf16 v[96:99], v[220:223], v[200:203], v[96:99]
	v_mfma_f32_16x16x32_bf16 v[84:87], v[228:231], v[192:195], v[84:87]
	v_mfma_f32_16x16x32_bf16 v[80:83], v[228:231], v[200:203], v[80:83]
	v_mfma_f32_16x16x32_bf16 v[68:71], v[236:239], v[192:195], v[68:71]
	v_mfma_f32_16x16x32_bf16 v[64:67], v[236:239], v[200:203], v[64:67]
	s_setprio 0
	s_barrier
	v_readfirstlane_b32 s91, v148
	v_lshl_add_u64 v[146:147], s[14:15], 0, v[128:129]
	s_mov_b32 m0, s91
	v_readfirstlane_b32 s91, v149
	s_add_u32 s92, s14, 0x40000
	ds_read_b128 v[204:207], v167 offset:16384
	ds_read_b128 v[212:215], v167 offset:17408
	ds_read_b128 v[216:219], v168 offset:16384
	ds_read_b128 v[220:223], v168 offset:17408
	ds_read_b128 v[224:227], v169 offset:16384
	ds_read_b128 v[228:231], v169 offset:17408
	ds_read_b128 v[232:235], v170 offset:16384
	ds_read_b128 v[236:239], v170 offset:17408
	global_load_lds_dwordx4 v[146:147], off
	v_lshl_add_u64 v[208:209], s[14:15], 0, v[130:131]
	s_mov_b32 m0, s91
	s_addc_u32 s93, s15, 0
	v_readfirstlane_b32 s91, v150
	global_load_lds_dwordx4 v[208:209], off
	v_lshl_add_u64 v[240:241], s[92:93], 0, v[128:129]
	s_mov_b32 m0, s91
	v_readfirstlane_b32 s91, v151
	global_load_lds_dwordx4 v[240:241], off
	v_lshl_add_u64 v[240:241], s[92:93], 0, v[130:131]
	s_mov_b32 m0, s91
	v_readfirstlane_b32 s91, v152
	global_load_lds_dwordx4 v[240:241], off
	v_lshl_add_u64 v[240:241], s[66:67], 0, v[128:129]
	s_mov_b32 m0, s91
	v_readfirstlane_b32 s91, v153
	global_load_lds_dwordx4 v[240:241], off
	v_lshl_add_u64 v[242:243], s[66:67], 0, v[130:131]
	s_mov_b32 m0, s91
	s_nop 0
	global_load_lds_dwordx4 v[242:243], off
	s_waitcnt vmcnt(8)
	s_waitcnt lgkmcnt(0)
	s_barrier
	s_setprio 1
	s_waitcnt lgkmcnt(0)
	v_mfma_f32_16x16x32_bf16 v[60:63], v[204:207], v[142:145], v[60:63]
	v_mfma_f32_16x16x32_bf16 v[56:59], v[204:207], v[180:183], v[56:59]
	v_mfma_f32_16x16x32_bf16 v[44:47], v[216:219], v[142:145], v[44:47]
	v_mfma_f32_16x16x32_bf16 v[40:43], v[216:219], v[180:183], v[40:43]
	v_mfma_f32_16x16x32_bf16 v[28:31], v[224:227], v[142:145], v[28:31]
	v_mfma_f32_16x16x32_bf16 v[24:27], v[224:227], v[180:183], v[24:27]
	v_mfma_f32_16x16x32_bf16 v[12:15], v[232:235], v[142:145], v[12:15]
	v_mfma_f32_16x16x32_bf16 v[8:11], v[232:235], v[180:183], v[8:11]
	v_mfma_f32_16x16x32_bf16 v[60:63], v[212:215], v[176:179], v[60:63]
	v_mfma_f32_16x16x32_bf16 v[56:59], v[212:215], v[184:187], v[56:59]
	v_mfma_f32_16x16x32_bf16 v[44:47], v[220:223], v[176:179], v[44:47]
	v_mfma_f32_16x16x32_bf16 v[40:43], v[220:223], v[184:187], v[40:43]
	v_mfma_f32_16x16x32_bf16 v[28:31], v[228:231], v[176:179], v[28:31]
	v_mfma_f32_16x16x32_bf16 v[24:27], v[228:231], v[184:187], v[24:27]
	v_mfma_f32_16x16x32_bf16 v[12:15], v[236:239], v[176:179], v[12:15]
	v_mfma_f32_16x16x32_bf16 v[8:11], v[236:239], v[184:187], v[8:11]
	s_setprio 0
	s_setprio 1
	v_mfma_f32_16x16x32_bf16 v[52:55], v[204:207], v[188:191], v[52:55]
	v_mfma_f32_16x16x32_bf16 v[48:51], v[204:207], v[196:199], v[48:51]
	v_mfma_f32_16x16x32_bf16 v[36:39], v[216:219], v[188:191], v[36:39]
	v_mfma_f32_16x16x32_bf16 v[32:35], v[216:219], v[196:199], v[32:35]
	v_mfma_f32_16x16x32_bf16 v[20:23], v[224:227], v[188:191], v[20:23]
	v_mfma_f32_16x16x32_bf16 v[16:19], v[224:227], v[196:199], v[16:19]
	v_mfma_f32_16x16x32_bf16 v[4:7], v[232:235], v[188:191], v[4:7]
	v_mfma_f32_16x16x32_bf16 v[0:3], v[232:235], v[196:199], v[0:3]
	v_mfma_f32_16x16x32_bf16 v[52:55], v[212:215], v[192:195], v[52:55]
	v_mfma_f32_16x16x32_bf16 v[48:51], v[212:215], v[200:203], v[48:51]
	v_mfma_f32_16x16x32_bf16 v[36:39], v[220:223], v[192:195], v[36:39]
	v_mfma_f32_16x16x32_bf16 v[32:35], v[220:223], v[200:203], v[32:35]
	v_mfma_f32_16x16x32_bf16 v[20:23], v[228:231], v[192:195], v[20:23]
	v_mfma_f32_16x16x32_bf16 v[16:19], v[228:231], v[200:203], v[16:19]
	v_mfma_f32_16x16x32_bf16 v[4:7], v[236:239], v[192:195], v[4:7]
	v_mfma_f32_16x16x32_bf16 v[0:3], v[236:239], v[200:203], v[0:3]
	s_setprio 0
	s_barrier
; #define STAGE(P, g) do { const char* g_ = (const char*)(g); \
;         __builtin_amdgcn_global_load_lds((const unsigned*)(g_ + so0), (lds_u32*)((lds_u8*)(P) + sb0), 16, 0, 0); \
;         __builtin_amdgcn_global_load_lds((const unsigned*)(g_ + so1), (lds_u32*)((lds_u8*)(P) + sb0 + 8192), 16, 0, 0); } while (0)
; #define LDA(dst, b, h) for (int m = 0; m < 4; ++m) for (int k = 0; k < 2; ++k) \
;         dst[m][k] = *reinterpret_cast<const bf16x8*>((char*)SA(b, h) + lds_byte(wr * 64 + m * 16 + fr, k * 32 + fq * 8))
; #define LDB(dst, b, h) for (int n = 0; n < 2; ++n) for (int k = 0; k < 2; ++k) \
;         dst[n][k] = *reinterpret_cast<const bf16x8*>((char*)SB(b, h) + lds_byte(wc * 32 + n * 16 + fr, k * 32 + fq * 8))
; #define MMA(ai, bj, At_, Bt_) do { __builtin_amdgcn_s_setprio(1); \
;         for (int m = 0; m < 4; ++m) for (int n = 0; n < 2; ++n) for (int k = 0; k < 2; ++k) \
;             acc[ai][bj][m][n] = __builtin_amdgcn_mfma_f32_16x16x32_bf16(At_[m][k], Bt_[n][k], acc[ai][bj][m][n], 0, 0, 0); \
;         __builtin_amdgcn_s_setprio(0); } while (0)
; #define WAIT_V(n) asm volatile("s_waitcnt vmcnt(" #n ")" ::: "memory")
; #define WAIT_L(n) asm volatile("s_waitcnt lgkmcnt(" #n ")" ::: "memory")
; #define BAR __builtin_amdgcn_s_barrier()
; #define SCHED __builtin_amdgcn_sched_barrier(0)
; template <int EPI, int K, int LNI = -1>
; DI void ph_gemm(const Params& p, const bf16_t* __restrict__ A, const bf16_t* __restrict__ Bt, int N, float* s_aux) {
;     ...
;             LDB(B0, 1, 0); LDB(B1, 1, 1); SCHED; LDA(At, 1, 0); STAGE(SA(0, 1), a2 + hstep);
;             WAIT_V(8); WAIT_L(0); BAR; MMA(0, 0, At, B0); MMA(0, 1, At, B1); BAR; SCHED;
	ds_read_b128 v[142:145], v173
	ds_read_b128 v[176:179], v173 offset:1024
	ds_read_b128 v[180:183], v173 offset:2048
	ds_read_b128 v[184:187], v173 offset:3072
	ds_read_b128 v[188:191], v174
	ds_read_b128 v[192:195], v174 offset:1024
	ds_read_b128 v[196:199], v174 offset:2048
	ds_read_b128 v[200:203], v174 offset:3072
	s_add_u32 s66, s66, 0x40000
	s_addc_u32 s67, s67, 0
	v_readfirstlane_b32 s91, v154
	v_lshl_add_u64 v[244:245], s[66:67], 0, v[128:129]
	s_mov_b32 m0, s91
	ds_read_b128 v[204:207], v167 offset:32768
	ds_read_b128 v[212:215], v167 offset:33792
	ds_read_b128 v[216:219], v168 offset:32768
	ds_read_b128 v[220:223], v168 offset:33792
	ds_read_b128 v[224:227], v169 offset:32768
	ds_read_b128 v[228:231], v169 offset:33792
	ds_read_b128 v[232:235], v170 offset:32768
	ds_read_b128 v[236:239], v170 offset:33792
	global_load_lds_dwordx4 v[244:245], off
	v_lshl_add_u64 v[244:245], s[66:67], 0, v[130:131]
	v_readfirstlane_b32 s66, v155
	s_mov_b32 m0, s66
	s_nop 0
	global_load_lds_dwordx4 v[244:245], off
	s_waitcnt vmcnt(8)
	s_waitcnt lgkmcnt(0)
	s_barrier
	s_setprio 1
	s_waitcnt lgkmcnt(0)
	v_mfma_f32_16x16x32_bf16 v[124:127], v[204:207], v[142:145], v[124:127]
	v_mfma_f32_16x16x32_bf16 v[120:123], v[204:207], v[180:183], v[120:123]
	v_mfma_f32_16x16x32_bf16 v[108:111], v[216:219], v[142:145], v[108:111]
	v_mfma_f32_16x16x32_bf16 v[104:107], v[216:219], v[180:183], v[104:107]
	v_mfma_f32_16x16x32_bf16 v[92:95], v[224:227], v[142:145], v[92:95]
	v_mfma_f32_16x16x32_bf16 v[88:91], v[224:227], v[180:183], v[88:91]
	v_mfma_f32_16x16x32_bf16 v[76:79], v[232:235], v[142:145], v[76:79]
	v_mfma_f32_16x16x32_bf16 v[72:75], v[232:235], v[180:183], v[72:75]
	v_mfma_f32_16x16x32_bf16 v[124:127], v[212:215], v[176:179], v[124:127]
	v_mfma_f32_16x16x32_bf16 v[120:123], v[212:215], v[184:187], v[120:123]
	v_mfma_f32_16x16x32_bf16 v[108:111], v[220:223], v[176:179], v[108:111]
	v_mfma_f32_16x16x32_bf16 v[104:107], v[220:223], v[184:187], v[104:107]
	v_mfma_f32_16x16x32_bf16 v[92:95], v[228:231], v[176:179], v[92:95]
	v_mfma_f32_16x16x32_bf16 v[88:91], v[228:231], v[184:187], v[88:91]
	v_mfma_f32_16x16x32_bf16 v[76:79], v[236:239], v[176:179], v[76:79]
	v_mfma_f32_16x16x32_bf16 v[72:75], v[236:239], v[184:187], v[72:75]
	s_setprio 0
	s_setprio 1
	v_mfma_f32_16x16x32_bf16 v[116:119], v[204:207], v[188:191], v[116:119]
	v_mfma_f32_16x16x32_bf16 v[112:115], v[204:207], v[196:199], v[112:115]
	v_mfma_f32_16x16x32_bf16 v[100:103], v[216:219], v[188:191], v[100:103]
	v_mfma_f32_16x16x32_bf16 v[96:99], v[216:219], v[196:199], v[96:99]
	v_mfma_f32_16x16x32_bf16 v[84:87], v[224:227], v[188:191], v[84:87]
	v_mfma_f32_16x16x32_bf16 v[80:83], v[224:227], v[196:199], v[80:83]
	v_mfma_f32_16x16x32_bf16 v[68:71], v[232:235], v[188:191], v[68:71]
	v_mfma_f32_16x16x32_bf16 v[64:67], v[232:235], v[196:199], v[64:67]
	v_mfma_f32_16x16x32_bf16 v[116:119], v[212:215], v[192:195], v[116:119]
	v_mfma_f32_16x16x32_bf16 v[112:115], v[212:215], v[200:203], v[112:115]
	v_mfma_f32_16x16x32_bf16 v[100:103], v[220:223], v[192:195], v[100:103]
	v_mfma_f32_16x16x32_bf16 v[96:99], v[220:223], v[200:203], v[96:99]
	v_mfma_f32_16x16x32_bf16 v[84:87], v[228:231], v[192:195], v[84:87]
	v_mfma_f32_16x16x32_bf16 v[80:83], v[228:231], v[200:203], v[80:83]
	v_mfma_f32_16x16x32_bf16 v[68:71], v[236:239], v[192:195], v[68:71]
	v_mfma_f32_16x16x32_bf16 v[64:67], v[236:239], v[200:203], v[64:67]
	s_setprio 0
	s_barrier
; #define STAGE(P, g) do { const char* g_ = (const char*)(g); \
;         __builtin_amdgcn_global_load_lds((const unsigned*)(g_ + so0), (lds_u32*)((lds_u8*)(P) + sb0), 16, 0, 0); \
;         __builtin_amdgcn_global_load_lds((const unsigned*)(g_ + so1), (lds_u32*)((lds_u8*)(P) + sb0 + 8192), 16, 0, 0); } while (0)
; #define LDA(dst, b, h) for (int m = 0; m < 4; ++m) for (int k = 0; k < 2; ++k) \
;         dst[m][k] = *reinterpret_cast<const bf16x8*>((char*)SA(b, h) + lds_byte(wr * 64 + m * 16 + fr, k * 32 + fq * 8))
; #define MMA(ai, bj, At_, Bt_) do { __builtin_amdgcn_s_setprio(1); \
;         for (int m = 0; m < 4; ++m) for (int n = 0; n < 2; ++n) for (int k = 0; k < 2; ++k) \
;             acc[ai][bj][m][n] = __builtin_amdgcn_mfma_f32_16x16x32_bf16(At_[m][k], Bt_[n][k], acc[ai][bj][m][n], 0, 0, 0); \
;         __builtin_amdgcn_s_setprio(0); } while (0)
; #define WAIT_V(n) asm volatile("s_waitcnt vmcnt(" #n ")" ::: "memory")
; #define WAIT_L(n) asm volatile("s_waitcnt lgkmcnt(" #n ")" ::: "memory")
; #define BAR __builtin_amdgcn_s_barrier()
; #define SCHED __builtin_amdgcn_sched_barrier(0)
; template <int EPI, int K, int LNI = -1>
; DI void ph_gemm(const Params& p, const bf16_t* __restrict__ A, const bf16_t* __restrict__ Bt, int N, float* s_aux) {
;     ...
;             LDA(At, 1, 1); STAGE(SB(1, 0), b3); STAGE(SB(1, 1), b3 + hstep); STAGE(SA(1, 0), a3);
;             WAIT_V(8); WAIT_L(0); BAR; MMA(1, 0, At, B0); MMA(1, 1, At, B1); BAR; SCHED;
;         }
;         if (wr == 0) BAR;
	v_readfirstlane_b32 s66, v156
	v_lshl_add_u64 v[146:147], v[146:147], 0, s[28:29]
	s_mov_b32 m0, s66
	v_readfirstlane_b32 s66, v157
	s_add_u32 s14, s14, 0x40080
	ds_read_b128 v[204:207], v167 offset:49152
	ds_read_b128 v[212:215], v167 offset:50176
	ds_read_b128 v[216:219], v168 offset:49152
	ds_read_b128 v[220:223], v168 offset:50176
	ds_read_b128 v[224:227], v169 offset:49152
	ds_read_b128 v[228:231], v169 offset:50176
	ds_read_b128 v[232:235], v170 offset:49152
	ds_read_b128 v[236:239], v170 offset:50176
	global_load_lds_dwordx4 v[146:147], off
	v_lshl_add_u64 v[146:147], v[208:209], 0, s[28:29]
	s_mov_b32 m0, s66
	s_addc_u32 s15, s15, 0
	v_readfirstlane_b32 s66, v160
	global_load_lds_dwordx4 v[146:147], off
	v_lshl_add_u64 v[146:147], s[14:15], 0, v[128:129]
	s_mov_b32 m0, s66
	s_nop 0
	global_load_lds_dwordx4 v[146:147], off
	v_lshl_add_u64 v[146:147], s[14:15], 0, v[130:131]
	v_readfirstlane_b32 s14, v161
	s_mov_b32 m0, s14
	v_readfirstlane_b32 s14, v158
	global_load_lds_dwordx4 v[146:147], off
	v_lshl_add_u64 v[146:147], v[240:241], 0, s[28:29]
	s_mov_b32 m0, s14
	v_readfirstlane_b32 s14, v159
	global_load_lds_dwordx4 v[146:147], off
	v_lshl_add_u64 v[146:147], v[242:243], 0, s[28:29]
	s_mov_b32 m0, s14
	s_nop 0
	global_load_lds_dwordx4 v[146:147], off
	s_waitcnt vmcnt(8)
	s_waitcnt lgkmcnt(0)
	s_barrier
	s_setprio 1
	s_waitcnt lgkmcnt(0)
	v_mfma_f32_16x16x32_bf16 v[60:63], v[204:207], v[142:145], v[60:63]
	v_mfma_f32_16x16x32_bf16 v[56:59], v[204:207], v[180:183], v[56:59]
	v_mfma_f32_16x16x32_bf16 v[44:47], v[216:219], v[142:145], v[44:47]
	v_mfma_f32_16x16x32_bf16 v[40:43], v[216:219], v[180:183], v[40:43]
	v_mfma_f32_16x16x32_bf16 v[28:31], v[224:227], v[142:145], v[28:31]
	v_mfma_f32_16x16x32_bf16 v[24:27], v[224:227], v[180:183], v[24:27]
	v_mfma_f32_16x16x32_bf16 v[12:15], v[232:235], v[142:145], v[12:15]
	v_mfma_f32_16x16x32_bf16 v[8:11], v[232:235], v[180:183], v[8:11]
	v_mfma_f32_16x16x32_bf16 v[60:63], v[212:215], v[176:179], v[60:63]
	v_mfma_f32_16x16x32_bf16 v[56:59], v[212:215], v[184:187], v[56:59]
	v_mfma_f32_16x16x32_bf16 v[44:47], v[220:223], v[176:179], v[44:47]
	v_mfma_f32_16x16x32_bf16 v[40:43], v[220:223], v[184:187], v[40:43]
	v_mfma_f32_16x16x32_bf16 v[28:31], v[228:231], v[176:179], v[28:31]
	v_mfma_f32_16x16x32_bf16 v[24:27], v[228:231], v[184:187], v[24:27]
	v_mfma_f32_16x16x32_bf16 v[12:15], v[236:239], v[176:179], v[12:15]
	v_mfma_f32_16x16x32_bf16 v[8:11], v[236:239], v[184:187], v[8:11]
	s_setprio 0
	s_setprio 1
	v_mfma_f32_16x16x32_bf16 v[52:55], v[204:207], v[188:191], v[52:55]
	v_mfma_f32_16x16x32_bf16 v[48:51], v[204:207], v[196:199], v[48:51]
	v_mfma_f32_16x16x32_bf16 v[36:39], v[216:219], v[188:191], v[36:39]
	v_mfma_f32_16x16x32_bf16 v[32:35], v[216:219], v[196:199], v[32:35]
	v_mfma_f32_16x16x32_bf16 v[20:23], v[224:227], v[188:191], v[20:23]
	v_mfma_f32_16x16x32_bf16 v[16:19], v[224:227], v[196:199], v[16:19]
	v_mfma_f32_16x16x32_bf16 v[4:7], v[232:235], v[188:191], v[4:7]
	v_mfma_f32_16x16x32_bf16 v[0:3], v[232:235], v[196:199], v[0:3]
	v_mfma_f32_16x16x32_bf16 v[52:55], v[212:215], v[192:195], v[52:55]
	v_mfma_f32_16x16x32_bf16 v[48:51], v[212:215], v[200:203], v[48:51]
	v_mfma_f32_16x16x32_bf16 v[36:39], v[220:223], v[192:195], v[36:39]
	v_mfma_f32_16x16x32_bf16 v[32:35], v[220:223], v[200:203], v[32:35]
	v_mfma_f32_16x16x32_bf16 v[20:23], v[228:231], v[192:195], v[20:23]
	v_mfma_f32_16x16x32_bf16 v[16:19], v[228:231], v[200:203], v[16:19]
	v_mfma_f32_16x16x32_bf16 v[4:7], v[236:239], v[192:195], v[4:7]
	v_mfma_f32_16x16x32_bf16 v[0:3], v[236:239], v[200:203], v[0:3]
	s_setprio 0
	s_add_i32 s80, s80, 2
	s_add_u32 s12, s12, 0x100
	s_addc_u32 s13, s13, 0
	s_cmp_gt_u32 s80, 13
	s_barrier
	s_cbranch_scc0 .LBB0_1144
	s_and_saveexec_b64 s[12:13], s[6:7]
	s_cbranch_execz .LBB0_1147
	s_barrier

; DI int opaque_tid() { int t = threadIdx.x; asm volatile("" : "+v"(t)); return t; }
; #define STAGE(P, g) do { const char* g_ = (const char*)(g); \
;         __builtin_amdgcn_global_load_lds((const unsigned*)(g_ + so0), (lds_u32*)((lds_u8*)(P) + sb0), 16, 0, 0); \
;         __builtin_amdgcn_global_load_lds((const unsigned*)(g_ + so1), (lds_u32*)((lds_u8*)(P) + sb0 + 8192), 16, 0, 0); } while (0)
; #define LDA(dst, b, h) for (int m = 0; m < 4; ++m) for (int k = 0; k < 2; ++k) \
;         dst[m][k] = *reinterpret_cast<const bf16x8*>((char*)SA(b, h) + lds_byte(wr * 64 + m * 16 + fr, k * 32 + fq * 8))
; #define LDB(dst, b, h) for (int n = 0; n < 2; ++n) for (int k = 0; k < 2; ++k) \
;         dst[n][k] = *reinterpret_cast<const bf16x8*>((char*)SB(b, h) + lds_byte(wc * 32 + n * 16 + fr, k * 32 + fq * 8))
; #define WAIT_V(n) asm volatile("s_waitcnt vmcnt(" #n ")" ::: "memory")
; template <int EPI, int K, int LNI = -1>
; DI void ph_gemm(const Params& p, const bf16_t* __restrict__ A, const bf16_t* __restrict__ Bt, int N, float* s_aux) {
;     ...
;         if (EPI == EPI_E5B) {
;             if (opaque_tid() < 256) {
;                 const int row = brow + (int)opaque_tid(); const int hd = bcol >> 9;
;                 const float* pp = (const float*)((unsigned char*)p.out + OFFO_PART) + (size_t)row * 256 + hd * 64;
;                 float sacc = 0.f;
; #pragma unroll
;                 for (int i = 0; i < 16; ++i) { const f32x4 v = *(const f32x4*)(pp + i * 4); sacc += (v[0] + v[1]) + (v[2] + v[3]); }
;                 sa[opaque_tid()] = __frsqrt_rn(sacc * (1.0f / 512.0f) + 1e-6f);
;             }
;         }
;         for (int t = 0; t < nt; t += 2) {
;             const bool last = (t == nt - 2);
;             const bf16_t* a1 = cA + (size_t)(t + 1) * kstep;
;             const bf16_t* a2 = last ? nA : cA + (size_t)(t + 2) * kstep; const bf16_t* b2 = last ? nB : cB + (size_t)(t + 2) * kstep;
;             const bf16_t* a3 = a2 + kstep; const bf16_t* b3 = b2 + kstep;
;             LDB(B0, 0, 0); LDB(B1, 0, 1); SCHED; LDA(At, 0, 0); STAGE(SA(1, 1), a1 + hstep);
;             WAIT_V(8); WAIT_L(0); BAR; MMA(0, 0, At, B0); MMA(0, 1, At, B1); BAR; SCHED;
;             LDA(At, 0, 1); STAGE(SB(0, 0), b2); STAGE(SB(0, 1), b2 + hstep); STAGE(SA(0, 0), a2);
;             WAIT_V(8); WAIT_L(0); BAR; MMA(1, 0, At, B0); MMA(1, 1, At, B1); BAR; SCHED;
.LBB0_1635:
	s_or_b64 exec, exec, s[48:49]
	s_ashr_i32 s45, s44, 31
	s_lshl_b64 s[48:49], s[44:45], 19
	s_add_u32 s43, s40, s48
	s_addc_u32 s45, s41, s49
	s_ashr_i32 s47, s46, 31
	s_lshl_b64 s[50:51], s[46:47], 19
	s_add_u32 s47, s22, s50
	s_addc_u32 s71, s23, s51
	s_add_u32 s72, s56, s12
	s_addc_u32 s73, s57, s13
	s_add_u32 s74, s66, s14
	v_lshl_add_u64 v[128:129], v[142:143], 0, s[12:13]
	v_lshl_add_u64 v[130:131], v[144:145], 0, s[12:13]
	s_addc_u32 s75, s67, s15
	s_mov_b32 s76, -2
	s_mov_b64 s[12:13], 0
	s_waitcnt vmcnt(0)
	ds_read_b128 v[132:135], v183
	ds_read_b128 v[146:149], v183 offset:1024
	ds_read_b128 v[150:153], v183 offset:2048
	ds_read_b128 v[154:157], v183 offset:3072
	ds_read_b128 v[192:195], v184
	ds_read_b128 v[196:199], v184 offset:1024
	ds_read_b128 v[200:203], v184 offset:2048
	ds_read_b128 v[204:207], v184 offset:3072
	s_add_u32 s14, s72, s12
	s_addc_u32 s15, s73, s13
	s_add_u32 s14, s14, 0xb840100
	s_addc_u32 s15, s15, 0
	s_add_u32 s77, s74, s12
	s_addc_u32 s78, s75, s13
	s_cmpk_eq_i32 s12, 0x700
	s_cselect_b32 s53, s45, s15
	s_cselect_b32 s52, s43, s14
	s_cselect_b32 s15, s71, s78
	s_cselect_b32 s14, s47, s77
	v_add_u32_e32 v140, 0xc000, v162
	v_lshl_add_u64 v[208:209], v[128:129], 0, s[12:13]
	v_readfirstlane_b32 s77, v140
	v_add_u32_e32 v140, 0xe000, v162
	s_mov_b32 m0, s77
	v_readfirstlane_b32 s77, v140
	ds_read_b128 v[212:215], v185
	ds_read_b128 v[216:219], v185 offset:1024
	ds_read_b128 v[220:223], v186
	ds_read_b128 v[224:227], v186 offset:1024
	ds_read_b128 v[228:231], v187
	ds_read_b128 v[232:235], v187 offset:1024
	ds_read_b128 v[236:239], v188
	ds_read_b128 v[240:243], v188 offset:1024
	global_load_lds_dwordx4 v[208:209], off
	v_lshl_add_u64 v[208:209], v[130:131], 0, s[12:13]
	s_mov_b32 m0, s77
	s_nop 0
	global_load_lds_dwordx4 v[208:209], off
	s_waitcnt vmcnt(8)
	s_waitcnt lgkmcnt(0)
	s_barrier
	s_setprio 1
	s_waitcnt lgkmcnt(0)
	v_mfma_f32_16x16x32_bf16 v[124:127], v[212:215], v[132:135], 0
	v_mfma_f32_16x16x32_bf16 v[120:123], v[212:215], v[150:153], 0
	v_mfma_f32_16x16x32_bf16 v[108:111], v[220:223], v[132:135], 0
	v_mfma_f32_16x16x32_bf16 v[104:107], v[220:223], v[150:153], 0
	v_mfma_f32_16x16x32_bf16 v[92:95], v[228:231], v[132:135], 0
	v_mfma_f32_16x16x32_bf16 v[88:91], v[228:231], v[150:153], 0
	v_mfma_f32_16x16x32_bf16 v[76:79], v[236:239], v[132:135], 0
	v_mfma_f32_16x16x32_bf16 v[72:75], v[236:239], v[150:153], 0
	v_mfma_f32_16x16x32_bf16 v[124:127], v[216:219], v[146:149], v[124:127]
	v_mfma_f32_16x16x32_bf16 v[120:123], v[216:219], v[154:157], v[120:123]
	v_mfma_f32_16x16x32_bf16 v[108:111], v[224:227], v[146:149], v[108:111]
	v_mfma_f32_16x16x32_bf16 v[104:107], v[224:227], v[154:157], v[104:107]
	v_mfma_f32_16x16x32_bf16 v[92:95], v[232:235], v[146:149], v[92:95]
	v_mfma_f32_16x16x32_bf16 v[88:91], v[232:235], v[154:157], v[88:91]
	v_mfma_f32_16x16x32_bf16 v[76:79], v[240:243], v[146:149], v[76:79]
	v_mfma_f32_16x16x32_bf16 v[72:75], v[240:243], v[154:157], v[72:75]
	s_setprio 0
	s_setprio 1
	v_mfma_f32_16x16x32_bf16 v[116:119], v[212:215], v[192:195], 0
	v_mfma_f32_16x16x32_bf16 v[112:115], v[212:215], v[200:203], 0
	v_mfma_f32_16x16x32_bf16 v[100:103], v[220:223], v[192:195], 0
	v_mfma_f32_16x16x32_bf16 v[96:99], v[220:223], v[200:203], 0
	v_mfma_f32_16x16x32_bf16 v[84:87], v[228:231], v[192:195], 0
	v_mfma_f32_16x16x32_bf16 v[80:83], v[228:231], v[200:203], 0
	v_mfma_f32_16x16x32_bf16 v[68:71], v[236:239], v[192:195], 0
	v_mfma_f32_16x16x32_bf16 v[64:67], v[236:239], v[200:203], 0
	v_mfma_f32_16x16x32_bf16 v[116:119], v[216:219], v[196:199], v[116:119]
	v_mfma_f32_16x16x32_bf16 v[112:115], v[216:219], v[204:207], v[112:115]
	v_mfma_f32_16x16x32_bf16 v[100:103], v[224:227], v[196:199], v[100:103]
	v_mfma_f32_16x16x32_bf16 v[96:99], v[224:227], v[204:207], v[96:99]
	v_mfma_f32_16x16x32_bf16 v[84:87], v[232:235], v[196:199], v[84:87]
	v_mfma_f32_16x16x32_bf16 v[80:83], v[232:235], v[204:207], v[80:83]
	v_mfma_f32_16x16x32_bf16 v[68:71], v[240:243], v[196:199], v[68:71]
	v_mfma_f32_16x16x32_bf16 v[64:67], v[240:243], v[204:207], v[64:67]
	s_setprio 0
	s_barrier
	v_readfirstlane_b32 s77, v158
	v_lshl_add_u64 v[208:209], s[14:15], 0, v[136:137]
	s_mov_b32 m0, s77
	v_readfirstlane_b32 s77, v159
	s_add_u32 s78, s14, 0x40000
	ds_read_b128 v[212:215], v185 offset:16384
	ds_read_b128 v[216:219], v185 offset:17408
	ds_read_b128 v[220:223], v186 offset:16384
	ds_read_b128 v[224:227], v186 offset:17408
	ds_read_b128 v[228:231], v187 offset:16384
	ds_read_b128 v[232:235], v187 offset:17408
	ds_read_b128 v[236:239], v188 offset:16384
	ds_read_b128 v[240:243], v188 offset:17408
	global_load_lds_dwordx4 v[208:209], off
	v_lshl_add_u64 v[244:245], s[14:15], 0, v[138:139]
	s_mov_b32 m0, s77
	s_addc_u32 s79, s15, 0
	v_readfirstlane_b32 s77, v160
	global_load_lds_dwordx4 v[244:245], off
	v_lshl_add_u64 v[246:247], s[78:79], 0, v[136:137]
	s_mov_b32 m0, s77
	v_readfirstlane_b32 s77, v161
	global_load_lds_dwordx4 v[246:247], off
	v_lshl_add_u64 v[246:247], s[78:79], 0, v[138:139]
	s_mov_b32 m0, s77
	v_readfirstlane_b32 s77, v162
	global_load_lds_dwordx4 v[246:247], off
	v_lshl_add_u64 v[246:247], s[52:53], 0, v[136:137]
	s_mov_b32 m0, s77
	v_readfirstlane_b32 s77, v163
	global_load_lds_dwordx4 v[246:247], off
	v_lshl_add_u64 v[248:249], s[52:53], 0, v[138:139]
	s_mov_b32 m0, s77
	s_nop 0
	global_load_lds_dwordx4 v[248:249], off
	s_waitcnt vmcnt(8)
	s_waitcnt lgkmcnt(0)
	s_barrier
; #define STAGE(P, g) do { const char* g_ = (const char*)(g); \
;         __builtin_amdgcn_global_load_lds((const unsigned*)(g_ + so0), (lds_u32*)((lds_u8*)(P) + sb0), 16, 0, 0); \
;         __builtin_amdgcn_global_load_lds((const unsigned*)(g_ + so1), (lds_u32*)((lds_u8*)(P) + sb0 + 8192), 16, 0, 0); } while (0)
; #define LDA(dst, b, h) for (int m = 0; m < 4; ++m) for (int k = 0; k < 2; ++k) \
;         dst[m][k] = *reinterpret_cast<const bf16x8*>((char*)SA(b, h) + lds_byte(wr * 64 + m * 16 + fr, k * 32 + fq * 8))
; #define LDB(dst, b, h) for (int n = 0; n < 2; ++n) for (int k = 0; k < 2; ++k) \
;         dst[n][k] = *reinterpret_cast<const bf16x8*>((char*)SB(b, h) + lds_byte(wc * 32 + n * 16 + fr, k * 32 + fq * 8))
; #define MMA(ai, bj, At_, Bt_) do { __builtin_amdgcn_s_setprio(1); \
;         for (int m = 0; m < 4; ++m) for (int n = 0; n < 2; ++n) for (int k = 0; k < 2; ++k) \
;             acc[ai][bj][m][n] = __builtin_amdgcn_mfma_f32_16x16x32_bf16(At_[m][k], Bt_[n][k], acc[ai][bj][m][n], 0, 0, 0); \
;         __builtin_amdgcn_s_setprio(0); } while (0)
; #define WAIT_V(n) asm volatile("s_waitcnt vmcnt(" #n ")" ::: "memory")
; #define WAIT_L(n) asm volatile("s_waitcnt lgkmcnt(" #n ")" ::: "memory")
; #define BAR __builtin_amdgcn_s_barrier()
; #define SCHED __builtin_amdgcn_sched_barrier(0)
; template <int EPI, int K, int LNI = -1>
; DI void ph_gemm(const Params& p, const bf16_t* __restrict__ A, const bf16_t* __restrict__ Bt, int N, float* s_aux) {
;     ...
;             WAIT_V(8); WAIT_L(0); BAR; MMA(0, 0, At, B0); MMA(0, 1, At, B1); BAR; SCHED;
;             LDA(At, 0, 1); STAGE(SB(0, 0), b2); STAGE(SB(0, 1), b2 + hstep); STAGE(SA(0, 0), a2);
;             WAIT_V(8); WAIT_L(0); BAR; MMA(1, 0, At, B0); MMA(1, 1, At, B1); BAR; SCHED;
;             LDB(B0, 1, 0); LDB(B1, 1, 1); SCHED; LDA(At, 1, 0); STAGE(SA(0, 1), a2 + hstep);
;             WAIT_V(8); WAIT_L(0); BAR; MMA(0, 0, At, B0); MMA(0, 1, At, B1); BAR; SCHED;
	s_setprio 1
	s_waitcnt lgkmcnt(0)
	v_mfma_f32_16x16x32_bf16 v[60:63], v[212:215], v[132:135], 0
	v_mfma_f32_16x16x32_bf16 v[56:59], v[212:215], v[150:153], 0
	v_mfma_f32_16x16x32_bf16 v[44:47], v[220:223], v[132:135], 0
	v_mfma_f32_16x16x32_bf16 v[40:43], v[220:223], v[150:153], 0
	v_mfma_f32_16x16x32_bf16 v[28:31], v[228:231], v[132:135], 0
	v_mfma_f32_16x16x32_bf16 v[24:27], v[228:231], v[150:153], 0
	v_mfma_f32_16x16x32_bf16 v[12:15], v[236:239], v[132:135], 0
	v_mfma_f32_16x16x32_bf16 v[8:11], v[236:239], v[150:153], 0
	v_mfma_f32_16x16x32_bf16 v[60:63], v[216:219], v[146:149], v[60:63]
	v_mfma_f32_16x16x32_bf16 v[56:59], v[216:219], v[154:157], v[56:59]
	v_mfma_f32_16x16x32_bf16 v[44:47], v[224:227], v[146:149], v[44:47]
	v_mfma_f32_16x16x32_bf16 v[40:43], v[224:227], v[154:157], v[40:43]
	v_mfma_f32_16x16x32_bf16 v[28:31], v[232:235], v[146:149], v[28:31]
	v_mfma_f32_16x16x32_bf16 v[24:27], v[232:235], v[154:157], v[24:27]
	v_mfma_f32_16x16x32_bf16 v[12:15], v[240:243], v[146:149], v[12:15]
	v_mfma_f32_16x16x32_bf16 v[8:11], v[240:243], v[154:157], v[8:11]
	s_setprio 0
	s_setprio 1
	v_mfma_f32_16x16x32_bf16 v[52:55], v[212:215], v[192:195], 0
	v_mfma_f32_16x16x32_bf16 v[48:51], v[212:215], v[200:203], 0
	v_mfma_f32_16x16x32_bf16 v[36:39], v[220:223], v[192:195], 0
	v_mfma_f32_16x16x32_bf16 v[32:35], v[220:223], v[200:203], 0
	v_mfma_f32_16x16x32_bf16 v[20:23], v[228:231], v[192:195], 0
	v_mfma_f32_16x16x32_bf16 v[16:19], v[228:231], v[200:203], 0
	v_mfma_f32_16x16x32_bf16 v[4:7], v[236:239], v[192:195], 0
	v_mfma_f32_16x16x32_bf16 v[0:3], v[236:239], v[200:203], 0
	v_mfma_f32_16x16x32_bf16 v[52:55], v[216:219], v[196:199], v[52:55]
	v_mfma_f32_16x16x32_bf16 v[48:51], v[216:219], v[204:207], v[48:51]
	v_mfma_f32_16x16x32_bf16 v[36:39], v[224:227], v[196:199], v[36:39]
	v_mfma_f32_16x16x32_bf16 v[32:35], v[224:227], v[204:207], v[32:35]
	v_mfma_f32_16x16x32_bf16 v[20:23], v[232:235], v[196:199], v[20:23]
	v_mfma_f32_16x16x32_bf16 v[16:19], v[232:235], v[204:207], v[16:19]
	v_mfma_f32_16x16x32_bf16 v[4:7], v[240:243], v[196:199], v[4:7]
	v_mfma_f32_16x16x32_bf16 v[0:3], v[240:243], v[204:207], v[0:3]
	s_setprio 0
	s_barrier
	ds_read_b128 v[132:135], v189
	ds_read_b128 v[146:149], v189 offset:1024
	ds_read_b128 v[150:153], v189 offset:2048
	ds_read_b128 v[154:157], v189 offset:3072
	ds_read_b128 v[192:195], v190
	ds_read_b128 v[196:199], v190 offset:1024
	ds_read_b128 v[200:203], v190 offset:2048
	ds_read_b128 v[204:207], v190 offset:3072
	s_add_u32 s52, s52, 0x40000
	s_addc_u32 s53, s53, 0
	v_readfirstlane_b32 s77, v164
	v_lshl_add_u64 v[250:251], s[52:53], 0, v[136:137]
	s_mov_b32 m0, s77
	ds_read_b128 v[212:215], v185 offset:32768
	ds_read_b128 v[216:219], v185 offset:33792
	ds_read_b128 v[220:223], v186 offset:32768
	ds_read_b128 v[224:227], v186 offset:33792
	ds_read_b128 v[228:231], v187 offset:32768
	ds_read_b128 v[232:235], v187 offset:33792
	ds_read_b128 v[236:239], v188 offset:32768
	ds_read_b128 v[240:243], v188 offset:33792
	global_load_lds_dwordx4 v[250:251], off
	v_lshl_add_u64 v[250:251], s[52:53], 0, v[138:139]
	v_readfirstlane_b32 s52, v165
	s_mov_b32 m0, s52
	s_nop 0
	global_load_lds_dwordx4 v[250:251], off
	s_waitcnt vmcnt(8)
	s_waitcnt lgkmcnt(0)
	s_barrier
	s_setprio 1
	s_waitcnt lgkmcnt(0)
	v_mfma_f32_16x16x32_bf16 v[124:127], v[212:215], v[132:135], v[124:127]
	v_mfma_f32_16x16x32_bf16 v[120:123], v[212:215], v[150:153], v[120:123]
	v_mfma_f32_16x16x32_bf16 v[108:111], v[220:223], v[132:135], v[108:111]
	v_mfma_f32_16x16x32_bf16 v[104:107], v[220:223], v[150:153], v[104:107]
	v_mfma_f32_16x16x32_bf16 v[92:95], v[228:231], v[132:135], v[92:95]
	v_mfma_f32_16x16x32_bf16 v[88:91], v[228:231], v[150:153], v[88:91]
	v_mfma_f32_16x16x32_bf16 v[76:79], v[236:239], v[132:135], v[76:79]
	v_mfma_f32_16x16x32_bf16 v[72:75], v[236:239], v[150:153], v[72:75]
	v_mfma_f32_16x16x32_bf16 v[124:127], v[216:219], v[146:149], v[124:127]
	v_mfma_f32_16x16x32_bf16 v[120:123], v[216:219], v[154:157], v[120:123]
	v_mfma_f32_16x16x32_bf16 v[108:111], v[224:227], v[146:149], v[108:111]
	v_mfma_f32_16x16x32_bf16 v[104:107], v[224:227], v[154:157], v[104:107]
	v_mfma_f32_16x16x32_bf16 v[92:95], v[232:235], v[146:149], v[92:95]
	v_mfma_f32_16x16x32_bf16 v[88:91], v[232:235], v[154:157], v[88:91]
	v_mfma_f32_16x16x32_bf16 v[76:79], v[240:243], v[146:149], v[76:79]
	v_mfma_f32_16x16x32_bf16 v[72:75], v[240:243], v[154:157], v[72:75]
	s_setprio 0
	s_setprio 1
	v_mfma_f32_16x16x32_bf16 v[116:119], v[212:215], v[192:195], v[116:119]
	v_mfma_f32_16x16x32_bf16 v[112:115], v[212:215], v[200:203], v[112:115]
	v_mfma_f32_16x16x32_bf16 v[100:103], v[220:223], v[192:195], v[100:103]
	v_mfma_f32_16x16x32_bf16 v[96:99], v[220:223], v[200:203], v[96:99]
	v_mfma_f32_16x16x32_bf16 v[84:87], v[228:231], v[192:195], v[84:87]
	v_mfma_f32_16x16x32_bf16 v[80:83], v[228:231], v[200:203], v[80:83]
	v_mfma_f32_16x16x32_bf16 v[68:71], v[236:239], v[192:195], v[68:71]
	v_mfma_f32_16x16x32_bf16 v[64:67], v[236:239], v[200:203], v[64:67]
	v_mfma_f32_16x16x32_bf16 v[116:119], v[216:219], v[196:199], v[116:119]
	v_mfma_f32_16x16x32_bf16 v[112:115], v[216:219], v[204:207], v[112:115]
	v_mfma_f32_16x16x32_bf16 v[100:103], v[224:227], v[196:199], v[100:103]
	v_mfma_f32_16x16x32_bf16 v[96:99], v[224:227], v[204:207], v[96:99]
	v_mfma_f32_16x16x32_bf16 v[84:87], v[232:235], v[196:199], v[84:87]
	v_mfma_f32_16x16x32_bf16 v[80:83], v[232:235], v[204:207], v[80:83]
	v_mfma_f32_16x16x32_bf16 v[68:71], v[240:243], v[196:199], v[68:71]
	v_mfma_f32_16x16x32_bf16 v[64:67], v[240:243], v[204:207], v[64:67]
	s_setprio 0
	s_barrier
; #define STAGE(P, g) do { const char* g_ = (const char*)(g); \
;         __builtin_amdgcn_global_load_lds((const unsigned*)(g_ + so0), (lds_u32*)((lds_u8*)(P) + sb0), 16, 0, 0); \
;         __builtin_amdgcn_global_load_lds((const unsigned*)(g_ + so1), (lds_u32*)((lds_u8*)(P) + sb0 + 8192), 16, 0, 0); } while (0)
; #define LDA(dst, b, h) for (int m = 0; m < 4; ++m) for (int k = 0; k < 2; ++k) \
;         dst[m][k] = *reinterpret_cast<const bf16x8*>((char*)SA(b, h) + lds_byte(wr * 64 + m * 16 + fr, k * 32 + fq * 8))
; #define LDB(dst, b, h) for (int n = 0; n < 2; ++n) for (int k = 0; k < 2; ++k) \
;         dst[n][k] = *reinterpret_cast<const bf16x8*>((char*)SB(b, h) + lds_byte(wc * 32 + n * 16 + fr, k * 32 + fq * 8))
; #define MMA(ai, bj, At_, Bt_) do { __builtin_amdgcn_s_setprio(1); \
;         for (int m = 0; m < 4; ++m) for (int n = 0; n < 2; ++n) for (int k = 0; k < 2; ++k) \
;             acc[ai][bj][m][n] = __builtin_amdgcn_mfma_f32_16x16x32_bf16(At_[m][k], Bt_[n][k], acc[ai][bj][m][n], 0, 0, 0); \
;         __builtin_amdgcn_s_setprio(0); } while (0)
; #define WAIT_V(n) asm volatile("s_waitcnt vmcnt(" #n ")" ::: "memory")
; #define WAIT_L(n) asm volatile("s_waitcnt lgkmcnt(" #n ")" ::: "memory")
; #define BAR __builtin_amdgcn_s_barrier()
; #define SCHED __builtin_amdgcn_sched_barrier(0)
; template <int EPI, int K, int LNI = -1>
; DI void ph_gemm(const Params& p, const bf16_t* __restrict__ A, const bf16_t* __restrict__ Bt, int N, float* s_aux) {
;     ...
;         for (int t = 0; t < nt; t += 2) {
;             const bool last = (t == nt - 2);
;             const bf16_t* a1 = cA + (size_t)(t + 1) * kstep;
;             const bf16_t* a2 = last ? nA : cA + (size_t)(t + 2) * kstep; const bf16_t* b2 = last ? nB : cB + (size_t)(t + 2) * kstep;
;             const bf16_t* a3 = a2 + kstep; const bf16_t* b3 = b2 + kstep;
;             LDB(B0, 0, 0); LDB(B1, 0, 1); SCHED; LDA(At, 0, 0); STAGE(SA(1, 1), a1 + hstep);
;             WAIT_V(8); WAIT_L(0); BAR; MMA(0, 0, At, B0); MMA(0, 1, At, B1); BAR; SCHED;
;     ...
;             LDA(At, 1, 1); STAGE(SB(1, 0), b3); STAGE(SB(1, 1), b3 + hstep); STAGE(SA(1, 0), a3);
;             WAIT_V(8); WAIT_L(0); BAR; MMA(1, 0, At, B0); MMA(1, 1, At, B1); BAR; SCHED;
	v_readfirstlane_b32 s52, v166
	v_lshl_add_u64 v[208:209], v[208:209], 0, s[26:27]
	s_mov_b32 m0, s52
	v_readfirstlane_b32 s52, v167
	s_add_u32 s14, s14, 0x40080
	ds_read_b128 v[212:215], v185 offset:49152
	ds_read_b128 v[216:219], v185 offset:50176
	ds_read_b128 v[220:223], v186 offset:49152
	ds_read_b128 v[224:227], v186 offset:50176
	ds_read_b128 v[228:231], v187 offset:49152
	ds_read_b128 v[232:235], v187 offset:50176
	ds_read_b128 v[236:239], v188 offset:49152
	ds_read_b128 v[240:243], v188 offset:50176
	global_load_lds_dwordx4 v[208:209], off
	v_lshl_add_u64 v[208:209], v[244:245], 0, s[26:27]
	s_mov_b32 m0, s52
	s_addc_u32 s15, s15, 0
	v_readfirstlane_b32 s52, v170
	global_load_lds_dwordx4 v[208:209], off
	v_lshl_add_u64 v[208:209], s[14:15], 0, v[136:137]
	s_mov_b32 m0, s52
	s_nop 0
	global_load_lds_dwordx4 v[208:209], off
	v_lshl_add_u64 v[208:209], s[14:15], 0, v[138:139]
	v_readfirstlane_b32 s14, v171
	s_mov_b32 m0, s14
	v_readfirstlane_b32 s14, v168
	global_load_lds_dwordx4 v[208:209], off
	v_lshl_add_u64 v[208:209], v[246:247], 0, s[26:27]
	s_mov_b32 m0, s14
	v_readfirstlane_b32 s14, v169
	global_load_lds_dwordx4 v[208:209], off
	v_lshl_add_u64 v[208:209], v[248:249], 0, s[26:27]
	s_mov_b32 m0, s14
	s_nop 0
	global_load_lds_dwordx4 v[208:209], off
	s_waitcnt vmcnt(8)
	s_waitcnt lgkmcnt(0)
	s_barrier
	s_setprio 1
	s_waitcnt lgkmcnt(0)
	v_mfma_f32_16x16x32_bf16 v[60:63], v[212:215], v[132:135], v[60:63]
	v_mfma_f32_16x16x32_bf16 v[56:59], v[212:215], v[150:153], v[56:59]
	v_mfma_f32_16x16x32_bf16 v[44:47], v[220:223], v[132:135], v[44:47]
	v_mfma_f32_16x16x32_bf16 v[40:43], v[220:223], v[150:153], v[40:43]
	v_mfma_f32_16x16x32_bf16 v[28:31], v[228:231], v[132:135], v[28:31]
	v_mfma_f32_16x16x32_bf16 v[24:27], v[228:231], v[150:153], v[24:27]
	v_mfma_f32_16x16x32_bf16 v[12:15], v[236:239], v[132:135], v[12:15]
	v_mfma_f32_16x16x32_bf16 v[8:11], v[236:239], v[150:153], v[8:11]
	v_mfma_f32_16x16x32_bf16 v[60:63], v[216:219], v[146:149], v[60:63]
	v_mfma_f32_16x16x32_bf16 v[56:59], v[216:219], v[154:157], v[56:59]
	v_mfma_f32_16x16x32_bf16 v[44:47], v[224:227], v[146:149], v[44:47]
	v_mfma_f32_16x16x32_bf16 v[40:43], v[224:227], v[154:157], v[40:43]
	v_mfma_f32_16x16x32_bf16 v[28:31], v[232:235], v[146:149], v[28:31]
	v_mfma_f32_16x16x32_bf16 v[24:27], v[232:235], v[154:157], v[24:27]
	v_mfma_f32_16x16x32_bf16 v[12:15], v[240:243], v[146:149], v[12:15]
	v_mfma_f32_16x16x32_bf16 v[8:11], v[240:243], v[154:157], v[8:11]
	s_setprio 0
	s_setprio 1
	v_mfma_f32_16x16x32_bf16 v[52:55], v[212:215], v[192:195], v[52:55]
	v_mfma_f32_16x16x32_bf16 v[48:51], v[212:215], v[200:203], v[48:51]
	v_mfma_f32_16x16x32_bf16 v[36:39], v[220:223], v[192:195], v[36:39]
	v_mfma_f32_16x16x32_bf16 v[32:35], v[220:223], v[200:203], v[32:35]
	v_mfma_f32_16x16x32_bf16 v[20:23], v[228:231], v[192:195], v[20:23]
	v_mfma_f32_16x16x32_bf16 v[16:19], v[228:231], v[200:203], v[16:19]
	v_mfma_f32_16x16x32_bf16 v[4:7], v[236:239], v[192:195], v[4:7]
	v_mfma_f32_16x16x32_bf16 v[0:3], v[236:239], v[200:203], v[0:3]
	v_mfma_f32_16x16x32_bf16 v[52:55], v[216:219], v[196:199], v[52:55]
	v_mfma_f32_16x16x32_bf16 v[48:51], v[216:219], v[204:207], v[48:51]
	v_mfma_f32_16x16x32_bf16 v[36:39], v[224:227], v[196:199], v[36:39]
	v_mfma_f32_16x16x32_bf16 v[32:35], v[224:227], v[204:207], v[32:35]
	v_mfma_f32_16x16x32_bf16 v[20:23], v[232:235], v[196:199], v[20:23]
	v_mfma_f32_16x16x32_bf16 v[16:19], v[232:235], v[204:207], v[16:19]
	v_mfma_f32_16x16x32_bf16 v[4:7], v[240:243], v[196:199], v[4:7]
	v_mfma_f32_16x16x32_bf16 v[0:3], v[240:243], v[204:207], v[0:3]
	s_setprio 0
	s_add_i32 s76, s76, 2
	s_add_u32 s12, s12, 0x100
	s_addc_u32 s13, s13, 0
	s_cmp_gt_u32 s76, 13
	s_barrier
.LBB0_1636:
	ds_read_b128 v[132:135], v183
	ds_read_b128 v[146:149], v183 offset:1024
	ds_read_b128 v[150:153], v183 offset:2048
	ds_read_b128 v[154:157], v183 offset:3072
	ds_read_b128 v[192:195], v184
	ds_read_b128 v[196:199], v184 offset:1024
	ds_read_b128 v[200:203], v184 offset:2048
	ds_read_b128 v[204:207], v184 offset:3072
	s_add_u32 s14, s72, s12
	s_addc_u32 s15, s73, s13
	s_add_u32 s14, s14, 0xb840100
	s_addc_u32 s15, s15, 0
	s_add_u32 s77, s74, s12
	s_addc_u32 s78, s75, s13
	s_cmpk_eq_i32 s12, 0x700
	s_cselect_b32 s53, s45, s15
	s_cselect_b32 s52, s43, s14
	s_cselect_b32 s15, s71, s78
	s_cselect_b32 s14, s47, s77
	v_add_u32_e32 v140, 0xc000, v162
	v_lshl_add_u64 v[208:209], v[128:129], 0, s[12:13]
	v_readfirstlane_b32 s77, v140
	v_add_u32_e32 v140, 0xe000, v162
	s_mov_b32 m0, s77
	v_readfirstlane_b32 s77, v140
	ds_read_b128 v[212:215], v185
	ds_read_b128 v[216:219], v185 offset:1024
	ds_read_b128 v[220:223], v186
	ds_read_b128 v[224:227], v186 offset:1024
	ds_read_b128 v[228:231], v187
	ds_read_b128 v[232:235], v187 offset:1024
	ds_read_b128 v[236:239], v188
	ds_read_b128 v[240:243], v188 offset:1024
	global_load_lds_dwordx4 v[208:209], off
	v_lshl_add_u64 v[208:209], v[130:131], 0, s[12:13]
	s_mov_b32 m0, s77
	s_nop 0
	global_load_lds_dwordx4 v[208:209], off
	s_waitcnt vmcnt(8)
	s_waitcnt lgkmcnt(0)
	s_barrier
; #define STAGE(P, g) do { const char* g_ = (const char*)(g); \
;         __builtin_amdgcn_global_load_lds((const unsigned*)(g_ + so0), (lds_u32*)((lds_u8*)(P) + sb0), 16, 0, 0); \
;         __builtin_amdgcn_global_load_lds((const unsigned*)(g_ + so1), (lds_u32*)((lds_u8*)(P) + sb0 + 8192), 16, 0, 0); } while (0)
; #define LDA(dst, b, h) for (int m = 0; m < 4; ++m) for (int k = 0; k < 2; ++k) \
;         dst[m][k] = *reinterpret_cast<const bf16x8*>((char*)SA(b, h) + lds_byte(wr * 64 + m * 16 + fr, k * 32 + fq * 8))
; #define LDB(dst, b, h) for (int n = 0; n < 2; ++n) for (int k = 0; k < 2; ++k) \
;         dst[n][k] = *reinterpret_cast<const bf16x8*>((char*)SB(b, h) + lds_byte(wc * 32 + n * 16 + fr, k * 32 + fq * 8))
; #define MMA(ai, bj, At_, Bt_) do { __builtin_amdgcn_s_setprio(1); \
;         for (int m = 0; m < 4; ++m) for (int n = 0; n < 2; ++n) for (int k = 0; k < 2; ++k) \
;             acc[ai][bj][m][n] = __builtin_amdgcn_mfma_f32_16x16x32_bf16(At_[m][k], Bt_[n][k], acc[ai][bj][m][n], 0, 0, 0); \
;         __builtin_amdgcn_s_setprio(0); } while (0)
; #define WAIT_V(n) asm volatile("s_waitcnt vmcnt(" #n ")" ::: "memory")
; #define WAIT_L(n) asm volatile("s_waitcnt lgkmcnt(" #n ")" ::: "memory")
; #define BAR __builtin_amdgcn_s_barrier()
; #define SCHED __builtin_amdgcn_sched_barrier(0)
; template <int EPI, int K, int LNI = -1>
; DI void ph_gemm(const Params& p, const bf16_t* __restrict__ A, const bf16_t* __restrict__ Bt, int N, float* s_aux) {
;     ...
;             WAIT_V(8); WAIT_L(0); BAR; MMA(0, 0, At, B0); MMA(0, 1, At, B1); BAR; SCHED;
;             LDA(At, 0, 1); STAGE(SB(0, 0), b2); STAGE(SB(0, 1), b2 + hstep); STAGE(SA(0, 0), a2);
;             WAIT_V(8); WAIT_L(0); BAR; MMA(1, 0, At, B0); MMA(1, 1, At, B1); BAR; SCHED;
;             LDB(B0, 1, 0); LDB(B1, 1, 1); SCHED; LDA(At, 1, 0); STAGE(SA(0, 1), a2 + hstep);
;             WAIT_V(8); WAIT_L(0); BAR; MMA(0, 0, At, B0); MMA(0, 1, At, B1); BAR; SCHED;
	s_setprio 1
	s_waitcnt lgkmcnt(0)
	v_mfma_f32_16x16x32_bf16 v[124:127], v[212:215], v[132:135], v[124:127]
	v_mfma_f32_16x16x32_bf16 v[120:123], v[212:215], v[150:153], v[120:123]
	v_mfma_f32_16x16x32_bf16 v[108:111], v[220:223], v[132:135], v[108:111]
	v_mfma_f32_16x16x32_bf16 v[104:107], v[220:223], v[150:153], v[104:107]
	v_mfma_f32_16x16x32_bf16 v[92:95], v[228:231], v[132:135], v[92:95]
	v_mfma_f32_16x16x32_bf16 v[88:91], v[228:231], v[150:153], v[88:91]
	v_mfma_f32_16x16x32_bf16 v[76:79], v[236:239], v[132:135], v[76:79]
	v_mfma_f32_16x16x32_bf16 v[72:75], v[236:239], v[150:153], v[72:75]
	v_mfma_f32_16x16x32_bf16 v[124:127], v[216:219], v[146:149], v[124:127]
	v_mfma_f32_16x16x32_bf16 v[120:123], v[216:219], v[154:157], v[120:123]
	v_mfma_f32_16x16x32_bf16 v[108:111], v[224:227], v[146:149], v[108:111]
	v_mfma_f32_16x16x32_bf16 v[104:107], v[224:227], v[154:157], v[104:107]
	v_mfma_f32_16x16x32_bf16 v[92:95], v[232:235], v[146:149], v[92:95]
	v_mfma_f32_16x16x32_bf16 v[88:91], v[232:235], v[154:157], v[88:91]
	v_mfma_f32_16x16x32_bf16 v[76:79], v[240:243], v[146:149], v[76:79]
	v_mfma_f32_16x16x32_bf16 v[72:75], v[240:243], v[154:157], v[72:75]
	s_setprio 0
	s_setprio 1
	v_mfma_f32_16x16x32_bf16 v[116:119], v[212:215], v[192:195], v[116:119]
	v_mfma_f32_16x16x32_bf16 v[112:115], v[212:215], v[200:203], v[112:115]
	v_mfma_f32_16x16x32_bf16 v[100:103], v[220:223], v[192:195], v[100:103]
	v_mfma_f32_16x16x32_bf16 v[96:99], v[220:223], v[200:203], v[96:99]
	v_mfma_f32_16x16x32_bf16 v[84:87], v[228:231], v[192:195], v[84:87]
	v_mfma_f32_16x16x32_bf16 v[80:83], v[228:231], v[200:203], v[80:83]
	v_mfma_f32_16x16x32_bf16 v[68:71], v[236:239], v[192:195], v[68:71]
	v_mfma_f32_16x16x32_bf16 v[64:67], v[236:239], v[200:203], v[64:67]
	v_mfma_f32_16x16x32_bf16 v[116:119], v[216:219], v[196:199], v[116:119]
	v_mfma_f32_16x16x32_bf16 v[112:115], v[216:219], v[204:207], v[112:115]
	v_mfma_f32_16x16x32_bf16 v[100:103], v[224:227], v[196:199], v[100:103]
	v_mfma_f32_16x16x32_bf16 v[96:99], v[224:227], v[204:207], v[96:99]
	v_mfma_f32_16x16x32_bf16 v[84:87], v[232:235], v[196:199], v[84:87]
	v_mfma_f32_16x16x32_bf16 v[80:83], v[232:235], v[204:207], v[80:83]
	v_mfma_f32_16x16x32_bf16 v[68:71], v[240:243], v[196:199], v[68:71]
	v_mfma_f32_16x16x32_bf16 v[64:67], v[240:243], v[204:207], v[64:67]
	s_setprio 0
	s_barrier
	v_readfirstlane_b32 s77, v158
	v_lshl_add_u64 v[208:209], s[14:15], 0, v[136:137]
	s_mov_b32 m0, s77
	v_readfirstlane_b32 s77, v159
	s_add_u32 s78, s14, 0x40000
	ds_read_b128 v[212:215], v185 offset:16384
	ds_read_b128 v[216:219], v185 offset:17408
	ds_read_b128 v[220:223], v186 offset:16384
	ds_read_b128 v[224:227], v186 offset:17408
	ds_read_b128 v[228:231], v187 offset:16384
	ds_read_b128 v[232:235], v187 offset:17408
	ds_read_b128 v[236:239], v188 offset:16384
	ds_read_b128 v[240:243], v188 offset:17408
	global_load_lds_dwordx4 v[208:209], off
	v_lshl_add_u64 v[244:245], s[14:15], 0, v[138:139]
	s_mov_b32 m0, s77
	s_addc_u32 s79, s15, 0
	v_readfirstlane_b32 s77, v160
	global_load_lds_dwordx4 v[244:245], off
	v_lshl_add_u64 v[246:247], s[78:79], 0, v[136:137]
	s_mov_b32 m0, s77
	v_readfirstlane_b32 s77, v161
	global_load_lds_dwordx4 v[246:247], off
	v_lshl_add_u64 v[246:247], s[78:79], 0, v[138:139]
	s_mov_b32 m0, s77
	v_readfirstlane_b32 s77, v162
	global_load_lds_dwordx4 v[246:247], off
	v_lshl_add_u64 v[246:247], s[52:53], 0, v[136:137]
	s_mov_b32 m0, s77
	v_readfirstlane_b32 s77, v163
	global_load_lds_dwordx4 v[246:247], off
	v_lshl_add_u64 v[248:249], s[52:53], 0, v[138:139]
	s_mov_b32 m0, s77
	s_nop 0
	global_load_lds_dwordx4 v[248:249], off
	s_waitcnt vmcnt(8)
	s_waitcnt lgkmcnt(0)
	s_barrier
	s_setprio 1
	s_waitcnt lgkmcnt(0)
	v_mfma_f32_16x16x32_bf16 v[60:63], v[212:215], v[132:135], v[60:63]
	v_mfma_f32_16x16x32_bf16 v[56:59], v[212:215], v[150:153], v[56:59]
	v_mfma_f32_16x16x32_bf16 v[44:47], v[220:223], v[132:135], v[44:47]
	v_mfma_f32_16x16x32_bf16 v[40:43], v[220:223], v[150:153], v[40:43]
	v_mfma_f32_16x16x32_bf16 v[28:31], v[228:231], v[132:135], v[28:31]
	v_mfma_f32_16x16x32_bf16 v[24:27], v[228:231], v[150:153], v[24:27]
	v_mfma_f32_16x16x32_bf16 v[12:15], v[236:239], v[132:135], v[12:15]
	v_mfma_f32_16x16x32_bf16 v[8:11], v[236:239], v[150:153], v[8:11]
	v_mfma_f32_16x16x32_bf16 v[60:63], v[216:219], v[146:149], v[60:63]
	v_mfma_f32_16x16x32_bf16 v[56:59], v[216:219], v[154:157], v[56:59]
	v_mfma_f32_16x16x32_bf16 v[44:47], v[224:227], v[146:149], v[44:47]
	v_mfma_f32_16x16x32_bf16 v[40:43], v[224:227], v[154:157], v[40:43]
	v_mfma_f32_16x16x32_bf16 v[28:31], v[232:235], v[146:149], v[28:31]
	v_mfma_f32_16x16x32_bf16 v[24:27], v[232:235], v[154:157], v[24:27]
	v_mfma_f32_16x16x32_bf16 v[12:15], v[240:243], v[146:149], v[12:15]
	v_mfma_f32_16x16x32_bf16 v[8:11], v[240:243], v[154:157], v[8:11]
	s_setprio 0
	s_setprio 1
	v_mfma_f32_16x16x32_bf16 v[52:55], v[212:215], v[192:195], v[52:55]
	v_mfma_f32_16x16x32_bf16 v[48:51], v[212:215], v[200:203], v[48:51]
	v_mfma_f32_16x16x32_bf16 v[36:39], v[220:223], v[192:195], v[36:39]
	v_mfma_f32_16x16x32_bf16 v[32:35], v[220:223], v[200:203], v[32:35]
	v_mfma_f32_16x16x32_bf16 v[20:23], v[228:231], v[192:195], v[20:23]
	v_mfma_f32_16x16x32_bf16 v[16:19], v[228:231], v[200:203], v[16:19]
	v_mfma_f32_16x16x32_bf16 v[4:7], v[236:239], v[192:195], v[4:7]
	v_mfma_f32_16x16x32_bf16 v[0:3], v[236:239], v[200:203], v[0:3]
	v_mfma_f32_16x16x32_bf16 v[52:55], v[216:219], v[196:199], v[52:55]
	v_mfma_f32_16x16x32_bf16 v[48:51], v[216:219], v[204:207], v[48:51]
	v_mfma_f32_16x16x32_bf16 v[36:39], v[224:227], v[196:199], v[36:39]
	v_mfma_f32_16x16x32_bf16 v[32:35], v[224:227], v[204:207], v[32:35]
	v_mfma_f32_16x16x32_bf16 v[20:23], v[232:235], v[196:199], v[20:23]
	v_mfma_f32_16x16x32_bf16 v[16:19], v[232:235], v[204:207], v[16:19]
	v_mfma_f32_16x16x32_bf16 v[4:7], v[240:243], v[196:199], v[4:7]
	v_mfma_f32_16x16x32_bf16 v[0:3], v[240:243], v[204:207], v[0:3]
	s_setprio 0
	s_barrier
; #define STAGE(P, g) do { const char* g_ = (const char*)(g); \
;         __builtin_amdgcn_global_load_lds((const unsigned*)(g_ + so0), (lds_u32*)((lds_u8*)(P) + sb0), 16, 0, 0); \
;         __builtin_amdgcn_global_load_lds((const unsigned*)(g_ + so1), (lds_u32*)((lds_u8*)(P) + sb0 + 8192), 16, 0, 0); } while (0)
; #define LDA(dst, b, h) for (int m = 0; m < 4; ++m) for (int k = 0; k < 2; ++k) \
;         dst[m][k] = *reinterpret_cast<const bf16x8*>((char*)SA(b, h) + lds_byte(wr * 64 + m * 16 + fr, k * 32 + fq * 8))
; #define LDB(dst, b, h) for (int n = 0; n < 2; ++n) for (int k = 0; k < 2; ++k) \
;         dst[n][k] = *reinterpret_cast<const bf16x8*>((char*)SB(b, h) + lds_byte(wc * 32 + n * 16 + fr, k * 32 + fq * 8))
; #define MMA(ai, bj, At_, Bt_) do { __builtin_amdgcn_s_setprio(1); \
;         for (int m = 0; m < 4; ++m) for (int n = 0; n < 2; ++n) for (int k = 0; k < 2; ++k) \
;             acc[ai][bj][m][n] = __builtin_amdgcn_mfma_f32_16x16x32_bf16(At_[m][k], Bt_[n][k], acc[ai][bj][m][n], 0, 0, 0); \
;         __builtin_amdgcn_s_setprio(0); } while (0)
; #define WAIT_V(n) asm volatile("s_waitcnt vmcnt(" #n ")" ::: "memory")
; #define WAIT_L(n) asm volatile("s_waitcnt lgkmcnt(" #n ")" ::: "memory")
; #define BAR __builtin_amdgcn_s_barrier()
; #define SCHED __builtin_amdgcn_sched_barrier(0)
; template <int EPI, int K, int LNI = -1>
; DI void ph_gemm(const Params& p, const bf16_t* __restrict__ A, const bf16_t* __restrict__ Bt, int N, float* s_aux) {
;     ...
;             LDB(B0, 1, 0); LDB(B1, 1, 1); SCHED; LDA(At, 1, 0); STAGE(SA(0, 1), a2 + hstep);
;             WAIT_V(8); WAIT_L(0); BAR; MMA(0, 0, At, B0); MMA(0, 1, At, B1); BAR; SCHED;
	ds_read_b128 v[132:135], v189
	ds_read_b128 v[146:149], v189 offset:1024
	ds_read_b128 v[150:153], v189 offset:2048
	ds_read_b128 v[154:157], v189 offset:3072
	ds_read_b128 v[192:195], v190
	ds_read_b128 v[196:199], v190 offset:1024
	ds_read_b128 v[200:203], v190 offset:2048
	ds_read_b128 v[204:207], v190 offset:3072
	s_add_u32 s52, s52, 0x40000
	s_addc_u32 s53, s53, 0
	v_readfirstlane_b32 s77, v164
	v_lshl_add_u64 v[250:251], s[52:53], 0, v[136:137]
	s_mov_b32 m0, s77
	ds_read_b128 v[212:215], v185 offset:32768
	ds_read_b128 v[216:219], v185 offset:33792
	ds_read_b128 v[220:223], v186 offset:32768
	ds_read_b128 v[224:227], v186 offset:33792
	ds_read_b128 v[228:231], v187 offset:32768
	ds_read_b128 v[232:235], v187 offset:33792
	ds_read_b128 v[236:239], v188 offset:32768
	ds_read_b128 v[240:243], v188 offset:33792
	global_load_lds_dwordx4 v[250:251], off
	v_lshl_add_u64 v[250:251], s[52:53], 0, v[138:139]
	v_readfirstlane_b32 s52, v165
	s_mov_b32 m0, s52
	s_nop 0
	global_load_lds_dwordx4 v[250:251], off
	s_waitcnt vmcnt(8)
	s_waitcnt lgkmcnt(0)
	s_barrier
	s_setprio 1
	s_waitcnt lgkmcnt(0)
	v_mfma_f32_16x16x32_bf16 v[124:127], v[212:215], v[132:135], v[124:127]
	v_mfma_f32_16x16x32_bf16 v[120:123], v[212:215], v[150:153], v[120:123]
	v_mfma_f32_16x16x32_bf16 v[108:111], v[220:223], v[132:135], v[108:111]
	v_mfma_f32_16x16x32_bf16 v[104:107], v[220:223], v[150:153], v[104:107]
	v_mfma_f32_16x16x32_bf16 v[92:95], v[228:231], v[132:135], v[92:95]
	v_mfma_f32_16x16x32_bf16 v[88:91], v[228:231], v[150:153], v[88:91]
	v_mfma_f32_16x16x32_bf16 v[76:79], v[236:239], v[132:135], v[76:79]
	v_mfma_f32_16x16x32_bf16 v[72:75], v[236:239], v[150:153], v[72:75]
	v_mfma_f32_16x16x32_bf16 v[124:127], v[216:219], v[146:149], v[124:127]
	v_mfma_f32_16x16x32_bf16 v[120:123], v[216:219], v[154:157], v[120:123]
	v_mfma_f32_16x16x32_bf16 v[108:111], v[224:227], v[146:149], v[108:111]
	v_mfma_f32_16x16x32_bf16 v[104:107], v[224:227], v[154:157], v[104:107]
	v_mfma_f32_16x16x32_bf16 v[92:95], v[232:235], v[146:149], v[92:95]
	v_mfma_f32_16x16x32_bf16 v[88:91], v[232:235], v[154:157], v[88:91]
	v_mfma_f32_16x16x32_bf16 v[76:79], v[240:243], v[146:149], v[76:79]
	v_mfma_f32_16x16x32_bf16 v[72:75], v[240:243], v[154:157], v[72:75]
	s_setprio 0
	s_setprio 1
	v_mfma_f32_16x16x32_bf16 v[116:119], v[212:215], v[192:195], v[116:119]
	v_mfma_f32_16x16x32_bf16 v[112:115], v[212:215], v[200:203], v[112:115]
	v_mfma_f32_16x16x32_bf16 v[100:103], v[220:223], v[192:195], v[100:103]
	v_mfma_f32_16x16x32_bf16 v[96:99], v[220:223], v[200:203], v[96:99]
	v_mfma_f32_16x16x32_bf16 v[84:87], v[228:231], v[192:195], v[84:87]
	v_mfma_f32_16x16x32_bf16 v[80:83], v[228:231], v[200:203], v[80:83]
	v_mfma_f32_16x16x32_bf16 v[68:71], v[236:239], v[192:195], v[68:71]
	v_mfma_f32_16x16x32_bf16 v[64:67], v[236:239], v[200:203], v[64:67]
	v_mfma_f32_16x16x32_bf16 v[116:119], v[216:219], v[196:199], v[116:119]
	v_mfma_f32_16x16x32_bf16 v[112:115], v[216:219], v[204:207], v[112:115]
	v_mfma_f32_16x16x32_bf16 v[100:103], v[224:227], v[196:199], v[100:103]
	v_mfma_f32_16x16x32_bf16 v[96:99], v[224:227], v[204:207], v[96:99]
	v_mfma_f32_16x16x32_bf16 v[84:87], v[232:235], v[196:199], v[84:87]
	v_mfma_f32_16x16x32_bf16 v[80:83], v[232:235], v[204:207], v[80:83]
	v_mfma_f32_16x16x32_bf16 v[68:71], v[240:243], v[196:199], v[68:71]
	v_mfma_f32_16x16x32_bf16 v[64:67], v[240:243], v[204:207], v[64:67]
	s_setprio 0
	s_barrier
; #define STAGE(P, g) do { const char* g_ = (const char*)(g); \
;         __builtin_amdgcn_global_load_lds((const unsigned*)(g_ + so0), (lds_u32*)((lds_u8*)(P) + sb0), 16, 0, 0); \
;         __builtin_amdgcn_global_load_lds((const unsigned*)(g_ + so1), (lds_u32*)((lds_u8*)(P) + sb0 + 8192), 16, 0, 0); } while (0)
; #define LDA(dst, b, h) for (int m = 0; m < 4; ++m) for (int k = 0; k < 2; ++k) \
;         dst[m][k] = *reinterpret_cast<const bf16x8*>((char*)SA(b, h) + lds_byte(wr * 64 + m * 16 + fr, k * 32 + fq * 8))
; #define MMA(ai, bj, At_, Bt_) do { __builtin_amdgcn_s_setprio(1); \
;         for (int m = 0; m < 4; ++m) for (int n = 0; n < 2; ++n) for (int k = 0; k < 2; ++k) \
;             acc[ai][bj][m][n] = __builtin_amdgcn_mfma_f32_16x16x32_bf16(At_[m][k], Bt_[n][k], acc[ai][bj][m][n], 0, 0, 0); \
;         __builtin_amdgcn_s_setprio(0); } while (0)
; #define WAIT_V(n) asm volatile("s_waitcnt vmcnt(" #n ")" ::: "memory")
; #define WAIT_L(n) asm volatile("s_waitcnt lgkmcnt(" #n ")" ::: "memory")
; #define BAR __builtin_amdgcn_s_barrier()
; #define SCHED __builtin_amdgcn_sched_barrier(0)
; template <int EPI, int K, int LNI = -1>
; DI void ph_gemm(const Params& p, const bf16_t* __restrict__ A, const bf16_t* __restrict__ Bt, int N, float* s_aux) {
;     ...
;             LDA(At, 1, 1); STAGE(SB(1, 0), b3); STAGE(SB(1, 1), b3 + hstep); STAGE(SA(1, 0), a3);
;             WAIT_V(8); WAIT_L(0); BAR; MMA(1, 0, At, B0); MMA(1, 1, At, B1); BAR; SCHED;
;         }
;         if (wr == 0) BAR;
	v_readfirstlane_b32 s52, v166
	v_lshl_add_u64 v[208:209], v[208:209], 0, s[26:27]
	s_mov_b32 m0, s52
	v_readfirstlane_b32 s52, v167
	s_add_u32 s14, s14, 0x40080
	ds_read_b128 v[212:215], v185 offset:49152
	ds_read_b128 v[216:219], v185 offset:50176
	ds_read_b128 v[220:223], v186 offset:49152
	ds_read_b128 v[224:227], v186 offset:50176
	ds_read_b128 v[228:231], v187 offset:49152
	ds_read_b128 v[232:235], v187 offset:50176
	ds_read_b128 v[236:239], v188 offset:49152
	ds_read_b128 v[240:243], v188 offset:50176
	global_load_lds_dwordx4 v[208:209], off
	v_lshl_add_u64 v[208:209], v[244:245], 0, s[26:27]
	s_mov_b32 m0, s52
	s_addc_u32 s15, s15, 0
	v_readfirstlane_b32 s52, v170
	global_load_lds_dwordx4 v[208:209], off
	v_lshl_add_u64 v[208:209], s[14:15], 0, v[136:137]
	s_mov_b32 m0, s52
	s_nop 0
	global_load_lds_dwordx4 v[208:209], off
	v_lshl_add_u64 v[208:209], s[14:15], 0, v[138:139]
	v_readfirstlane_b32 s14, v171
	s_mov_b32 m0, s14
	v_readfirstlane_b32 s14, v168
	global_load_lds_dwordx4 v[208:209], off
	v_lshl_add_u64 v[208:209], v[246:247], 0, s[26:27]
	s_mov_b32 m0, s14
	v_readfirstlane_b32 s14, v169
	global_load_lds_dwordx4 v[208:209], off
	v_lshl_add_u64 v[208:209], v[248:249], 0, s[26:27]
	s_mov_b32 m0, s14
	s_nop 0
	global_load_lds_dwordx4 v[208:209], off
	s_waitcnt vmcnt(8)
	s_waitcnt lgkmcnt(0)
	s_barrier
	s_setprio 1
	s_waitcnt lgkmcnt(0)
	v_mfma_f32_16x16x32_bf16 v[60:63], v[212:215], v[132:135], v[60:63]
	v_mfma_f32_16x16x32_bf16 v[56:59], v[212:215], v[150:153], v[56:59]
	v_mfma_f32_16x16x32_bf16 v[44:47], v[220:223], v[132:135], v[44:47]
	v_mfma_f32_16x16x32_bf16 v[40:43], v[220:223], v[150:153], v[40:43]
	v_mfma_f32_16x16x32_bf16 v[28:31], v[228:231], v[132:135], v[28:31]
	v_mfma_f32_16x16x32_bf16 v[24:27], v[228:231], v[150:153], v[24:27]
	v_mfma_f32_16x16x32_bf16 v[12:15], v[236:239], v[132:135], v[12:15]
	v_mfma_f32_16x16x32_bf16 v[8:11], v[236:239], v[150:153], v[8:11]
	v_mfma_f32_16x16x32_bf16 v[60:63], v[216:219], v[146:149], v[60:63]
	v_mfma_f32_16x16x32_bf16 v[56:59], v[216:219], v[154:157], v[56:59]
	v_mfma_f32_16x16x32_bf16 v[44:47], v[224:227], v[146:149], v[44:47]
	v_mfma_f32_16x16x32_bf16 v[40:43], v[224:227], v[154:157], v[40:43]
	v_mfma_f32_16x16x32_bf16 v[28:31], v[232:235], v[146:149], v[28:31]
	v_mfma_f32_16x16x32_bf16 v[24:27], v[232:235], v[154:157], v[24:27]
	v_mfma_f32_16x16x32_bf16 v[12:15], v[240:243], v[146:149], v[12:15]
	v_mfma_f32_16x16x32_bf16 v[8:11], v[240:243], v[154:157], v[8:11]
	s_setprio 0
	s_setprio 1
	v_mfma_f32_16x16x32_bf16 v[52:55], v[212:215], v[192:195], v[52:55]
	v_mfma_f32_16x16x32_bf16 v[48:51], v[212:215], v[200:203], v[48:51]
	v_mfma_f32_16x16x32_bf16 v[36:39], v[220:223], v[192:195], v[36:39]
	v_mfma_f32_16x16x32_bf16 v[32:35], v[220:223], v[200:203], v[32:35]
	v_mfma_f32_16x16x32_bf16 v[20:23], v[228:231], v[192:195], v[20:23]
	v_mfma_f32_16x16x32_bf16 v[16:19], v[228:231], v[200:203], v[16:19]
	v_mfma_f32_16x16x32_bf16 v[4:7], v[236:239], v[192:195], v[4:7]
	v_mfma_f32_16x16x32_bf16 v[0:3], v[236:239], v[200:203], v[0:3]
	v_mfma_f32_16x16x32_bf16 v[52:55], v[216:219], v[196:199], v[52:55]
	v_mfma_f32_16x16x32_bf16 v[48:51], v[216:219], v[204:207], v[48:51]
	v_mfma_f32_16x16x32_bf16 v[36:39], v[224:227], v[196:199], v[36:39]
	v_mfma_f32_16x16x32_bf16 v[32:35], v[224:227], v[204:207], v[32:35]
	v_mfma_f32_16x16x32_bf16 v[20:23], v[232:235], v[196:199], v[20:23]
	v_mfma_f32_16x16x32_bf16 v[16:19], v[232:235], v[204:207], v[16:19]
	v_mfma_f32_16x16x32_bf16 v[4:7], v[240:243], v[196:199], v[4:7]
	v_mfma_f32_16x16x32_bf16 v[0:3], v[240:243], v[204:207], v[0:3]
	s_setprio 0
	s_add_i32 s76, s76, 2
	s_add_u32 s12, s12, 0x100
	s_addc_u32 s13, s13, 0
	s_cmp_gt_u32 s76, 13
	s_barrier
	s_cbranch_scc0 .LBB0_1636
	s_and_saveexec_b64 s[12:13], s[8:9]
	s_cbranch_execz .LBB0_1639
	s_barrier

; #define STAGE(P, g) do { const char* g_ = (const char*)(g); \
;         __builtin_amdgcn_global_load_lds((const unsigned*)(g_ + so0), (lds_u32*)((lds_u8*)(P) + sb0), 16, 0, 0); \
;         __builtin_amdgcn_global_load_lds((const unsigned*)(g_ + so1), (lds_u32*)((lds_u8*)(P) + sb0 + 8192), 16, 0, 0); } while (0)
; #define LDA(dst, b, h) for (int m = 0; m < 4; ++m) for (int k = 0; k < 2; ++k) \
;         dst[m][k] = *reinterpret_cast<const bf16x8*>((char*)SA(b, h) + lds_byte(wr * 64 + m * 16 + fr, k * 32 + fq * 8))
; #define LDB(dst, b, h) for (int n = 0; n < 2; ++n) for (int k = 0; k < 2; ++k) \
;         dst[n][k] = *reinterpret_cast<const bf16x8*>((char*)SB(b, h) + lds_byte(wc * 32 + n * 16 + fr, k * 32 + fq * 8))
; #define MMA(ai, bj, At_, Bt_) do { __builtin_amdgcn_s_setprio(1); \
;         for (int m = 0; m < 4; ++m) for (int n = 0; n < 2; ++n) for (int k = 0; k < 2; ++k) \
;             acc[ai][bj][m][n] = __builtin_amdgcn_mfma_f32_16x16x32_bf16(At_[m][k], Bt_[n][k], acc[ai][bj][m][n], 0, 0, 0); \
;         __builtin_amdgcn_s_setprio(0); } while (0)
; #define WAIT_V(n) asm volatile("s_waitcnt vmcnt(" #n ")" ::: "memory")
; #define WAIT_L(n) asm volatile("s_waitcnt lgkmcnt(" #n ")" ::: "memory")
; #define BAR __builtin_amdgcn_s_barrier()
; #define SCHED __builtin_amdgcn_sched_barrier(0)
; template <int EPI, int K, int LNI = -1>
; DI void ph_gemm(const Params& p, const bf16_t* __restrict__ A, const bf16_t* __restrict__ Bt, int N, float* s_aux) {
;     ...
;         for (int t = 0; t < nt; t += 2) {
;             const bool last = (t == nt - 2);
;             const bf16_t* a1 = cA + (size_t)(t + 1) * kstep;
;             const bf16_t* a2 = last ? nA : cA + (size_t)(t + 2) * kstep; const bf16_t* b2 = last ? nB : cB + (size_t)(t + 2) * kstep;
;             const bf16_t* a3 = a2 + kstep; const bf16_t* b3 = b2 + kstep;
;             LDB(B0, 0, 0); LDB(B1, 0, 1); SCHED; LDA(At, 0, 0); STAGE(SA(1, 1), a1 + hstep);
;             WAIT_V(8); WAIT_L(0); BAR; MMA(0, 0, At, B0); MMA(0, 1, At, B1); BAR; SCHED;
;             LDA(At, 0, 1); STAGE(SB(0, 0), b2); STAGE(SB(0, 1), b2 + hstep); STAGE(SA(0, 0), a2);
;             WAIT_V(8); WAIT_L(0); BAR; MMA(1, 0, At, B0); MMA(1, 1, At, B1); BAR; SCHED;
.LBB0_1716:
	s_ashr_i32 s21, s20, 31
	s_lshl_b64 s[22:23], s[20:21], 20
	s_add_u32 s21, s36, s22
	s_addc_u32 s52, s37, s23
	s_ashr_i32 s15, s14, 31
	s_lshl_b64 s[24:25], s[14:15], 20
	s_add_u32 s15, s3, s24
	s_addc_u32 s53, s35, s25
	s_add_u32 s60, s56, s42
	s_addc_u32 s61, s57, s43
	s_add_u32 s66, s48, s44
	v_lshl_add_u64 v[128:129], v[140:141], 0, s[42:43]
	v_lshl_add_u64 v[130:131], v[142:143], 0, s[42:43]
	s_addc_u32 s67, s49, s45
	s_mov_b32 s68, -2
	s_mov_b64 s[42:43], 0
	ds_read_b128 v[132:135], v177
	ds_read_b128 v[144:147], v177 offset:1024
	ds_read_b128 v[148:151], v177 offset:2048
	ds_read_b128 v[152:155], v177 offset:3072
	ds_read_b128 v[156:159], v178
	ds_read_b128 v[188:191], v178 offset:1024
	ds_read_b128 v[192:195], v178 offset:2048
	ds_read_b128 v[196:199], v178 offset:3072
	s_add_u32 s44, s60, s42
	s_addc_u32 s45, s61, s43
	s_add_u32 s44, s44, 0xfa70100
	s_addc_u32 s45, s45, 0
	s_add_u32 s69, s66, s42
	s_addc_u32 s70, s67, s43
	s_cmpk_eq_i32 s42, 0xf00
	s_cselect_b32 s47, s52, s45
	s_cselect_b32 s46, s21, s44
	s_cselect_b32 s45, s53, s70
	s_cselect_b32 s44, s15, s69
	v_readfirstlane_b32 s69, v183
	v_lshl_add_u64 v[208:209], v[128:129], 0, s[42:43]
	s_mov_b32 m0, s69
	v_readfirstlane_b32 s69, v184
	ds_read_b128 v[200:203], v179
	ds_read_b128 v[204:207], v179 offset:1024
	ds_read_b128 v[212:215], v180
	ds_read_b128 v[216:219], v180 offset:1024
	ds_read_b128 v[220:223], v181
	ds_read_b128 v[224:227], v181 offset:1024
	ds_read_b128 v[228:231], v182
	ds_read_b128 v[232:235], v182 offset:1024
	global_load_lds_dwordx4 v[208:209], off
	v_lshl_add_u64 v[208:209], v[130:131], 0, s[42:43]
	s_mov_b32 m0, s69
	s_nop 0
	global_load_lds_dwordx4 v[208:209], off
	s_waitcnt vmcnt(8)
	s_waitcnt lgkmcnt(0)
	s_barrier
	s_setprio 1
	s_waitcnt lgkmcnt(0)
	v_mfma_f32_16x16x32_bf16 v[124:127], v[200:203], v[132:135], 0
	v_mfma_f32_16x16x32_bf16 v[120:123], v[200:203], v[148:151], 0
	v_mfma_f32_16x16x32_bf16 v[108:111], v[212:215], v[132:135], 0
	v_mfma_f32_16x16x32_bf16 v[104:107], v[212:215], v[148:151], 0
	v_mfma_f32_16x16x32_bf16 v[92:95], v[220:223], v[132:135], 0
	v_mfma_f32_16x16x32_bf16 v[88:91], v[220:223], v[148:151], 0
	v_mfma_f32_16x16x32_bf16 v[76:79], v[228:231], v[132:135], 0
	v_mfma_f32_16x16x32_bf16 v[72:75], v[228:231], v[148:151], 0
	v_mfma_f32_16x16x32_bf16 v[124:127], v[204:207], v[144:147], v[124:127]
	v_mfma_f32_16x16x32_bf16 v[120:123], v[204:207], v[152:155], v[120:123]
	v_mfma_f32_16x16x32_bf16 v[108:111], v[216:219], v[144:147], v[108:111]
	v_mfma_f32_16x16x32_bf16 v[104:107], v[216:219], v[152:155], v[104:107]
	v_mfma_f32_16x16x32_bf16 v[92:95], v[224:227], v[144:147], v[92:95]
	v_mfma_f32_16x16x32_bf16 v[88:91], v[224:227], v[152:155], v[88:91]
	v_mfma_f32_16x16x32_bf16 v[76:79], v[232:235], v[144:147], v[76:79]
	v_mfma_f32_16x16x32_bf16 v[72:75], v[232:235], v[152:155], v[72:75]
	s_setprio 0
	s_setprio 1
	v_mfma_f32_16x16x32_bf16 v[116:119], v[200:203], v[156:159], 0
	v_mfma_f32_16x16x32_bf16 v[112:115], v[200:203], v[192:195], 0
	v_mfma_f32_16x16x32_bf16 v[100:103], v[212:215], v[156:159], 0
	v_mfma_f32_16x16x32_bf16 v[96:99], v[212:215], v[192:195], 0
	v_mfma_f32_16x16x32_bf16 v[84:87], v[220:223], v[156:159], 0
	v_mfma_f32_16x16x32_bf16 v[80:83], v[220:223], v[192:195], 0
	v_mfma_f32_16x16x32_bf16 v[68:71], v[228:231], v[156:159], 0
	v_mfma_f32_16x16x32_bf16 v[64:67], v[228:231], v[192:195], 0
	v_mfma_f32_16x16x32_bf16 v[116:119], v[204:207], v[188:191], v[116:119]
	v_mfma_f32_16x16x32_bf16 v[112:115], v[204:207], v[196:199], v[112:115]
	v_mfma_f32_16x16x32_bf16 v[100:103], v[216:219], v[188:191], v[100:103]
	v_mfma_f32_16x16x32_bf16 v[96:99], v[216:219], v[196:199], v[96:99]
	v_mfma_f32_16x16x32_bf16 v[84:87], v[224:227], v[188:191], v[84:87]
	v_mfma_f32_16x16x32_bf16 v[80:83], v[224:227], v[196:199], v[80:83]
	v_mfma_f32_16x16x32_bf16 v[68:71], v[232:235], v[188:191], v[68:71]
	v_mfma_f32_16x16x32_bf16 v[64:67], v[232:235], v[196:199], v[64:67]
	s_setprio 0
	s_barrier
	v_readfirstlane_b32 s69, v160
	v_lshl_add_u64 v[208:209], s[44:45], 0, v[136:137]
	s_mov_b32 m0, s69
	v_readfirstlane_b32 s69, v161
	s_add_u32 s70, s44, 0x80000
	ds_read_b128 v[200:203], v179 offset:16384
	ds_read_b128 v[204:207], v179 offset:17408
	ds_read_b128 v[212:215], v180 offset:16384
	ds_read_b128 v[216:219], v180 offset:17408
	ds_read_b128 v[220:223], v181 offset:16384
	ds_read_b128 v[224:227], v181 offset:17408
	ds_read_b128 v[228:231], v182 offset:16384
	ds_read_b128 v[232:235], v182 offset:17408
	global_load_lds_dwordx4 v[208:209], off
	v_lshl_add_u64 v[236:237], s[44:45], 0, v[138:139]
	s_mov_b32 m0, s69
	s_addc_u32 s71, s45, 0
	v_readfirstlane_b32 s69, v162
	global_load_lds_dwordx4 v[236:237], off
	v_lshl_add_u64 v[238:239], s[70:71], 0, v[136:137]
	s_mov_b32 m0, s69
	v_readfirstlane_b32 s69, v163
	global_load_lds_dwordx4 v[238:239], off
	v_lshl_add_u64 v[238:239], s[70:71], 0, v[138:139]
	s_mov_b32 m0, s69
	v_readfirstlane_b32 s69, v164
	global_load_lds_dwordx4 v[238:239], off
	v_lshl_add_u64 v[238:239], s[46:47], 0, v[136:137]
	s_mov_b32 m0, s69
	v_readfirstlane_b32 s69, v165
	global_load_lds_dwordx4 v[238:239], off
	v_lshl_add_u64 v[240:241], s[46:47], 0, v[138:139]
	s_mov_b32 m0, s69
	s_nop 0
	global_load_lds_dwordx4 v[240:241], off
	s_waitcnt vmcnt(8)
	s_waitcnt lgkmcnt(0)
	s_barrier
; #define STAGE(P, g) do { const char* g_ = (const char*)(g); \
;         __builtin_amdgcn_global_load_lds((const unsigned*)(g_ + so0), (lds_u32*)((lds_u8*)(P) + sb0), 16, 0, 0); \
;         __builtin_amdgcn_global_load_lds((const unsigned*)(g_ + so1), (lds_u32*)((lds_u8*)(P) + sb0 + 8192), 16, 0, 0); } while (0)
; #define LDA(dst, b, h) for (int m = 0; m < 4; ++m) for (int k = 0; k < 2; ++k) \
;         dst[m][k] = *reinterpret_cast<const bf16x8*>((char*)SA(b, h) + lds_byte(wr * 64 + m * 16 + fr, k * 32 + fq * 8))
; #define LDB(dst, b, h) for (int n = 0; n < 2; ++n) for (int k = 0; k < 2; ++k) \
;         dst[n][k] = *reinterpret_cast<const bf16x8*>((char*)SB(b, h) + lds_byte(wc * 32 + n * 16 + fr, k * 32 + fq * 8))
; #define MMA(ai, bj, At_, Bt_) do { __builtin_amdgcn_s_setprio(1); \
;         for (int m = 0; m < 4; ++m) for (int n = 0; n < 2; ++n) for (int k = 0; k < 2; ++k) \
;             acc[ai][bj][m][n] = __builtin_amdgcn_mfma_f32_16x16x32_bf16(At_[m][k], Bt_[n][k], acc[ai][bj][m][n], 0, 0, 0); \
;         __builtin_amdgcn_s_setprio(0); } while (0)
; #define WAIT_V(n) asm volatile("s_waitcnt vmcnt(" #n ")" ::: "memory")
; #define WAIT_L(n) asm volatile("s_waitcnt lgkmcnt(" #n ")" ::: "memory")
; #define BAR __builtin_amdgcn_s_barrier()
; #define SCHED __builtin_amdgcn_sched_barrier(0)
; template <int EPI, int K, int LNI = -1>
; DI void ph_gemm(const Params& p, const bf16_t* __restrict__ A, const bf16_t* __restrict__ Bt, int N, float* s_aux) {
;     ...
;             WAIT_V(8); WAIT_L(0); BAR; MMA(0, 0, At, B0); MMA(0, 1, At, B1); BAR; SCHED;
;             LDA(At, 0, 1); STAGE(SB(0, 0), b2); STAGE(SB(0, 1), b2 + hstep); STAGE(SA(0, 0), a2);
;             WAIT_V(8); WAIT_L(0); BAR; MMA(1, 0, At, B0); MMA(1, 1, At, B1); BAR; SCHED;
;             LDB(B0, 1, 0); LDB(B1, 1, 1); SCHED; LDA(At, 1, 0); STAGE(SA(0, 1), a2 + hstep);
;             WAIT_V(8); WAIT_L(0); BAR; MMA(0, 0, At, B0); MMA(0, 1, At, B1); BAR; SCHED;
;             LDA(At, 1, 1); STAGE(SB(1, 0), b3); STAGE(SB(1, 1), b3 + hstep); STAGE(SA(1, 0), a3);
;             WAIT_V(8); WAIT_L(0); BAR; MMA(1, 0, At, B0); MMA(1, 1, At, B1); BAR; SCHED;
	s_setprio 1
	s_waitcnt lgkmcnt(0)
	v_mfma_f32_16x16x32_bf16 v[60:63], v[200:203], v[132:135], 0
	v_mfma_f32_16x16x32_bf16 v[56:59], v[200:203], v[148:151], 0
	v_mfma_f32_16x16x32_bf16 v[44:47], v[212:215], v[132:135], 0
	v_mfma_f32_16x16x32_bf16 v[40:43], v[212:215], v[148:151], 0
	v_mfma_f32_16x16x32_bf16 v[28:31], v[220:223], v[132:135], 0
	v_mfma_f32_16x16x32_bf16 v[24:27], v[220:223], v[148:151], 0
	v_mfma_f32_16x16x32_bf16 v[12:15], v[228:231], v[132:135], 0
	v_mfma_f32_16x16x32_bf16 v[8:11], v[228:231], v[148:151], 0
	v_mfma_f32_16x16x32_bf16 v[60:63], v[204:207], v[144:147], v[60:63]
	v_mfma_f32_16x16x32_bf16 v[56:59], v[204:207], v[152:155], v[56:59]
	v_mfma_f32_16x16x32_bf16 v[44:47], v[216:219], v[144:147], v[44:47]
	v_mfma_f32_16x16x32_bf16 v[40:43], v[216:219], v[152:155], v[40:43]
	v_mfma_f32_16x16x32_bf16 v[28:31], v[224:227], v[144:147], v[28:31]
	v_mfma_f32_16x16x32_bf16 v[24:27], v[224:227], v[152:155], v[24:27]
	v_mfma_f32_16x16x32_bf16 v[12:15], v[232:235], v[144:147], v[12:15]
	v_mfma_f32_16x16x32_bf16 v[8:11], v[232:235], v[152:155], v[8:11]
	s_setprio 0
	s_setprio 1
	v_mfma_f32_16x16x32_bf16 v[52:55], v[200:203], v[156:159], 0
	v_mfma_f32_16x16x32_bf16 v[48:51], v[200:203], v[192:195], 0
	v_mfma_f32_16x16x32_bf16 v[36:39], v[212:215], v[156:159], 0
	v_mfma_f32_16x16x32_bf16 v[32:35], v[212:215], v[192:195], 0
	v_mfma_f32_16x16x32_bf16 v[20:23], v[220:223], v[156:159], 0
	v_mfma_f32_16x16x32_bf16 v[16:19], v[220:223], v[192:195], 0
	v_mfma_f32_16x16x32_bf16 v[4:7], v[228:231], v[156:159], 0
	v_mfma_f32_16x16x32_bf16 v[0:3], v[228:231], v[192:195], 0
	v_mfma_f32_16x16x32_bf16 v[52:55], v[204:207], v[188:191], v[52:55]
	v_mfma_f32_16x16x32_bf16 v[48:51], v[204:207], v[196:199], v[48:51]
	v_mfma_f32_16x16x32_bf16 v[36:39], v[216:219], v[188:191], v[36:39]
	v_mfma_f32_16x16x32_bf16 v[32:35], v[216:219], v[196:199], v[32:35]
	v_mfma_f32_16x16x32_bf16 v[20:23], v[224:227], v[188:191], v[20:23]
	v_mfma_f32_16x16x32_bf16 v[16:19], v[224:227], v[196:199], v[16:19]
	v_mfma_f32_16x16x32_bf16 v[4:7], v[232:235], v[188:191], v[4:7]
	v_mfma_f32_16x16x32_bf16 v[0:3], v[232:235], v[196:199], v[0:3]
	s_setprio 0
	s_barrier
	ds_read_b128 v[132:135], v185
	ds_read_b128 v[144:147], v185 offset:1024
	ds_read_b128 v[148:151], v185 offset:2048
	ds_read_b128 v[152:155], v185 offset:3072
	ds_read_b128 v[156:159], v186
	ds_read_b128 v[188:191], v186 offset:1024
	ds_read_b128 v[192:195], v186 offset:2048
	ds_read_b128 v[196:199], v186 offset:3072
	s_add_u32 s46, s46, 0x80000
	s_addc_u32 s47, s47, 0
	v_readfirstlane_b32 s69, v166
	v_lshl_add_u64 v[242:243], s[46:47], 0, v[136:137]
	s_mov_b32 m0, s69
	ds_read_b128 v[200:203], v179 offset:32768
	ds_read_b128 v[204:207], v179 offset:33792
	ds_read_b128 v[212:215], v180 offset:32768
	ds_read_b128 v[216:219], v180 offset:33792
	ds_read_b128 v[220:223], v181 offset:32768
	ds_read_b128 v[224:227], v181 offset:33792
	ds_read_b128 v[228:231], v182 offset:32768
	ds_read_b128 v[232:235], v182 offset:33792
	global_load_lds_dwordx4 v[242:243], off
	v_lshl_add_u64 v[242:243], s[46:47], 0, v[138:139]
	v_readfirstlane_b32 s46, v167
	s_mov_b32 m0, s46
	s_nop 0
	global_load_lds_dwordx4 v[242:243], off
	s_waitcnt vmcnt(8)
	s_waitcnt lgkmcnt(0)
	s_barrier
	s_setprio 1
	s_waitcnt lgkmcnt(0)
	v_mfma_f32_16x16x32_bf16 v[124:127], v[200:203], v[132:135], v[124:127]
	v_mfma_f32_16x16x32_bf16 v[120:123], v[200:203], v[148:151], v[120:123]
	v_mfma_f32_16x16x32_bf16 v[108:111], v[212:215], v[132:135], v[108:111]
	v_mfma_f32_16x16x32_bf16 v[104:107], v[212:215], v[148:151], v[104:107]
	v_mfma_f32_16x16x32_bf16 v[92:95], v[220:223], v[132:135], v[92:95]
	v_mfma_f32_16x16x32_bf16 v[88:91], v[220:223], v[148:151], v[88:91]
	v_mfma_f32_16x16x32_bf16 v[76:79], v[228:231], v[132:135], v[76:79]
	v_mfma_f32_16x16x32_bf16 v[72:75], v[228:231], v[148:151], v[72:75]
	v_mfma_f32_16x16x32_bf16 v[124:127], v[204:207], v[144:147], v[124:127]
	v_mfma_f32_16x16x32_bf16 v[120:123], v[204:207], v[152:155], v[120:123]
	v_mfma_f32_16x16x32_bf16 v[108:111], v[216:219], v[144:147], v[108:111]
	v_mfma_f32_16x16x32_bf16 v[104:107], v[216:219], v[152:155], v[104:107]
	v_mfma_f32_16x16x32_bf16 v[92:95], v[224:227], v[144:147], v[92:95]
	v_mfma_f32_16x16x32_bf16 v[88:91], v[224:227], v[152:155], v[88:91]
	v_mfma_f32_16x16x32_bf16 v[76:79], v[232:235], v[144:147], v[76:79]
	v_mfma_f32_16x16x32_bf16 v[72:75], v[232:235], v[152:155], v[72:75]
	s_setprio 0
	s_setprio 1
	v_mfma_f32_16x16x32_bf16 v[116:119], v[200:203], v[156:159], v[116:119]
	v_mfma_f32_16x16x32_bf16 v[112:115], v[200:203], v[192:195], v[112:115]
	v_mfma_f32_16x16x32_bf16 v[100:103], v[212:215], v[156:159], v[100:103]
	v_mfma_f32_16x16x32_bf16 v[96:99], v[212:215], v[192:195], v[96:99]
	v_mfma_f32_16x16x32_bf16 v[84:87], v[220:223], v[156:159], v[84:87]
	v_mfma_f32_16x16x32_bf16 v[80:83], v[220:223], v[192:195], v[80:83]
	v_mfma_f32_16x16x32_bf16 v[68:71], v[228:231], v[156:159], v[68:71]
	v_mfma_f32_16x16x32_bf16 v[64:67], v[228:231], v[192:195], v[64:67]
	v_mfma_f32_16x16x32_bf16 v[116:119], v[204:207], v[188:191], v[116:119]
	v_mfma_f32_16x16x32_bf16 v[112:115], v[204:207], v[196:199], v[112:115]
	v_mfma_f32_16x16x32_bf16 v[100:103], v[216:219], v[188:191], v[100:103]
	v_mfma_f32_16x16x32_bf16 v[96:99], v[216:219], v[196:199], v[96:99]
	v_mfma_f32_16x16x32_bf16 v[84:87], v[224:227], v[188:191], v[84:87]
	v_mfma_f32_16x16x32_bf16 v[80:83], v[224:227], v[196:199], v[80:83]
	v_mfma_f32_16x16x32_bf16 v[68:71], v[232:235], v[188:191], v[68:71]
	v_mfma_f32_16x16x32_bf16 v[64:67], v[232:235], v[196:199], v[64:67]
	s_setprio 0
	s_barrier
; #define STAGE(P, g) do { const char* g_ = (const char*)(g); \
;         __builtin_amdgcn_global_load_lds((const unsigned*)(g_ + so0), (lds_u32*)((lds_u8*)(P) + sb0), 16, 0, 0); \
;         __builtin_amdgcn_global_load_lds((const unsigned*)(g_ + so1), (lds_u32*)((lds_u8*)(P) + sb0 + 8192), 16, 0, 0); } while (0)
; #define LDA(dst, b, h) for (int m = 0; m < 4; ++m) for (int k = 0; k < 2; ++k) \
;         dst[m][k] = *reinterpret_cast<const bf16x8*>((char*)SA(b, h) + lds_byte(wr * 64 + m * 16 + fr, k * 32 + fq * 8))
; #define LDB(dst, b, h) for (int n = 0; n < 2; ++n) for (int k = 0; k < 2; ++k) \
;         dst[n][k] = *reinterpret_cast<const bf16x8*>((char*)SB(b, h) + lds_byte(wc * 32 + n * 16 + fr, k * 32 + fq * 8))
; #define MMA(ai, bj, At_, Bt_) do { __builtin_amdgcn_s_setprio(1); \
;         for (int m = 0; m < 4; ++m) for (int n = 0; n < 2; ++n) for (int k = 0; k < 2; ++k) \
;             acc[ai][bj][m][n] = __builtin_amdgcn_mfma_f32_16x16x32_bf16(At_[m][k], Bt_[n][k], acc[ai][bj][m][n], 0, 0, 0); \
;         __builtin_amdgcn_s_setprio(0); } while (0)
; template <int EPI, int K, int LNI = -1>
; DI void ph_gemm(const Params& p, const bf16_t* __restrict__ A, const bf16_t* __restrict__ Bt, int N, float* s_aux) {
;     ...
;         for (int t = 0; t < nt; t += 2) {
;             const bool last = (t == nt - 2);
;             const bf16_t* a1 = cA + (size_t)(t + 1) * kstep;
;             const bf16_t* a2 = last ? nA : cA + (size_t)(t + 2) * kstep; const bf16_t* b2 = last ? nB : cB + (size_t)(t + 2) * kstep;
;             const bf16_t* a3 = a2 + kstep; const bf16_t* b3 = b2 + kstep;
;             LDB(B0, 0, 0); LDB(B1, 0, 1); SCHED; LDA(At, 0, 0); STAGE(SA(1, 1), a1 + hstep);
;             WAIT_V(8); WAIT_L(0); BAR; MMA(0, 0, At, B0); MMA(0, 1, At, B1); BAR; SCHED;
;             LDA(At, 0, 1); STAGE(SB(0, 0), b2); STAGE(SB(0, 1), b2 + hstep); STAGE(SA(0, 0), a2);
;             WAIT_V(8); WAIT_L(0); BAR; MMA(1, 0, At, B0); MMA(1, 1, At, B1); BAR; SCHED;
;             LDB(B0, 1, 0); LDB(B1, 1, 1); SCHED; LDA(At, 1, 0); STAGE(SA(0, 1), a2 + hstep);
;             WAIT_V(8); WAIT_L(0); BAR; MMA(0, 0, At, B0); MMA(0, 1, At, B1); BAR; SCHED;
;             LDA(At, 1, 1); STAGE(SB(1, 0), b3); STAGE(SB(1, 1), b3 + hstep); STAGE(SA(1, 0), a3);
;             WAIT_V(8); WAIT_L(0); BAR; MMA(1, 0, At, B0); MMA(1, 1, At, B1); BAR; SCHED;
;         }
	v_readfirstlane_b32 s46, v168
	v_lshl_add_u64 v[208:209], v[208:209], 0, s[10:11]
	s_mov_b32 m0, s46
	v_readfirstlane_b32 s46, v169
	s_add_u32 s44, s44, 0x80080
	ds_read_b128 v[200:203], v179 offset:49152
	ds_read_b128 v[204:207], v179 offset:50176
	ds_read_b128 v[212:215], v180 offset:49152
	ds_read_b128 v[216:219], v180 offset:50176
	ds_read_b128 v[220:223], v181 offset:49152
	ds_read_b128 v[224:227], v181 offset:50176
	ds_read_b128 v[228:231], v182 offset:49152
	ds_read_b128 v[232:235], v182 offset:50176
	global_load_lds_dwordx4 v[208:209], off
	v_lshl_add_u64 v[208:209], v[236:237], 0, s[10:11]
	s_mov_b32 m0, s46
	s_addc_u32 s45, s45, 0
	v_readfirstlane_b32 s46, v172
	global_load_lds_dwordx4 v[208:209], off
	v_lshl_add_u64 v[208:209], s[44:45], 0, v[136:137]
	s_mov_b32 m0, s46
	s_nop 0
	global_load_lds_dwordx4 v[208:209], off
	v_lshl_add_u64 v[208:209], s[44:45], 0, v[138:139]
	v_readfirstlane_b32 s44, v173
	s_mov_b32 m0, s44
	v_readfirstlane_b32 s44, v170
	global_load_lds_dwordx4 v[208:209], off
	v_lshl_add_u64 v[208:209], v[238:239], 0, s[10:11]
	s_mov_b32 m0, s44
	v_readfirstlane_b32 s44, v171
	global_load_lds_dwordx4 v[208:209], off
	v_lshl_add_u64 v[208:209], v[240:241], 0, s[10:11]
	s_mov_b32 m0, s44
	s_nop 0
	global_load_lds_dwordx4 v[208:209], off
	s_waitcnt vmcnt(8)
	s_waitcnt lgkmcnt(0)
	s_barrier
	s_setprio 1
	s_waitcnt lgkmcnt(0)
	v_mfma_f32_16x16x32_bf16 v[60:63], v[200:203], v[132:135], v[60:63]
	v_mfma_f32_16x16x32_bf16 v[56:59], v[200:203], v[148:151], v[56:59]
	v_mfma_f32_16x16x32_bf16 v[44:47], v[212:215], v[132:135], v[44:47]
	v_mfma_f32_16x16x32_bf16 v[40:43], v[212:215], v[148:151], v[40:43]
	v_mfma_f32_16x16x32_bf16 v[28:31], v[220:223], v[132:135], v[28:31]
	v_mfma_f32_16x16x32_bf16 v[24:27], v[220:223], v[148:151], v[24:27]
	v_mfma_f32_16x16x32_bf16 v[12:15], v[228:231], v[132:135], v[12:15]
	v_mfma_f32_16x16x32_bf16 v[8:11], v[228:231], v[148:151], v[8:11]
	v_mfma_f32_16x16x32_bf16 v[60:63], v[204:207], v[144:147], v[60:63]
	v_mfma_f32_16x16x32_bf16 v[56:59], v[204:207], v[152:155], v[56:59]
	v_mfma_f32_16x16x32_bf16 v[44:47], v[216:219], v[144:147], v[44:47]
	v_mfma_f32_16x16x32_bf16 v[40:43], v[216:219], v[152:155], v[40:43]
	v_mfma_f32_16x16x32_bf16 v[28:31], v[224:227], v[144:147], v[28:31]
	v_mfma_f32_16x16x32_bf16 v[24:27], v[224:227], v[152:155], v[24:27]
	v_mfma_f32_16x16x32_bf16 v[12:15], v[232:235], v[144:147], v[12:15]
	v_mfma_f32_16x16x32_bf16 v[8:11], v[232:235], v[152:155], v[8:11]
	s_setprio 0
	s_setprio 1
	v_mfma_f32_16x16x32_bf16 v[52:55], v[200:203], v[156:159], v[52:55]
	v_mfma_f32_16x16x32_bf16 v[48:51], v[200:203], v[192:195], v[48:51]
	v_mfma_f32_16x16x32_bf16 v[36:39], v[212:215], v[156:159], v[36:39]
	v_mfma_f32_16x16x32_bf16 v[32:35], v[212:215], v[192:195], v[32:35]
	v_mfma_f32_16x16x32_bf16 v[20:23], v[220:223], v[156:159], v[20:23]
	v_mfma_f32_16x16x32_bf16 v[16:19], v[220:223], v[192:195], v[16:19]
	v_mfma_f32_16x16x32_bf16 v[4:7], v[228:231], v[156:159], v[4:7]
	v_mfma_f32_16x16x32_bf16 v[0:3], v[228:231], v[192:195], v[0:3]
	v_mfma_f32_16x16x32_bf16 v[52:55], v[204:207], v[188:191], v[52:55]
	v_mfma_f32_16x16x32_bf16 v[48:51], v[204:207], v[196:199], v[48:51]
	v_mfma_f32_16x16x32_bf16 v[36:39], v[216:219], v[188:191], v[36:39]
	v_mfma_f32_16x16x32_bf16 v[32:35], v[216:219], v[196:199], v[32:35]
	v_mfma_f32_16x16x32_bf16 v[20:23], v[224:227], v[188:191], v[20:23]
	v_mfma_f32_16x16x32_bf16 v[16:19], v[224:227], v[196:199], v[16:19]
	v_mfma_f32_16x16x32_bf16 v[4:7], v[232:235], v[188:191], v[4:7]
	v_mfma_f32_16x16x32_bf16 v[0:3], v[232:235], v[196:199], v[0:3]
	s_setprio 0
	s_add_i32 s68, s68, 2
	s_add_u32 s42, s42, 0x100
	s_addc_u32 s43, s43, 0
	s_cmp_gt_u32 s68, 29
	s_barrier
.LBB0_1717:
	ds_read_b128 v[132:135], v177
	ds_read_b128 v[144:147], v177 offset:1024
	ds_read_b128 v[148:151], v177 offset:2048
	ds_read_b128 v[152:155], v177 offset:3072
	ds_read_b128 v[156:159], v178
	ds_read_b128 v[188:191], v178 offset:1024
	ds_read_b128 v[192:195], v178 offset:2048
	ds_read_b128 v[196:199], v178 offset:3072
	s_add_u32 s44, s60, s42
	s_addc_u32 s45, s61, s43
	s_add_u32 s44, s44, 0xfa70100
	s_addc_u32 s45, s45, 0
	s_add_u32 s69, s66, s42
	s_addc_u32 s70, s67, s43
	s_cmpk_eq_i32 s42, 0xf00
	s_cselect_b32 s47, s52, s45
	s_cselect_b32 s46, s21, s44
	s_cselect_b32 s45, s53, s70
	s_cselect_b32 s44, s15, s69
	v_readfirstlane_b32 s69, v183
	v_lshl_add_u64 v[208:209], v[128:129], 0, s[42:43]
	s_mov_b32 m0, s69
	v_readfirstlane_b32 s69, v184
	ds_read_b128 v[200:203], v179
	ds_read_b128 v[204:207], v179 offset:1024
	ds_read_b128 v[212:215], v180
	ds_read_b128 v[216:219], v180 offset:1024
	ds_read_b128 v[220:223], v181
	ds_read_b128 v[224:227], v181 offset:1024
	ds_read_b128 v[228:231], v182
	ds_read_b128 v[232:235], v182 offset:1024
	global_load_lds_dwordx4 v[208:209], off
	v_lshl_add_u64 v[208:209], v[130:131], 0, s[42:43]
	s_mov_b32 m0, s69
	s_nop 0
	global_load_lds_dwordx4 v[208:209], off
	s_waitcnt vmcnt(8)
	s_waitcnt lgkmcnt(0)
	s_barrier
; #define STAGE(P, g) do { const char* g_ = (const char*)(g); \
;         __builtin_amdgcn_global_load_lds((const unsigned*)(g_ + so0), (lds_u32*)((lds_u8*)(P) + sb0), 16, 0, 0); \
;         __builtin_amdgcn_global_load_lds((const unsigned*)(g_ + so1), (lds_u32*)((lds_u8*)(P) + sb0 + 8192), 16, 0, 0); } while (0)
; #define LDA(dst, b, h) for (int m = 0; m < 4; ++m) for (int k = 0; k < 2; ++k) \
;         dst[m][k] = *reinterpret_cast<const bf16x8*>((char*)SA(b, h) + lds_byte(wr * 64 + m * 16 + fr, k * 32 + fq * 8))
; #define LDB(dst, b, h) for (int n = 0; n < 2; ++n) for (int k = 0; k < 2; ++k) \
;         dst[n][k] = *reinterpret_cast<const bf16x8*>((char*)SB(b, h) + lds_byte(wc * 32 + n * 16 + fr, k * 32 + fq * 8))
; #define MMA(ai, bj, At_, Bt_) do { __builtin_amdgcn_s_setprio(1); \
;         for (int m = 0; m < 4; ++m) for (int n = 0; n < 2; ++n) for (int k = 0; k < 2; ++k) \
;             acc[ai][bj][m][n] = __builtin_amdgcn_mfma_f32_16x16x32_bf16(At_[m][k], Bt_[n][k], acc[ai][bj][m][n], 0, 0, 0); \
;         __builtin_amdgcn_s_setprio(0); } while (0)
; #define WAIT_V(n) asm volatile("s_waitcnt vmcnt(" #n ")" ::: "memory")
; #define WAIT_L(n) asm volatile("s_waitcnt lgkmcnt(" #n ")" ::: "memory")
; #define BAR __builtin_amdgcn_s_barrier()
; #define SCHED __builtin_amdgcn_sched_barrier(0)
; template <int EPI, int K, int LNI = -1>
; DI void ph_gemm(const Params& p, const bf16_t* __restrict__ A, const bf16_t* __restrict__ Bt, int N, float* s_aux) {
;     ...
;             LDB(B0, 0, 0); LDB(B1, 0, 1); SCHED; LDA(At, 0, 0); STAGE(SA(1, 1), a1 + hstep);
;             WAIT_V(8); WAIT_L(0); BAR; MMA(0, 0, At, B0); MMA(0, 1, At, B1); BAR; SCHED;
;             LDA(At, 0, 1); STAGE(SB(0, 0), b2); STAGE(SB(0, 1), b2 + hstep); STAGE(SA(0, 0), a2);
;             WAIT_V(8); WAIT_L(0); BAR; MMA(1, 0, At, B0); MMA(1, 1, At, B1); BAR; SCHED;
;             LDB(B0, 1, 0); LDB(B1, 1, 1); SCHED; LDA(At, 1, 0); STAGE(SA(0, 1), a2 + hstep);
;             WAIT_V(8); WAIT_L(0); BAR; MMA(0, 0, At, B0); MMA(0, 1, At, B1); BAR; SCHED;
;             LDA(At, 1, 1); STAGE(SB(1, 0), b3); STAGE(SB(1, 1), b3 + hstep); STAGE(SA(1, 0), a3);
;             WAIT_V(8); WAIT_L(0); BAR; MMA(1, 0, At, B0); MMA(1, 1, At, B1); BAR; SCHED;
	s_setprio 1
	s_waitcnt lgkmcnt(0)
	v_mfma_f32_16x16x32_bf16 v[124:127], v[200:203], v[132:135], v[124:127]
	v_mfma_f32_16x16x32_bf16 v[120:123], v[200:203], v[148:151], v[120:123]
	v_mfma_f32_16x16x32_bf16 v[108:111], v[212:215], v[132:135], v[108:111]
	v_mfma_f32_16x16x32_bf16 v[104:107], v[212:215], v[148:151], v[104:107]
	v_mfma_f32_16x16x32_bf16 v[92:95], v[220:223], v[132:135], v[92:95]
	v_mfma_f32_16x16x32_bf16 v[88:91], v[220:223], v[148:151], v[88:91]
	v_mfma_f32_16x16x32_bf16 v[76:79], v[228:231], v[132:135], v[76:79]
	v_mfma_f32_16x16x32_bf16 v[72:75], v[228:231], v[148:151], v[72:75]
	v_mfma_f32_16x16x32_bf16 v[124:127], v[204:207], v[144:147], v[124:127]
	v_mfma_f32_16x16x32_bf16 v[120:123], v[204:207], v[152:155], v[120:123]
	v_mfma_f32_16x16x32_bf16 v[108:111], v[216:219], v[144:147], v[108:111]
	v_mfma_f32_16x16x32_bf16 v[104:107], v[216:219], v[152:155], v[104:107]
	v_mfma_f32_16x16x32_bf16 v[92:95], v[224:227], v[144:147], v[92:95]
	v_mfma_f32_16x16x32_bf16 v[88:91], v[224:227], v[152:155], v[88:91]
	v_mfma_f32_16x16x32_bf16 v[76:79], v[232:235], v[144:147], v[76:79]
	v_mfma_f32_16x16x32_bf16 v[72:75], v[232:235], v[152:155], v[72:75]
	s_setprio 0
	s_setprio 1
	v_mfma_f32_16x16x32_bf16 v[116:119], v[200:203], v[156:159], v[116:119]
	v_mfma_f32_16x16x32_bf16 v[112:115], v[200:203], v[192:195], v[112:115]
	v_mfma_f32_16x16x32_bf16 v[100:103], v[212:215], v[156:159], v[100:103]
	v_mfma_f32_16x16x32_bf16 v[96:99], v[212:215], v[192:195], v[96:99]
	v_mfma_f32_16x16x32_bf16 v[84:87], v[220:223], v[156:159], v[84:87]
	v_mfma_f32_16x16x32_bf16 v[80:83], v[220:223], v[192:195], v[80:83]
	v_mfma_f32_16x16x32_bf16 v[68:71], v[228:231], v[156:159], v[68:71]
	v_mfma_f32_16x16x32_bf16 v[64:67], v[228:231], v[192:195], v[64:67]
	v_mfma_f32_16x16x32_bf16 v[116:119], v[204:207], v[188:191], v[116:119]
	v_mfma_f32_16x16x32_bf16 v[112:115], v[204:207], v[196:199], v[112:115]
	v_mfma_f32_16x16x32_bf16 v[100:103], v[216:219], v[188:191], v[100:103]
	v_mfma_f32_16x16x32_bf16 v[96:99], v[216:219], v[196:199], v[96:99]
	v_mfma_f32_16x16x32_bf16 v[84:87], v[224:227], v[188:191], v[84:87]
	v_mfma_f32_16x16x32_bf16 v[80:83], v[224:227], v[196:199], v[80:83]
	v_mfma_f32_16x16x32_bf16 v[68:71], v[232:235], v[188:191], v[68:71]
	v_mfma_f32_16x16x32_bf16 v[64:67], v[232:235], v[196:199], v[64:67]
	s_setprio 0
	s_barrier
	v_readfirstlane_b32 s69, v160
	v_lshl_add_u64 v[208:209], s[44:45], 0, v[136:137]
	s_mov_b32 m0, s69
	v_readfirstlane_b32 s69, v161
	s_add_u32 s70, s44, 0x80000
	ds_read_b128 v[200:203], v179 offset:16384
	ds_read_b128 v[204:207], v179 offset:17408
	ds_read_b128 v[212:215], v180 offset:16384
	ds_read_b128 v[216:219], v180 offset:17408
	ds_read_b128 v[220:223], v181 offset:16384
	ds_read_b128 v[224:227], v181 offset:17408
	ds_read_b128 v[228:231], v182 offset:16384
	ds_read_b128 v[232:235], v182 offset:17408
	global_load_lds_dwordx4 v[208:209], off
	v_lshl_add_u64 v[236:237], s[44:45], 0, v[138:139]
	s_mov_b32 m0, s69
	s_addc_u32 s71, s45, 0
	v_readfirstlane_b32 s69, v162
	global_load_lds_dwordx4 v[236:237], off
	v_lshl_add_u64 v[238:239], s[70:71], 0, v[136:137]
	s_mov_b32 m0, s69
	v_readfirstlane_b32 s69, v163
	global_load_lds_dwordx4 v[238:239], off
	v_lshl_add_u64 v[238:239], s[70:71], 0, v[138:139]
	s_mov_b32 m0, s69
	v_readfirstlane_b32 s69, v164
	global_load_lds_dwordx4 v[238:239], off
	v_lshl_add_u64 v[238:239], s[46:47], 0, v[136:137]
	s_mov_b32 m0, s69
	v_readfirstlane_b32 s69, v165
	global_load_lds_dwordx4 v[238:239], off
	v_lshl_add_u64 v[240:241], s[46:47], 0, v[138:139]
	s_mov_b32 m0, s69
	s_nop 0
	global_load_lds_dwordx4 v[240:241], off
	s_waitcnt vmcnt(8)
	s_waitcnt lgkmcnt(0)
	s_barrier
	s_setprio 1
	s_waitcnt lgkmcnt(0)
	v_mfma_f32_16x16x32_bf16 v[60:63], v[200:203], v[132:135], v[60:63]
	v_mfma_f32_16x16x32_bf16 v[56:59], v[200:203], v[148:151], v[56:59]
	v_mfma_f32_16x16x32_bf16 v[44:47], v[212:215], v[132:135], v[44:47]
	v_mfma_f32_16x16x32_bf16 v[40:43], v[212:215], v[148:151], v[40:43]
	v_mfma_f32_16x16x32_bf16 v[28:31], v[220:223], v[132:135], v[28:31]
	v_mfma_f32_16x16x32_bf16 v[24:27], v[220:223], v[148:151], v[24:27]
	v_mfma_f32_16x16x32_bf16 v[12:15], v[228:231], v[132:135], v[12:15]
	v_mfma_f32_16x16x32_bf16 v[8:11], v[228:231], v[148:151], v[8:11]
	v_mfma_f32_16x16x32_bf16 v[60:63], v[204:207], v[144:147], v[60:63]
	v_mfma_f32_16x16x32_bf16 v[56:59], v[204:207], v[152:155], v[56:59]
	v_mfma_f32_16x16x32_bf16 v[44:47], v[216:219], v[144:147], v[44:47]
	v_mfma_f32_16x16x32_bf16 v[40:43], v[216:219], v[152:155], v[40:43]
	v_mfma_f32_16x16x32_bf16 v[28:31], v[224:227], v[144:147], v[28:31]
	v_mfma_f32_16x16x32_bf16 v[24:27], v[224:227], v[152:155], v[24:27]
	v_mfma_f32_16x16x32_bf16 v[12:15], v[232:235], v[144:147], v[12:15]
	v_mfma_f32_16x16x32_bf16 v[8:11], v[232:235], v[152:155], v[8:11]
	s_setprio 0
	s_setprio 1
	v_mfma_f32_16x16x32_bf16 v[52:55], v[200:203], v[156:159], v[52:55]
	v_mfma_f32_16x16x32_bf16 v[48:51], v[200:203], v[192:195], v[48:51]
	v_mfma_f32_16x16x32_bf16 v[36:39], v[212:215], v[156:159], v[36:39]
	v_mfma_f32_16x16x32_bf16 v[32:35], v[212:215], v[192:195], v[32:35]
	v_mfma_f32_16x16x32_bf16 v[20:23], v[220:223], v[156:159], v[20:23]
	v_mfma_f32_16x16x32_bf16 v[16:19], v[220:223], v[192:195], v[16:19]
	v_mfma_f32_16x16x32_bf16 v[4:7], v[228:231], v[156:159], v[4:7]
	v_mfma_f32_16x16x32_bf16 v[0:3], v[228:231], v[192:195], v[0:3]
	v_mfma_f32_16x16x32_bf16 v[52:55], v[204:207], v[188:191], v[52:55]
	v_mfma_f32_16x16x32_bf16 v[48:51], v[204:207], v[196:199], v[48:51]
	v_mfma_f32_16x16x32_bf16 v[36:39], v[216:219], v[188:191], v[36:39]
	v_mfma_f32_16x16x32_bf16 v[32:35], v[216:219], v[196:199], v[32:35]
	v_mfma_f32_16x16x32_bf16 v[20:23], v[224:227], v[188:191], v[20:23]
	v_mfma_f32_16x16x32_bf16 v[16:19], v[224:227], v[196:199], v[16:19]
	v_mfma_f32_16x16x32_bf16 v[4:7], v[232:235], v[188:191], v[4:7]
	v_mfma_f32_16x16x32_bf16 v[0:3], v[232:235], v[196:199], v[0:3]
	s_setprio 0
	s_barrier
; #define STAGE(P, g) do { const char* g_ = (const char*)(g); \
;         __builtin_amdgcn_global_load_lds((const unsigned*)(g_ + so0), (lds_u32*)((lds_u8*)(P) + sb0), 16, 0, 0); \
;         __builtin_amdgcn_global_load_lds((const unsigned*)(g_ + so1), (lds_u32*)((lds_u8*)(P) + sb0 + 8192), 16, 0, 0); } while (0)
; #define LDA(dst, b, h) for (int m = 0; m < 4; ++m) for (int k = 0; k < 2; ++k) \
;         dst[m][k] = *reinterpret_cast<const bf16x8*>((char*)SA(b, h) + lds_byte(wr * 64 + m * 16 + fr, k * 32 + fq * 8))
; #define LDB(dst, b, h) for (int n = 0; n < 2; ++n) for (int k = 0; k < 2; ++k) \
;         dst[n][k] = *reinterpret_cast<const bf16x8*>((char*)SB(b, h) + lds_byte(wc * 32 + n * 16 + fr, k * 32 + fq * 8))
; #define MMA(ai, bj, At_, Bt_) do { __builtin_amdgcn_s_setprio(1); \
;         for (int m = 0; m < 4; ++m) for (int n = 0; n < 2; ++n) for (int k = 0; k < 2; ++k) \
;             acc[ai][bj][m][n] = __builtin_amdgcn_mfma_f32_16x16x32_bf16(At_[m][k], Bt_[n][k], acc[ai][bj][m][n], 0, 0, 0); \
;         __builtin_amdgcn_s_setprio(0); } while (0)
; #define WAIT_V(n) asm volatile("s_waitcnt vmcnt(" #n ")" ::: "memory")
; #define WAIT_L(n) asm volatile("s_waitcnt lgkmcnt(" #n ")" ::: "memory")
; #define BAR __builtin_amdgcn_s_barrier()
; #define SCHED __builtin_amdgcn_sched_barrier(0)
; template <int EPI, int K, int LNI = -1>
; DI void ph_gemm(const Params& p, const bf16_t* __restrict__ A, const bf16_t* __restrict__ Bt, int N, float* s_aux) {
;     ...
;             LDB(B0, 1, 0); LDB(B1, 1, 1); SCHED; LDA(At, 1, 0); STAGE(SA(0, 1), a2 + hstep);
;             WAIT_V(8); WAIT_L(0); BAR; MMA(0, 0, At, B0); MMA(0, 1, At, B1); BAR; SCHED;
	ds_read_b128 v[132:135], v185
	ds_read_b128 v[144:147], v185 offset:1024
	ds_read_b128 v[148:151], v185 offset:2048
	ds_read_b128 v[152:155], v185 offset:3072
	ds_read_b128 v[156:159], v186
	ds_read_b128 v[188:191], v186 offset:1024
	ds_read_b128 v[192:195], v186 offset:2048
	ds_read_b128 v[196:199], v186 offset:3072
	s_add_u32 s46, s46, 0x80000
	s_addc_u32 s47, s47, 0
	v_readfirstlane_b32 s69, v166
	v_lshl_add_u64 v[242:243], s[46:47], 0, v[136:137]
	s_mov_b32 m0, s69
	ds_read_b128 v[200:203], v179 offset:32768
	ds_read_b128 v[204:207], v179 offset:33792
	ds_read_b128 v[212:215], v180 offset:32768
	ds_read_b128 v[216:219], v180 offset:33792
	ds_read_b128 v[220:223], v181 offset:32768
	ds_read_b128 v[224:227], v181 offset:33792
	ds_read_b128 v[228:231], v182 offset:32768
	ds_read_b128 v[232:235], v182 offset:33792
	global_load_lds_dwordx4 v[242:243], off
	v_lshl_add_u64 v[242:243], s[46:47], 0, v[138:139]
	v_readfirstlane_b32 s46, v167
	s_mov_b32 m0, s46
	s_nop 0
	global_load_lds_dwordx4 v[242:243], off
	s_waitcnt vmcnt(8)
	s_waitcnt lgkmcnt(0)
	s_barrier
	s_setprio 1
	s_waitcnt lgkmcnt(0)
	v_mfma_f32_16x16x32_bf16 v[124:127], v[200:203], v[132:135], v[124:127]
	v_mfma_f32_16x16x32_bf16 v[120:123], v[200:203], v[148:151], v[120:123]
	v_mfma_f32_16x16x32_bf16 v[108:111], v[212:215], v[132:135], v[108:111]
	v_mfma_f32_16x16x32_bf16 v[104:107], v[212:215], v[148:151], v[104:107]
	v_mfma_f32_16x16x32_bf16 v[92:95], v[220:223], v[132:135], v[92:95]
	v_mfma_f32_16x16x32_bf16 v[88:91], v[220:223], v[148:151], v[88:91]
	v_mfma_f32_16x16x32_bf16 v[76:79], v[228:231], v[132:135], v[76:79]
	v_mfma_f32_16x16x32_bf16 v[72:75], v[228:231], v[148:151], v[72:75]
	v_mfma_f32_16x16x32_bf16 v[124:127], v[204:207], v[144:147], v[124:127]
	v_mfma_f32_16x16x32_bf16 v[120:123], v[204:207], v[152:155], v[120:123]
	v_mfma_f32_16x16x32_bf16 v[108:111], v[216:219], v[144:147], v[108:111]
	v_mfma_f32_16x16x32_bf16 v[104:107], v[216:219], v[152:155], v[104:107]
	v_mfma_f32_16x16x32_bf16 v[92:95], v[224:227], v[144:147], v[92:95]
	v_mfma_f32_16x16x32_bf16 v[88:91], v[224:227], v[152:155], v[88:91]
	v_mfma_f32_16x16x32_bf16 v[76:79], v[232:235], v[144:147], v[76:79]
	v_mfma_f32_16x16x32_bf16 v[72:75], v[232:235], v[152:155], v[72:75]
	s_setprio 0
	s_setprio 1
	v_mfma_f32_16x16x32_bf16 v[116:119], v[200:203], v[156:159], v[116:119]
	v_mfma_f32_16x16x32_bf16 v[112:115], v[200:203], v[192:195], v[112:115]
	v_mfma_f32_16x16x32_bf16 v[100:103], v[212:215], v[156:159], v[100:103]
	v_mfma_f32_16x16x32_bf16 v[96:99], v[212:215], v[192:195], v[96:99]
	v_mfma_f32_16x16x32_bf16 v[84:87], v[220:223], v[156:159], v[84:87]
	v_mfma_f32_16x16x32_bf16 v[80:83], v[220:223], v[192:195], v[80:83]
	v_mfma_f32_16x16x32_bf16 v[68:71], v[228:231], v[156:159], v[68:71]
	v_mfma_f32_16x16x32_bf16 v[64:67], v[228:231], v[192:195], v[64:67]
	v_mfma_f32_16x16x32_bf16 v[116:119], v[204:207], v[188:191], v[116:119]
	v_mfma_f32_16x16x32_bf16 v[112:115], v[204:207], v[196:199], v[112:115]
	v_mfma_f32_16x16x32_bf16 v[100:103], v[216:219], v[188:191], v[100:103]
	v_mfma_f32_16x16x32_bf16 v[96:99], v[216:219], v[196:199], v[96:99]
	v_mfma_f32_16x16x32_bf16 v[84:87], v[224:227], v[188:191], v[84:87]
	v_mfma_f32_16x16x32_bf16 v[80:83], v[224:227], v[196:199], v[80:83]
	v_mfma_f32_16x16x32_bf16 v[68:71], v[232:235], v[188:191], v[68:71]
	v_mfma_f32_16x16x32_bf16 v[64:67], v[232:235], v[196:199], v[64:67]
	s_setprio 0
	s_barrier
; #define STAGE(P, g) do { const char* g_ = (const char*)(g); \
;         __builtin_amdgcn_global_load_lds((const unsigned*)(g_ + so0), (lds_u32*)((lds_u8*)(P) + sb0), 16, 0, 0); \
;         __builtin_amdgcn_global_load_lds((const unsigned*)(g_ + so1), (lds_u32*)((lds_u8*)(P) + sb0 + 8192), 16, 0, 0); } while (0)
; #define LDA(dst, b, h) for (int m = 0; m < 4; ++m) for (int k = 0; k < 2; ++k) \
;         dst[m][k] = *reinterpret_cast<const bf16x8*>((char*)SA(b, h) + lds_byte(wr * 64 + m * 16 + fr, k * 32 + fq * 8))
; #define MMA(ai, bj, At_, Bt_) do { __builtin_amdgcn_s_setprio(1); \
;         for (int m = 0; m < 4; ++m) for (int n = 0; n < 2; ++n) for (int k = 0; k < 2; ++k) \
;             acc[ai][bj][m][n] = __builtin_amdgcn_mfma_f32_16x16x32_bf16(At_[m][k], Bt_[n][k], acc[ai][bj][m][n], 0, 0, 0); \
;         __builtin_amdgcn_s_setprio(0); } while (0)
; #define WAIT_V(n) asm volatile("s_waitcnt vmcnt(" #n ")" ::: "memory")
; #define WAIT_L(n) asm volatile("s_waitcnt lgkmcnt(" #n ")" ::: "memory")
; #define BAR __builtin_amdgcn_s_barrier()
; #define SCHED __builtin_amdgcn_sched_barrier(0)
; template <int EPI, int K, int LNI = -1>
; DI void ph_gemm(const Params& p, const bf16_t* __restrict__ A, const bf16_t* __restrict__ Bt, int N, float* s_aux) {
;     ...
;             LDA(At, 1, 1); STAGE(SB(1, 0), b3); STAGE(SB(1, 1), b3 + hstep); STAGE(SA(1, 0), a3);
;             WAIT_V(8); WAIT_L(0); BAR; MMA(1, 0, At, B0); MMA(1, 1, At, B1); BAR; SCHED;
;         }
	v_readfirstlane_b32 s46, v168
	v_lshl_add_u64 v[208:209], v[208:209], 0, s[10:11]
	s_mov_b32 m0, s46
	v_readfirstlane_b32 s46, v169
	s_add_u32 s44, s44, 0x80080
	ds_read_b128 v[200:203], v179 offset:49152
	ds_read_b128 v[204:207], v179 offset:50176
	ds_read_b128 v[212:215], v180 offset:49152
	ds_read_b128 v[216:219], v180 offset:50176
	ds_read_b128 v[220:223], v181 offset:49152
	ds_read_b128 v[224:227], v181 offset:50176
	ds_read_b128 v[228:231], v182 offset:49152
	ds_read_b128 v[232:235], v182 offset:50176
	global_load_lds_dwordx4 v[208:209], off
	v_lshl_add_u64 v[208:209], v[236:237], 0, s[10:11]
	s_mov_b32 m0, s46
	s_addc_u32 s45, s45, 0
	v_readfirstlane_b32 s46, v172
	global_load_lds_dwordx4 v[208:209], off
	v_lshl_add_u64 v[208:209], s[44:45], 0, v[136:137]
	s_mov_b32 m0, s46
	s_nop 0
	global_load_lds_dwordx4 v[208:209], off
	v_lshl_add_u64 v[208:209], s[44:45], 0, v[138:139]
	v_readfirstlane_b32 s44, v173
	s_mov_b32 m0, s44
	v_readfirstlane_b32 s44, v170
	global_load_lds_dwordx4 v[208:209], off
	v_lshl_add_u64 v[208:209], v[238:239], 0, s[10:11]
	s_mov_b32 m0, s44
	v_readfirstlane_b32 s44, v171
	global_load_lds_dwordx4 v[208:209], off
	v_lshl_add_u64 v[208:209], v[240:241], 0, s[10:11]
	s_mov_b32 m0, s44
	s_nop 0
	global_load_lds_dwordx4 v[208:209], off
	s_waitcnt vmcnt(8)
	s_waitcnt lgkmcnt(0)
	s_barrier
	s_setprio 1
	s_waitcnt lgkmcnt(0)
	v_mfma_f32_16x16x32_bf16 v[60:63], v[200:203], v[132:135], v[60:63]
	v_mfma_f32_16x16x32_bf16 v[56:59], v[200:203], v[148:151], v[56:59]
	v_mfma_f32_16x16x32_bf16 v[44:47], v[212:215], v[132:135], v[44:47]
	v_mfma_f32_16x16x32_bf16 v[40:43], v[212:215], v[148:151], v[40:43]
	v_mfma_f32_16x16x32_bf16 v[28:31], v[220:223], v[132:135], v[28:31]
	v_mfma_f32_16x16x32_bf16 v[24:27], v[220:223], v[148:151], v[24:27]
	v_mfma_f32_16x16x32_bf16 v[12:15], v[228:231], v[132:135], v[12:15]
	v_mfma_f32_16x16x32_bf16 v[8:11], v[228:231], v[148:151], v[8:11]
	v_mfma_f32_16x16x32_bf16 v[60:63], v[204:207], v[144:147], v[60:63]
	v_mfma_f32_16x16x32_bf16 v[56:59], v[204:207], v[152:155], v[56:59]
	v_mfma_f32_16x16x32_bf16 v[44:47], v[216:219], v[144:147], v[44:47]
	v_mfma_f32_16x16x32_bf16 v[40:43], v[216:219], v[152:155], v[40:43]
	v_mfma_f32_16x16x32_bf16 v[28:31], v[224:227], v[144:147], v[28:31]
	v_mfma_f32_16x16x32_bf16 v[24:27], v[224:227], v[152:155], v[24:27]
	v_mfma_f32_16x16x32_bf16 v[12:15], v[232:235], v[144:147], v[12:15]
	v_mfma_f32_16x16x32_bf16 v[8:11], v[232:235], v[152:155], v[8:11]
	s_setprio 0
	s_setprio 1
	v_mfma_f32_16x16x32_bf16 v[52:55], v[200:203], v[156:159], v[52:55]
	v_mfma_f32_16x16x32_bf16 v[48:51], v[200:203], v[192:195], v[48:51]
	v_mfma_f32_16x16x32_bf16 v[36:39], v[212:215], v[156:159], v[36:39]
	v_mfma_f32_16x16x32_bf16 v[32:35], v[212:215], v[192:195], v[32:35]
	v_mfma_f32_16x16x32_bf16 v[20:23], v[220:223], v[156:159], v[20:23]
	v_mfma_f32_16x16x32_bf16 v[16:19], v[220:223], v[192:195], v[16:19]
	v_mfma_f32_16x16x32_bf16 v[4:7], v[228:231], v[156:159], v[4:7]
	v_mfma_f32_16x16x32_bf16 v[0:3], v[228:231], v[192:195], v[0:3]
	v_mfma_f32_16x16x32_bf16 v[52:55], v[204:207], v[188:191], v[52:55]
	v_mfma_f32_16x16x32_bf16 v[48:51], v[204:207], v[196:199], v[48:51]
	v_mfma_f32_16x16x32_bf16 v[36:39], v[216:219], v[188:191], v[36:39]
	v_mfma_f32_16x16x32_bf16 v[32:35], v[216:219], v[196:199], v[32:35]
	v_mfma_f32_16x16x32_bf16 v[20:23], v[224:227], v[188:191], v[20:23]
	v_mfma_f32_16x16x32_bf16 v[16:19], v[224:227], v[196:199], v[16:19]
	v_mfma_f32_16x16x32_bf16 v[4:7], v[232:235], v[188:191], v[4:7]
	v_mfma_f32_16x16x32_bf16 v[0:3], v[232:235], v[196:199], v[0:3]
	s_setprio 0
	s_add_i32 s68, s68, 2
	s_add_u32 s42, s42, 0x100
	s_addc_u32 s43, s43, 0
	s_cmp_gt_u32 s68, 29
	s_barrier
	s_cbranch_scc0 .LBB0_1717
	s_and_saveexec_b64 s[42:43], s[8:9]
	s_cbranch_execz .LBB0_1720
	s_barrier

; DI int opaque_tid() { int t = threadIdx.x; asm volatile("" : "+v"(t)); return t; }
; #define STAGE(P, g) do { const char* g_ = (const char*)(g); \
;         __builtin_amdgcn_global_load_lds((const unsigned*)(g_ + so0), (lds_u32*)((lds_u8*)(P) + sb0), 16, 0, 0); \
;         __builtin_amdgcn_global_load_lds((const unsigned*)(g_ + so1), (lds_u32*)((lds_u8*)(P) + sb0 + 8192), 16, 0, 0); } while (0)
; #define WAIT_V(n) asm volatile("s_waitcnt vmcnt(" #n ")" ::: "memory")
; #define WAIT_L(n) asm volatile("s_waitcnt lgkmcnt(" #n ")" ::: "memory")
; template <int EPI, int K, int LNI = -1>
; DI void ph_gemm(const Params& p, const bf16_t* __restrict__ A, const bf16_t* __restrict__ Bt, int N, float* s_aux) {
;     ...
;         const int itn = it + (int)gridDim.x;
;         const bool has_next = itn < nwg;
;         int npm = pm, npn = pn;
;         if (has_next) unit(itn, npm, npn);
;         const bf16_t* nA = A + (size_t)npm * 256 * K; const bf16_t* nB = Bt + (size_t)npn * 256 * K;
;         const int brow = pm * 256, bcol = pn * 256;
;         float* sa = s_aux + (cnt & 1) * 512;
;         if (EPI == EPI_E5B) {
;             if (opaque_tid() < 256) {
;                 const int row = brow + (int)opaque_tid(); const int hd = bcol >> 9;
;                 const float* pp = (const float*)((unsigned char*)p.out + OFFO_PART) + (size_t)row * 256 + hd * 64;
;                 float sacc = 0.f;
; #pragma unroll
;                 for (int i = 0; i < 16; ++i) { const f32x4 v = *(const f32x4*)(pp + i * 4); sacc += (v[0] + v[1]) + (v[2] + v[3]); }
;                 sa[opaque_tid()] = __frsqrt_rn(sacc * (1.0f / 512.0f) + 1e-6f);
;             }
;         }
;         for (int t = 0; t < nt; t += 2) {
;             const bool last = (t == nt - 2);
;             const bf16_t* a1 = cA + (size_t)(t + 1) * kstep;
;             const bf16_t* a2 = last ? nA : cA + (size_t)(t + 2) * kstep; const bf16_t* b2 = last ? nB : cB + (size_t)(t + 2) * kstep;
;             const bf16_t* a3 = a2 + kstep; const bf16_t* b3 = b2 + kstep;
;             LDB(B0, 0, 0); LDB(B1, 0, 1); SCHED; LDA(At, 0, 0); STAGE(SA(1, 1), a1 + hstep);
;             WAIT_V(8); WAIT_L(0); BAR; MMA(0, 0, At, B0); MMA(0, 1, At, B1); BAR; SCHED;
;             LDA(At, 0, 1); STAGE(SB(0, 0), b2); STAGE(SB(0, 1), b2 + hstep); STAGE(SA(0, 0), a2);
;             WAIT_V(8); WAIT_L(0); BAR; MMA(1, 0, At, B0); MMA(1, 1, At, B1); BAR; SCHED;
.LBB0_1852:
	s_ashr_i32 s21, s20, 31
	s_lshl_b64 s[24:25], s[20:21], 19
	s_add_u32 s21, s40, s24
	s_addc_u32 s52, s41, s25
	s_ashr_i32 s23, s22, 31
	s_lshl_b64 s[26:27], s[22:23], 19
	s_add_u32 s23, s10, s26
	s_addc_u32 s53, s11, s27
	s_add_u32 s60, s56, s44
	s_addc_u32 s61, s57, s45
	s_add_u32 s66, s43, s46
	v_lshl_add_u64 v[136:137], v[132:133], 0, s[44:45]
	v_lshl_add_u64 v[138:139], v[134:135], 0, s[44:45]
	s_addc_u32 s67, s50, s47
	s_mov_b32 s68, -2
	s_mov_b64 s[44:45], 0
	ds_read_b128 v[166:169], v156
	ds_read_b128 v[170:173], v156 offset:1024
	ds_read_b128 v[174:177], v156 offset:2048
	ds_read_b128 v[178:181], v156 offset:3072
	ds_read_b128 v[182:185], v157
	ds_read_b128 v[186:189], v157 offset:1024
	ds_read_b128 v[190:193], v157 offset:2048
	ds_read_b128 v[194:197], v157 offset:3072
	s_add_u32 s46, s60, s44
	s_addc_u32 s47, s61, s45
	s_add_u32 s46, s46, 0xb840100
	s_addc_u32 s47, s47, 0
	s_add_u32 s69, s66, s44
	s_addc_u32 s70, s67, s45
	s_cmpk_eq_i32 s44, 0x700
	s_cselect_b32 s49, s52, s47
	s_cselect_b32 s48, s21, s46
	s_cselect_b32 s47, s53, s70
	s_cselect_b32 s46, s23, s69
	v_readfirstlane_b32 s69, v162
	v_lshl_add_u64 v[232:233], v[136:137], 0, s[44:45]
	s_mov_b32 m0, s69
	v_readfirstlane_b32 s69, v163
	ds_read_b128 v[198:201], v158
	ds_read_b128 v[202:205], v158 offset:1024
	ds_read_b128 v[206:209], v159
	ds_read_b128 v[212:215], v159 offset:1024
	ds_read_b128 v[216:219], v160
	ds_read_b128 v[220:223], v160 offset:1024
	ds_read_b128 v[224:227], v161
	ds_read_b128 v[228:231], v161 offset:1024
	global_load_lds_dwordx4 v[232:233], off
	v_lshl_add_u64 v[232:233], v[138:139], 0, s[44:45]
	s_mov_b32 m0, s69
	s_nop 0
	global_load_lds_dwordx4 v[232:233], off
	s_waitcnt vmcnt(8)
	s_waitcnt lgkmcnt(0)
	s_barrier
	s_setprio 1
	s_waitcnt lgkmcnt(0)
	v_mfma_f32_16x16x32_bf16 v[124:127], v[198:201], v[166:169], 0
	v_mfma_f32_16x16x32_bf16 v[120:123], v[198:201], v[174:177], 0
	v_mfma_f32_16x16x32_bf16 v[108:111], v[206:209], v[166:169], 0
	v_mfma_f32_16x16x32_bf16 v[104:107], v[206:209], v[174:177], 0
	v_mfma_f32_16x16x32_bf16 v[92:95], v[216:219], v[166:169], 0
	v_mfma_f32_16x16x32_bf16 v[88:91], v[216:219], v[174:177], 0
	v_mfma_f32_16x16x32_bf16 v[76:79], v[224:227], v[166:169], 0
	v_mfma_f32_16x16x32_bf16 v[72:75], v[224:227], v[174:177], 0
	v_mfma_f32_16x16x32_bf16 v[124:127], v[202:205], v[170:173], v[124:127]
	v_mfma_f32_16x16x32_bf16 v[120:123], v[202:205], v[178:181], v[120:123]
	v_mfma_f32_16x16x32_bf16 v[108:111], v[212:215], v[170:173], v[108:111]
	v_mfma_f32_16x16x32_bf16 v[104:107], v[212:215], v[178:181], v[104:107]
	v_mfma_f32_16x16x32_bf16 v[92:95], v[220:223], v[170:173], v[92:95]
	v_mfma_f32_16x16x32_bf16 v[88:91], v[220:223], v[178:181], v[88:91]
	v_mfma_f32_16x16x32_bf16 v[76:79], v[228:231], v[170:173], v[76:79]
	v_mfma_f32_16x16x32_bf16 v[72:75], v[228:231], v[178:181], v[72:75]
	s_setprio 0
	s_setprio 1
	v_mfma_f32_16x16x32_bf16 v[116:119], v[198:201], v[182:185], 0
	v_mfma_f32_16x16x32_bf16 v[112:115], v[198:201], v[190:193], 0
	v_mfma_f32_16x16x32_bf16 v[100:103], v[206:209], v[182:185], 0
	v_mfma_f32_16x16x32_bf16 v[96:99], v[206:209], v[190:193], 0
	v_mfma_f32_16x16x32_bf16 v[84:87], v[216:219], v[182:185], 0
	v_mfma_f32_16x16x32_bf16 v[80:83], v[216:219], v[190:193], 0
	v_mfma_f32_16x16x32_bf16 v[68:71], v[224:227], v[182:185], 0
	v_mfma_f32_16x16x32_bf16 v[64:67], v[224:227], v[190:193], 0
	v_mfma_f32_16x16x32_bf16 v[116:119], v[202:205], v[186:189], v[116:119]
	v_mfma_f32_16x16x32_bf16 v[112:115], v[202:205], v[194:197], v[112:115]
	v_mfma_f32_16x16x32_bf16 v[100:103], v[212:215], v[186:189], v[100:103]
	v_mfma_f32_16x16x32_bf16 v[96:99], v[212:215], v[194:197], v[96:99]
	v_mfma_f32_16x16x32_bf16 v[84:87], v[220:223], v[186:189], v[84:87]
	v_mfma_f32_16x16x32_bf16 v[80:83], v[220:223], v[194:197], v[80:83]
	v_mfma_f32_16x16x32_bf16 v[68:71], v[228:231], v[186:189], v[68:71]
	v_mfma_f32_16x16x32_bf16 v[64:67], v[228:231], v[194:197], v[64:67]
	s_setprio 0
	s_barrier
	v_readfirstlane_b32 s69, v140
	v_lshl_add_u64 v[232:233], s[46:47], 0, v[128:129]
	s_mov_b32 m0, s69
	v_readfirstlane_b32 s69, v141
	s_add_u32 s70, s46, 0x40000
	ds_read_b128 v[198:201], v158 offset:16384
	ds_read_b128 v[202:205], v158 offset:17408
	ds_read_b128 v[206:209], v159 offset:16384
	ds_read_b128 v[212:215], v159 offset:17408
	ds_read_b128 v[216:219], v160 offset:16384
	ds_read_b128 v[220:223], v160 offset:17408
	ds_read_b128 v[224:227], v161 offset:16384
	ds_read_b128 v[228:231], v161 offset:17408
	global_load_lds_dwordx4 v[232:233], off
	v_lshl_add_u64 v[234:235], s[46:47], 0, v[130:131]
	s_mov_b32 m0, s69
	s_addc_u32 s71, s47, 0
	v_readfirstlane_b32 s69, v142
	global_load_lds_dwordx4 v[234:235], off
	v_lshl_add_u64 v[236:237], s[70:71], 0, v[128:129]
	s_mov_b32 m0, s69
	v_readfirstlane_b32 s69, v143
	global_load_lds_dwordx4 v[236:237], off
	v_lshl_add_u64 v[236:237], s[70:71], 0, v[130:131]
	s_mov_b32 m0, s69
	v_readfirstlane_b32 s69, v144
	global_load_lds_dwordx4 v[236:237], off
	v_lshl_add_u64 v[236:237], s[48:49], 0, v[128:129]
	s_mov_b32 m0, s69
	v_readfirstlane_b32 s69, v145
	global_load_lds_dwordx4 v[236:237], off
	v_lshl_add_u64 v[238:239], s[48:49], 0, v[130:131]
	s_mov_b32 m0, s69
	s_nop 0
	global_load_lds_dwordx4 v[238:239], off
	s_waitcnt vmcnt(8)
	s_waitcnt lgkmcnt(0)
	s_barrier
; #define STAGE(P, g) do { const char* g_ = (const char*)(g); \
;         __builtin_amdgcn_global_load_lds((const unsigned*)(g_ + so0), (lds_u32*)((lds_u8*)(P) + sb0), 16, 0, 0); \
;         __builtin_amdgcn_global_load_lds((const unsigned*)(g_ + so1), (lds_u32*)((lds_u8*)(P) + sb0 + 8192), 16, 0, 0); } while (0)
; #define LDA(dst, b, h) for (int m = 0; m < 4; ++m) for (int k = 0; k < 2; ++k) \
;         dst[m][k] = *reinterpret_cast<const bf16x8*>((char*)SA(b, h) + lds_byte(wr * 64 + m * 16 + fr, k * 32 + fq * 8))
; #define LDB(dst, b, h) for (int n = 0; n < 2; ++n) for (int k = 0; k < 2; ++k) \
;         dst[n][k] = *reinterpret_cast<const bf16x8*>((char*)SB(b, h) + lds_byte(wc * 32 + n * 16 + fr, k * 32 + fq * 8))
; #define MMA(ai, bj, At_, Bt_) do { __builtin_amdgcn_s_setprio(1); \
;         for (int m = 0; m < 4; ++m) for (int n = 0; n < 2; ++n) for (int k = 0; k < 2; ++k) \
;             acc[ai][bj][m][n] = __builtin_amdgcn_mfma_f32_16x16x32_bf16(At_[m][k], Bt_[n][k], acc[ai][bj][m][n], 0, 0, 0); \
;         __builtin_amdgcn_s_setprio(0); } while (0)
; #define WAIT_V(n) asm volatile("s_waitcnt vmcnt(" #n ")" ::: "memory")
; #define WAIT_L(n) asm volatile("s_waitcnt lgkmcnt(" #n ")" ::: "memory")
; #define BAR __builtin_amdgcn_s_barrier()
; #define SCHED __builtin_amdgcn_sched_barrier(0)
; template <int EPI, int K, int LNI = -1>
; DI void ph_gemm(const Params& p, const bf16_t* __restrict__ A, const bf16_t* __restrict__ Bt, int N, float* s_aux) {
;     ...
;             WAIT_V(8); WAIT_L(0); BAR; MMA(0, 0, At, B0); MMA(0, 1, At, B1); BAR; SCHED;
;             LDA(At, 0, 1); STAGE(SB(0, 0), b2); STAGE(SB(0, 1), b2 + hstep); STAGE(SA(0, 0), a2);
;             WAIT_V(8); WAIT_L(0); BAR; MMA(1, 0, At, B0); MMA(1, 1, At, B1); BAR; SCHED;
;             LDB(B0, 1, 0); LDB(B1, 1, 1); SCHED; LDA(At, 1, 0); STAGE(SA(0, 1), a2 + hstep);
;             WAIT_V(8); WAIT_L(0); BAR; MMA(0, 0, At, B0); MMA(0, 1, At, B1); BAR; SCHED;
	s_setprio 1
	s_waitcnt lgkmcnt(0)
	v_mfma_f32_16x16x32_bf16 v[60:63], v[198:201], v[166:169], 0
	v_mfma_f32_16x16x32_bf16 v[56:59], v[198:201], v[174:177], 0
	v_mfma_f32_16x16x32_bf16 v[44:47], v[206:209], v[166:169], 0
	v_mfma_f32_16x16x32_bf16 v[40:43], v[206:209], v[174:177], 0
	v_mfma_f32_16x16x32_bf16 v[28:31], v[216:219], v[166:169], 0
	v_mfma_f32_16x16x32_bf16 v[24:27], v[216:219], v[174:177], 0
	v_mfma_f32_16x16x32_bf16 v[12:15], v[224:227], v[166:169], 0
	v_mfma_f32_16x16x32_bf16 v[8:11], v[224:227], v[174:177], 0
	v_mfma_f32_16x16x32_bf16 v[60:63], v[202:205], v[170:173], v[60:63]
	v_mfma_f32_16x16x32_bf16 v[56:59], v[202:205], v[178:181], v[56:59]
	v_mfma_f32_16x16x32_bf16 v[44:47], v[212:215], v[170:173], v[44:47]
	v_mfma_f32_16x16x32_bf16 v[40:43], v[212:215], v[178:181], v[40:43]
	v_mfma_f32_16x16x32_bf16 v[28:31], v[220:223], v[170:173], v[28:31]
	v_mfma_f32_16x16x32_bf16 v[24:27], v[220:223], v[178:181], v[24:27]
	v_mfma_f32_16x16x32_bf16 v[12:15], v[228:231], v[170:173], v[12:15]
	v_mfma_f32_16x16x32_bf16 v[8:11], v[228:231], v[178:181], v[8:11]
	s_setprio 0
	s_setprio 1
	v_mfma_f32_16x16x32_bf16 v[52:55], v[198:201], v[182:185], 0
	v_mfma_f32_16x16x32_bf16 v[48:51], v[198:201], v[190:193], 0
	v_mfma_f32_16x16x32_bf16 v[36:39], v[206:209], v[182:185], 0
	v_mfma_f32_16x16x32_bf16 v[32:35], v[206:209], v[190:193], 0
	v_mfma_f32_16x16x32_bf16 v[20:23], v[216:219], v[182:185], 0
	v_mfma_f32_16x16x32_bf16 v[16:19], v[216:219], v[190:193], 0
	v_mfma_f32_16x16x32_bf16 v[4:7], v[224:227], v[182:185], 0
	v_mfma_f32_16x16x32_bf16 v[0:3], v[224:227], v[190:193], 0
	v_mfma_f32_16x16x32_bf16 v[52:55], v[202:205], v[186:189], v[52:55]
	v_mfma_f32_16x16x32_bf16 v[48:51], v[202:205], v[194:197], v[48:51]
	v_mfma_f32_16x16x32_bf16 v[36:39], v[212:215], v[186:189], v[36:39]
	v_mfma_f32_16x16x32_bf16 v[32:35], v[212:215], v[194:197], v[32:35]
	v_mfma_f32_16x16x32_bf16 v[20:23], v[220:223], v[186:189], v[20:23]
	v_mfma_f32_16x16x32_bf16 v[16:19], v[220:223], v[194:197], v[16:19]
	v_mfma_f32_16x16x32_bf16 v[4:7], v[228:231], v[186:189], v[4:7]
	v_mfma_f32_16x16x32_bf16 v[0:3], v[228:231], v[194:197], v[0:3]
	s_setprio 0
	s_barrier
	ds_read_b128 v[166:169], v164
	ds_read_b128 v[170:173], v164 offset:1024
	ds_read_b128 v[174:177], v164 offset:2048
	ds_read_b128 v[178:181], v164 offset:3072
	ds_read_b128 v[182:185], v165
	ds_read_b128 v[186:189], v165 offset:1024
	ds_read_b128 v[190:193], v165 offset:2048
	ds_read_b128 v[194:197], v165 offset:3072
	s_add_u32 s48, s48, 0x40000
	s_addc_u32 s49, s49, 0
	v_readfirstlane_b32 s69, v146
	v_lshl_add_u64 v[240:241], s[48:49], 0, v[128:129]
	s_mov_b32 m0, s69
	ds_read_b128 v[198:201], v158 offset:32768
	ds_read_b128 v[202:205], v158 offset:33792
	ds_read_b128 v[206:209], v159 offset:32768
	ds_read_b128 v[212:215], v159 offset:33792
	ds_read_b128 v[216:219], v160 offset:32768
	ds_read_b128 v[220:223], v160 offset:33792
	ds_read_b128 v[224:227], v161 offset:32768
	ds_read_b128 v[228:231], v161 offset:33792
	global_load_lds_dwordx4 v[240:241], off
	v_lshl_add_u64 v[240:241], s[48:49], 0, v[130:131]
	v_readfirstlane_b32 s48, v147
	s_mov_b32 m0, s48
	s_nop 0
	global_load_lds_dwordx4 v[240:241], off
	s_waitcnt vmcnt(8)
	s_waitcnt lgkmcnt(0)
	s_barrier
	s_setprio 1
	s_waitcnt lgkmcnt(0)
	v_mfma_f32_16x16x32_bf16 v[124:127], v[198:201], v[166:169], v[124:127]
	v_mfma_f32_16x16x32_bf16 v[120:123], v[198:201], v[174:177], v[120:123]
	v_mfma_f32_16x16x32_bf16 v[108:111], v[206:209], v[166:169], v[108:111]
	v_mfma_f32_16x16x32_bf16 v[104:107], v[206:209], v[174:177], v[104:107]
	v_mfma_f32_16x16x32_bf16 v[92:95], v[216:219], v[166:169], v[92:95]
	v_mfma_f32_16x16x32_bf16 v[88:91], v[216:219], v[174:177], v[88:91]
	v_mfma_f32_16x16x32_bf16 v[76:79], v[224:227], v[166:169], v[76:79]
	v_mfma_f32_16x16x32_bf16 v[72:75], v[224:227], v[174:177], v[72:75]
	v_mfma_f32_16x16x32_bf16 v[124:127], v[202:205], v[170:173], v[124:127]
	v_mfma_f32_16x16x32_bf16 v[120:123], v[202:205], v[178:181], v[120:123]
	v_mfma_f32_16x16x32_bf16 v[108:111], v[212:215], v[170:173], v[108:111]
	v_mfma_f32_16x16x32_bf16 v[104:107], v[212:215], v[178:181], v[104:107]
	v_mfma_f32_16x16x32_bf16 v[92:95], v[220:223], v[170:173], v[92:95]
	v_mfma_f32_16x16x32_bf16 v[88:91], v[220:223], v[178:181], v[88:91]
	v_mfma_f32_16x16x32_bf16 v[76:79], v[228:231], v[170:173], v[76:79]
	v_mfma_f32_16x16x32_bf16 v[72:75], v[228:231], v[178:181], v[72:75]
	s_setprio 0
	s_setprio 1
	v_mfma_f32_16x16x32_bf16 v[116:119], v[198:201], v[182:185], v[116:119]
	v_mfma_f32_16x16x32_bf16 v[112:115], v[198:201], v[190:193], v[112:115]
	v_mfma_f32_16x16x32_bf16 v[100:103], v[206:209], v[182:185], v[100:103]
	v_mfma_f32_16x16x32_bf16 v[96:99], v[206:209], v[190:193], v[96:99]
	v_mfma_f32_16x16x32_bf16 v[84:87], v[216:219], v[182:185], v[84:87]
	v_mfma_f32_16x16x32_bf16 v[80:83], v[216:219], v[190:193], v[80:83]
	v_mfma_f32_16x16x32_bf16 v[68:71], v[224:227], v[182:185], v[68:71]
	v_mfma_f32_16x16x32_bf16 v[64:67], v[224:227], v[190:193], v[64:67]
	v_mfma_f32_16x16x32_bf16 v[116:119], v[202:205], v[186:189], v[116:119]
	v_mfma_f32_16x16x32_bf16 v[112:115], v[202:205], v[194:197], v[112:115]
	v_mfma_f32_16x16x32_bf16 v[100:103], v[212:215], v[186:189], v[100:103]
	v_mfma_f32_16x16x32_bf16 v[96:99], v[212:215], v[194:197], v[96:99]
	v_mfma_f32_16x16x32_bf16 v[84:87], v[220:223], v[186:189], v[84:87]
	v_mfma_f32_16x16x32_bf16 v[80:83], v[220:223], v[194:197], v[80:83]
	v_mfma_f32_16x16x32_bf16 v[68:71], v[228:231], v[186:189], v[68:71]
	v_mfma_f32_16x16x32_bf16 v[64:67], v[228:231], v[194:197], v[64:67]
	s_setprio 0
	s_barrier
; #define STAGE(P, g) do { const char* g_ = (const char*)(g); \
;         __builtin_amdgcn_global_load_lds((const unsigned*)(g_ + so0), (lds_u32*)((lds_u8*)(P) + sb0), 16, 0, 0); \
;         __builtin_amdgcn_global_load_lds((const unsigned*)(g_ + so1), (lds_u32*)((lds_u8*)(P) + sb0 + 8192), 16, 0, 0); } while (0)
; #define LDA(dst, b, h) for (int m = 0; m < 4; ++m) for (int k = 0; k < 2; ++k) \
;         dst[m][k] = *reinterpret_cast<const bf16x8*>((char*)SA(b, h) + lds_byte(wr * 64 + m * 16 + fr, k * 32 + fq * 8))
; #define LDB(dst, b, h) for (int n = 0; n < 2; ++n) for (int k = 0; k < 2; ++k) \
;         dst[n][k] = *reinterpret_cast<const bf16x8*>((char*)SB(b, h) + lds_byte(wc * 32 + n * 16 + fr, k * 32 + fq * 8))
; #define MMA(ai, bj, At_, Bt_) do { __builtin_amdgcn_s_setprio(1); \
;         for (int m = 0; m < 4; ++m) for (int n = 0; n < 2; ++n) for (int k = 0; k < 2; ++k) \
;             acc[ai][bj][m][n] = __builtin_amdgcn_mfma_f32_16x16x32_bf16(At_[m][k], Bt_[n][k], acc[ai][bj][m][n], 0, 0, 0); \
;         __builtin_amdgcn_s_setprio(0); } while (0)
; template <int EPI, int K, int LNI = -1>
; DI void ph_gemm(const Params& p, const bf16_t* __restrict__ A, const bf16_t* __restrict__ Bt, int N, float* s_aux) {
;     ...
;         for (int t = 0; t < nt; t += 2) {
;             const bool last = (t == nt - 2);
;             const bf16_t* a1 = cA + (size_t)(t + 1) * kstep;
;             const bf16_t* a2 = last ? nA : cA + (size_t)(t + 2) * kstep; const bf16_t* b2 = last ? nB : cB + (size_t)(t + 2) * kstep;
;             const bf16_t* a3 = a2 + kstep; const bf16_t* b3 = b2 + kstep;
;             LDB(B0, 0, 0); LDB(B1, 0, 1); SCHED; LDA(At, 0, 0); STAGE(SA(1, 1), a1 + hstep);
;             WAIT_V(8); WAIT_L(0); BAR; MMA(0, 0, At, B0); MMA(0, 1, At, B1); BAR; SCHED;
;             LDA(At, 0, 1); STAGE(SB(0, 0), b2); STAGE(SB(0, 1), b2 + hstep); STAGE(SA(0, 0), a2);
;             WAIT_V(8); WAIT_L(0); BAR; MMA(1, 0, At, B0); MMA(1, 1, At, B1); BAR; SCHED;
;             LDB(B0, 1, 0); LDB(B1, 1, 1); SCHED; LDA(At, 1, 0); STAGE(SA(0, 1), a2 + hstep);
;             WAIT_V(8); WAIT_L(0); BAR; MMA(0, 0, At, B0); MMA(0, 1, At, B1); BAR; SCHED;
;             LDA(At, 1, 1); STAGE(SB(1, 0), b3); STAGE(SB(1, 1), b3 + hstep); STAGE(SA(1, 0), a3);
;             WAIT_V(8); WAIT_L(0); BAR; MMA(1, 0, At, B0); MMA(1, 1, At, B1); BAR; SCHED;
;         }
	v_readfirstlane_b32 s48, v148
	v_lshl_add_u64 v[232:233], v[232:233], 0, s[12:13]
	s_mov_b32 m0, s48
	v_readfirstlane_b32 s48, v149
	s_add_u32 s46, s46, 0x40080
	ds_read_b128 v[198:201], v158 offset:49152
	ds_read_b128 v[202:205], v158 offset:50176
	ds_read_b128 v[206:209], v159 offset:49152
	ds_read_b128 v[212:215], v159 offset:50176
	ds_read_b128 v[216:219], v160 offset:49152
	ds_read_b128 v[220:223], v160 offset:50176
	ds_read_b128 v[224:227], v161 offset:49152
	ds_read_b128 v[228:231], v161 offset:50176
	global_load_lds_dwordx4 v[232:233], off
	v_lshl_add_u64 v[232:233], v[234:235], 0, s[12:13]
	s_mov_b32 m0, s48
	s_addc_u32 s47, s47, 0
	v_readfirstlane_b32 s48, v152
	global_load_lds_dwordx4 v[232:233], off
	v_lshl_add_u64 v[232:233], s[46:47], 0, v[128:129]
	s_mov_b32 m0, s48
	s_nop 0
	global_load_lds_dwordx4 v[232:233], off
	v_lshl_add_u64 v[232:233], s[46:47], 0, v[130:131]
	v_readfirstlane_b32 s46, v153
	s_mov_b32 m0, s46
	v_readfirstlane_b32 s46, v150
	global_load_lds_dwordx4 v[232:233], off
	v_lshl_add_u64 v[232:233], v[236:237], 0, s[12:13]
	s_mov_b32 m0, s46
	v_readfirstlane_b32 s46, v151
	global_load_lds_dwordx4 v[232:233], off
	v_lshl_add_u64 v[232:233], v[238:239], 0, s[12:13]
	s_mov_b32 m0, s46
	s_nop 0
	global_load_lds_dwordx4 v[232:233], off
	s_waitcnt vmcnt(8)
	s_waitcnt lgkmcnt(0)
	s_barrier
	s_setprio 1
	s_waitcnt lgkmcnt(0)
	v_mfma_f32_16x16x32_bf16 v[60:63], v[198:201], v[166:169], v[60:63]
	v_mfma_f32_16x16x32_bf16 v[56:59], v[198:201], v[174:177], v[56:59]
	v_mfma_f32_16x16x32_bf16 v[44:47], v[206:209], v[166:169], v[44:47]
	v_mfma_f32_16x16x32_bf16 v[40:43], v[206:209], v[174:177], v[40:43]
	v_mfma_f32_16x16x32_bf16 v[28:31], v[216:219], v[166:169], v[28:31]
	v_mfma_f32_16x16x32_bf16 v[24:27], v[216:219], v[174:177], v[24:27]
	v_mfma_f32_16x16x32_bf16 v[12:15], v[224:227], v[166:169], v[12:15]
	v_mfma_f32_16x16x32_bf16 v[8:11], v[224:227], v[174:177], v[8:11]
	v_mfma_f32_16x16x32_bf16 v[60:63], v[202:205], v[170:173], v[60:63]
	v_mfma_f32_16x16x32_bf16 v[56:59], v[202:205], v[178:181], v[56:59]
	v_mfma_f32_16x16x32_bf16 v[44:47], v[212:215], v[170:173], v[44:47]
	v_mfma_f32_16x16x32_bf16 v[40:43], v[212:215], v[178:181], v[40:43]
	v_mfma_f32_16x16x32_bf16 v[28:31], v[220:223], v[170:173], v[28:31]
	v_mfma_f32_16x16x32_bf16 v[24:27], v[220:223], v[178:181], v[24:27]
	v_mfma_f32_16x16x32_bf16 v[12:15], v[228:231], v[170:173], v[12:15]
	v_mfma_f32_16x16x32_bf16 v[8:11], v[228:231], v[178:181], v[8:11]
	s_setprio 0
	s_setprio 1
	v_mfma_f32_16x16x32_bf16 v[52:55], v[198:201], v[182:185], v[52:55]
	v_mfma_f32_16x16x32_bf16 v[48:51], v[198:201], v[190:193], v[48:51]
	v_mfma_f32_16x16x32_bf16 v[36:39], v[206:209], v[182:185], v[36:39]
	v_mfma_f32_16x16x32_bf16 v[32:35], v[206:209], v[190:193], v[32:35]
	v_mfma_f32_16x16x32_bf16 v[20:23], v[216:219], v[182:185], v[20:23]
	v_mfma_f32_16x16x32_bf16 v[16:19], v[216:219], v[190:193], v[16:19]
	v_mfma_f32_16x16x32_bf16 v[4:7], v[224:227], v[182:185], v[4:7]
	v_mfma_f32_16x16x32_bf16 v[0:3], v[224:227], v[190:193], v[0:3]
	v_mfma_f32_16x16x32_bf16 v[52:55], v[202:205], v[186:189], v[52:55]
	v_mfma_f32_16x16x32_bf16 v[48:51], v[202:205], v[194:197], v[48:51]
	v_mfma_f32_16x16x32_bf16 v[36:39], v[212:215], v[186:189], v[36:39]
	v_mfma_f32_16x16x32_bf16 v[32:35], v[212:215], v[194:197], v[32:35]
	v_mfma_f32_16x16x32_bf16 v[20:23], v[220:223], v[186:189], v[20:23]
	v_mfma_f32_16x16x32_bf16 v[16:19], v[220:223], v[194:197], v[16:19]
	v_mfma_f32_16x16x32_bf16 v[4:7], v[228:231], v[186:189], v[4:7]
	v_mfma_f32_16x16x32_bf16 v[0:3], v[228:231], v[194:197], v[0:3]
	s_setprio 0
	s_add_i32 s68, s68, 2
	s_add_u32 s44, s44, 0x100
	s_addc_u32 s45, s45, 0
	s_cmp_gt_u32 s68, 13
	s_barrier
.LBB0_1853:
	ds_read_b128 v[166:169], v156
	ds_read_b128 v[170:173], v156 offset:1024
	ds_read_b128 v[174:177], v156 offset:2048
	ds_read_b128 v[178:181], v156 offset:3072
	ds_read_b128 v[182:185], v157
	ds_read_b128 v[186:189], v157 offset:1024
	ds_read_b128 v[190:193], v157 offset:2048
	ds_read_b128 v[194:197], v157 offset:3072
	s_add_u32 s46, s60, s44
	s_addc_u32 s47, s61, s45
	s_add_u32 s46, s46, 0xb840100
	s_addc_u32 s47, s47, 0
	s_add_u32 s69, s66, s44
	s_addc_u32 s70, s67, s45
	s_cmpk_eq_i32 s44, 0x700
	s_cselect_b32 s49, s52, s47
	s_cselect_b32 s48, s21, s46
	s_cselect_b32 s47, s53, s70
	s_cselect_b32 s46, s23, s69
	v_readfirstlane_b32 s69, v162
	v_lshl_add_u64 v[232:233], v[136:137], 0, s[44:45]
	s_mov_b32 m0, s69
	v_readfirstlane_b32 s69, v163
	ds_read_b128 v[198:201], v158
	ds_read_b128 v[202:205], v158 offset:1024
	ds_read_b128 v[206:209], v159
	ds_read_b128 v[212:215], v159 offset:1024
	ds_read_b128 v[216:219], v160
	ds_read_b128 v[220:223], v160 offset:1024
	ds_read_b128 v[224:227], v161
	ds_read_b128 v[228:231], v161 offset:1024
	global_load_lds_dwordx4 v[232:233], off
	v_lshl_add_u64 v[232:233], v[138:139], 0, s[44:45]
	s_mov_b32 m0, s69
	s_nop 0
	global_load_lds_dwordx4 v[232:233], off
	s_waitcnt vmcnt(8)
	s_waitcnt lgkmcnt(0)
	s_barrier
; #define STAGE(P, g) do { const char* g_ = (const char*)(g); \
;         __builtin_amdgcn_global_load_lds((const unsigned*)(g_ + so0), (lds_u32*)((lds_u8*)(P) + sb0), 16, 0, 0); \
;         __builtin_amdgcn_global_load_lds((const unsigned*)(g_ + so1), (lds_u32*)((lds_u8*)(P) + sb0 + 8192), 16, 0, 0); } while (0)
; #define LDA(dst, b, h) for (int m = 0; m < 4; ++m) for (int k = 0; k < 2; ++k) \
;         dst[m][k] = *reinterpret_cast<const bf16x8*>((char*)SA(b, h) + lds_byte(wr * 64 + m * 16 + fr, k * 32 + fq * 8))
; #define LDB(dst, b, h) for (int n = 0; n < 2; ++n) for (int k = 0; k < 2; ++k) \
;         dst[n][k] = *reinterpret_cast<const bf16x8*>((char*)SB(b, h) + lds_byte(wc * 32 + n * 16 + fr, k * 32 + fq * 8))
; #define MMA(ai, bj, At_, Bt_) do { __builtin_amdgcn_s_setprio(1); \
;         for (int m = 0; m < 4; ++m) for (int n = 0; n < 2; ++n) for (int k = 0; k < 2; ++k) \
;             acc[ai][bj][m][n] = __builtin_amdgcn_mfma_f32_16x16x32_bf16(At_[m][k], Bt_[n][k], acc[ai][bj][m][n], 0, 0, 0); \
;         __builtin_amdgcn_s_setprio(0); } while (0)
; #define WAIT_V(n) asm volatile("s_waitcnt vmcnt(" #n ")" ::: "memory")
; #define WAIT_L(n) asm volatile("s_waitcnt lgkmcnt(" #n ")" ::: "memory")
; #define BAR __builtin_amdgcn_s_barrier()
; #define SCHED __builtin_amdgcn_sched_barrier(0)
; template <int EPI, int K, int LNI = -1>
; DI void ph_gemm(const Params& p, const bf16_t* __restrict__ A, const bf16_t* __restrict__ Bt, int N, float* s_aux) {
;     ...
;             LDB(B0, 0, 0); LDB(B1, 0, 1); SCHED; LDA(At, 0, 0); STAGE(SA(1, 1), a1 + hstep);
;             WAIT_V(8); WAIT_L(0); BAR; MMA(0, 0, At, B0); MMA(0, 1, At, B1); BAR; SCHED;
;             LDA(At, 0, 1); STAGE(SB(0, 0), b2); STAGE(SB(0, 1), b2 + hstep); STAGE(SA(0, 0), a2);
;             WAIT_V(8); WAIT_L(0); BAR; MMA(1, 0, At, B0); MMA(1, 1, At, B1); BAR; SCHED;
;             LDB(B0, 1, 0); LDB(B1, 1, 1); SCHED; LDA(At, 1, 0); STAGE(SA(0, 1), a2 + hstep);
;             WAIT_V(8); WAIT_L(0); BAR; MMA(0, 0, At, B0); MMA(0, 1, At, B1); BAR; SCHED;
;             LDA(At, 1, 1); STAGE(SB(1, 0), b3); STAGE(SB(1, 1), b3 + hstep); STAGE(SA(1, 0), a3);
;             WAIT_V(8); WAIT_L(0); BAR; MMA(1, 0, At, B0); MMA(1, 1, At, B1); BAR; SCHED;
	s_setprio 1
	s_waitcnt lgkmcnt(0)
	v_mfma_f32_16x16x32_bf16 v[124:127], v[198:201], v[166:169], v[124:127]
	v_mfma_f32_16x16x32_bf16 v[120:123], v[198:201], v[174:177], v[120:123]
	v_mfma_f32_16x16x32_bf16 v[108:111], v[206:209], v[166:169], v[108:111]
	v_mfma_f32_16x16x32_bf16 v[104:107], v[206:209], v[174:177], v[104:107]
	v_mfma_f32_16x16x32_bf16 v[92:95], v[216:219], v[166:169], v[92:95]
	v_mfma_f32_16x16x32_bf16 v[88:91], v[216:219], v[174:177], v[88:91]
	v_mfma_f32_16x16x32_bf16 v[76:79], v[224:227], v[166:169], v[76:79]
	v_mfma_f32_16x16x32_bf16 v[72:75], v[224:227], v[174:177], v[72:75]
	v_mfma_f32_16x16x32_bf16 v[124:127], v[202:205], v[170:173], v[124:127]
	v_mfma_f32_16x16x32_bf16 v[120:123], v[202:205], v[178:181], v[120:123]
	v_mfma_f32_16x16x32_bf16 v[108:111], v[212:215], v[170:173], v[108:111]
	v_mfma_f32_16x16x32_bf16 v[104:107], v[212:215], v[178:181], v[104:107]
	v_mfma_f32_16x16x32_bf16 v[92:95], v[220:223], v[170:173], v[92:95]
	v_mfma_f32_16x16x32_bf16 v[88:91], v[220:223], v[178:181], v[88:91]
	v_mfma_f32_16x16x32_bf16 v[76:79], v[228:231], v[170:173], v[76:79]
	v_mfma_f32_16x16x32_bf16 v[72:75], v[228:231], v[178:181], v[72:75]
	s_setprio 0
	s_setprio 1
	v_mfma_f32_16x16x32_bf16 v[116:119], v[198:201], v[182:185], v[116:119]
	v_mfma_f32_16x16x32_bf16 v[112:115], v[198:201], v[190:193], v[112:115]
	v_mfma_f32_16x16x32_bf16 v[100:103], v[206:209], v[182:185], v[100:103]
	v_mfma_f32_16x16x32_bf16 v[96:99], v[206:209], v[190:193], v[96:99]
	v_mfma_f32_16x16x32_bf16 v[84:87], v[216:219], v[182:185], v[84:87]
	v_mfma_f32_16x16x32_bf16 v[80:83], v[216:219], v[190:193], v[80:83]
	v_mfma_f32_16x16x32_bf16 v[68:71], v[224:227], v[182:185], v[68:71]
	v_mfma_f32_16x16x32_bf16 v[64:67], v[224:227], v[190:193], v[64:67]
	v_mfma_f32_16x16x32_bf16 v[116:119], v[202:205], v[186:189], v[116:119]
	v_mfma_f32_16x16x32_bf16 v[112:115], v[202:205], v[194:197], v[112:115]
	v_mfma_f32_16x16x32_bf16 v[100:103], v[212:215], v[186:189], v[100:103]
	v_mfma_f32_16x16x32_bf16 v[96:99], v[212:215], v[194:197], v[96:99]
	v_mfma_f32_16x16x32_bf16 v[84:87], v[220:223], v[186:189], v[84:87]
	v_mfma_f32_16x16x32_bf16 v[80:83], v[220:223], v[194:197], v[80:83]
	v_mfma_f32_16x16x32_bf16 v[68:71], v[228:231], v[186:189], v[68:71]
	v_mfma_f32_16x16x32_bf16 v[64:67], v[228:231], v[194:197], v[64:67]
	s_setprio 0
	s_barrier
	v_readfirstlane_b32 s69, v140
	v_lshl_add_u64 v[232:233], s[46:47], 0, v[128:129]
	s_mov_b32 m0, s69
	v_readfirstlane_b32 s69, v141
	s_add_u32 s70, s46, 0x40000
	ds_read_b128 v[198:201], v158 offset:16384
	ds_read_b128 v[202:205], v158 offset:17408
	ds_read_b128 v[206:209], v159 offset:16384
	ds_read_b128 v[212:215], v159 offset:17408
	ds_read_b128 v[216:219], v160 offset:16384
	ds_read_b128 v[220:223], v160 offset:17408
	ds_read_b128 v[224:227], v161 offset:16384
	ds_read_b128 v[228:231], v161 offset:17408
	global_load_lds_dwordx4 v[232:233], off
	v_lshl_add_u64 v[234:235], s[46:47], 0, v[130:131]
	s_mov_b32 m0, s69
	s_addc_u32 s71, s47, 0
	v_readfirstlane_b32 s69, v142
	global_load_lds_dwordx4 v[234:235], off
	v_lshl_add_u64 v[236:237], s[70:71], 0, v[128:129]
	s_mov_b32 m0, s69
	v_readfirstlane_b32 s69, v143
	global_load_lds_dwordx4 v[236:237], off
	v_lshl_add_u64 v[236:237], s[70:71], 0, v[130:131]
	s_mov_b32 m0, s69
	v_readfirstlane_b32 s69, v144
	global_load_lds_dwordx4 v[236:237], off
	v_lshl_add_u64 v[236:237], s[48:49], 0, v[128:129]
	s_mov_b32 m0, s69
	v_readfirstlane_b32 s69, v145
	global_load_lds_dwordx4 v[236:237], off
	v_lshl_add_u64 v[238:239], s[48:49], 0, v[130:131]
	s_mov_b32 m0, s69
	s_nop 0
	global_load_lds_dwordx4 v[238:239], off
	s_waitcnt vmcnt(8)
	s_waitcnt lgkmcnt(0)
	s_barrier
	s_setprio 1
	s_waitcnt lgkmcnt(0)
	v_mfma_f32_16x16x32_bf16 v[60:63], v[198:201], v[166:169], v[60:63]
	v_mfma_f32_16x16x32_bf16 v[56:59], v[198:201], v[174:177], v[56:59]
	v_mfma_f32_16x16x32_bf16 v[44:47], v[206:209], v[166:169], v[44:47]
	v_mfma_f32_16x16x32_bf16 v[40:43], v[206:209], v[174:177], v[40:43]
	v_mfma_f32_16x16x32_bf16 v[28:31], v[216:219], v[166:169], v[28:31]
	v_mfma_f32_16x16x32_bf16 v[24:27], v[216:219], v[174:177], v[24:27]
	v_mfma_f32_16x16x32_bf16 v[12:15], v[224:227], v[166:169], v[12:15]
	v_mfma_f32_16x16x32_bf16 v[8:11], v[224:227], v[174:177], v[8:11]
	v_mfma_f32_16x16x32_bf16 v[60:63], v[202:205], v[170:173], v[60:63]
	v_mfma_f32_16x16x32_bf16 v[56:59], v[202:205], v[178:181], v[56:59]
	v_mfma_f32_16x16x32_bf16 v[44:47], v[212:215], v[170:173], v[44:47]
	v_mfma_f32_16x16x32_bf16 v[40:43], v[212:215], v[178:181], v[40:43]
	v_mfma_f32_16x16x32_bf16 v[28:31], v[220:223], v[170:173], v[28:31]
	v_mfma_f32_16x16x32_bf16 v[24:27], v[220:223], v[178:181], v[24:27]
	v_mfma_f32_16x16x32_bf16 v[12:15], v[228:231], v[170:173], v[12:15]
	v_mfma_f32_16x16x32_bf16 v[8:11], v[228:231], v[178:181], v[8:11]
	s_setprio 0
	s_setprio 1
	v_mfma_f32_16x16x32_bf16 v[52:55], v[198:201], v[182:185], v[52:55]
	v_mfma_f32_16x16x32_bf16 v[48:51], v[198:201], v[190:193], v[48:51]
	v_mfma_f32_16x16x32_bf16 v[36:39], v[206:209], v[182:185], v[36:39]
	v_mfma_f32_16x16x32_bf16 v[32:35], v[206:209], v[190:193], v[32:35]
	v_mfma_f32_16x16x32_bf16 v[20:23], v[216:219], v[182:185], v[20:23]
	v_mfma_f32_16x16x32_bf16 v[16:19], v[216:219], v[190:193], v[16:19]
	v_mfma_f32_16x16x32_bf16 v[4:7], v[224:227], v[182:185], v[4:7]
	v_mfma_f32_16x16x32_bf16 v[0:3], v[224:227], v[190:193], v[0:3]
	v_mfma_f32_16x16x32_bf16 v[52:55], v[202:205], v[186:189], v[52:55]
	v_mfma_f32_16x16x32_bf16 v[48:51], v[202:205], v[194:197], v[48:51]
	v_mfma_f32_16x16x32_bf16 v[36:39], v[212:215], v[186:189], v[36:39]
	v_mfma_f32_16x16x32_bf16 v[32:35], v[212:215], v[194:197], v[32:35]
	v_mfma_f32_16x16x32_bf16 v[20:23], v[220:223], v[186:189], v[20:23]
	v_mfma_f32_16x16x32_bf16 v[16:19], v[220:223], v[194:197], v[16:19]
	v_mfma_f32_16x16x32_bf16 v[4:7], v[228:231], v[186:189], v[4:7]
	v_mfma_f32_16x16x32_bf16 v[0:3], v[228:231], v[194:197], v[0:3]
	s_setprio 0
	s_barrier
; #define STAGE(P, g) do { const char* g_ = (const char*)(g); \
;         __builtin_amdgcn_global_load_lds((const unsigned*)(g_ + so0), (lds_u32*)((lds_u8*)(P) + sb0), 16, 0, 0); \
;         __builtin_amdgcn_global_load_lds((const unsigned*)(g_ + so1), (lds_u32*)((lds_u8*)(P) + sb0 + 8192), 16, 0, 0); } while (0)
; #define LDA(dst, b, h) for (int m = 0; m < 4; ++m) for (int k = 0; k < 2; ++k) \
;         dst[m][k] = *reinterpret_cast<const bf16x8*>((char*)SA(b, h) + lds_byte(wr * 64 + m * 16 + fr, k * 32 + fq * 8))
; #define LDB(dst, b, h) for (int n = 0; n < 2; ++n) for (int k = 0; k < 2; ++k) \
;         dst[n][k] = *reinterpret_cast<const bf16x8*>((char*)SB(b, h) + lds_byte(wc * 32 + n * 16 + fr, k * 32 + fq * 8))
; #define MMA(ai, bj, At_, Bt_) do { __builtin_amdgcn_s_setprio(1); \
;         for (int m = 0; m < 4; ++m) for (int n = 0; n < 2; ++n) for (int k = 0; k < 2; ++k) \
;             acc[ai][bj][m][n] = __builtin_amdgcn_mfma_f32_16x16x32_bf16(At_[m][k], Bt_[n][k], acc[ai][bj][m][n], 0, 0, 0); \
;         __builtin_amdgcn_s_setprio(0); } while (0)
; #define WAIT_V(n) asm volatile("s_waitcnt vmcnt(" #n ")" ::: "memory")
; #define WAIT_L(n) asm volatile("s_waitcnt lgkmcnt(" #n ")" ::: "memory")
; #define BAR __builtin_amdgcn_s_barrier()
; #define SCHED __builtin_amdgcn_sched_barrier(0)
; template <int EPI, int K, int LNI = -1>
; DI void ph_gemm(const Params& p, const bf16_t* __restrict__ A, const bf16_t* __restrict__ Bt, int N, float* s_aux) {
;     ...
;             LDB(B0, 1, 0); LDB(B1, 1, 1); SCHED; LDA(At, 1, 0); STAGE(SA(0, 1), a2 + hstep);
;             WAIT_V(8); WAIT_L(0); BAR; MMA(0, 0, At, B0); MMA(0, 1, At, B1); BAR; SCHED;
	ds_read_b128 v[166:169], v164
	ds_read_b128 v[170:173], v164 offset:1024
	ds_read_b128 v[174:177], v164 offset:2048
	ds_read_b128 v[178:181], v164 offset:3072
	ds_read_b128 v[182:185], v165
	ds_read_b128 v[186:189], v165 offset:1024
	ds_read_b128 v[190:193], v165 offset:2048
	ds_read_b128 v[194:197], v165 offset:3072
	s_add_u32 s48, s48, 0x40000
	s_addc_u32 s49, s49, 0
	v_readfirstlane_b32 s69, v146
	v_lshl_add_u64 v[240:241], s[48:49], 0, v[128:129]
	s_mov_b32 m0, s69
	ds_read_b128 v[198:201], v158 offset:32768
	ds_read_b128 v[202:205], v158 offset:33792
	ds_read_b128 v[206:209], v159 offset:32768
	ds_read_b128 v[212:215], v159 offset:33792
	ds_read_b128 v[216:219], v160 offset:32768
	ds_read_b128 v[220:223], v160 offset:33792
	ds_read_b128 v[224:227], v161 offset:32768
	ds_read_b128 v[228:231], v161 offset:33792
	global_load_lds_dwordx4 v[240:241], off
	v_lshl_add_u64 v[240:241], s[48:49], 0, v[130:131]
	v_readfirstlane_b32 s48, v147
	s_mov_b32 m0, s48
	s_nop 0
	global_load_lds_dwordx4 v[240:241], off
	s_waitcnt vmcnt(8)
	s_waitcnt lgkmcnt(0)
	s_barrier
	s_setprio 1
	s_waitcnt lgkmcnt(0)
	v_mfma_f32_16x16x32_bf16 v[124:127], v[198:201], v[166:169], v[124:127]
	v_mfma_f32_16x16x32_bf16 v[120:123], v[198:201], v[174:177], v[120:123]
	v_mfma_f32_16x16x32_bf16 v[108:111], v[206:209], v[166:169], v[108:111]
	v_mfma_f32_16x16x32_bf16 v[104:107], v[206:209], v[174:177], v[104:107]
	v_mfma_f32_16x16x32_bf16 v[92:95], v[216:219], v[166:169], v[92:95]
	v_mfma_f32_16x16x32_bf16 v[88:91], v[216:219], v[174:177], v[88:91]
	v_mfma_f32_16x16x32_bf16 v[76:79], v[224:227], v[166:169], v[76:79]
	v_mfma_f32_16x16x32_bf16 v[72:75], v[224:227], v[174:177], v[72:75]
	v_mfma_f32_16x16x32_bf16 v[124:127], v[202:205], v[170:173], v[124:127]
	v_mfma_f32_16x16x32_bf16 v[120:123], v[202:205], v[178:181], v[120:123]
	v_mfma_f32_16x16x32_bf16 v[108:111], v[212:215], v[170:173], v[108:111]
	v_mfma_f32_16x16x32_bf16 v[104:107], v[212:215], v[178:181], v[104:107]
	v_mfma_f32_16x16x32_bf16 v[92:95], v[220:223], v[170:173], v[92:95]
	v_mfma_f32_16x16x32_bf16 v[88:91], v[220:223], v[178:181], v[88:91]
	v_mfma_f32_16x16x32_bf16 v[76:79], v[228:231], v[170:173], v[76:79]
	v_mfma_f32_16x16x32_bf16 v[72:75], v[228:231], v[178:181], v[72:75]
	s_setprio 0
	s_setprio 1
	v_mfma_f32_16x16x32_bf16 v[116:119], v[198:201], v[182:185], v[116:119]
	v_mfma_f32_16x16x32_bf16 v[112:115], v[198:201], v[190:193], v[112:115]
	v_mfma_f32_16x16x32_bf16 v[100:103], v[206:209], v[182:185], v[100:103]
	v_mfma_f32_16x16x32_bf16 v[96:99], v[206:209], v[190:193], v[96:99]
	v_mfma_f32_16x16x32_bf16 v[84:87], v[216:219], v[182:185], v[84:87]
	v_mfma_f32_16x16x32_bf16 v[80:83], v[216:219], v[190:193], v[80:83]
	v_mfma_f32_16x16x32_bf16 v[68:71], v[224:227], v[182:185], v[68:71]
	v_mfma_f32_16x16x32_bf16 v[64:67], v[224:227], v[190:193], v[64:67]
	v_mfma_f32_16x16x32_bf16 v[116:119], v[202:205], v[186:189], v[116:119]
	v_mfma_f32_16x16x32_bf16 v[112:115], v[202:205], v[194:197], v[112:115]
	v_mfma_f32_16x16x32_bf16 v[100:103], v[212:215], v[186:189], v[100:103]
	v_mfma_f32_16x16x32_bf16 v[96:99], v[212:215], v[194:197], v[96:99]
	v_mfma_f32_16x16x32_bf16 v[84:87], v[220:223], v[186:189], v[84:87]
	v_mfma_f32_16x16x32_bf16 v[80:83], v[220:223], v[194:197], v[80:83]
	v_mfma_f32_16x16x32_bf16 v[68:71], v[228:231], v[186:189], v[68:71]
	v_mfma_f32_16x16x32_bf16 v[64:67], v[228:231], v[194:197], v[64:67]
	s_setprio 0
	s_barrier
; #define STAGE(P, g) do { const char* g_ = (const char*)(g); \
;         __builtin_amdgcn_global_load_lds((const unsigned*)(g_ + so0), (lds_u32*)((lds_u8*)(P) + sb0), 16, 0, 0); \
;         __builtin_amdgcn_global_load_lds((const unsigned*)(g_ + so1), (lds_u32*)((lds_u8*)(P) + sb0 + 8192), 16, 0, 0); } while (0)
; #define LDA(dst, b, h) for (int m = 0; m < 4; ++m) for (int k = 0; k < 2; ++k) \
;         dst[m][k] = *reinterpret_cast<const bf16x8*>((char*)SA(b, h) + lds_byte(wr * 64 + m * 16 + fr, k * 32 + fq * 8))
; #define MMA(ai, bj, At_, Bt_) do { __builtin_amdgcn_s_setprio(1); \
;         for (int m = 0; m < 4; ++m) for (int n = 0; n < 2; ++n) for (int k = 0; k < 2; ++k) \
;             acc[ai][bj][m][n] = __builtin_amdgcn_mfma_f32_16x16x32_bf16(At_[m][k], Bt_[n][k], acc[ai][bj][m][n], 0, 0, 0); \
;         __builtin_amdgcn_s_setprio(0); } while (0)
; #define WAIT_V(n) asm volatile("s_waitcnt vmcnt(" #n ")" ::: "memory")
; #define WAIT_L(n) asm volatile("s_waitcnt lgkmcnt(" #n ")" ::: "memory")
; #define BAR __builtin_amdgcn_s_barrier()
; #define SCHED __builtin_amdgcn_sched_barrier(0)
; template <int EPI, int K, int LNI = -1>
; DI void ph_gemm(const Params& p, const bf16_t* __restrict__ A, const bf16_t* __restrict__ Bt, int N, float* s_aux) {
;     ...
;             LDA(At, 1, 1); STAGE(SB(1, 0), b3); STAGE(SB(1, 1), b3 + hstep); STAGE(SA(1, 0), a3);
;             WAIT_V(8); WAIT_L(0); BAR; MMA(1, 0, At, B0); MMA(1, 1, At, B1); BAR; SCHED;
;         }
	v_readfirstlane_b32 s48, v148
	v_lshl_add_u64 v[232:233], v[232:233], 0, s[12:13]
	s_mov_b32 m0, s48
	v_readfirstlane_b32 s48, v149
	s_add_u32 s46, s46, 0x40080
	ds_read_b128 v[198:201], v158 offset:49152
	ds_read_b128 v[202:205], v158 offset:50176
	ds_read_b128 v[206:209], v159 offset:49152
	ds_read_b128 v[212:215], v159 offset:50176
	ds_read_b128 v[216:219], v160 offset:49152
	ds_read_b128 v[220:223], v160 offset:50176
	ds_read_b128 v[224:227], v161 offset:49152
	ds_read_b128 v[228:231], v161 offset:50176
	global_load_lds_dwordx4 v[232:233], off
	v_lshl_add_u64 v[232:233], v[234:235], 0, s[12:13]
	s_mov_b32 m0, s48
	s_addc_u32 s47, s47, 0
	v_readfirstlane_b32 s48, v152
	global_load_lds_dwordx4 v[232:233], off
	v_lshl_add_u64 v[232:233], s[46:47], 0, v[128:129]
	s_mov_b32 m0, s48
	s_nop 0
	global_load_lds_dwordx4 v[232:233], off
	v_lshl_add_u64 v[232:233], s[46:47], 0, v[130:131]
	v_readfirstlane_b32 s46, v153
	s_mov_b32 m0, s46
	v_readfirstlane_b32 s46, v150
	global_load_lds_dwordx4 v[232:233], off
	v_lshl_add_u64 v[232:233], v[236:237], 0, s[12:13]
	s_mov_b32 m0, s46
	v_readfirstlane_b32 s46, v151
	global_load_lds_dwordx4 v[232:233], off
	v_lshl_add_u64 v[232:233], v[238:239], 0, s[12:13]
	s_mov_b32 m0, s46
	s_nop 0
	global_load_lds_dwordx4 v[232:233], off
	s_waitcnt vmcnt(8)
	s_waitcnt lgkmcnt(0)
	s_barrier
	s_setprio 1
	s_waitcnt lgkmcnt(0)
	v_mfma_f32_16x16x32_bf16 v[60:63], v[198:201], v[166:169], v[60:63]
	v_mfma_f32_16x16x32_bf16 v[56:59], v[198:201], v[174:177], v[56:59]
	v_mfma_f32_16x16x32_bf16 v[44:47], v[206:209], v[166:169], v[44:47]
	v_mfma_f32_16x16x32_bf16 v[40:43], v[206:209], v[174:177], v[40:43]
	v_mfma_f32_16x16x32_bf16 v[28:31], v[216:219], v[166:169], v[28:31]
	v_mfma_f32_16x16x32_bf16 v[24:27], v[216:219], v[174:177], v[24:27]
	v_mfma_f32_16x16x32_bf16 v[12:15], v[224:227], v[166:169], v[12:15]
	v_mfma_f32_16x16x32_bf16 v[8:11], v[224:227], v[174:177], v[8:11]
	v_mfma_f32_16x16x32_bf16 v[60:63], v[202:205], v[170:173], v[60:63]
	v_mfma_f32_16x16x32_bf16 v[56:59], v[202:205], v[178:181], v[56:59]
	v_mfma_f32_16x16x32_bf16 v[44:47], v[212:215], v[170:173], v[44:47]
	v_mfma_f32_16x16x32_bf16 v[40:43], v[212:215], v[178:181], v[40:43]
	v_mfma_f32_16x16x32_bf16 v[28:31], v[220:223], v[170:173], v[28:31]
	v_mfma_f32_16x16x32_bf16 v[24:27], v[220:223], v[178:181], v[24:27]
	v_mfma_f32_16x16x32_bf16 v[12:15], v[228:231], v[170:173], v[12:15]
	v_mfma_f32_16x16x32_bf16 v[8:11], v[228:231], v[178:181], v[8:11]
	s_setprio 0
	s_setprio 1
	v_mfma_f32_16x16x32_bf16 v[52:55], v[198:201], v[182:185], v[52:55]
	v_mfma_f32_16x16x32_bf16 v[48:51], v[198:201], v[190:193], v[48:51]
	v_mfma_f32_16x16x32_bf16 v[36:39], v[206:209], v[182:185], v[36:39]
	v_mfma_f32_16x16x32_bf16 v[32:35], v[206:209], v[190:193], v[32:35]
	v_mfma_f32_16x16x32_bf16 v[20:23], v[216:219], v[182:185], v[20:23]
	v_mfma_f32_16x16x32_bf16 v[16:19], v[216:219], v[190:193], v[16:19]
	v_mfma_f32_16x16x32_bf16 v[4:7], v[224:227], v[182:185], v[4:7]
	v_mfma_f32_16x16x32_bf16 v[0:3], v[224:227], v[190:193], v[0:3]
	v_mfma_f32_16x16x32_bf16 v[52:55], v[202:205], v[186:189], v[52:55]
	v_mfma_f32_16x16x32_bf16 v[48:51], v[202:205], v[194:197], v[48:51]
	v_mfma_f32_16x16x32_bf16 v[36:39], v[212:215], v[186:189], v[36:39]
	v_mfma_f32_16x16x32_bf16 v[32:35], v[212:215], v[194:197], v[32:35]
	v_mfma_f32_16x16x32_bf16 v[20:23], v[220:223], v[186:189], v[20:23]
	v_mfma_f32_16x16x32_bf16 v[16:19], v[220:223], v[194:197], v[16:19]
	v_mfma_f32_16x16x32_bf16 v[4:7], v[228:231], v[186:189], v[4:7]
	v_mfma_f32_16x16x32_bf16 v[0:3], v[228:231], v[194:197], v[0:3]
	s_setprio 0
	s_add_i32 s68, s68, 2
	s_add_u32 s44, s44, 0x100
	s_addc_u32 s45, s45, 0
	s_cmp_gt_u32 s68, 13
	s_barrier
	s_cbranch_scc0 .LBB0_1853
	s_and_saveexec_b64 s[44:45], s[8:9]
	s_cbranch_execz .LBB0_1856
	s_barrier

; DI int opaque_tid() { int t = threadIdx.x; asm volatile("" : "+v"(t)); return t; }
; #define STAGE(P, g) do { const char* g_ = (const char*)(g); \
;         __builtin_amdgcn_global_load_lds((const unsigned*)(g_ + so0), (lds_u32*)((lds_u8*)(P) + sb0), 16, 0, 0); \
;         __builtin_amdgcn_global_load_lds((const unsigned*)(g_ + so1), (lds_u32*)((lds_u8*)(P) + sb0 + 8192), 16, 0, 0); } while (0)
; #define WAIT_V(n) asm volatile("s_waitcnt vmcnt(" #n ")" ::: "memory")
; #define WAIT_L(n) asm volatile("s_waitcnt lgkmcnt(" #n ")" ::: "memory")
; template <int EPI, int K, int LNI = -1>
; DI void ph_gemm(const Params& p, const bf16_t* __restrict__ A, const bf16_t* __restrict__ Bt, int N, float* s_aux) {
;     ...
;         const int itn = it + (int)gridDim.x;
;         const bool has_next = itn < nwg;
;         int npm = pm, npn = pn;
;         if (has_next) unit(itn, npm, npn);
;         const bf16_t* nA = A + (size_t)npm * 256 * K; const bf16_t* nB = Bt + (size_t)npn * 256 * K;
;         const int brow = pm * 256, bcol = pn * 256;
;         float* sa = s_aux + (cnt & 1) * 512;
;         if (EPI == EPI_E5B) {
;             if (opaque_tid() < 256) {
;                 const int row = brow + (int)opaque_tid(); const int hd = bcol >> 9;
;                 const float* pp = (const float*)((unsigned char*)p.out + OFFO_PART) + (size_t)row * 256 + hd * 64;
;                 float sacc = 0.f;
; #pragma unroll
;                 for (int i = 0; i < 16; ++i) { const f32x4 v = *(const f32x4*)(pp + i * 4); sacc += (v[0] + v[1]) + (v[2] + v[3]); }
;                 sa[opaque_tid()] = __frsqrt_rn(sacc * (1.0f / 512.0f) + 1e-6f);
;             }
;         }
;         for (int t = 0; t < nt; t += 2) {
;             const bool last = (t == nt - 2);
;             const bf16_t* a1 = cA + (size_t)(t + 1) * kstep;
;             const bf16_t* a2 = last ? nA : cA + (size_t)(t + 2) * kstep; const bf16_t* b2 = last ? nB : cB + (size_t)(t + 2) * kstep;
;             const bf16_t* a3 = a2 + kstep; const bf16_t* b3 = b2 + kstep;
;             LDB(B0, 0, 0); LDB(B1, 0, 1); SCHED; LDA(At, 0, 0); STAGE(SA(1, 1), a1 + hstep);
;             WAIT_V(8); WAIT_L(0); BAR; MMA(0, 0, At, B0); MMA(0, 1, At, B1); BAR; SCHED;
;             LDA(At, 0, 1); STAGE(SB(0, 0), b2); STAGE(SB(0, 1), b2 + hstep); STAGE(SA(0, 0), a2);
;             WAIT_V(8); WAIT_L(0); BAR; MMA(1, 0, At, B0); MMA(1, 1, At, B1); BAR; SCHED;
.LBB0_1929:
	s_ashr_i32 s15, s14, 31
	s_lshl_b64 s[20:21], s[14:15], 21
	s_add_u32 s15, s36, s20
	s_addc_u32 s46, s37, s21
	s_ashr_i32 s13, s12, 31
	s_lshl_b64 s[22:23], s[12:13], 21
	s_add_u32 s13, s3, s22
	s_addc_u32 s47, s35, s23
	s_add_u32 s48, s56, s28
	s_addc_u32 s49, s57, s29
	s_add_u32 s50, s42, s38
	v_lshl_add_u64 v[128:129], v[140:141], 0, s[28:29]
	v_lshl_add_u64 v[130:131], v[142:143], 0, s[28:29]
	s_addc_u32 s51, s43, s39
	s_mov_b32 s52, -2
	s_mov_b64 s[28:29], 0
	ds_read_b128 v[132:135], v177
	ds_read_b128 v[144:147], v177 offset:1024
	ds_read_b128 v[148:151], v177 offset:2048
	ds_read_b128 v[152:155], v177 offset:3072
	ds_read_b128 v[156:159], v178
	ds_read_b128 v[188:191], v178 offset:1024
	ds_read_b128 v[192:195], v178 offset:2048
	ds_read_b128 v[196:199], v178 offset:3072
	s_add_u32 s38, s48, s28
	s_addc_u32 s39, s49, s29
	s_add_u32 s38, s38, 0xfa70100
	s_addc_u32 s39, s39, 0
	s_add_u32 s53, s50, s28
	s_addc_u32 s60, s51, s29
	s_cmpk_eq_i32 s28, 0x1f00
	s_cselect_b32 s41, s46, s39
	s_cselect_b32 s40, s15, s38
	s_cselect_b32 s39, s47, s60
	s_cselect_b32 s38, s13, s53
	v_readfirstlane_b32 s53, v183
	v_lshl_add_u64 v[208:209], v[128:129], 0, s[28:29]
	s_mov_b32 m0, s53
	v_readfirstlane_b32 s53, v184
	ds_read_b128 v[200:203], v179
	ds_read_b128 v[204:207], v179 offset:1024
	ds_read_b128 v[212:215], v180
	ds_read_b128 v[216:219], v180 offset:1024
	ds_read_b128 v[220:223], v181
	ds_read_b128 v[224:227], v181 offset:1024
	ds_read_b128 v[228:231], v182
	ds_read_b128 v[232:235], v182 offset:1024
	global_load_lds_dwordx4 v[208:209], off
	v_lshl_add_u64 v[208:209], v[130:131], 0, s[28:29]
	s_mov_b32 m0, s53
	s_nop 0
	global_load_lds_dwordx4 v[208:209], off
	s_waitcnt vmcnt(8)
	s_waitcnt lgkmcnt(0)
	s_barrier
	s_setprio 1
	s_waitcnt lgkmcnt(0)
	v_mfma_f32_16x16x32_bf16 v[124:127], v[200:203], v[132:135], 0
	v_mfma_f32_16x16x32_bf16 v[120:123], v[200:203], v[148:151], 0
	v_mfma_f32_16x16x32_bf16 v[108:111], v[212:215], v[132:135], 0
	v_mfma_f32_16x16x32_bf16 v[104:107], v[212:215], v[148:151], 0
	v_mfma_f32_16x16x32_bf16 v[92:95], v[220:223], v[132:135], 0
	v_mfma_f32_16x16x32_bf16 v[88:91], v[220:223], v[148:151], 0
	v_mfma_f32_16x16x32_bf16 v[76:79], v[228:231], v[132:135], 0
	v_mfma_f32_16x16x32_bf16 v[72:75], v[228:231], v[148:151], 0
	v_mfma_f32_16x16x32_bf16 v[124:127], v[204:207], v[144:147], v[124:127]
	v_mfma_f32_16x16x32_bf16 v[120:123], v[204:207], v[152:155], v[120:123]
	v_mfma_f32_16x16x32_bf16 v[108:111], v[216:219], v[144:147], v[108:111]
	v_mfma_f32_16x16x32_bf16 v[104:107], v[216:219], v[152:155], v[104:107]
	v_mfma_f32_16x16x32_bf16 v[92:95], v[224:227], v[144:147], v[92:95]
	v_mfma_f32_16x16x32_bf16 v[88:91], v[224:227], v[152:155], v[88:91]
	v_mfma_f32_16x16x32_bf16 v[76:79], v[232:235], v[144:147], v[76:79]
	v_mfma_f32_16x16x32_bf16 v[72:75], v[232:235], v[152:155], v[72:75]
	s_setprio 0
	s_setprio 1
	v_mfma_f32_16x16x32_bf16 v[116:119], v[200:203], v[156:159], 0
	v_mfma_f32_16x16x32_bf16 v[112:115], v[200:203], v[192:195], 0
	v_mfma_f32_16x16x32_bf16 v[100:103], v[212:215], v[156:159], 0
	v_mfma_f32_16x16x32_bf16 v[96:99], v[212:215], v[192:195], 0
	v_mfma_f32_16x16x32_bf16 v[84:87], v[220:223], v[156:159], 0
	v_mfma_f32_16x16x32_bf16 v[80:83], v[220:223], v[192:195], 0
	v_mfma_f32_16x16x32_bf16 v[68:71], v[228:231], v[156:159], 0
	v_mfma_f32_16x16x32_bf16 v[64:67], v[228:231], v[192:195], 0
	v_mfma_f32_16x16x32_bf16 v[116:119], v[204:207], v[188:191], v[116:119]
	v_mfma_f32_16x16x32_bf16 v[112:115], v[204:207], v[196:199], v[112:115]
	v_mfma_f32_16x16x32_bf16 v[100:103], v[216:219], v[188:191], v[100:103]
	v_mfma_f32_16x16x32_bf16 v[96:99], v[216:219], v[196:199], v[96:99]
	v_mfma_f32_16x16x32_bf16 v[84:87], v[224:227], v[188:191], v[84:87]
	v_mfma_f32_16x16x32_bf16 v[80:83], v[224:227], v[196:199], v[80:83]
	v_mfma_f32_16x16x32_bf16 v[68:71], v[232:235], v[188:191], v[68:71]
	v_mfma_f32_16x16x32_bf16 v[64:67], v[232:235], v[196:199], v[64:67]
	s_setprio 0
	s_barrier
	v_readfirstlane_b32 s53, v160
	v_lshl_add_u64 v[208:209], s[38:39], 0, v[136:137]
	s_mov_b32 m0, s53
	v_readfirstlane_b32 s53, v161
	s_add_u32 s60, s38, 0x100000
	ds_read_b128 v[200:203], v179 offset:16384
	ds_read_b128 v[204:207], v179 offset:17408
	ds_read_b128 v[212:215], v180 offset:16384
	ds_read_b128 v[216:219], v180 offset:17408
	ds_read_b128 v[220:223], v181 offset:16384
	ds_read_b128 v[224:227], v181 offset:17408
	ds_read_b128 v[228:231], v182 offset:16384
	ds_read_b128 v[232:235], v182 offset:17408
	global_load_lds_dwordx4 v[208:209], off
	v_lshl_add_u64 v[236:237], s[38:39], 0, v[138:139]
	s_mov_b32 m0, s53
	s_addc_u32 s61, s39, 0
	v_readfirstlane_b32 s53, v162
	global_load_lds_dwordx4 v[236:237], off
	v_lshl_add_u64 v[238:239], s[60:61], 0, v[136:137]
	s_mov_b32 m0, s53
	v_readfirstlane_b32 s53, v163
	global_load_lds_dwordx4 v[238:239], off
	v_lshl_add_u64 v[238:239], s[60:61], 0, v[138:139]
	s_mov_b32 m0, s53
	v_readfirstlane_b32 s53, v164
	global_load_lds_dwordx4 v[238:239], off
	v_lshl_add_u64 v[238:239], s[40:41], 0, v[136:137]
	s_mov_b32 m0, s53
	v_readfirstlane_b32 s53, v165
	global_load_lds_dwordx4 v[238:239], off
	v_lshl_add_u64 v[240:241], s[40:41], 0, v[138:139]
	s_mov_b32 m0, s53
	s_nop 0
	global_load_lds_dwordx4 v[240:241], off
	s_waitcnt vmcnt(8)
	s_waitcnt lgkmcnt(0)
	s_barrier
; #define STAGE(P, g) do { const char* g_ = (const char*)(g); \
;         __builtin_amdgcn_global_load_lds((const unsigned*)(g_ + so0), (lds_u32*)((lds_u8*)(P) + sb0), 16, 0, 0); \
;         __builtin_amdgcn_global_load_lds((const unsigned*)(g_ + so1), (lds_u32*)((lds_u8*)(P) + sb0 + 8192), 16, 0, 0); } while (0)
; #define LDA(dst, b, h) for (int m = 0; m < 4; ++m) for (int k = 0; k < 2; ++k) \
;         dst[m][k] = *reinterpret_cast<const bf16x8*>((char*)SA(b, h) + lds_byte(wr * 64 + m * 16 + fr, k * 32 + fq * 8))
; #define LDB(dst, b, h) for (int n = 0; n < 2; ++n) for (int k = 0; k < 2; ++k) \
;         dst[n][k] = *reinterpret_cast<const bf16x8*>((char*)SB(b, h) + lds_byte(wc * 32 + n * 16 + fr, k * 32 + fq * 8))
; #define MMA(ai, bj, At_, Bt_) do { __builtin_amdgcn_s_setprio(1); \
;         for (int m = 0; m < 4; ++m) for (int n = 0; n < 2; ++n) for (int k = 0; k < 2; ++k) \
;             acc[ai][bj][m][n] = __builtin_amdgcn_mfma_f32_16x16x32_bf16(At_[m][k], Bt_[n][k], acc[ai][bj][m][n], 0, 0, 0); \
;         __builtin_amdgcn_s_setprio(0); } while (0)
; #define WAIT_V(n) asm volatile("s_waitcnt vmcnt(" #n ")" ::: "memory")
; #define WAIT_L(n) asm volatile("s_waitcnt lgkmcnt(" #n ")" ::: "memory")
; #define BAR __builtin_amdgcn_s_barrier()
; #define SCHED __builtin_amdgcn_sched_barrier(0)
; template <int EPI, int K, int LNI = -1>
; DI void ph_gemm(const Params& p, const bf16_t* __restrict__ A, const bf16_t* __restrict__ Bt, int N, float* s_aux) {
;     ...
;             WAIT_V(8); WAIT_L(0); BAR; MMA(0, 0, At, B0); MMA(0, 1, At, B1); BAR; SCHED;
;             LDA(At, 0, 1); STAGE(SB(0, 0), b2); STAGE(SB(0, 1), b2 + hstep); STAGE(SA(0, 0), a2);
;             WAIT_V(8); WAIT_L(0); BAR; MMA(1, 0, At, B0); MMA(1, 1, At, B1); BAR; SCHED;
;             LDB(B0, 1, 0); LDB(B1, 1, 1); SCHED; LDA(At, 1, 0); STAGE(SA(0, 1), a2 + hstep);
;             WAIT_V(8); WAIT_L(0); BAR; MMA(0, 0, At, B0); MMA(0, 1, At, B1); BAR; SCHED;
	s_setprio 1
	s_waitcnt lgkmcnt(0)
	v_mfma_f32_16x16x32_bf16 v[60:63], v[200:203], v[132:135], 0
	v_mfma_f32_16x16x32_bf16 v[56:59], v[200:203], v[148:151], 0
	v_mfma_f32_16x16x32_bf16 v[44:47], v[212:215], v[132:135], 0
	v_mfma_f32_16x16x32_bf16 v[40:43], v[212:215], v[148:151], 0
	v_mfma_f32_16x16x32_bf16 v[28:31], v[220:223], v[132:135], 0
	v_mfma_f32_16x16x32_bf16 v[24:27], v[220:223], v[148:151], 0
	v_mfma_f32_16x16x32_bf16 v[12:15], v[228:231], v[132:135], 0
	v_mfma_f32_16x16x32_bf16 v[8:11], v[228:231], v[148:151], 0
	v_mfma_f32_16x16x32_bf16 v[60:63], v[204:207], v[144:147], v[60:63]
	v_mfma_f32_16x16x32_bf16 v[56:59], v[204:207], v[152:155], v[56:59]
	v_mfma_f32_16x16x32_bf16 v[44:47], v[216:219], v[144:147], v[44:47]
	v_mfma_f32_16x16x32_bf16 v[40:43], v[216:219], v[152:155], v[40:43]
	v_mfma_f32_16x16x32_bf16 v[28:31], v[224:227], v[144:147], v[28:31]
	v_mfma_f32_16x16x32_bf16 v[24:27], v[224:227], v[152:155], v[24:27]
	v_mfma_f32_16x16x32_bf16 v[12:15], v[232:235], v[144:147], v[12:15]
	v_mfma_f32_16x16x32_bf16 v[8:11], v[232:235], v[152:155], v[8:11]
	s_setprio 0
	s_setprio 1
	v_mfma_f32_16x16x32_bf16 v[52:55], v[200:203], v[156:159], 0
	v_mfma_f32_16x16x32_bf16 v[48:51], v[200:203], v[192:195], 0
	v_mfma_f32_16x16x32_bf16 v[36:39], v[212:215], v[156:159], 0
	v_mfma_f32_16x16x32_bf16 v[32:35], v[212:215], v[192:195], 0
	v_mfma_f32_16x16x32_bf16 v[20:23], v[220:223], v[156:159], 0
	v_mfma_f32_16x16x32_bf16 v[16:19], v[220:223], v[192:195], 0
	v_mfma_f32_16x16x32_bf16 v[4:7], v[228:231], v[156:159], 0
	v_mfma_f32_16x16x32_bf16 v[0:3], v[228:231], v[192:195], 0
	v_mfma_f32_16x16x32_bf16 v[52:55], v[204:207], v[188:191], v[52:55]
	v_mfma_f32_16x16x32_bf16 v[48:51], v[204:207], v[196:199], v[48:51]
	v_mfma_f32_16x16x32_bf16 v[36:39], v[216:219], v[188:191], v[36:39]
	v_mfma_f32_16x16x32_bf16 v[32:35], v[216:219], v[196:199], v[32:35]
	v_mfma_f32_16x16x32_bf16 v[20:23], v[224:227], v[188:191], v[20:23]
	v_mfma_f32_16x16x32_bf16 v[16:19], v[224:227], v[196:199], v[16:19]
	v_mfma_f32_16x16x32_bf16 v[4:7], v[232:235], v[188:191], v[4:7]
	v_mfma_f32_16x16x32_bf16 v[0:3], v[232:235], v[196:199], v[0:3]
	s_setprio 0
	s_barrier
	ds_read_b128 v[132:135], v185
	ds_read_b128 v[144:147], v185 offset:1024
	ds_read_b128 v[148:151], v185 offset:2048
	ds_read_b128 v[152:155], v185 offset:3072
	ds_read_b128 v[156:159], v186
	ds_read_b128 v[188:191], v186 offset:1024
	ds_read_b128 v[192:195], v186 offset:2048
	ds_read_b128 v[196:199], v186 offset:3072
	s_add_u32 s40, s40, 0x100000
	s_addc_u32 s41, s41, 0
	v_readfirstlane_b32 s53, v166
	v_lshl_add_u64 v[242:243], s[40:41], 0, v[136:137]
	s_mov_b32 m0, s53
	ds_read_b128 v[200:203], v179 offset:32768
	ds_read_b128 v[204:207], v179 offset:33792
	ds_read_b128 v[212:215], v180 offset:32768
	ds_read_b128 v[216:219], v180 offset:33792
	ds_read_b128 v[220:223], v181 offset:32768
	ds_read_b128 v[224:227], v181 offset:33792
	ds_read_b128 v[228:231], v182 offset:32768
	ds_read_b128 v[232:235], v182 offset:33792
	global_load_lds_dwordx4 v[242:243], off
	v_lshl_add_u64 v[242:243], s[40:41], 0, v[138:139]
	v_readfirstlane_b32 s40, v167
	s_mov_b32 m0, s40
	s_nop 0
	global_load_lds_dwordx4 v[242:243], off
	s_waitcnt vmcnt(8)
	s_waitcnt lgkmcnt(0)
	s_barrier
	s_setprio 1
	s_waitcnt lgkmcnt(0)
	v_mfma_f32_16x16x32_bf16 v[124:127], v[200:203], v[132:135], v[124:127]
	v_mfma_f32_16x16x32_bf16 v[120:123], v[200:203], v[148:151], v[120:123]
	v_mfma_f32_16x16x32_bf16 v[108:111], v[212:215], v[132:135], v[108:111]
	v_mfma_f32_16x16x32_bf16 v[104:107], v[212:215], v[148:151], v[104:107]
	v_mfma_f32_16x16x32_bf16 v[92:95], v[220:223], v[132:135], v[92:95]
	v_mfma_f32_16x16x32_bf16 v[88:91], v[220:223], v[148:151], v[88:91]
	v_mfma_f32_16x16x32_bf16 v[76:79], v[228:231], v[132:135], v[76:79]
	v_mfma_f32_16x16x32_bf16 v[72:75], v[228:231], v[148:151], v[72:75]
	v_mfma_f32_16x16x32_bf16 v[124:127], v[204:207], v[144:147], v[124:127]
	v_mfma_f32_16x16x32_bf16 v[120:123], v[204:207], v[152:155], v[120:123]
	v_mfma_f32_16x16x32_bf16 v[108:111], v[216:219], v[144:147], v[108:111]
	v_mfma_f32_16x16x32_bf16 v[104:107], v[216:219], v[152:155], v[104:107]
	v_mfma_f32_16x16x32_bf16 v[92:95], v[224:227], v[144:147], v[92:95]
	v_mfma_f32_16x16x32_bf16 v[88:91], v[224:227], v[152:155], v[88:91]
	v_mfma_f32_16x16x32_bf16 v[76:79], v[232:235], v[144:147], v[76:79]
	v_mfma_f32_16x16x32_bf16 v[72:75], v[232:235], v[152:155], v[72:75]
	s_setprio 0
	s_setprio 1
	v_mfma_f32_16x16x32_bf16 v[116:119], v[200:203], v[156:159], v[116:119]
	v_mfma_f32_16x16x32_bf16 v[112:115], v[200:203], v[192:195], v[112:115]
	v_mfma_f32_16x16x32_bf16 v[100:103], v[212:215], v[156:159], v[100:103]
	v_mfma_f32_16x16x32_bf16 v[96:99], v[212:215], v[192:195], v[96:99]
	v_mfma_f32_16x16x32_bf16 v[84:87], v[220:223], v[156:159], v[84:87]
	v_mfma_f32_16x16x32_bf16 v[80:83], v[220:223], v[192:195], v[80:83]
	v_mfma_f32_16x16x32_bf16 v[68:71], v[228:231], v[156:159], v[68:71]
	v_mfma_f32_16x16x32_bf16 v[64:67], v[228:231], v[192:195], v[64:67]
	v_mfma_f32_16x16x32_bf16 v[116:119], v[204:207], v[188:191], v[116:119]
	v_mfma_f32_16x16x32_bf16 v[112:115], v[204:207], v[196:199], v[112:115]
	v_mfma_f32_16x16x32_bf16 v[100:103], v[216:219], v[188:191], v[100:103]
	v_mfma_f32_16x16x32_bf16 v[96:99], v[216:219], v[196:199], v[96:99]
	v_mfma_f32_16x16x32_bf16 v[84:87], v[224:227], v[188:191], v[84:87]
	v_mfma_f32_16x16x32_bf16 v[80:83], v[224:227], v[196:199], v[80:83]
	v_mfma_f32_16x16x32_bf16 v[68:71], v[232:235], v[188:191], v[68:71]
	v_mfma_f32_16x16x32_bf16 v[64:67], v[232:235], v[196:199], v[64:67]
	s_setprio 0
	s_barrier
; #define STAGE(P, g) do { const char* g_ = (const char*)(g); \
;         __builtin_amdgcn_global_load_lds((const unsigned*)(g_ + so0), (lds_u32*)((lds_u8*)(P) + sb0), 16, 0, 0); \
;         __builtin_amdgcn_global_load_lds((const unsigned*)(g_ + so1), (lds_u32*)((lds_u8*)(P) + sb0 + 8192), 16, 0, 0); } while (0)
; #define LDA(dst, b, h) for (int m = 0; m < 4; ++m) for (int k = 0; k < 2; ++k) \
;         dst[m][k] = *reinterpret_cast<const bf16x8*>((char*)SA(b, h) + lds_byte(wr * 64 + m * 16 + fr, k * 32 + fq * 8))
; #define LDB(dst, b, h) for (int n = 0; n < 2; ++n) for (int k = 0; k < 2; ++k) \
;         dst[n][k] = *reinterpret_cast<const bf16x8*>((char*)SB(b, h) + lds_byte(wc * 32 + n * 16 + fr, k * 32 + fq * 8))
; #define MMA(ai, bj, At_, Bt_) do { __builtin_amdgcn_s_setprio(1); \
;         for (int m = 0; m < 4; ++m) for (int n = 0; n < 2; ++n) for (int k = 0; k < 2; ++k) \
;             acc[ai][bj][m][n] = __builtin_amdgcn_mfma_f32_16x16x32_bf16(At_[m][k], Bt_[n][k], acc[ai][bj][m][n], 0, 0, 0); \
;         __builtin_amdgcn_s_setprio(0); } while (0)
; template <int EPI, int K, int LNI = -1>
; DI void ph_gemm(const Params& p, const bf16_t* __restrict__ A, const bf16_t* __restrict__ Bt, int N, float* s_aux) {
;     ...
;         for (int t = 0; t < nt; t += 2) {
;             const bool last = (t == nt - 2);
;             const bf16_t* a1 = cA + (size_t)(t + 1) * kstep;
;             const bf16_t* a2 = last ? nA : cA + (size_t)(t + 2) * kstep; const bf16_t* b2 = last ? nB : cB + (size_t)(t + 2) * kstep;
;             const bf16_t* a3 = a2 + kstep; const bf16_t* b3 = b2 + kstep;
;             LDB(B0, 0, 0); LDB(B1, 0, 1); SCHED; LDA(At, 0, 0); STAGE(SA(1, 1), a1 + hstep);
;             WAIT_V(8); WAIT_L(0); BAR; MMA(0, 0, At, B0); MMA(0, 1, At, B1); BAR; SCHED;
;             LDA(At, 0, 1); STAGE(SB(0, 0), b2); STAGE(SB(0, 1), b2 + hstep); STAGE(SA(0, 0), a2);
;             WAIT_V(8); WAIT_L(0); BAR; MMA(1, 0, At, B0); MMA(1, 1, At, B1); BAR; SCHED;
;             LDB(B0, 1, 0); LDB(B1, 1, 1); SCHED; LDA(At, 1, 0); STAGE(SA(0, 1), a2 + hstep);
;             WAIT_V(8); WAIT_L(0); BAR; MMA(0, 0, At, B0); MMA(0, 1, At, B1); BAR; SCHED;
;             LDA(At, 1, 1); STAGE(SB(1, 0), b3); STAGE(SB(1, 1), b3 + hstep); STAGE(SA(1, 0), a3);
;             WAIT_V(8); WAIT_L(0); BAR; MMA(1, 0, At, B0); MMA(1, 1, At, B1); BAR; SCHED;
;         }
	v_readfirstlane_b32 s40, v168
	v_lshl_add_u64 v[208:209], v[208:209], 0, s[8:9]
	s_mov_b32 m0, s40
	v_readfirstlane_b32 s40, v169
	s_add_u32 s38, s38, 0x100080
	ds_read_b128 v[200:203], v179 offset:49152
	ds_read_b128 v[204:207], v179 offset:50176
	ds_read_b128 v[212:215], v180 offset:49152
	ds_read_b128 v[216:219], v180 offset:50176
	ds_read_b128 v[220:223], v181 offset:49152
	ds_read_b128 v[224:227], v181 offset:50176
	ds_read_b128 v[228:231], v182 offset:49152
	ds_read_b128 v[232:235], v182 offset:50176
	global_load_lds_dwordx4 v[208:209], off
	v_lshl_add_u64 v[208:209], v[236:237], 0, s[8:9]
	s_mov_b32 m0, s40
	s_addc_u32 s39, s39, 0
	v_readfirstlane_b32 s40, v172
	global_load_lds_dwordx4 v[208:209], off
	v_lshl_add_u64 v[208:209], s[38:39], 0, v[136:137]
	s_mov_b32 m0, s40
	s_nop 0
	global_load_lds_dwordx4 v[208:209], off
	v_lshl_add_u64 v[208:209], s[38:39], 0, v[138:139]
	v_readfirstlane_b32 s38, v173
	s_mov_b32 m0, s38
	v_readfirstlane_b32 s38, v170
	global_load_lds_dwordx4 v[208:209], off
	v_lshl_add_u64 v[208:209], v[238:239], 0, s[8:9]
	s_mov_b32 m0, s38
	v_readfirstlane_b32 s38, v171
	global_load_lds_dwordx4 v[208:209], off
	v_lshl_add_u64 v[208:209], v[240:241], 0, s[8:9]
	s_mov_b32 m0, s38
	s_nop 0
	global_load_lds_dwordx4 v[208:209], off
	s_waitcnt vmcnt(8)
	s_waitcnt lgkmcnt(0)
	s_barrier
	s_setprio 1
	s_waitcnt lgkmcnt(0)
	v_mfma_f32_16x16x32_bf16 v[60:63], v[200:203], v[132:135], v[60:63]
	v_mfma_f32_16x16x32_bf16 v[56:59], v[200:203], v[148:151], v[56:59]
	v_mfma_f32_16x16x32_bf16 v[44:47], v[212:215], v[132:135], v[44:47]
	v_mfma_f32_16x16x32_bf16 v[40:43], v[212:215], v[148:151], v[40:43]
	v_mfma_f32_16x16x32_bf16 v[28:31], v[220:223], v[132:135], v[28:31]
	v_mfma_f32_16x16x32_bf16 v[24:27], v[220:223], v[148:151], v[24:27]
	v_mfma_f32_16x16x32_bf16 v[12:15], v[228:231], v[132:135], v[12:15]
	v_mfma_f32_16x16x32_bf16 v[8:11], v[228:231], v[148:151], v[8:11]
	v_mfma_f32_16x16x32_bf16 v[60:63], v[204:207], v[144:147], v[60:63]
	v_mfma_f32_16x16x32_bf16 v[56:59], v[204:207], v[152:155], v[56:59]
	v_mfma_f32_16x16x32_bf16 v[44:47], v[216:219], v[144:147], v[44:47]
	v_mfma_f32_16x16x32_bf16 v[40:43], v[216:219], v[152:155], v[40:43]
	v_mfma_f32_16x16x32_bf16 v[28:31], v[224:227], v[144:147], v[28:31]
	v_mfma_f32_16x16x32_bf16 v[24:27], v[224:227], v[152:155], v[24:27]
	v_mfma_f32_16x16x32_bf16 v[12:15], v[232:235], v[144:147], v[12:15]
	v_mfma_f32_16x16x32_bf16 v[8:11], v[232:235], v[152:155], v[8:11]
	s_setprio 0
	s_setprio 1
	v_mfma_f32_16x16x32_bf16 v[52:55], v[200:203], v[156:159], v[52:55]
	v_mfma_f32_16x16x32_bf16 v[48:51], v[200:203], v[192:195], v[48:51]
	v_mfma_f32_16x16x32_bf16 v[36:39], v[212:215], v[156:159], v[36:39]
	v_mfma_f32_16x16x32_bf16 v[32:35], v[212:215], v[192:195], v[32:35]
	v_mfma_f32_16x16x32_bf16 v[20:23], v[220:223], v[156:159], v[20:23]
	v_mfma_f32_16x16x32_bf16 v[16:19], v[220:223], v[192:195], v[16:19]
	v_mfma_f32_16x16x32_bf16 v[4:7], v[228:231], v[156:159], v[4:7]
	v_mfma_f32_16x16x32_bf16 v[0:3], v[228:231], v[192:195], v[0:3]
	v_mfma_f32_16x16x32_bf16 v[52:55], v[204:207], v[188:191], v[52:55]
	v_mfma_f32_16x16x32_bf16 v[48:51], v[204:207], v[196:199], v[48:51]
	v_mfma_f32_16x16x32_bf16 v[36:39], v[216:219], v[188:191], v[36:39]
	v_mfma_f32_16x16x32_bf16 v[32:35], v[216:219], v[196:199], v[32:35]
	v_mfma_f32_16x16x32_bf16 v[20:23], v[224:227], v[188:191], v[20:23]
	v_mfma_f32_16x16x32_bf16 v[16:19], v[224:227], v[196:199], v[16:19]
	v_mfma_f32_16x16x32_bf16 v[4:7], v[232:235], v[188:191], v[4:7]
	v_mfma_f32_16x16x32_bf16 v[0:3], v[232:235], v[196:199], v[0:3]
	s_setprio 0
	s_add_i32 s52, s52, 2
	s_add_u32 s28, s28, 0x100
	s_addc_u32 s29, s29, 0
	s_cmp_gt_u32 s52, 61
	s_barrier
.LBB0_1930:
	ds_read_b128 v[132:135], v177
	ds_read_b128 v[144:147], v177 offset:1024
	ds_read_b128 v[148:151], v177 offset:2048
	ds_read_b128 v[152:155], v177 offset:3072
	ds_read_b128 v[156:159], v178
	ds_read_b128 v[188:191], v178 offset:1024
	ds_read_b128 v[192:195], v178 offset:2048
	ds_read_b128 v[196:199], v178 offset:3072
	s_add_u32 s38, s48, s28
	s_addc_u32 s39, s49, s29
	s_add_u32 s38, s38, 0xfa70100
	s_addc_u32 s39, s39, 0
	s_add_u32 s53, s50, s28
	s_addc_u32 s60, s51, s29
	s_cmpk_eq_i32 s28, 0x1f00
	s_cselect_b32 s41, s46, s39
	s_cselect_b32 s40, s15, s38
	s_cselect_b32 s39, s47, s60
	s_cselect_b32 s38, s13, s53
	v_readfirstlane_b32 s53, v183
	v_lshl_add_u64 v[208:209], v[128:129], 0, s[28:29]
	s_mov_b32 m0, s53
	v_readfirstlane_b32 s53, v184
	ds_read_b128 v[200:203], v179
	ds_read_b128 v[204:207], v179 offset:1024
	ds_read_b128 v[212:215], v180
	ds_read_b128 v[216:219], v180 offset:1024
	ds_read_b128 v[220:223], v181
	ds_read_b128 v[224:227], v181 offset:1024
	ds_read_b128 v[228:231], v182
	ds_read_b128 v[232:235], v182 offset:1024
	global_load_lds_dwordx4 v[208:209], off
	v_lshl_add_u64 v[208:209], v[130:131], 0, s[28:29]
	s_mov_b32 m0, s53
	s_nop 0
	global_load_lds_dwordx4 v[208:209], off
	s_waitcnt vmcnt(8)
	s_waitcnt lgkmcnt(0)
	s_barrier
; #define STAGE(P, g) do { const char* g_ = (const char*)(g); \
;         __builtin_amdgcn_global_load_lds((const unsigned*)(g_ + so0), (lds_u32*)((lds_u8*)(P) + sb0), 16, 0, 0); \
;         __builtin_amdgcn_global_load_lds((const unsigned*)(g_ + so1), (lds_u32*)((lds_u8*)(P) + sb0 + 8192), 16, 0, 0); } while (0)
; #define LDA(dst, b, h) for (int m = 0; m < 4; ++m) for (int k = 0; k < 2; ++k) \
;         dst[m][k] = *reinterpret_cast<const bf16x8*>((char*)SA(b, h) + lds_byte(wr * 64 + m * 16 + fr, k * 32 + fq * 8))
; #define LDB(dst, b, h) for (int n = 0; n < 2; ++n) for (int k = 0; k < 2; ++k) \
;         dst[n][k] = *reinterpret_cast<const bf16x8*>((char*)SB(b, h) + lds_byte(wc * 32 + n * 16 + fr, k * 32 + fq * 8))
; #define MMA(ai, bj, At_, Bt_) do { __builtin_amdgcn_s_setprio(1); \
;         for (int m = 0; m < 4; ++m) for (int n = 0; n < 2; ++n) for (int k = 0; k < 2; ++k) \
;             acc[ai][bj][m][n] = __builtin_amdgcn_mfma_f32_16x16x32_bf16(At_[m][k], Bt_[n][k], acc[ai][bj][m][n], 0, 0, 0); \
;         __builtin_amdgcn_s_setprio(0); } while (0)
; #define WAIT_V(n) asm volatile("s_waitcnt vmcnt(" #n ")" ::: "memory")
; #define WAIT_L(n) asm volatile("s_waitcnt lgkmcnt(" #n ")" ::: "memory")
; #define BAR __builtin_amdgcn_s_barrier()
; #define SCHED __builtin_amdgcn_sched_barrier(0)
; template <int EPI, int K, int LNI = -1>
; DI void ph_gemm(const Params& p, const bf16_t* __restrict__ A, const bf16_t* __restrict__ Bt, int N, float* s_aux) {
;     ...
;             LDB(B0, 0, 0); LDB(B1, 0, 1); SCHED; LDA(At, 0, 0); STAGE(SA(1, 1), a1 + hstep);
;             WAIT_V(8); WAIT_L(0); BAR; MMA(0, 0, At, B0); MMA(0, 1, At, B1); BAR; SCHED;
;             LDA(At, 0, 1); STAGE(SB(0, 0), b2); STAGE(SB(0, 1), b2 + hstep); STAGE(SA(0, 0), a2);
;             WAIT_V(8); WAIT_L(0); BAR; MMA(1, 0, At, B0); MMA(1, 1, At, B1); BAR; SCHED;
;             LDB(B0, 1, 0); LDB(B1, 1, 1); SCHED; LDA(At, 1, 0); STAGE(SA(0, 1), a2 + hstep);
;             WAIT_V(8); WAIT_L(0); BAR; MMA(0, 0, At, B0); MMA(0, 1, At, B1); BAR; SCHED;
;             LDA(At, 1, 1); STAGE(SB(1, 0), b3); STAGE(SB(1, 1), b3 + hstep); STAGE(SA(1, 0), a3);
;             WAIT_V(8); WAIT_L(0); BAR; MMA(1, 0, At, B0); MMA(1, 1, At, B1); BAR; SCHED;
	s_setprio 1
	s_waitcnt lgkmcnt(0)
	v_mfma_f32_16x16x32_bf16 v[124:127], v[200:203], v[132:135], v[124:127]
	v_mfma_f32_16x16x32_bf16 v[120:123], v[200:203], v[148:151], v[120:123]
	v_mfma_f32_16x16x32_bf16 v[108:111], v[212:215], v[132:135], v[108:111]
	v_mfma_f32_16x16x32_bf16 v[104:107], v[212:215], v[148:151], v[104:107]
	v_mfma_f32_16x16x32_bf16 v[92:95], v[220:223], v[132:135], v[92:95]
	v_mfma_f32_16x16x32_bf16 v[88:91], v[220:223], v[148:151], v[88:91]
	v_mfma_f32_16x16x32_bf16 v[76:79], v[228:231], v[132:135], v[76:79]
	v_mfma_f32_16x16x32_bf16 v[72:75], v[228:231], v[148:151], v[72:75]
	v_mfma_f32_16x16x32_bf16 v[124:127], v[204:207], v[144:147], v[124:127]
	v_mfma_f32_16x16x32_bf16 v[120:123], v[204:207], v[152:155], v[120:123]
	v_mfma_f32_16x16x32_bf16 v[108:111], v[216:219], v[144:147], v[108:111]
	v_mfma_f32_16x16x32_bf16 v[104:107], v[216:219], v[152:155], v[104:107]
	v_mfma_f32_16x16x32_bf16 v[92:95], v[224:227], v[144:147], v[92:95]
	v_mfma_f32_16x16x32_bf16 v[88:91], v[224:227], v[152:155], v[88:91]
	v_mfma_f32_16x16x32_bf16 v[76:79], v[232:235], v[144:147], v[76:79]
	v_mfma_f32_16x16x32_bf16 v[72:75], v[232:235], v[152:155], v[72:75]
	s_setprio 0
	s_setprio 1
	v_mfma_f32_16x16x32_bf16 v[116:119], v[200:203], v[156:159], v[116:119]
	v_mfma_f32_16x16x32_bf16 v[112:115], v[200:203], v[192:195], v[112:115]
	v_mfma_f32_16x16x32_bf16 v[100:103], v[212:215], v[156:159], v[100:103]
	v_mfma_f32_16x16x32_bf16 v[96:99], v[212:215], v[192:195], v[96:99]
	v_mfma_f32_16x16x32_bf16 v[84:87], v[220:223], v[156:159], v[84:87]
	v_mfma_f32_16x16x32_bf16 v[80:83], v[220:223], v[192:195], v[80:83]
	v_mfma_f32_16x16x32_bf16 v[68:71], v[228:231], v[156:159], v[68:71]
	v_mfma_f32_16x16x32_bf16 v[64:67], v[228:231], v[192:195], v[64:67]
	v_mfma_f32_16x16x32_bf16 v[116:119], v[204:207], v[188:191], v[116:119]
	v_mfma_f32_16x16x32_bf16 v[112:115], v[204:207], v[196:199], v[112:115]
	v_mfma_f32_16x16x32_bf16 v[100:103], v[216:219], v[188:191], v[100:103]
	v_mfma_f32_16x16x32_bf16 v[96:99], v[216:219], v[196:199], v[96:99]
	v_mfma_f32_16x16x32_bf16 v[84:87], v[224:227], v[188:191], v[84:87]
	v_mfma_f32_16x16x32_bf16 v[80:83], v[224:227], v[196:199], v[80:83]
	v_mfma_f32_16x16x32_bf16 v[68:71], v[232:235], v[188:191], v[68:71]
	v_mfma_f32_16x16x32_bf16 v[64:67], v[232:235], v[196:199], v[64:67]
	s_setprio 0
	s_barrier
	v_readfirstlane_b32 s53, v160
	v_lshl_add_u64 v[208:209], s[38:39], 0, v[136:137]
	s_mov_b32 m0, s53
	v_readfirstlane_b32 s53, v161
	s_add_u32 s60, s38, 0x100000
	ds_read_b128 v[200:203], v179 offset:16384
	ds_read_b128 v[204:207], v179 offset:17408
	ds_read_b128 v[212:215], v180 offset:16384
	ds_read_b128 v[216:219], v180 offset:17408
	ds_read_b128 v[220:223], v181 offset:16384
	ds_read_b128 v[224:227], v181 offset:17408
	ds_read_b128 v[228:231], v182 offset:16384
	ds_read_b128 v[232:235], v182 offset:17408
	global_load_lds_dwordx4 v[208:209], off
	v_lshl_add_u64 v[236:237], s[38:39], 0, v[138:139]
	s_mov_b32 m0, s53
	s_addc_u32 s61, s39, 0
	v_readfirstlane_b32 s53, v162
	global_load_lds_dwordx4 v[236:237], off
	v_lshl_add_u64 v[238:239], s[60:61], 0, v[136:137]
	s_mov_b32 m0, s53
	v_readfirstlane_b32 s53, v163
	global_load_lds_dwordx4 v[238:239], off
	v_lshl_add_u64 v[238:239], s[60:61], 0, v[138:139]
	s_mov_b32 m0, s53
	v_readfirstlane_b32 s53, v164
	global_load_lds_dwordx4 v[238:239], off
	v_lshl_add_u64 v[238:239], s[40:41], 0, v[136:137]
	s_mov_b32 m0, s53
	v_readfirstlane_b32 s53, v165
	global_load_lds_dwordx4 v[238:239], off
	v_lshl_add_u64 v[240:241], s[40:41], 0, v[138:139]
	s_mov_b32 m0, s53
	s_nop 0
	global_load_lds_dwordx4 v[240:241], off
	s_waitcnt vmcnt(8)
	s_waitcnt lgkmcnt(0)
	s_barrier
	s_setprio 1
	s_waitcnt lgkmcnt(0)
	v_mfma_f32_16x16x32_bf16 v[60:63], v[200:203], v[132:135], v[60:63]
	v_mfma_f32_16x16x32_bf16 v[56:59], v[200:203], v[148:151], v[56:59]
	v_mfma_f32_16x16x32_bf16 v[44:47], v[212:215], v[132:135], v[44:47]
	v_mfma_f32_16x16x32_bf16 v[40:43], v[212:215], v[148:151], v[40:43]
	v_mfma_f32_16x16x32_bf16 v[28:31], v[220:223], v[132:135], v[28:31]
	v_mfma_f32_16x16x32_bf16 v[24:27], v[220:223], v[148:151], v[24:27]
	v_mfma_f32_16x16x32_bf16 v[12:15], v[228:231], v[132:135], v[12:15]
	v_mfma_f32_16x16x32_bf16 v[8:11], v[228:231], v[148:151], v[8:11]
	v_mfma_f32_16x16x32_bf16 v[60:63], v[204:207], v[144:147], v[60:63]
	v_mfma_f32_16x16x32_bf16 v[56:59], v[204:207], v[152:155], v[56:59]
	v_mfma_f32_16x16x32_bf16 v[44:47], v[216:219], v[144:147], v[44:47]
	v_mfma_f32_16x16x32_bf16 v[40:43], v[216:219], v[152:155], v[40:43]
	v_mfma_f32_16x16x32_bf16 v[28:31], v[224:227], v[144:147], v[28:31]
	v_mfma_f32_16x16x32_bf16 v[24:27], v[224:227], v[152:155], v[24:27]
	v_mfma_f32_16x16x32_bf16 v[12:15], v[232:235], v[144:147], v[12:15]
	v_mfma_f32_16x16x32_bf16 v[8:11], v[232:235], v[152:155], v[8:11]
	s_setprio 0
	s_setprio 1
	v_mfma_f32_16x16x32_bf16 v[52:55], v[200:203], v[156:159], v[52:55]
	v_mfma_f32_16x16x32_bf16 v[48:51], v[200:203], v[192:195], v[48:51]
	v_mfma_f32_16x16x32_bf16 v[36:39], v[212:215], v[156:159], v[36:39]
	v_mfma_f32_16x16x32_bf16 v[32:35], v[212:215], v[192:195], v[32:35]
	v_mfma_f32_16x16x32_bf16 v[20:23], v[220:223], v[156:159], v[20:23]
	v_mfma_f32_16x16x32_bf16 v[16:19], v[220:223], v[192:195], v[16:19]
	v_mfma_f32_16x16x32_bf16 v[4:7], v[228:231], v[156:159], v[4:7]
	v_mfma_f32_16x16x32_bf16 v[0:3], v[228:231], v[192:195], v[0:3]
	v_mfma_f32_16x16x32_bf16 v[52:55], v[204:207], v[188:191], v[52:55]
	v_mfma_f32_16x16x32_bf16 v[48:51], v[204:207], v[196:199], v[48:51]
	v_mfma_f32_16x16x32_bf16 v[36:39], v[216:219], v[188:191], v[36:39]
	v_mfma_f32_16x16x32_bf16 v[32:35], v[216:219], v[196:199], v[32:35]
	v_mfma_f32_16x16x32_bf16 v[20:23], v[224:227], v[188:191], v[20:23]
	v_mfma_f32_16x16x32_bf16 v[16:19], v[224:227], v[196:199], v[16:19]
	v_mfma_f32_16x16x32_bf16 v[4:7], v[232:235], v[188:191], v[4:7]
	v_mfma_f32_16x16x32_bf16 v[0:3], v[232:235], v[196:199], v[0:3]
	s_setprio 0
	s_barrier
; #define STAGE(P, g) do { const char* g_ = (const char*)(g); \
;         __builtin_amdgcn_global_load_lds((const unsigned*)(g_ + so0), (lds_u32*)((lds_u8*)(P) + sb0), 16, 0, 0); \
;         __builtin_amdgcn_global_load_lds((const unsigned*)(g_ + so1), (lds_u32*)((lds_u8*)(P) + sb0 + 8192), 16, 0, 0); } while (0)
; #define LDA(dst, b, h) for (int m = 0; m < 4; ++m) for (int k = 0; k < 2; ++k) \
;         dst[m][k] = *reinterpret_cast<const bf16x8*>((char*)SA(b, h) + lds_byte(wr * 64 + m * 16 + fr, k * 32 + fq * 8))
; #define LDB(dst, b, h) for (int n = 0; n < 2; ++n) for (int k = 0; k < 2; ++k) \
;         dst[n][k] = *reinterpret_cast<const bf16x8*>((char*)SB(b, h) + lds_byte(wc * 32 + n * 16 + fr, k * 32 + fq * 8))
; #define MMA(ai, bj, At_, Bt_) do { __builtin_amdgcn_s_setprio(1); \
;         for (int m = 0; m < 4; ++m) for (int n = 0; n < 2; ++n) for (int k = 0; k < 2; ++k) \
;             acc[ai][bj][m][n] = __builtin_amdgcn_mfma_f32_16x16x32_bf16(At_[m][k], Bt_[n][k], acc[ai][bj][m][n], 0, 0, 0); \
;         __builtin_amdgcn_s_setprio(0); } while (0)
; #define WAIT_V(n) asm volatile("s_waitcnt vmcnt(" #n ")" ::: "memory")
; #define WAIT_L(n) asm volatile("s_waitcnt lgkmcnt(" #n ")" ::: "memory")
; #define BAR __builtin_amdgcn_s_barrier()
; #define SCHED __builtin_amdgcn_sched_barrier(0)
; template <int EPI, int K, int LNI = -1>
; DI void ph_gemm(const Params& p, const bf16_t* __restrict__ A, const bf16_t* __restrict__ Bt, int N, float* s_aux) {
;     ...
;             LDB(B0, 1, 0); LDB(B1, 1, 1); SCHED; LDA(At, 1, 0); STAGE(SA(0, 1), a2 + hstep);
;             WAIT_V(8); WAIT_L(0); BAR; MMA(0, 0, At, B0); MMA(0, 1, At, B1); BAR; SCHED;
	ds_read_b128 v[132:135], v185
	ds_read_b128 v[144:147], v185 offset:1024
	ds_read_b128 v[148:151], v185 offset:2048
	ds_read_b128 v[152:155], v185 offset:3072
	ds_read_b128 v[156:159], v186
	ds_read_b128 v[188:191], v186 offset:1024
	ds_read_b128 v[192:195], v186 offset:2048
	ds_read_b128 v[196:199], v186 offset:3072
	s_add_u32 s40, s40, 0x100000
	s_addc_u32 s41, s41, 0
	v_readfirstlane_b32 s53, v166
	v_lshl_add_u64 v[242:243], s[40:41], 0, v[136:137]
	s_mov_b32 m0, s53
	ds_read_b128 v[200:203], v179 offset:32768
	ds_read_b128 v[204:207], v179 offset:33792
	ds_read_b128 v[212:215], v180 offset:32768
	ds_read_b128 v[216:219], v180 offset:33792
	ds_read_b128 v[220:223], v181 offset:32768
	ds_read_b128 v[224:227], v181 offset:33792
	ds_read_b128 v[228:231], v182 offset:32768
	ds_read_b128 v[232:235], v182 offset:33792
	global_load_lds_dwordx4 v[242:243], off
	v_lshl_add_u64 v[242:243], s[40:41], 0, v[138:139]
	v_readfirstlane_b32 s40, v167
	s_mov_b32 m0, s40
	s_nop 0
	global_load_lds_dwordx4 v[242:243], off
	s_waitcnt vmcnt(8)
	s_waitcnt lgkmcnt(0)
	s_barrier
	s_setprio 1
	s_waitcnt lgkmcnt(0)
	v_mfma_f32_16x16x32_bf16 v[124:127], v[200:203], v[132:135], v[124:127]
	v_mfma_f32_16x16x32_bf16 v[120:123], v[200:203], v[148:151], v[120:123]
	v_mfma_f32_16x16x32_bf16 v[108:111], v[212:215], v[132:135], v[108:111]
	v_mfma_f32_16x16x32_bf16 v[104:107], v[212:215], v[148:151], v[104:107]
	v_mfma_f32_16x16x32_bf16 v[92:95], v[220:223], v[132:135], v[92:95]
	v_mfma_f32_16x16x32_bf16 v[88:91], v[220:223], v[148:151], v[88:91]
	v_mfma_f32_16x16x32_bf16 v[76:79], v[228:231], v[132:135], v[76:79]
	v_mfma_f32_16x16x32_bf16 v[72:75], v[228:231], v[148:151], v[72:75]
	v_mfma_f32_16x16x32_bf16 v[124:127], v[204:207], v[144:147], v[124:127]
	v_mfma_f32_16x16x32_bf16 v[120:123], v[204:207], v[152:155], v[120:123]
	v_mfma_f32_16x16x32_bf16 v[108:111], v[216:219], v[144:147], v[108:111]
	v_mfma_f32_16x16x32_bf16 v[104:107], v[216:219], v[152:155], v[104:107]
	v_mfma_f32_16x16x32_bf16 v[92:95], v[224:227], v[144:147], v[92:95]
	v_mfma_f32_16x16x32_bf16 v[88:91], v[224:227], v[152:155], v[88:91]
	v_mfma_f32_16x16x32_bf16 v[76:79], v[232:235], v[144:147], v[76:79]
	v_mfma_f32_16x16x32_bf16 v[72:75], v[232:235], v[152:155], v[72:75]
	s_setprio 0
	s_setprio 1
	v_mfma_f32_16x16x32_bf16 v[116:119], v[200:203], v[156:159], v[116:119]
	v_mfma_f32_16x16x32_bf16 v[112:115], v[200:203], v[192:195], v[112:115]
	v_mfma_f32_16x16x32_bf16 v[100:103], v[212:215], v[156:159], v[100:103]
	v_mfma_f32_16x16x32_bf16 v[96:99], v[212:215], v[192:195], v[96:99]
	v_mfma_f32_16x16x32_bf16 v[84:87], v[220:223], v[156:159], v[84:87]
	v_mfma_f32_16x16x32_bf16 v[80:83], v[220:223], v[192:195], v[80:83]
	v_mfma_f32_16x16x32_bf16 v[68:71], v[228:231], v[156:159], v[68:71]
	v_mfma_f32_16x16x32_bf16 v[64:67], v[228:231], v[192:195], v[64:67]
	v_mfma_f32_16x16x32_bf16 v[116:119], v[204:207], v[188:191], v[116:119]
	v_mfma_f32_16x16x32_bf16 v[112:115], v[204:207], v[196:199], v[112:115]
	v_mfma_f32_16x16x32_bf16 v[100:103], v[216:219], v[188:191], v[100:103]
	v_mfma_f32_16x16x32_bf16 v[96:99], v[216:219], v[196:199], v[96:99]
	v_mfma_f32_16x16x32_bf16 v[84:87], v[224:227], v[188:191], v[84:87]
	v_mfma_f32_16x16x32_bf16 v[80:83], v[224:227], v[196:199], v[80:83]
	v_mfma_f32_16x16x32_bf16 v[68:71], v[232:235], v[188:191], v[68:71]
	v_mfma_f32_16x16x32_bf16 v[64:67], v[232:235], v[196:199], v[64:67]
	s_setprio 0
	s_barrier
; #define STAGE(P, g) do { const char* g_ = (const char*)(g); \
;         __builtin_amdgcn_global_load_lds((const unsigned*)(g_ + so0), (lds_u32*)((lds_u8*)(P) + sb0), 16, 0, 0); \
;         __builtin_amdgcn_global_load_lds((const unsigned*)(g_ + so1), (lds_u32*)((lds_u8*)(P) + sb0 + 8192), 16, 0, 0); } while (0)
; #define LDA(dst, b, h) for (int m = 0; m < 4; ++m) for (int k = 0; k < 2; ++k) \
;         dst[m][k] = *reinterpret_cast<const bf16x8*>((char*)SA(b, h) + lds_byte(wr * 64 + m * 16 + fr, k * 32 + fq * 8))
; #define MMA(ai, bj, At_, Bt_) do { __builtin_amdgcn_s_setprio(1); \
;         for (int m = 0; m < 4; ++m) for (int n = 0; n < 2; ++n) for (int k = 0; k < 2; ++k) \
;             acc[ai][bj][m][n] = __builtin_amdgcn_mfma_f32_16x16x32_bf16(At_[m][k], Bt_[n][k], acc[ai][bj][m][n], 0, 0, 0); \
;         __builtin_amdgcn_s_setprio(0); } while (0)
; #define WAIT_V(n) asm volatile("s_waitcnt vmcnt(" #n ")" ::: "memory")
; #define WAIT_L(n) asm volatile("s_waitcnt lgkmcnt(" #n ")" ::: "memory")
; #define BAR __builtin_amdgcn_s_barrier()
; #define SCHED __builtin_amdgcn_sched_barrier(0)
; template <int EPI, int K, int LNI = -1>
; DI void ph_gemm(const Params& p, const bf16_t* __restrict__ A, const bf16_t* __restrict__ Bt, int N, float* s_aux) {
;     ...
;             LDA(At, 1, 1); STAGE(SB(1, 0), b3); STAGE(SB(1, 1), b3 + hstep); STAGE(SA(1, 0), a3);
;             WAIT_V(8); WAIT_L(0); BAR; MMA(1, 0, At, B0); MMA(1, 1, At, B1); BAR; SCHED;
;         }
	v_readfirstlane_b32 s40, v168
	v_lshl_add_u64 v[208:209], v[208:209], 0, s[8:9]
	s_mov_b32 m0, s40
	v_readfirstlane_b32 s40, v169
	s_add_u32 s38, s38, 0x100080
	ds_read_b128 v[200:203], v179 offset:49152
	ds_read_b128 v[204:207], v179 offset:50176
	ds_read_b128 v[212:215], v180 offset:49152
	ds_read_b128 v[216:219], v180 offset:50176
	ds_read_b128 v[220:223], v181 offset:49152
	ds_read_b128 v[224:227], v181 offset:50176
	ds_read_b128 v[228:231], v182 offset:49152
	ds_read_b128 v[232:235], v182 offset:50176
	global_load_lds_dwordx4 v[208:209], off
	v_lshl_add_u64 v[208:209], v[236:237], 0, s[8:9]
	s_mov_b32 m0, s40
	s_addc_u32 s39, s39, 0
	v_readfirstlane_b32 s40, v172
	global_load_lds_dwordx4 v[208:209], off
	v_lshl_add_u64 v[208:209], s[38:39], 0, v[136:137]
	s_mov_b32 m0, s40
	s_nop 0
	global_load_lds_dwordx4 v[208:209], off
	v_lshl_add_u64 v[208:209], s[38:39], 0, v[138:139]
	v_readfirstlane_b32 s38, v173
	s_mov_b32 m0, s38
	v_readfirstlane_b32 s38, v170
	global_load_lds_dwordx4 v[208:209], off
	v_lshl_add_u64 v[208:209], v[238:239], 0, s[8:9]
	s_mov_b32 m0, s38
	v_readfirstlane_b32 s38, v171
	global_load_lds_dwordx4 v[208:209], off
	v_lshl_add_u64 v[208:209], v[240:241], 0, s[8:9]
	s_mov_b32 m0, s38
	s_nop 0
	global_load_lds_dwordx4 v[208:209], off
	s_waitcnt vmcnt(8)
	s_waitcnt lgkmcnt(0)
	s_barrier
	s_setprio 1
	s_waitcnt lgkmcnt(0)
	v_mfma_f32_16x16x32_bf16 v[60:63], v[200:203], v[132:135], v[60:63]
	v_mfma_f32_16x16x32_bf16 v[56:59], v[200:203], v[148:151], v[56:59]
	v_mfma_f32_16x16x32_bf16 v[44:47], v[212:215], v[132:135], v[44:47]
	v_mfma_f32_16x16x32_bf16 v[40:43], v[212:215], v[148:151], v[40:43]
	v_mfma_f32_16x16x32_bf16 v[28:31], v[220:223], v[132:135], v[28:31]
	v_mfma_f32_16x16x32_bf16 v[24:27], v[220:223], v[148:151], v[24:27]
	v_mfma_f32_16x16x32_bf16 v[12:15], v[228:231], v[132:135], v[12:15]
	v_mfma_f32_16x16x32_bf16 v[8:11], v[228:231], v[148:151], v[8:11]
	v_mfma_f32_16x16x32_bf16 v[60:63], v[204:207], v[144:147], v[60:63]
	v_mfma_f32_16x16x32_bf16 v[56:59], v[204:207], v[152:155], v[56:59]
	v_mfma_f32_16x16x32_bf16 v[44:47], v[216:219], v[144:147], v[44:47]
	v_mfma_f32_16x16x32_bf16 v[40:43], v[216:219], v[152:155], v[40:43]
	v_mfma_f32_16x16x32_bf16 v[28:31], v[224:227], v[144:147], v[28:31]
	v_mfma_f32_16x16x32_bf16 v[24:27], v[224:227], v[152:155], v[24:27]
	v_mfma_f32_16x16x32_bf16 v[12:15], v[232:235], v[144:147], v[12:15]
	v_mfma_f32_16x16x32_bf16 v[8:11], v[232:235], v[152:155], v[8:11]
	s_setprio 0
	s_setprio 1
	v_mfma_f32_16x16x32_bf16 v[52:55], v[200:203], v[156:159], v[52:55]
	v_mfma_f32_16x16x32_bf16 v[48:51], v[200:203], v[192:195], v[48:51]
	v_mfma_f32_16x16x32_bf16 v[36:39], v[212:215], v[156:159], v[36:39]
	v_mfma_f32_16x16x32_bf16 v[32:35], v[212:215], v[192:195], v[32:35]
	v_mfma_f32_16x16x32_bf16 v[20:23], v[220:223], v[156:159], v[20:23]
	v_mfma_f32_16x16x32_bf16 v[16:19], v[220:223], v[192:195], v[16:19]
	v_mfma_f32_16x16x32_bf16 v[4:7], v[228:231], v[156:159], v[4:7]
	v_mfma_f32_16x16x32_bf16 v[0:3], v[228:231], v[192:195], v[0:3]
	v_mfma_f32_16x16x32_bf16 v[52:55], v[204:207], v[188:191], v[52:55]
	v_mfma_f32_16x16x32_bf16 v[48:51], v[204:207], v[196:199], v[48:51]
	v_mfma_f32_16x16x32_bf16 v[36:39], v[216:219], v[188:191], v[36:39]
	v_mfma_f32_16x16x32_bf16 v[32:35], v[216:219], v[196:199], v[32:35]
	v_mfma_f32_16x16x32_bf16 v[20:23], v[224:227], v[188:191], v[20:23]
	v_mfma_f32_16x16x32_bf16 v[16:19], v[224:227], v[196:199], v[16:19]
	v_mfma_f32_16x16x32_bf16 v[4:7], v[232:235], v[188:191], v[4:7]
	v_mfma_f32_16x16x32_bf16 v[0:3], v[232:235], v[196:199], v[0:3]
	s_setprio 0
	s_add_i32 s52, s52, 2
	s_add_u32 s28, s28, 0x100
	s_addc_u32 s29, s29, 0
	s_cmp_gt_u32 s52, 61
	s_barrier
	s_cbranch_scc0 .LBB0_1930
	s_and_saveexec_b64 s[28:29], s[6:7]
	s_cbranch_execz .LBB0_1933
	s_barrier
